# attention K/V tile loads from SGPR bases + 32-bit lane offsets (no per-tile 64-bit VALU address math) in MLA and diff loops; GEMM loops without s_setprio flips and with SGPR-base LDS-DMA
# speedup vs baseline: 1.0191x; 1.0112x over previous
; #define PG8_STAGE(bufoff, gbase, voff) do { _Pragma("unroll") for (int _i = 0; _i < 2; ++_i) \
;         __builtin_amdgcn_global_load_lds((const unsigned*)((const char*)(gbase) + (voff)[_i]), (LAS unsigned*)(lds + (bufoff) + ldsw + _i * 8192), 16, 0, 0); } while (0)
; #define PG8_LDA(dst, b, h) do { _Pragma("unroll") for (int m = 0; m < 4; ++m) _Pragma("unroll") for (int k = 0; k < 2; ++k) dst[m][k] = *(const LAS bf16x8*)(lds + PG8_SA(b, h) + aoff + m * 2048 + k * 1024); } while (0)
; #define PG8_LDB(dst, b, h) do { _Pragma("unroll") for (int n = 0; n < 2; ++n) _Pragma("unroll") for (int k = 0; k < 2; ++k) dst[n][k] = *(const LAS bf16x8*)(lds + PG8_SB(b, h) + boff + n * 2048 + k * 1024); } while (0)
; #define PG8_MMA(ai, bj, At, Bt) do { __builtin_amdgcn_s_setprio(1); _Pragma("unroll") for (int m = 0; m < 4; ++m) _Pragma("unroll") for (int n = 0; n < 2; ++n) _Pragma("unroll") for (int k = 0; k < 2; ++k) \
;         acc[ai][bj][m][n] = __builtin_amdgcn_mfma_f32_16x16x32_bf16(Bt[n][k], At[m][k], acc[ai][bj][m][n], 0, 0, 0); __builtin_amdgcn_s_setprio(0); } while (0)
; #define PG8_WAIT_V(n) asm volatile("s_waitcnt vmcnt(" #n ")" ::: "memory")
; #define PG8_WAIT_L(n) asm volatile("s_waitcnt lgkmcnt(" #n ")" ::: "memory")
; #define PG8_BAR __builtin_amdgcn_s_barrier()
; #define PG8_SCHED __builtin_amdgcn_sched_barrier(0)
; template <class Epi, class Sched>
; __device__ __forceinline__ void gemm_phase(LAS unsigned char* lds, const Gemm g, const Sched& S, const Epi& E, const int tid) {
;     ...
;             PG8_LDB(B0, 0, 0); PG8_SCHED; PG8_LDA(At, 0, 0); PG8_STAGE(PG8_SA(1, 1), a1 + hstep, voffA);
;             PG8_WAIT_L(8); PG8_BAR; PG8_WAIT_L(0); PG8_MMA(0, 0, At, B0); PG8_BAR; PG8_SCHED;
;             PG8_LDB(B1, 0, 1); PG8_STAGE(PG8_SB(0, 0), b2, voffB);
;             PG8_BAR; PG8_WAIT_L(0); PG8_MMA(0, 1, At, B1); PG8_BAR;
;             PG8_LDA(At, 0, 1); PG8_STAGE(PG8_SA(0, 0), a2, voffA);
;             PG8_BAR; PG8_WAIT_L(0); PG8_MMA(1, 0, At, B0); PG8_BAR; PG8_SCHED;
;             PG8_STAGE(PG8_SB(0, 1), b2 + hstep, voffB);
;             PG8_WAIT_V(6); PG8_BAR; PG8_MMA(1, 1, At, B1); PG8_BAR;
.LBB0_277:
	s_add_u32 s18, s16, 0xfff80080
	s_addc_u32 s19, s17, -1
	s_add_i32 s53, 0, 0x10000
	v_add_u32_e32 v156, s53, v141
	ds_read_b128 v[144:147], v156
	ds_read_b128 v[148:151], v156 offset:1024
	ds_read_b128 v[152:155], v156 offset:2048
	ds_read_b128 v[156:159], v156 offset:3072
	s_cmp_eq_u32 s52, 28
	s_cselect_b32 s21, s11, s19
	s_cselect_b32 s20, s25, s18
	s_cselect_b32 s19, s7, s51
	s_cselect_b32 s18, s49, s50
	s_add_i32 m0, s5, 0xc000
	ds_read_b128 v[160:163], v143
	ds_read_b128 v[164:167], v143 offset:1024
	ds_read_b128 v[168:171], v143 offset:2048
	ds_read_b128 v[172:175], v143 offset:3072
	ds_read_b128 v[176:179], v143 offset:4096
	ds_read_b128 v[180:183], v143 offset:5120
	ds_read_b128 v[184:187], v143 offset:6144
	global_load_lds_dwordx4 v136, s[16:17]
	s_add_i32 m0, s5, 0xe000
	ds_read_b128 v[188:191], v143 offset:7168
	global_load_lds_dwordx4 v138, s[16:17]
	s_waitcnt lgkmcnt(8)
	s_barrier
	s_waitcnt lgkmcnt(0)
	v_mfma_f32_16x16x32_bf16 v[126:129], v[144:147], v[160:163], v[126:129]
	v_mfma_f32_16x16x32_bf16 v[122:125], v[152:155], v[160:163], v[122:125]
	v_mfma_f32_16x16x32_bf16 v[118:121], v[144:147], v[168:171], v[118:121]
	v_mfma_f32_16x16x32_bf16 v[114:117], v[152:155], v[168:171], v[114:117]
	v_mfma_f32_16x16x32_bf16 v[102:105], v[144:147], v[176:179], v[102:105]
	v_mfma_f32_16x16x32_bf16 v[98:101], v[152:155], v[176:179], v[98:101]
	v_mfma_f32_16x16x32_bf16 v[86:89], v[144:147], v[184:187], v[86:89]
	v_mfma_f32_16x16x32_bf16 v[82:85], v[152:155], v[184:187], v[82:85]
	v_mfma_f32_16x16x32_bf16 v[126:129], v[148:151], v[164:167], v[126:129]
	v_mfma_f32_16x16x32_bf16 v[122:125], v[156:159], v[164:167], v[122:125]
	v_mfma_f32_16x16x32_bf16 v[118:121], v[148:151], v[172:175], v[118:121]
	v_mfma_f32_16x16x32_bf16 v[114:117], v[156:159], v[172:175], v[114:117]
	v_mfma_f32_16x16x32_bf16 v[102:105], v[148:151], v[180:183], v[102:105]
	v_mfma_f32_16x16x32_bf16 v[98:101], v[156:159], v[180:183], v[98:101]
	v_mfma_f32_16x16x32_bf16 v[86:89], v[148:151], v[188:191], v[86:89]
	v_mfma_f32_16x16x32_bf16 v[82:85], v[156:159], v[188:191], v[82:85]
	s_barrier
	s_add_i32 s56, 0, 0x14000
	s_add_i32 s53, s53, s42
	v_add_u32_e32 v204, s56, v141
	s_mov_b32 m0, s53
	ds_read_b128 v[192:195], v204
	ds_read_b128 v[196:199], v204 offset:1024
	ds_read_b128 v[200:203], v204 offset:2048
	ds_read_b128 v[204:207], v204 offset:3072
	global_load_lds_dwordx4 v0, s[18:19]
	s_add_i32 m0, s53, 0x2000
	s_nop 0
	global_load_lds_dwordx4 v134, s[18:19]
	s_barrier
	s_waitcnt lgkmcnt(0)
	v_mfma_f32_16x16x32_bf16 v[110:113], v[192:195], v[160:163], v[110:113]
	v_mfma_f32_16x16x32_bf16 v[106:109], v[200:203], v[160:163], v[106:109]
	v_mfma_f32_16x16x32_bf16 v[94:97], v[192:195], v[168:171], v[94:97]
	v_mfma_f32_16x16x32_bf16 v[90:93], v[200:203], v[168:171], v[90:93]
	v_mfma_f32_16x16x32_bf16 v[78:81], v[192:195], v[176:179], v[78:81]
	v_mfma_f32_16x16x32_bf16 v[74:77], v[200:203], v[176:179], v[74:77]
	v_mfma_f32_16x16x32_bf16 v[70:73], v[192:195], v[184:187], v[70:73]
	v_mfma_f32_16x16x32_bf16 v[66:69], v[200:203], v[184:187], v[66:69]
	v_mfma_f32_16x16x32_bf16 v[110:113], v[196:199], v[164:167], v[110:113]
	v_mfma_f32_16x16x32_bf16 v[106:109], v[204:207], v[164:167], v[106:109]
	v_mfma_f32_16x16x32_bf16 v[94:97], v[196:199], v[172:175], v[94:97]
	v_mfma_f32_16x16x32_bf16 v[90:93], v[204:207], v[172:175], v[90:93]
	v_mfma_f32_16x16x32_bf16 v[78:81], v[196:199], v[180:183], v[78:81]
	v_mfma_f32_16x16x32_bf16 v[74:77], v[204:207], v[180:183], v[74:77]
	v_mfma_f32_16x16x32_bf16 v[70:73], v[196:199], v[188:191], v[70:73]
	v_mfma_f32_16x16x32_bf16 v[66:69], v[204:207], v[188:191], v[66:69]
	s_mov_b32 m0, s5
	v_lshl_add_u64 v[214:215], s[20:21], 0, v[130:131]
	s_barrier
	ds_read_b128 v[160:163], v143 offset:16384
	ds_read_b128 v[164:167], v143 offset:17408
	ds_read_b128 v[168:171], v143 offset:18432
	ds_read_b128 v[172:175], v143 offset:19456
	ds_read_b128 v[176:179], v143 offset:20480
	ds_read_b128 v[180:183], v143 offset:21504
	ds_read_b128 v[184:187], v143 offset:22528
	ds_read_b128 v[188:191], v143 offset:23552
	global_load_lds_dwordx4 v[214:215], off
	s_mov_b32 m0, s43
	v_lshl_add_u64 v[216:217], s[20:21], 0, v[132:133]
	global_load_lds_dwordx4 v[216:217], off
	s_barrier
	s_waitcnt lgkmcnt(0)
	v_mfma_f32_16x16x32_bf16 v[62:65], v[144:147], v[160:163], v[62:65]
	v_mfma_f32_16x16x32_bf16 v[58:61], v[152:155], v[160:163], v[58:61]
	v_mfma_f32_16x16x32_bf16 v[54:57], v[144:147], v[168:171], v[54:57]
	v_mfma_f32_16x16x32_bf16 v[50:53], v[152:155], v[168:171], v[50:53]
	v_mfma_f32_16x16x32_bf16 v[38:41], v[144:147], v[176:179], v[38:41]
	v_mfma_f32_16x16x32_bf16 v[34:37], v[152:155], v[176:179], v[34:37]
	v_mfma_f32_16x16x32_bf16 v[22:25], v[144:147], v[184:187], v[22:25]
	v_mfma_f32_16x16x32_bf16 v[18:21], v[152:155], v[184:187], v[18:21]
	v_mfma_f32_16x16x32_bf16 v[62:65], v[148:151], v[164:167], v[62:65]
	v_mfma_f32_16x16x32_bf16 v[58:61], v[156:159], v[164:167], v[58:61]
	v_mfma_f32_16x16x32_bf16 v[54:57], v[148:151], v[172:175], v[54:57]
	v_mfma_f32_16x16x32_bf16 v[50:53], v[156:159], v[172:175], v[50:53]
	v_mfma_f32_16x16x32_bf16 v[38:41], v[148:151], v[180:183], v[38:41]
	v_mfma_f32_16x16x32_bf16 v[34:37], v[156:159], v[180:183], v[34:37]
	v_mfma_f32_16x16x32_bf16 v[22:25], v[148:151], v[188:191], v[22:25]
	v_mfma_f32_16x16x32_bf16 v[18:21], v[156:159], v[188:191], v[18:21]
	s_barrier
	s_add_u32 s54, s18, 0x80000
	s_addc_u32 s55, s19, 0
	s_add_i32 s53, s56, s42
	s_mov_b32 m0, s53
	s_nop 0
	global_load_lds_dwordx4 v0, s[54:55]
	s_add_i32 m0, s53, 0x2000
	s_nop 0
	global_load_lds_dwordx4 v134, s[54:55]
	s_waitcnt vmcnt(6)
	s_barrier
; #define PG8_STAGE(bufoff, gbase, voff) do { _Pragma("unroll") for (int _i = 0; _i < 2; ++_i) \
;         __builtin_amdgcn_global_load_lds((const unsigned*)((const char*)(gbase) + (voff)[_i]), (LAS unsigned*)(lds + (bufoff) + ldsw + _i * 8192), 16, 0, 0); } while (0)
; #define PG8_LDA(dst, b, h) do { _Pragma("unroll") for (int m = 0; m < 4; ++m) _Pragma("unroll") for (int k = 0; k < 2; ++k) dst[m][k] = *(const LAS bf16x8*)(lds + PG8_SA(b, h) + aoff + m * 2048 + k * 1024); } while (0)
; #define PG8_LDB(dst, b, h) do { _Pragma("unroll") for (int n = 0; n < 2; ++n) _Pragma("unroll") for (int k = 0; k < 2; ++k) dst[n][k] = *(const LAS bf16x8*)(lds + PG8_SB(b, h) + boff + n * 2048 + k * 1024); } while (0)
; #define PG8_MMA(ai, bj, At, Bt) do { __builtin_amdgcn_s_setprio(1); _Pragma("unroll") for (int m = 0; m < 4; ++m) _Pragma("unroll") for (int n = 0; n < 2; ++n) _Pragma("unroll") for (int k = 0; k < 2; ++k) \
;         acc[ai][bj][m][n] = __builtin_amdgcn_mfma_f32_16x16x32_bf16(Bt[n][k], At[m][k], acc[ai][bj][m][n], 0, 0, 0); __builtin_amdgcn_s_setprio(0); } while (0)
; #define PG8_WAIT_V(n) asm volatile("s_waitcnt vmcnt(" #n ")" ::: "memory")
; #define PG8_WAIT_L(n) asm volatile("s_waitcnt lgkmcnt(" #n ")" ::: "memory")
; #define PG8_BAR __builtin_amdgcn_s_barrier()
; #define PG8_SCHED __builtin_amdgcn_sched_barrier(0)
; template <class Epi, class Sched>
; __device__ __forceinline__ void gemm_phase(LAS unsigned char* lds, const Gemm g, const Sched& S, const Epi& E, const int tid) {
;     ...
;             PG8_BAR; PG8_WAIT_L(0); PG8_MMA(1, 0, At, B0); PG8_BAR; PG8_SCHED;
;             PG8_STAGE(PG8_SB(0, 1), b2 + hstep, voffB);
;             PG8_WAIT_V(6); PG8_BAR; PG8_MMA(1, 1, At, B1); PG8_BAR;
;             PG8_LDB(B0, 1, 0); PG8_SCHED; PG8_LDA(At, 1, 0); PG8_STAGE(PG8_SA(0, 1), a2 + hstep, voffA);
;             PG8_WAIT_L(8); PG8_BAR; PG8_WAIT_L(0); PG8_MMA(0, 0, At, B0); PG8_BAR; PG8_SCHED;
;             PG8_LDB(B1, 1, 1); PG8_STAGE(PG8_SB(1, 0), b3, voffB);
;             PG8_BAR; PG8_WAIT_L(0); PG8_MMA(0, 1, At, B1); PG8_BAR;
;             PG8_LDA(At, 1, 1); PG8_STAGE(PG8_SA(1, 0), a3, voffA);
	v_mfma_f32_16x16x32_bf16 v[46:49], v[192:195], v[160:163], v[46:49]
	v_mfma_f32_16x16x32_bf16 v[42:45], v[200:203], v[160:163], v[42:45]
	v_mfma_f32_16x16x32_bf16 v[30:33], v[192:195], v[168:171], v[30:33]
	v_mfma_f32_16x16x32_bf16 v[26:29], v[200:203], v[168:171], v[26:29]
	v_mfma_f32_16x16x32_bf16 v[14:17], v[192:195], v[176:179], v[14:17]
	v_mfma_f32_16x16x32_bf16 v[10:13], v[200:203], v[176:179], v[10:13]
	v_mfma_f32_16x16x32_bf16 v[6:9], v[192:195], v[184:187], v[6:9]
	v_mfma_f32_16x16x32_bf16 v[2:5], v[200:203], v[184:187], v[2:5]
	v_mfma_f32_16x16x32_bf16 v[46:49], v[196:199], v[164:167], v[46:49]
	v_mfma_f32_16x16x32_bf16 v[42:45], v[204:207], v[164:167], v[42:45]
	v_mfma_f32_16x16x32_bf16 v[30:33], v[196:199], v[172:175], v[30:33]
	v_mfma_f32_16x16x32_bf16 v[26:29], v[204:207], v[172:175], v[26:29]
	v_mfma_f32_16x16x32_bf16 v[14:17], v[196:199], v[180:183], v[14:17]
	v_mfma_f32_16x16x32_bf16 v[10:13], v[204:207], v[180:183], v[10:13]
	v_mfma_f32_16x16x32_bf16 v[6:9], v[196:199], v[188:191], v[6:9]
	v_mfma_f32_16x16x32_bf16 v[2:5], v[204:207], v[188:191], v[2:5]
	s_add_i32 s53, 0, 0x18000
	v_add_u32_e32 v156, s53, v141
	s_barrier
	ds_read_b128 v[144:147], v156
	ds_read_b128 v[148:151], v156 offset:1024
	ds_read_b128 v[152:155], v156 offset:2048
	ds_read_b128 v[156:159], v156 offset:3072
	s_add_u32 s20, s20, 0x80000
	s_addc_u32 s21, s21, 0
	s_mov_b32 m0, s44
	ds_read_b128 v[160:163], v143 offset:32768
	ds_read_b128 v[164:167], v143 offset:33792
	ds_read_b128 v[168:171], v143 offset:34816
	ds_read_b128 v[172:175], v143 offset:35840
	ds_read_b128 v[176:179], v143 offset:36864
	ds_read_b128 v[180:183], v143 offset:37888
	ds_read_b128 v[184:187], v143 offset:38912
	global_load_lds_dwordx4 v130, s[20:21]
	s_mov_b32 m0, s45
	ds_read_b128 v[188:191], v143 offset:39936
	global_load_lds_dwordx4 v132, s[20:21]
	s_waitcnt lgkmcnt(8)
	s_barrier
	s_waitcnt lgkmcnt(0)
	v_mfma_f32_16x16x32_bf16 v[126:129], v[144:147], v[160:163], v[126:129]
	v_mfma_f32_16x16x32_bf16 v[122:125], v[152:155], v[160:163], v[122:125]
	v_mfma_f32_16x16x32_bf16 v[118:121], v[144:147], v[168:171], v[118:121]
	v_mfma_f32_16x16x32_bf16 v[114:117], v[152:155], v[168:171], v[114:117]
	v_mfma_f32_16x16x32_bf16 v[102:105], v[144:147], v[176:179], v[102:105]
	v_mfma_f32_16x16x32_bf16 v[98:101], v[152:155], v[176:179], v[98:101]
	v_mfma_f32_16x16x32_bf16 v[86:89], v[144:147], v[184:187], v[86:89]
	v_mfma_f32_16x16x32_bf16 v[82:85], v[152:155], v[184:187], v[82:85]
	v_mfma_f32_16x16x32_bf16 v[126:129], v[148:151], v[164:167], v[126:129]
	v_mfma_f32_16x16x32_bf16 v[122:125], v[156:159], v[164:167], v[122:125]
	v_mfma_f32_16x16x32_bf16 v[118:121], v[148:151], v[172:175], v[118:121]
	v_mfma_f32_16x16x32_bf16 v[114:117], v[156:159], v[172:175], v[114:117]
	v_mfma_f32_16x16x32_bf16 v[102:105], v[148:151], v[180:183], v[102:105]
	v_mfma_f32_16x16x32_bf16 v[98:101], v[156:159], v[180:183], v[98:101]
	v_mfma_f32_16x16x32_bf16 v[86:89], v[148:151], v[188:191], v[86:89]
	v_mfma_f32_16x16x32_bf16 v[82:85], v[156:159], v[188:191], v[82:85]
	s_barrier
	s_add_i32 s20, 0, 0x1c000
	s_add_i32 s21, s53, s42
	v_add_u32_e32 v204, s20, v141
	s_add_u32 s98, s18, s36
	s_addc_u32 s99, s19, s37
	s_mov_b32 m0, s21
	ds_read_b128 v[192:195], v204
	ds_read_b128 v[196:199], v204 offset:1024
	ds_read_b128 v[200:203], v204 offset:2048
	ds_read_b128 v[204:207], v204 offset:3072
	global_load_lds_dwordx4 v0, s[98:99]
	s_add_i32 m0, s21, 0x2000
	s_add_u32 s98, s18, s36
	s_addc_u32 s99, s19, s37
	global_load_lds_dwordx4 v134, s[98:99]
	s_barrier
	s_waitcnt lgkmcnt(0)
	v_mfma_f32_16x16x32_bf16 v[110:113], v[192:195], v[160:163], v[110:113]
	v_mfma_f32_16x16x32_bf16 v[106:109], v[200:203], v[160:163], v[106:109]
	v_mfma_f32_16x16x32_bf16 v[94:97], v[192:195], v[168:171], v[94:97]
	v_mfma_f32_16x16x32_bf16 v[90:93], v[200:203], v[168:171], v[90:93]
	v_mfma_f32_16x16x32_bf16 v[78:81], v[192:195], v[176:179], v[78:81]
	v_mfma_f32_16x16x32_bf16 v[74:77], v[200:203], v[176:179], v[74:77]
	v_mfma_f32_16x16x32_bf16 v[70:73], v[192:195], v[184:187], v[70:73]
	v_mfma_f32_16x16x32_bf16 v[66:69], v[200:203], v[184:187], v[66:69]
	v_mfma_f32_16x16x32_bf16 v[110:113], v[196:199], v[164:167], v[110:113]
	v_mfma_f32_16x16x32_bf16 v[106:109], v[204:207], v[164:167], v[106:109]
	v_mfma_f32_16x16x32_bf16 v[94:97], v[196:199], v[172:175], v[94:97]
	v_mfma_f32_16x16x32_bf16 v[90:93], v[204:207], v[172:175], v[90:93]
	v_mfma_f32_16x16x32_bf16 v[78:81], v[196:199], v[180:183], v[78:81]
	v_mfma_f32_16x16x32_bf16 v[74:77], v[204:207], v[180:183], v[74:77]
	v_mfma_f32_16x16x32_bf16 v[70:73], v[196:199], v[188:191], v[70:73]
	v_mfma_f32_16x16x32_bf16 v[66:69], v[204:207], v[188:191], v[66:69]
	s_mov_b32 m0, s28
	v_lshl_add_u64 v[208:209], v[214:215], 0, s[36:37]
	s_barrier
	ds_read_b128 v[160:163], v143 offset:49152
	ds_read_b128 v[164:167], v143 offset:50176
	ds_read_b128 v[168:171], v143 offset:51200
	ds_read_b128 v[172:175], v143 offset:52224
	ds_read_b128 v[176:179], v143 offset:53248
	ds_read_b128 v[180:183], v143 offset:54272
	ds_read_b128 v[184:187], v143 offset:55296
	ds_read_b128 v[188:191], v143 offset:56320
	global_load_lds_dwordx4 v[208:209], off
	s_mov_b32 m0, s29
	v_lshl_add_u64 v[208:209], v[216:217], 0, s[36:37]
	global_load_lds_dwordx4 v[208:209], off
	s_barrier
; #define PG8_STAGE(bufoff, gbase, voff) do { _Pragma("unroll") for (int _i = 0; _i < 2; ++_i) \
;         __builtin_amdgcn_global_load_lds((const unsigned*)((const char*)(gbase) + (voff)[_i]), (LAS unsigned*)(lds + (bufoff) + ldsw + _i * 8192), 16, 0, 0); } while (0)
; #define PG8_LDA(dst, b, h) do { _Pragma("unroll") for (int m = 0; m < 4; ++m) _Pragma("unroll") for (int k = 0; k < 2; ++k) dst[m][k] = *(const LAS bf16x8*)(lds + PG8_SA(b, h) + aoff + m * 2048 + k * 1024); } while (0)
; #define PG8_LDB(dst, b, h) do { _Pragma("unroll") for (int n = 0; n < 2; ++n) _Pragma("unroll") for (int k = 0; k < 2; ++k) dst[n][k] = *(const LAS bf16x8*)(lds + PG8_SB(b, h) + boff + n * 2048 + k * 1024); } while (0)
; #define PG8_MMA(ai, bj, At, Bt) do { __builtin_amdgcn_s_setprio(1); _Pragma("unroll") for (int m = 0; m < 4; ++m) _Pragma("unroll") for (int n = 0; n < 2; ++n) _Pragma("unroll") for (int k = 0; k < 2; ++k) \
;         acc[ai][bj][m][n] = __builtin_amdgcn_mfma_f32_16x16x32_bf16(Bt[n][k], At[m][k], acc[ai][bj][m][n], 0, 0, 0); __builtin_amdgcn_s_setprio(0); } while (0)
; #define PG8_WAIT_V(n) asm volatile("s_waitcnt vmcnt(" #n ")" ::: "memory")
; #define PG8_WAIT_L(n) asm volatile("s_waitcnt lgkmcnt(" #n ")" ::: "memory")
; #define PG8_BAR __builtin_amdgcn_s_barrier()
; #define PG8_SCHED __builtin_amdgcn_sched_barrier(0)
; template <class Epi, class Sched>
; __device__ __forceinline__ void gemm_phase(LAS unsigned char* lds, const Gemm g, const Sched& S, const Epi& E, const int tid) {
;     ...
;             PG8_WAIT_L(8); PG8_BAR; PG8_WAIT_L(0); PG8_MMA(0, 0, At, B0); PG8_BAR; PG8_SCHED;
;             PG8_LDB(B1, 1, 1); PG8_STAGE(PG8_SB(1, 0), b3, voffB);
;             PG8_BAR; PG8_WAIT_L(0); PG8_MMA(0, 1, At, B1); PG8_BAR;
;             PG8_LDA(At, 1, 1); PG8_STAGE(PG8_SA(1, 0), a3, voffA);
;             PG8_BAR; PG8_WAIT_L(0); PG8_MMA(1, 0, At, B0); PG8_BAR; PG8_SCHED;
;             PG8_STAGE(PG8_SB(1, 1), b3 + hstep, voffB);
;             PG8_WAIT_V(6); PG8_BAR; PG8_MMA(1, 1, At, B1); PG8_BAR;
;         }
	s_waitcnt lgkmcnt(0)
	v_mfma_f32_16x16x32_bf16 v[62:65], v[144:147], v[160:163], v[62:65]
	v_mfma_f32_16x16x32_bf16 v[58:61], v[152:155], v[160:163], v[58:61]
	v_mfma_f32_16x16x32_bf16 v[54:57], v[144:147], v[168:171], v[54:57]
	v_mfma_f32_16x16x32_bf16 v[50:53], v[152:155], v[168:171], v[50:53]
	v_mfma_f32_16x16x32_bf16 v[38:41], v[144:147], v[176:179], v[38:41]
	v_mfma_f32_16x16x32_bf16 v[34:37], v[152:155], v[176:179], v[34:37]
	v_mfma_f32_16x16x32_bf16 v[22:25], v[144:147], v[184:187], v[22:25]
	v_mfma_f32_16x16x32_bf16 v[18:21], v[152:155], v[184:187], v[18:21]
	v_mfma_f32_16x16x32_bf16 v[62:65], v[148:151], v[164:167], v[62:65]
	v_mfma_f32_16x16x32_bf16 v[58:61], v[156:159], v[164:167], v[58:61]
	v_mfma_f32_16x16x32_bf16 v[54:57], v[148:151], v[172:175], v[54:57]
	v_mfma_f32_16x16x32_bf16 v[50:53], v[156:159], v[172:175], v[50:53]
	v_mfma_f32_16x16x32_bf16 v[38:41], v[148:151], v[180:183], v[38:41]
	v_mfma_f32_16x16x32_bf16 v[34:37], v[156:159], v[180:183], v[34:37]
	v_mfma_f32_16x16x32_bf16 v[22:25], v[148:151], v[188:191], v[22:25]
	v_mfma_f32_16x16x32_bf16 v[18:21], v[156:159], v[188:191], v[18:21]
	s_barrier
	s_add_u32 s18, s18, 0x80080
	s_addc_u32 s19, s19, 0
	s_add_i32 s20, s20, s42
	s_mov_b32 m0, s20
	s_nop 0
	global_load_lds_dwordx4 v0, s[18:19]
	s_add_i32 m0, s20, 0x2000
	s_nop 0
	global_load_lds_dwordx4 v134, s[18:19]
	s_waitcnt vmcnt(6)
	s_barrier
	v_mfma_f32_16x16x32_bf16 v[46:49], v[192:195], v[160:163], v[46:49]
	v_mfma_f32_16x16x32_bf16 v[42:45], v[200:203], v[160:163], v[42:45]
	v_mfma_f32_16x16x32_bf16 v[30:33], v[192:195], v[168:171], v[30:33]
	v_mfma_f32_16x16x32_bf16 v[26:29], v[200:203], v[168:171], v[26:29]
	v_mfma_f32_16x16x32_bf16 v[14:17], v[192:195], v[176:179], v[14:17]
	v_mfma_f32_16x16x32_bf16 v[10:13], v[200:203], v[176:179], v[10:13]
	v_mfma_f32_16x16x32_bf16 v[6:9], v[192:195], v[184:187], v[6:9]
	v_mfma_f32_16x16x32_bf16 v[2:5], v[200:203], v[184:187], v[2:5]
	v_mfma_f32_16x16x32_bf16 v[46:49], v[196:199], v[164:167], v[46:49]
	v_mfma_f32_16x16x32_bf16 v[42:45], v[204:207], v[164:167], v[42:45]
	v_mfma_f32_16x16x32_bf16 v[30:33], v[196:199], v[172:175], v[30:33]
	v_mfma_f32_16x16x32_bf16 v[26:29], v[204:207], v[172:175], v[26:29]
	v_mfma_f32_16x16x32_bf16 v[14:17], v[196:199], v[180:183], v[14:17]
	v_mfma_f32_16x16x32_bf16 v[10:13], v[204:207], v[180:183], v[10:13]
	v_mfma_f32_16x16x32_bf16 v[6:9], v[196:199], v[188:191], v[6:9]
	v_mfma_f32_16x16x32_bf16 v[2:5], v[204:207], v[188:191], v[2:5]
	s_add_i32 s52, s52, 2
	s_add_u32 s16, s16, 0x100
	s_addc_u32 s17, s17, 0
	s_add_u32 s50, s50, 0x100
	s_addc_u32 s51, s51, 0
	s_cmp_gt_u32 s52, 29
	s_barrier
	s_cbranch_scc0 .LBB0_277
; DI unsigned cvtpk(float lo, float hi) { const f32x2 v = {lo, hi}; const bf16x2n r = __builtin_convertvector(v, bf16x2n); return __builtin_bit_cast(unsigned, r); }
;     __device__ __forceinline__ void operator()(const f32x4 (&acc)[2][2][4][2], const Unit& u, int wr, int wc, int fr, int fq) const {
;     ...
; #pragma unroll
;         for (int ai = 0; ai < 2; ++ai)
; #pragma unroll
;             for (int m = 0; m < 4; ++m) { bf16_t* rowp = O + (size_t)(row0 + ai * HALF + m * 16) * ldc + col0;
; #pragma unroll
;                 for (int bj = 0; bj < 2; ++bj) { const f32x4 v0 = acc[ai][bj][m][0], v1 = acc[ai][bj][m][1];
;                     u32x4 w; w.x = cvtpk(v0[0], v0[1]); w.y = cvtpk(v0[2], v0[3]); w.z = cvtpk(v1[0], v1[1]); w.w = cvtpk(v1[2], v1[3]);
;                     *(u32x4*)(rowp + bj * HALF) = w; } }
; template <class Epi, class Sched>
; __device__ __forceinline__ void gemm_phase(LAS unsigned char* lds, const Gemm g, const Sched& S, const Epi& E, const int tid) {
;     ...
;         if constexpr (!Epi::AFTER_DRAIN) { if constexpr (Epi::PRELOAD) E(acc, cur, wr, wc, fr, fq, lds); else E(acc, cur, wr, wc, fr, fq); S.done(cur); }
;         if (!has_next) break;
; #pragma unroll
;         for (int a = 0; a < 2; ++a)
; #pragma unroll
;             for (int b = 0; b < 2; ++b)
; #pragma unroll
;                 for (int m = 0; m < 4; ++m)
; #pragma unroll
;                     for (int n = 0; n < 2; ++n) acc[a][b][m][n] = (f32x4){0.f, 0.f, 0.f, 0.f};
;         cur = nxt; cA = nA; cB = nB; ++ui;
	v_lshl_or_b32 v144, s24, 8, v142
	v_lshl_add_u32 v150, s4, 8, v140
	v_ashrrev_i32_e32 v145, 31, v144
	v_mov_b64_e32 v[146:147], s[2:3]
	s_movk_i32 s4, 0x2e00
	v_cvt_pk_bf16_f32 v70, v70, v71
	v_cvt_pk_bf16_f32 v71, v72, v73
	v_cvt_pk_bf16_f32 v72, v66, v67
	v_add_u32_e32 v66, 0x80, v150
	v_mad_i64_i32 v[148:149], s[16:17], v150, s4, v[146:147]
	v_lshlrev_b64 v[144:145], 1, v[144:145]
	v_cvt_pk_bf16_f32 v110, v110, v111
	v_cvt_pk_bf16_f32 v111, v112, v113
	v_cvt_pk_bf16_f32 v112, v106, v107
	v_or_b32_e32 v106, 16, v150
	v_mad_i64_i32 v[66:67], s[16:17], v66, s4, v[146:147]
	v_cvt_pk_bf16_f32 v46, v46, v47
	v_cvt_pk_bf16_f32 v47, v48, v49
	v_cvt_pk_bf16_f32 v48, v42, v43
	v_add_u32_e32 v42, 0x90, v150
	v_lshl_add_u64 v[148:149], v[148:149], 0, v[144:145]
	v_cvt_pk_bf16_f32 v113, v108, v109
	v_mad_i64_i32 v[106:107], s[16:17], v106, s4, v[146:147]
	v_cvt_pk_bf16_f32 v94, v94, v95
	v_cvt_pk_bf16_f32 v95, v96, v97
	v_cvt_pk_bf16_f32 v96, v90, v91
	v_or_b32_e32 v90, 32, v150
	v_lshl_add_u64 v[66:67], v[66:67], 0, v[144:145]
	v_cvt_pk_bf16_f32 v49, v44, v45
	v_mad_i64_i32 v[42:43], s[16:17], v42, s4, v[146:147]
	v_cvt_pk_bf16_f32 v30, v30, v31
	v_cvt_pk_bf16_f32 v31, v32, v33
	v_cvt_pk_bf16_f32 v32, v26, v27
	v_add_u32_e32 v26, 0xa0, v150
	global_store_dwordx4 v[148:149], v[110:113], off offset:256
	v_cvt_pk_bf16_f32 v97, v92, v93
	v_mad_i64_i32 v[90:91], s[16:17], v90, s4, v[146:147]
	v_lshl_add_u64 v[110:111], v[106:107], 0, v[144:145]
	v_cvt_pk_bf16_f32 v78, v78, v79
	v_cvt_pk_bf16_f32 v79, v80, v81
	v_cvt_pk_bf16_f32 v80, v74, v75
	v_or_b32_e32 v74, 48, v150
	global_store_dwordx4 v[66:67], v[46:49], off offset:256
	v_cvt_pk_bf16_f32 v33, v28, v29
	v_mad_i64_i32 v[26:27], s[16:17], v26, s4, v[146:147]
	v_lshl_add_u64 v[46:47], v[42:43], 0, v[144:145]
	v_cvt_pk_bf16_f32 v14, v14, v15
	v_cvt_pk_bf16_f32 v15, v16, v17
	v_cvt_pk_bf16_f32 v16, v10, v11
	v_add_u32_e32 v10, 0xb0, v150
	global_store_dwordx4 v[110:111], v[94:97], off offset:256
	v_cvt_pk_bf16_f32 v81, v76, v77
	v_mad_i64_i32 v[74:75], s[16:17], v74, s4, v[146:147]
	v_lshl_add_u64 v[94:95], v[90:91], 0, v[144:145]
	global_store_dwordx4 v[46:47], v[30:33], off offset:256
	v_cvt_pk_bf16_f32 v17, v12, v13
	v_mad_i64_i32 v[10:11], s[16:17], v10, s4, v[146:147]
	v_lshl_add_u64 v[30:31], v[26:27], 0, v[144:145]
	v_cvt_pk_bf16_f32 v126, v126, v127
	v_cvt_pk_bf16_f32 v127, v128, v129
	v_cvt_pk_bf16_f32 v128, v122, v123
	v_cvt_pk_bf16_f32 v129, v124, v125
	v_cvt_pk_bf16_f32 v106, v118, v119
	v_cvt_pk_bf16_f32 v107, v120, v121
	v_cvt_pk_bf16_f32 v108, v114, v115
	v_cvt_pk_bf16_f32 v109, v116, v117
	v_cvt_pk_bf16_f32 v90, v102, v103
	v_cvt_pk_bf16_f32 v91, v104, v105
	v_cvt_pk_bf16_f32 v92, v98, v99
	v_cvt_pk_bf16_f32 v93, v100, v101
	global_store_dwordx4 v[94:95], v[78:81], off offset:256
	v_cvt_pk_bf16_f32 v76, v82, v83
	v_cvt_pk_bf16_f32 v77, v84, v85
	v_lshl_add_u64 v[78:79], v[74:75], 0, v[144:145]
	v_cvt_pk_bf16_f32 v74, v86, v87
	v_cvt_pk_bf16_f32 v75, v88, v89
	v_cvt_pk_bf16_f32 v73, v68, v69
	v_cvt_pk_bf16_f32 v62, v62, v63
	v_cvt_pk_bf16_f32 v63, v64, v65
	v_cvt_pk_bf16_f32 v64, v58, v59
	v_cvt_pk_bf16_f32 v65, v60, v61
	v_cvt_pk_bf16_f32 v42, v54, v55
	v_cvt_pk_bf16_f32 v43, v56, v57
	v_cvt_pk_bf16_f32 v44, v50, v51
	v_cvt_pk_bf16_f32 v45, v52, v53
	v_cvt_pk_bf16_f32 v26, v38, v39
	v_cvt_pk_bf16_f32 v27, v40, v41
	v_cvt_pk_bf16_f32 v28, v34, v35
	v_cvt_pk_bf16_f32 v29, v36, v37
	global_store_dwordx4 v[30:31], v[14:17], off offset:256
	v_cvt_pk_bf16_f32 v12, v18, v19
	v_cvt_pk_bf16_f32 v13, v20, v21
	v_lshl_add_u64 v[14:15], v[10:11], 0, v[144:145]
	v_cvt_pk_bf16_f32 v10, v22, v23
	v_cvt_pk_bf16_f32 v11, v24, v25
	v_cvt_pk_bf16_f32 v6, v6, v7
	v_cvt_pk_bf16_f32 v7, v8, v9
	v_cvt_pk_bf16_f32 v8, v2, v3
	v_cvt_pk_bf16_f32 v9, v4, v5
	s_and_b64 vcc, exec, s[0:1]
	s_mov_b32 s24, s6
	s_mov_b32 s4, s10
	s_mov_b64 s[18:19], s[14:15]
	s_mov_b64 s[16:17], s[12:13]
	s_mov_b64 s[52:53], 0xc000
	s_mov_b64 s[54:55], 0x8000
	global_store_dwordx4 v[148:149], v[126:129], off
	global_store_dwordx4 v[110:111], v[106:109], off
	global_store_dwordx4 v[94:95], v[90:93], off
	global_store_dwordx4 v[78:79], v[74:77], off
	global_store_dwordx4 v[78:79], v[70:73], off offset:256
	global_store_dwordx4 v[66:67], v[62:65], off
	global_store_dwordx4 v[46:47], v[42:45], off
	global_store_dwordx4 v[30:31], v[26:29], off
	global_store_dwordx4 v[14:15], v[10:13], off
	global_store_dwordx4 v[14:15], v[6:9], off offset:256
	s_cbranch_vccz .LBB0_270
	s_waitcnt vmcnt(0)
	s_cmpk_gt_u32 s22, 0xff
	s_cbranch_scc1 .LBB0_281
	s_barrier

; #define PG8_STAGE(bufoff, gbase, voff) do { _Pragma("unroll") for (int _i = 0; _i < 2; ++_i) \
;         __builtin_amdgcn_global_load_lds((const unsigned*)((const char*)(gbase) + (voff)[_i]), (LAS unsigned*)(lds + (bufoff) + ldsw + _i * 8192), 16, 0, 0); } while (0)
; #define PG8_LDA(dst, b, h) do { _Pragma("unroll") for (int m = 0; m < 4; ++m) _Pragma("unroll") for (int k = 0; k < 2; ++k) dst[m][k] = *(const LAS bf16x8*)(lds + PG8_SA(b, h) + aoff + m * 2048 + k * 1024); } while (0)
; #define PG8_LDB(dst, b, h) do { _Pragma("unroll") for (int n = 0; n < 2; ++n) _Pragma("unroll") for (int k = 0; k < 2; ++k) dst[n][k] = *(const LAS bf16x8*)(lds + PG8_SB(b, h) + boff + n * 2048 + k * 1024); } while (0)
; #define PG8_WAIT_V(n) asm volatile("s_waitcnt vmcnt(" #n ")" ::: "memory")
; template <class Epi, class Sched>
; __device__ __forceinline__ void gemm_phase(LAS unsigned char* lds, const Gemm g, const Sched& S, const Epi& E, const int tid) {
;     ...
;         const bool has_next = S.next(ui + 1, nxt);
;         const char* nA = has_next ? (const char*)g.A + (size_t)nxt.pm * tstep + (size_t)nxt.ks * nxt.nt * kstep : cA; const char* nB = has_next ? (const char*)g.Bt + (size_t)nxt.pn * tstep + (size_t)nxt.ks * nxt.nt * kstep : cB;
;         const int nt = cur.nt;
;         for (int t = 0; t < nt; t += 2) {
;             const bool last = (t == nt - 2);
;             const char* a1 = cA + (size_t)(t + 1) * kstep;
;             const char* a2 = last ? nA : cA + (size_t)(t + 2) * kstep; const char* b2 = last ? nB : cB + (size_t)(t + 2) * kstep;
;             const char* a3 = a2 + kstep; const char* b3 = b2 + kstep;
;             if (last && has_next) S.a_ready(nxt);
;             if constexpr (Epi::PRELOAD) { if (last) E.preload(cur, lds, wid, lane); }
;             PG8_LDB(B0, 0, 0); PG8_SCHED; PG8_LDA(At, 0, 0); PG8_STAGE(PG8_SA(1, 1), a1 + hstep, voffA);
;             PG8_WAIT_L(8); PG8_BAR; PG8_WAIT_L(0); PG8_MMA(0, 0, At, B0); PG8_BAR; PG8_SCHED;
;             PG8_LDB(B1, 0, 1); PG8_STAGE(PG8_SB(0, 0), b2, voffB);
;             PG8_BAR; PG8_WAIT_L(0); PG8_MMA(0, 1, At, B1); PG8_BAR;
;             PG8_LDA(At, 0, 1); PG8_STAGE(PG8_SA(0, 0), a2, voffA);
;             PG8_BAR; PG8_WAIT_L(0); PG8_MMA(1, 0, At, B0); PG8_BAR; PG8_SCHED;
;             PG8_STAGE(PG8_SB(0, 1), b2 + hstep, voffB);
;             PG8_WAIT_V(6); PG8_BAR; PG8_MMA(1, 1, At, B1); PG8_BAR;
.LBB0_538:
	s_add_i32 s74, s22, 2
	s_add_u32 s38, s2, 0x80
	s_addc_u32 s23, s3, 0
	s_add_i32 s75, 0, 0x10000
	v_add_u32_e32 v0, s75, v160
	ds_read_b128 v[144:147], v0
	ds_read_b128 v[164:167], v0 offset:1024
	ds_read_b128 v[168:171], v0 offset:2048
	ds_read_b128 v[172:175], v0 offset:3072
	s_cmp_eq_u32 s24, s22
	s_cselect_b32 s22, s20, s38
	s_cselect_b32 s23, s21, s23
	s_cselect_b32 s39, s5, s29
	s_cselect_b32 s38, s4, s25
	v_lshl_add_u64 v[148:149], s[2:3], 0, v[138:139]
	s_add_i32 m0, s56, 0xc000
	ds_read_b128 v[176:179], v162
	ds_read_b128 v[180:183], v162 offset:1024
	ds_read_b128 v[184:187], v162 offset:2048
	ds_read_b128 v[188:191], v162 offset:3072
	ds_read_b128 v[192:195], v162 offset:4096
	ds_read_b128 v[196:199], v162 offset:5120
	ds_read_b128 v[200:203], v162 offset:6144
	ds_read_b128 v[204:207], v162 offset:7168
	global_load_lds_dwordx4 v[148:149], off
	s_add_i32 m0, s56, 0xe000
	v_lshl_add_u64 v[148:149], s[2:3], 0, v[140:141]
	global_load_lds_dwordx4 v[148:149], off
	s_waitcnt lgkmcnt(8)
	s_barrier
	s_waitcnt lgkmcnt(0)
	v_mfma_f32_16x16x32_bf16 v[126:129], v[144:147], v[176:179], v[126:129]
	v_mfma_f32_16x16x32_bf16 v[122:125], v[168:171], v[176:179], v[122:125]
	v_mfma_f32_16x16x32_bf16 v[110:113], v[144:147], v[184:187], v[110:113]
	v_mfma_f32_16x16x32_bf16 v[106:109], v[168:171], v[184:187], v[106:109]
	v_mfma_f32_16x16x32_bf16 v[94:97], v[144:147], v[192:195], v[94:97]
	v_mfma_f32_16x16x32_bf16 v[90:93], v[168:171], v[192:195], v[90:93]
	v_mfma_f32_16x16x32_bf16 v[78:81], v[144:147], v[200:203], v[78:81]
	v_mfma_f32_16x16x32_bf16 v[74:77], v[168:171], v[200:203], v[74:77]
	v_mfma_f32_16x16x32_bf16 v[126:129], v[164:167], v[180:183], v[126:129]
	v_mfma_f32_16x16x32_bf16 v[122:125], v[172:175], v[180:183], v[122:125]
	v_mfma_f32_16x16x32_bf16 v[110:113], v[164:167], v[188:191], v[110:113]
	v_mfma_f32_16x16x32_bf16 v[106:109], v[172:175], v[188:191], v[106:109]
	v_mfma_f32_16x16x32_bf16 v[94:97], v[164:167], v[196:199], v[94:97]
	v_mfma_f32_16x16x32_bf16 v[90:93], v[172:175], v[196:199], v[90:93]
	v_mfma_f32_16x16x32_bf16 v[78:81], v[164:167], v[204:207], v[78:81]
	v_mfma_f32_16x16x32_bf16 v[74:77], v[172:175], v[204:207], v[74:77]
	s_barrier
	s_add_i32 s76, 0, 0x14000
	s_add_i32 s75, s75, s51
	v_add_u32_e32 v0, s76, v160
	v_lshl_add_u64 v[148:149], s[38:39], 0, v[132:133]
	s_mov_b32 m0, s75
	ds_read_b128 v[208:211], v0
	ds_read_b128 v[214:217], v0 offset:1024
	ds_read_b128 v[218:221], v0 offset:2048
	ds_read_b128 v[222:225], v0 offset:3072
	global_load_lds_dwordx4 v[148:149], off
	s_add_i32 m0, s75, 0x2000
	v_lshl_add_u64 v[226:227], s[38:39], 0, v[136:137]
	global_load_lds_dwordx4 v[226:227], off
	s_barrier
	s_waitcnt lgkmcnt(0)
	v_mfma_f32_16x16x32_bf16 v[118:121], v[208:211], v[176:179], v[118:121]
	v_mfma_f32_16x16x32_bf16 v[114:117], v[218:221], v[176:179], v[114:117]
	v_mfma_f32_16x16x32_bf16 v[102:105], v[208:211], v[184:187], v[102:105]
	v_mfma_f32_16x16x32_bf16 v[98:101], v[218:221], v[184:187], v[98:101]
	v_mfma_f32_16x16x32_bf16 v[86:89], v[208:211], v[192:195], v[86:89]
	v_mfma_f32_16x16x32_bf16 v[82:85], v[218:221], v[192:195], v[82:85]
	v_mfma_f32_16x16x32_bf16 v[70:73], v[208:211], v[200:203], v[70:73]
	v_mfma_f32_16x16x32_bf16 v[66:69], v[218:221], v[200:203], v[66:69]
	v_mfma_f32_16x16x32_bf16 v[118:121], v[214:217], v[180:183], v[118:121]
	v_mfma_f32_16x16x32_bf16 v[114:117], v[222:225], v[180:183], v[114:117]
	v_mfma_f32_16x16x32_bf16 v[102:105], v[214:217], v[188:191], v[102:105]
	v_mfma_f32_16x16x32_bf16 v[98:101], v[222:225], v[188:191], v[98:101]
	v_mfma_f32_16x16x32_bf16 v[86:89], v[214:217], v[196:199], v[86:89]
	v_mfma_f32_16x16x32_bf16 v[82:85], v[222:225], v[196:199], v[82:85]
	v_mfma_f32_16x16x32_bf16 v[70:73], v[214:217], v[204:207], v[70:73]
	v_mfma_f32_16x16x32_bf16 v[66:69], v[222:225], v[204:207], v[66:69]
	s_mov_b32 m0, s56
	v_lshl_add_u64 v[228:229], s[22:23], 0, v[130:131]
	s_barrier
	ds_read_b128 v[176:179], v162 offset:16384
	ds_read_b128 v[180:183], v162 offset:17408
	ds_read_b128 v[184:187], v162 offset:18432
	ds_read_b128 v[188:191], v162 offset:19456
	ds_read_b128 v[192:195], v162 offset:20480
	ds_read_b128 v[196:199], v162 offset:21504
	ds_read_b128 v[200:203], v162 offset:22528
	ds_read_b128 v[204:207], v162 offset:23552
	global_load_lds_dwordx4 v[228:229], off
	s_mov_b32 m0, s57
	v_lshl_add_u64 v[230:231], s[22:23], 0, v[134:135]
	global_load_lds_dwordx4 v[230:231], off
	s_barrier
	s_waitcnt lgkmcnt(0)
	v_mfma_f32_16x16x32_bf16 v[62:65], v[144:147], v[176:179], v[62:65]
	v_mfma_f32_16x16x32_bf16 v[58:61], v[168:171], v[176:179], v[58:61]
	v_mfma_f32_16x16x32_bf16 v[46:49], v[144:147], v[184:187], v[46:49]
	v_mfma_f32_16x16x32_bf16 v[42:45], v[168:171], v[184:187], v[42:45]
	v_mfma_f32_16x16x32_bf16 v[30:33], v[144:147], v[192:195], v[30:33]
	v_mfma_f32_16x16x32_bf16 v[26:29], v[168:171], v[192:195], v[26:29]
	v_mfma_f32_16x16x32_bf16 v[14:17], v[144:147], v[200:203], v[14:17]
	v_mfma_f32_16x16x32_bf16 v[10:13], v[168:171], v[200:203], v[10:13]
	v_mfma_f32_16x16x32_bf16 v[62:65], v[164:167], v[180:183], v[62:65]
	v_mfma_f32_16x16x32_bf16 v[58:61], v[172:175], v[180:183], v[58:61]
	v_mfma_f32_16x16x32_bf16 v[46:49], v[164:167], v[188:191], v[46:49]
	v_mfma_f32_16x16x32_bf16 v[42:45], v[172:175], v[188:191], v[42:45]
	v_mfma_f32_16x16x32_bf16 v[30:33], v[164:167], v[196:199], v[30:33]
	v_mfma_f32_16x16x32_bf16 v[26:29], v[172:175], v[196:199], v[26:29]
	v_mfma_f32_16x16x32_bf16 v[14:17], v[164:167], v[204:207], v[14:17]
	v_mfma_f32_16x16x32_bf16 v[10:13], v[172:175], v[204:207], v[10:13]
	s_barrier
; #define PG8_STAGE(bufoff, gbase, voff) do { _Pragma("unroll") for (int _i = 0; _i < 2; ++_i) \
;         __builtin_amdgcn_global_load_lds((const unsigned*)((const char*)(gbase) + (voff)[_i]), (LAS unsigned*)(lds + (bufoff) + ldsw + _i * 8192), 16, 0, 0); } while (0)
; #define PG8_LDA(dst, b, h) do { _Pragma("unroll") for (int m = 0; m < 4; ++m) _Pragma("unroll") for (int k = 0; k < 2; ++k) dst[m][k] = *(const LAS bf16x8*)(lds + PG8_SA(b, h) + aoff + m * 2048 + k * 1024); } while (0)
; #define PG8_LDB(dst, b, h) do { _Pragma("unroll") for (int n = 0; n < 2; ++n) _Pragma("unroll") for (int k = 0; k < 2; ++k) dst[n][k] = *(const LAS bf16x8*)(lds + PG8_SB(b, h) + boff + n * 2048 + k * 1024); } while (0)
; #define PG8_MMA(ai, bj, At, Bt) do { __builtin_amdgcn_s_setprio(1); _Pragma("unroll") for (int m = 0; m < 4; ++m) _Pragma("unroll") for (int n = 0; n < 2; ++n) _Pragma("unroll") for (int k = 0; k < 2; ++k) \
;         acc[ai][bj][m][n] = __builtin_amdgcn_mfma_f32_16x16x32_bf16(Bt[n][k], At[m][k], acc[ai][bj][m][n], 0, 0, 0); __builtin_amdgcn_s_setprio(0); } while (0)
; #define PG8_WAIT_V(n) asm volatile("s_waitcnt vmcnt(" #n ")" ::: "memory")
; #define PG8_WAIT_L(n) asm volatile("s_waitcnt lgkmcnt(" #n ")" ::: "memory")
; #define PG8_BAR __builtin_amdgcn_s_barrier()
; #define PG8_SCHED __builtin_amdgcn_sched_barrier(0)
; template <class Epi, class Sched>
; __device__ __forceinline__ void gemm_phase(LAS unsigned char* lds, const Gemm g, const Sched& S, const Epi& E, const int tid) {
;     ...
;             PG8_LDA(At, 0, 1); PG8_STAGE(PG8_SA(0, 0), a2, voffA);
;             PG8_BAR; PG8_WAIT_L(0); PG8_MMA(1, 0, At, B0); PG8_BAR; PG8_SCHED;
;             PG8_STAGE(PG8_SB(0, 1), b2 + hstep, voffB);
;             PG8_WAIT_V(6); PG8_BAR; PG8_MMA(1, 1, At, B1); PG8_BAR;
;             PG8_LDB(B0, 1, 0); PG8_SCHED; PG8_LDA(At, 1, 0); PG8_STAGE(PG8_SA(0, 1), a2 + hstep, voffA);
;             PG8_WAIT_L(8); PG8_BAR; PG8_WAIT_L(0); PG8_MMA(0, 0, At, B0); PG8_BAR; PG8_SCHED;
;             PG8_LDB(B1, 1, 1); PG8_STAGE(PG8_SB(1, 0), b3, voffB);
;             PG8_BAR; PG8_WAIT_L(0); PG8_MMA(0, 1, At, B1); PG8_BAR;
;             PG8_LDA(At, 1, 1); PG8_STAGE(PG8_SA(1, 0), a3, voffA);
	s_add_u32 s38, s38, s8
	s_addc_u32 s39, s39, 0
	s_add_i32 s75, s76, s51
	v_lshl_add_u64 v[244:245], s[38:39], 0, v[132:133]
	s_mov_b32 m0, s75
	v_lshl_add_u64 v[246:247], s[38:39], 0, v[136:137]
	global_load_lds_dwordx4 v[244:245], off
	s_add_i32 m0, s75, 0x2000
	s_nop 0
	global_load_lds_dwordx4 v[246:247], off
	s_waitcnt vmcnt(6)
	s_barrier
	v_mfma_f32_16x16x32_bf16 v[54:57], v[208:211], v[176:179], v[54:57]
	v_mfma_f32_16x16x32_bf16 v[50:53], v[218:221], v[176:179], v[50:53]
	v_mfma_f32_16x16x32_bf16 v[38:41], v[208:211], v[184:187], v[38:41]
	v_mfma_f32_16x16x32_bf16 v[34:37], v[218:221], v[184:187], v[34:37]
	v_mfma_f32_16x16x32_bf16 v[22:25], v[208:211], v[192:195], v[22:25]
	v_mfma_f32_16x16x32_bf16 v[18:21], v[218:221], v[192:195], v[18:21]
	v_mfma_f32_16x16x32_bf16 v[6:9], v[208:211], v[200:203], v[6:9]
	v_mfma_f32_16x16x32_bf16 v[2:5], v[218:221], v[200:203], v[2:5]
	v_mfma_f32_16x16x32_bf16 v[54:57], v[214:217], v[180:183], v[54:57]
	v_mfma_f32_16x16x32_bf16 v[50:53], v[222:225], v[180:183], v[50:53]
	v_mfma_f32_16x16x32_bf16 v[38:41], v[214:217], v[188:191], v[38:41]
	v_mfma_f32_16x16x32_bf16 v[34:37], v[222:225], v[188:191], v[34:37]
	v_mfma_f32_16x16x32_bf16 v[22:25], v[214:217], v[196:199], v[22:25]
	v_mfma_f32_16x16x32_bf16 v[18:21], v[222:225], v[196:199], v[18:21]
	v_mfma_f32_16x16x32_bf16 v[6:9], v[214:217], v[204:207], v[6:9]
	v_mfma_f32_16x16x32_bf16 v[2:5], v[222:225], v[204:207], v[2:5]
	s_add_i32 s38, 0, 0x18000
	v_add_u32_e32 v0, s38, v160
	s_barrier
	ds_read_b128 v[144:147], v0
	ds_read_b128 v[164:167], v0 offset:1024
	ds_read_b128 v[168:171], v0 offset:2048
	ds_read_b128 v[172:175], v0 offset:3072
	s_add_u32 s22, s22, s8
	s_addc_u32 s23, s23, 0
	s_mov_b32 m0, s58
	ds_read_b128 v[176:179], v162 offset:32768
	ds_read_b128 v[180:183], v162 offset:33792
	ds_read_b128 v[184:187], v162 offset:34816
	ds_read_b128 v[188:191], v162 offset:35840
	ds_read_b128 v[192:195], v162 offset:36864
	ds_read_b128 v[196:199], v162 offset:37888
	ds_read_b128 v[200:203], v162 offset:38912
	global_load_lds_dwordx4 v130, s[22:23]
	s_mov_b32 m0, s59
	ds_read_b128 v[204:207], v162 offset:39936
	global_load_lds_dwordx4 v134, s[22:23]
	s_waitcnt lgkmcnt(8)
	s_barrier
	s_waitcnt lgkmcnt(0)
	v_mfma_f32_16x16x32_bf16 v[126:129], v[144:147], v[176:179], v[126:129]
	v_mfma_f32_16x16x32_bf16 v[122:125], v[168:171], v[176:179], v[122:125]
	v_mfma_f32_16x16x32_bf16 v[110:113], v[144:147], v[184:187], v[110:113]
	v_mfma_f32_16x16x32_bf16 v[106:109], v[168:171], v[184:187], v[106:109]
	v_mfma_f32_16x16x32_bf16 v[94:97], v[144:147], v[192:195], v[94:97]
	v_mfma_f32_16x16x32_bf16 v[90:93], v[168:171], v[192:195], v[90:93]
	v_mfma_f32_16x16x32_bf16 v[78:81], v[144:147], v[200:203], v[78:81]
	v_mfma_f32_16x16x32_bf16 v[74:77], v[168:171], v[200:203], v[74:77]
	v_mfma_f32_16x16x32_bf16 v[126:129], v[164:167], v[180:183], v[126:129]
	v_mfma_f32_16x16x32_bf16 v[122:125], v[172:175], v[180:183], v[122:125]
	v_mfma_f32_16x16x32_bf16 v[110:113], v[164:167], v[188:191], v[110:113]
	v_mfma_f32_16x16x32_bf16 v[106:109], v[172:175], v[188:191], v[106:109]
	v_mfma_f32_16x16x32_bf16 v[94:97], v[164:167], v[196:199], v[94:97]
	v_mfma_f32_16x16x32_bf16 v[90:93], v[172:175], v[196:199], v[90:93]
	v_mfma_f32_16x16x32_bf16 v[78:81], v[164:167], v[204:207], v[78:81]
	v_mfma_f32_16x16x32_bf16 v[74:77], v[172:175], v[204:207], v[74:77]
	s_barrier
	s_add_i32 s22, 0, 0x1c000
	s_add_i32 s23, s38, s51
	v_add_u32_e32 v0, s22, v160
	v_lshl_add_u64 v[148:149], v[148:149], 0, s[36:37]
	s_mov_b32 m0, s23
	ds_read_b128 v[208:211], v0
	ds_read_b128 v[214:217], v0 offset:1024
	ds_read_b128 v[218:221], v0 offset:2048
	ds_read_b128 v[222:225], v0 offset:3072
	global_load_lds_dwordx4 v[148:149], off
	s_add_i32 m0, s23, 0x2000
	v_lshl_add_u64 v[148:149], v[226:227], 0, s[36:37]
	global_load_lds_dwordx4 v[148:149], off
	s_barrier
	s_waitcnt lgkmcnt(0)
	v_mfma_f32_16x16x32_bf16 v[118:121], v[208:211], v[176:179], v[118:121]
	v_mfma_f32_16x16x32_bf16 v[114:117], v[218:221], v[176:179], v[114:117]
	v_mfma_f32_16x16x32_bf16 v[102:105], v[208:211], v[184:187], v[102:105]
	v_mfma_f32_16x16x32_bf16 v[98:101], v[218:221], v[184:187], v[98:101]
	v_mfma_f32_16x16x32_bf16 v[86:89], v[208:211], v[192:195], v[86:89]
	v_mfma_f32_16x16x32_bf16 v[82:85], v[218:221], v[192:195], v[82:85]
	v_mfma_f32_16x16x32_bf16 v[70:73], v[208:211], v[200:203], v[70:73]
	v_mfma_f32_16x16x32_bf16 v[66:69], v[218:221], v[200:203], v[66:69]
	v_mfma_f32_16x16x32_bf16 v[118:121], v[214:217], v[180:183], v[118:121]
	v_mfma_f32_16x16x32_bf16 v[114:117], v[222:225], v[180:183], v[114:117]
	v_mfma_f32_16x16x32_bf16 v[102:105], v[214:217], v[188:191], v[102:105]
	v_mfma_f32_16x16x32_bf16 v[98:101], v[222:225], v[188:191], v[98:101]
	v_mfma_f32_16x16x32_bf16 v[86:89], v[214:217], v[196:199], v[86:89]
	v_mfma_f32_16x16x32_bf16 v[82:85], v[222:225], v[196:199], v[82:85]
	v_mfma_f32_16x16x32_bf16 v[70:73], v[214:217], v[204:207], v[70:73]
	v_mfma_f32_16x16x32_bf16 v[66:69], v[222:225], v[204:207], v[66:69]
	s_mov_b32 m0, s61
	v_lshl_add_u64 v[148:149], v[228:229], 0, s[36:37]
	s_barrier
; #define PG8_STAGE(bufoff, gbase, voff) do { _Pragma("unroll") for (int _i = 0; _i < 2; ++_i) \
;         __builtin_amdgcn_global_load_lds((const unsigned*)((const char*)(gbase) + (voff)[_i]), (LAS unsigned*)(lds + (bufoff) + ldsw + _i * 8192), 16, 0, 0); } while (0)
; #define PG8_LDA(dst, b, h) do { _Pragma("unroll") for (int m = 0; m < 4; ++m) _Pragma("unroll") for (int k = 0; k < 2; ++k) dst[m][k] = *(const LAS bf16x8*)(lds + PG8_SA(b, h) + aoff + m * 2048 + k * 1024); } while (0)
; #define PG8_BAR __builtin_amdgcn_s_barrier()
;     __device__ __forceinline__ void operator()(const f32x4 (&acc)[2][2][4][2], const Unit& u, int wr, int wc, int fr, int fq) const {
;         const int row0 = u.pm * BM + wr * 64 + fr; const int col0 = u.pn * BM + wc * 32 + 8 * fq;
; #pragma unroll
;         for (int ai = 0; ai < 2; ++ai)
; #pragma unroll
;             for (int m = 0; m < 4; ++m) { const int row = row0 + ai * HALF + m * 16; int b, tok; if (row < MLAT) { b = row >> 13; tok = CTX + (row & (SEQ - 1)); } else { b = (row - MLAT) >> 8; tok = (row - MLAT) & (CTX - 1); }
; #pragma unroll
;                 for (int bj = 0; bj < 2; ++bj) { const int col = col0 + bj * HALF; bf16_t* dst;
;                     if (mode == 0) { const int h = col / 192, d = col - h * 192; dst = Q + ((size_t)(b * 4 + h) * LTOT + tok) * 192 + d; }
;                     else { const int h = col >> 8, d = col & 255; dst = d < 128 ? K + ((size_t)(b * 4 + h) * LTOT + tok) * 192 + d : V + ((size_t)(b * 4 + h) * LTOT + tok) * 128 + (d - 128); }
; template <class Epi, class Sched>
; __device__ __forceinline__ void gemm_phase(LAS unsigned char* lds, const Gemm g, const Sched& S, const Epi& E, const int tid) {
;     ...
;             PG8_WAIT_L(8); PG8_BAR; PG8_WAIT_L(0); PG8_MMA(0, 0, At, B0); PG8_BAR; PG8_SCHED;
;             PG8_LDB(B1, 1, 1); PG8_STAGE(PG8_SB(1, 0), b3, voffB);
;             PG8_BAR; PG8_WAIT_L(0); PG8_MMA(0, 1, At, B1); PG8_BAR;
;             PG8_LDA(At, 1, 1); PG8_STAGE(PG8_SA(1, 0), a3, voffA);
;             PG8_BAR; PG8_WAIT_L(0); PG8_MMA(1, 0, At, B0); PG8_BAR; PG8_SCHED;
;             PG8_STAGE(PG8_SB(1, 1), b3 + hstep, voffB);
;             PG8_WAIT_V(6); PG8_BAR; PG8_MMA(1, 1, At, B1); PG8_BAR;
;         }
;         if constexpr (!Epi::AFTER_DRAIN) { if constexpr (Epi::PRELOAD) E(acc, cur, wr, wc, fr, fq, lds); else E(acc, cur, wr, wc, fr, fq); S.done(cur); }
	ds_read_b128 v[176:179], v162 offset:49152
	ds_read_b128 v[180:183], v162 offset:50176
	ds_read_b128 v[184:187], v162 offset:51200
	ds_read_b128 v[188:191], v162 offset:52224
	ds_read_b128 v[192:195], v162 offset:53248
	ds_read_b128 v[196:199], v162 offset:54272
	ds_read_b128 v[200:203], v162 offset:55296
	ds_read_b128 v[204:207], v162 offset:56320
	global_load_lds_dwordx4 v[148:149], off
	s_mov_b32 m0, s62
	v_lshl_add_u64 v[148:149], v[230:231], 0, s[36:37]
	global_load_lds_dwordx4 v[148:149], off
	s_barrier
	s_waitcnt lgkmcnt(0)
	v_mfma_f32_16x16x32_bf16 v[62:65], v[144:147], v[176:179], v[62:65]
	v_mfma_f32_16x16x32_bf16 v[58:61], v[168:171], v[176:179], v[58:61]
	v_mfma_f32_16x16x32_bf16 v[46:49], v[144:147], v[184:187], v[46:49]
	v_mfma_f32_16x16x32_bf16 v[42:45], v[168:171], v[184:187], v[42:45]
	v_mfma_f32_16x16x32_bf16 v[30:33], v[144:147], v[192:195], v[30:33]
	v_mfma_f32_16x16x32_bf16 v[26:29], v[168:171], v[192:195], v[26:29]
	v_mfma_f32_16x16x32_bf16 v[14:17], v[144:147], v[200:203], v[14:17]
	v_mfma_f32_16x16x32_bf16 v[10:13], v[168:171], v[200:203], v[10:13]
	v_mfma_f32_16x16x32_bf16 v[62:65], v[164:167], v[180:183], v[62:65]
	v_mfma_f32_16x16x32_bf16 v[58:61], v[172:175], v[180:183], v[58:61]
	v_mfma_f32_16x16x32_bf16 v[46:49], v[164:167], v[188:191], v[46:49]
	v_mfma_f32_16x16x32_bf16 v[42:45], v[172:175], v[188:191], v[42:45]
	v_mfma_f32_16x16x32_bf16 v[30:33], v[164:167], v[196:199], v[30:33]
	v_mfma_f32_16x16x32_bf16 v[26:29], v[172:175], v[196:199], v[26:29]
	v_mfma_f32_16x16x32_bf16 v[14:17], v[164:167], v[204:207], v[14:17]
	v_mfma_f32_16x16x32_bf16 v[10:13], v[172:175], v[204:207], v[10:13]
	s_barrier
	s_add_i32 s22, s22, s51
	s_mov_b32 m0, s22
	v_lshl_add_u64 v[144:145], v[244:245], 0, s[36:37]
	global_load_lds_dwordx4 v[144:145], off
	s_add_i32 m0, s22, 0x2000
	v_lshl_add_u64 v[144:145], v[246:247], 0, s[36:37]
	global_load_lds_dwordx4 v[144:145], off
	s_waitcnt vmcnt(6)
	s_barrier
	v_mfma_f32_16x16x32_bf16 v[54:57], v[208:211], v[176:179], v[54:57]
	v_mfma_f32_16x16x32_bf16 v[50:53], v[218:221], v[176:179], v[50:53]
	v_mfma_f32_16x16x32_bf16 v[38:41], v[208:211], v[184:187], v[38:41]
	v_mfma_f32_16x16x32_bf16 v[34:37], v[218:221], v[184:187], v[34:37]
	v_mfma_f32_16x16x32_bf16 v[22:25], v[208:211], v[192:195], v[22:25]
	v_mfma_f32_16x16x32_bf16 v[18:21], v[218:221], v[192:195], v[18:21]
	v_mfma_f32_16x16x32_bf16 v[6:9], v[208:211], v[200:203], v[6:9]
	v_mfma_f32_16x16x32_bf16 v[2:5], v[218:221], v[200:203], v[2:5]
	v_mfma_f32_16x16x32_bf16 v[54:57], v[214:217], v[180:183], v[54:57]
	v_mfma_f32_16x16x32_bf16 v[50:53], v[222:225], v[180:183], v[50:53]
	v_mfma_f32_16x16x32_bf16 v[38:41], v[214:217], v[188:191], v[38:41]
	v_mfma_f32_16x16x32_bf16 v[34:37], v[222:225], v[188:191], v[34:37]
	v_mfma_f32_16x16x32_bf16 v[22:25], v[214:217], v[196:199], v[22:25]
	v_mfma_f32_16x16x32_bf16 v[18:21], v[222:225], v[196:199], v[18:21]
	v_mfma_f32_16x16x32_bf16 v[6:9], v[214:217], v[204:207], v[6:9]
	v_mfma_f32_16x16x32_bf16 v[2:5], v[222:225], v[204:207], v[2:5]
	s_add_u32 s2, s2, 0x100
	s_addc_u32 s3, s3, 0
	s_add_u32 s25, s25, 0x100
	s_addc_u32 s29, s29, 0
	s_cmp_ge_i32 s74, s63
	s_mov_b32 s22, s74
	s_barrier
	s_cbranch_scc0 .LBB0_538
	s_lshl_b32 s24, s28, 8
	s_add_i32 s24, s24, s64
	s_add_i32 s2, s24, 0xffffc000
	v_mov_b32_e32 v0, 0x1fcf
	v_or_b32_e32 v163, s24, v156
	s_lshr_b32 s25, s2, 8
	v_bitop3_b32 v0, s24, v0, v156 bitop3:0xc8
	v_mov_b32_e32 v144, 0xcf
	s_movk_i32 s2, 0x4000
	s_ashr_i32 s28, s24, 13
	v_add_u32_e32 v0, 0x100, v0
	v_bitop3_b32 v144, s24, v144, v156 bitop3:0xc8
	v_cmp_gt_i32_e32 vcc, s2, v163
	v_mov_b32_e32 v145, s28
	v_lshl_or_b32 v142, s60, 8, v161
	v_cndmask_b32_e32 v0, v144, v0, vcc
	v_mov_b32_e32 v144, s25
	v_cndmask_b32_e32 v144, v144, v145, vcc
	v_lshlrev_b32_e32 v166, 2, v144
	v_add_u32_e32 v144, s60, v166
	v_mad_i64_i32 v[146:147], s[2:3], v144, s33, v[0:1]
	v_and_b32_e32 v144, 0x78, v142
	s_mov_b64 s[2:3], -1
	s_and_b64 vcc, exec, s[14:15]
	v_lshlrev_b32_e32 v144, 1, v144
	s_cbranch_vccz .LBB0_541
	v_mov_b64_e32 v[148:149], s[10:11]
	v_mad_u64_u32 v[148:149], s[2:3], v146, s27, v[148:149]
	v_mov_b32_e32 v164, v149
	v_mad_u64_u32 v[164:165], s[2:3], v147, s27, v[164:165]
	v_mov_b32_e32 v149, v164
	v_mov_b32_e32 v145, v1
	v_lshl_add_u64 v[148:149], v[148:149], 0, v[144:145]
	s_mov_b64 s[2:3], 0

; #define LAS __attribute__((address_space(3)))
; DI int v_st(int k, int c) { const int kk = (k & ~0xC) | ((k & 4) << 1) | ((k & 8) >> 1); return ((kk >> 3) * 4 + (c >> 5)) * 512 + ((kk & 7) * 32 + (c & 31)) * 2; }
; DI int v_rd_base(int lane) { return ((lane & 3) << 3) | (((lane >> 2) & 3) << 6) | (((lane >> 4) & 1) << 5) | (((lane >> 5) & 1) << 8); }
; #define SLOAD(i, k0) do { sr_[i].vs0 = *reinterpret_cast<const bf16x8*>(&Vh[(long)((k0) + sr) * DV + sc]); sr_[i].vs1 = *reinterpret_cast<const bf16x8*>(&Vh[(long)((k0) + 32 + sr) * DV + sc]); \
;     _Pragma("unroll") for (int _c = 0; _c < NKC; ++_c) sr_[i].ks[_c] = *reinterpret_cast<const bf16x8*>(&Kh[(long)((k0) + krow[_c]) * DQK + kcol[_c]]); } while (0)
; #define SWRITE(b, i) do { *(LAS bf16x8*)(V_lds + (b) * SHM_V + vst0) = sr_[i].vs0; *(LAS bf16x8*)(V_lds + (b) * SHM_V + vst1) = sr_[i].vs1; \
;     _Pragma("unroll") for (int _c = 0; _c < NKC; ++_c) *(LAS bf16x8*)(K_lds + (b) * SHM_K + kswz<DQK>(krow[_c], kcol[_c] * 2)) = sr_[i].ks[_c]; } while (0)
; template <int DQK, int SDEPTH, bool OUT_BF16, int QREG = DQK / 16, bool OUT_F16 = false> ...
;     ...
;       for (int d0 = 0; d0 < 4; ++d0) *(LAS u32x4*)(Qp + (8 - QREG + d0) * 1024) = f[d0];
;     }
;   }
;     ...
;   const int sr = tid >> 4, sc = (tid & 15) * 8, vst0 = v_st(sr, sc), vst1 = v_st(32 + sr, sc);
;   int krow[NKC], kcol[NKC];
; #pragma unroll
;   for (int i = 0; i < NKC; ++i) { const int ci = tid + i * 512; krow[i] = ci / CPR; kcol[i] = (ci % CPR) * 8; }
;   const int vb0 = (int)(uintptr_t)V_lds + v_rd_base(lane);
;   struct { bf16x8 vs0, vs1, ks[NKC]; } sr_[SDEPTH];
;     ...
;   f32x16 pA0, pA1, pB0, pB1; float mnA, mnB, alA, alB; bf16x8 pa0, pa1, pa2, pa3; const int NT = seq / KVBLK;
;   constexpr int SE = 0, SO = SDEPTH - 1;
;   SLOAD(SE, 0); asm volatile("s_waitcnt vmcnt(0)" ::: "memory"); SWRITE(0, SE); __syncthreads();
.LBB0_747:
	s_waitcnt vmcnt(3)
	ds_write_b128 v162, v[2:5] offset:4096
	s_waitcnt vmcnt(2)
	ds_write_b128 v162, v[6:9] offset:5120
	s_waitcnt vmcnt(1)
	ds_write_b128 v162, v[10:13] offset:6144
	s_waitcnt vmcnt(0)
	ds_write_b128 v162, v[14:17] offset:7168
	v_ashrrev_i32_e32 v2, 4, v34
	v_and_b32_e32 v5, 0xfffff0, v2
	v_lshlrev_b32_e32 v6, 1, v2
	v_lshlrev_b32_e32 v3, 3, v84
	v_and_or_b32 v5, v6, 8, v5
	v_and_b32_e32 v4, 0x78, v3
	v_lshrrev_b32_e32 v5, 1, v5
	v_bfe_u32 v3, v3, 5, 2
	v_or_b32_e32 v5, v5, v3
	v_lshrrev_b32_e32 v6, 1, v2
	v_lshlrev_b32_e32 v22, 9, v5
	v_and_b32_e32 v5, 3, v2
	v_and_or_b32 v5, v6, 4, v5
	v_add_u32_e32 v6, 32, v2
	v_and_b32_e32 v7, 0xfffff0, v6
	v_lshlrev_b32_e32 v8, 1, v6
	v_and_or_b32 v7, v8, 8, v7
	v_lshrrev_b32_e32 v7, 1, v7
	v_or_b32_e32 v3, v7, v3
	v_mul_hi_i32 v7, v34, s31
	v_lshrrev_b32_e32 v8, 31, v7
	v_ashrrev_i32_e32 v7, 2, v7
	v_add_u32_e32 v58, v7, v8
	v_mul_lo_u32 v7, v58, 24
	v_sub_u32_e32 v24, v34, v7
	v_add_u32_e32 v7, 0x200, v34
	v_mul_hi_i32 v8, v7, s31
	v_lshrrev_b32_e32 v9, 31, v8
	v_ashrrev_i32_e32 v8, 2, v8
	v_add_u32_e32 v62, v8, v9
	v_mul_lo_u32 v8, v62, 24
	v_sub_u32_e32 v25, v7, v8
	v_add_u32_e32 v7, 0x400, v34
	v_mul_hi_i32 v8, v7, s31
	v_lshrrev_b32_e32 v9, 31, v8
	v_ashrrev_i32_e32 v8, 2, v8
	v_lshlrev_b32_e32 v23, 6, v5
	v_lshlrev_b32_e32 v5, 4, v84
	v_add_u32_e32 v68, v8, v9
	s_mul_i32 s1, s38, 0x210000
	v_lshlrev_b32_e32 v3, 9, v3
	v_mul_lo_u32 v8, v68, 24
	v_and_b32_e32 v27, 48, v5
	s_mul_hi_i32 s0, s38, 0x210000
	s_add_u32 s1, s4, s1
	v_sub_u32_e32 v26, v7, v8
	v_or3_b32 v28, v3, v23, v27
	v_lshlrev_b32_e32 v3, 3, v85
	v_and_b32_e32 v5, 0xc0, v35
	v_lshlrev_b32_e32 v7, 1, v85
	s_addc_u32 s0, s5, s0
	v_and_or_b32 v5, v3, 24, v5
	v_and_b32_e32 v7, 32, v7
	v_and_b32_e32 v3, 0x100, v3
	s_add_u32 s2, s1, 0x44874000
	v_or3_b32 v86, v5, v7, v3
	v_ashrrev_i32_e32 v3, 31, v2
	s_addc_u32 s3, s0, 0
	v_lshlrev_b64 v[70:71], 8, v[2:3]
	v_lshl_add_u64 v[2:3], s[2:3], 0, v[70:71]
	v_lshlrev_b32_e32 v8, 1, v4
	v_mov_b32_e32 v9, v1
	v_lshl_add_u64 v[54:55], v[2:3], 0, v[8:9]
	s_mul_i32 s1, s38, 0x318000
	global_load_dwordx4 v[2:5], v[54:55], off
	s_mul_hi_i32 s0, s38, 0x318000
	s_add_u32 s1, s4, s1
	s_addc_u32 s8, s5, s0
	s_add_u32 s0, s1, 0x42fb4000
	s_addc_u32 s1, s8, 0
	v_and_b32_e32 v18, 0x3fffffc0, v34
	s_add_i32 s8, 0, 0x14000
	v_lshl_add_u32 v143, v18, 2, s8
	v_lshlrev_b32_e32 v10, 3, v24
	v_lshlrev_b32_e32 v14, 3, v25
	v_lshlrev_b32_e32 v18, 3, v26
	v_ashrrev_i32_e32 v7, 31, v6
	v_lshlrev_b64 v[6:7], 8, v[6:7]
	v_ashrrev_i32_e32 v11, 31, v10
	v_mov_b64_e32 v[66:67], s[0:1]
	v_ashrrev_i32_e32 v15, 31, v14
	v_ashrrev_i32_e32 v19, 31, v18
	v_lshl_add_u64 v[6:7], s[2:3], 0, v[6:7]
	v_mad_i64_i32 v[12:13], s[0:1], v58, s27, v[66:67]
	v_lshlrev_b64 v[74:75], 1, v[10:11]
	v_mad_i64_i32 v[16:17], s[0:1], v62, s27, v[66:67]
	v_lshlrev_b64 v[78:79], 1, v[14:15]
	v_mad_i64_i32 v[20:21], s[0:1], v68, s27, v[66:67]
	v_lshlrev_b64 v[82:83], 1, v[18:19]
	v_lshl_add_u64 v[6:7], v[6:7], 0, v[8:9]
	v_lshl_add_u64 v[10:11], v[12:13], 0, v[74:75]
	v_lshl_add_u64 v[14:15], v[16:17], 0, v[78:79]
	v_lshl_add_u64 v[18:19], v[20:21], 0, v[82:83]
	global_load_dwordx4 v[6:9], v[6:7], off
	v_or3_b32 v22, v22, v23, v27
	global_load_dwordx4 v[10:13], v[10:11], off
	v_add_u32_e32 v167, 0, v22
	global_load_dwordx4 v[14:17], v[14:15], off
	v_mad_i64_i32 v[72:73], s[2:3], v58, s27, 0
	global_load_dwordx4 v[18:21], v[18:19], off
	s_waitcnt vmcnt(0)
	v_mad_i64_i32 v[76:77], s[0:1], v62, s27, 0
	v_mad_i64_i32 v[80:81], s[0:1], v68, s27, 0
	v_mad_u32_u24 v57, v160, s27, 0
	v_add_u32_e32 v168, 0, v28
	v_or_b32_e32 v50, 32, v0
	s_movk_i32 s0, 0x4000
	s_mov_b32 s8, s9
	s_mov_b32 s10, s9
	s_mov_b32 s11, s9
	s_mov_b32 s12, s9
	s_mov_b32 s13, s9
	s_mov_b32 s14, s9
	s_mov_b32 s15, s9
	s_mov_b32 s16, s9
	s_mov_b32 s17, s9
	s_mov_b32 s18, s9
	s_mov_b32 s19, s9
	s_mov_b32 s20, s9
	s_mov_b32 s21, s9
	s_mov_b32 s22, s9
	s_mov_b32 s23, s9
	s_mov_b32 s41, 2
	v_add_u32_e32 v163, 0, v86
	v_lshl_add_u32 v164, v160, 2, v143
	v_mov_b32_e32 v166, 0
	s_waitcnt vmcnt(4)
	ds_write_b128 v167, v[2:5]
	v_bitop3_b32 v2, v58, v24, 7 bitop3:0x6c
	v_lshl_add_u32 v2, v2, 4, 0
	v_add_u32_e32 v169, v2, v72
	v_bitop3_b32 v2, v62, v25, 7 bitop3:0x6c
	v_lshl_add_u32 v2, v2, 4, 0
	v_add_u32_e32 v170, v2, v76
	v_bitop3_b32 v2, v68, v26, 7 bitop3:0x6c
	v_lshl_add_u32 v2, v2, 4, 0
	v_add_u32_e32 v171, v2, v80
	v_lshlrev_b32_e32 v2, 4, v160
	v_and_b32_e32 v56, 0x70, v2
	v_xad_u32 v172, v0, v56, v57
	v_xad_u32 v173, v50, v56, v57
	v_add_u32_e32 v58, 64, v58
	v_add_u32_e32 v62, 64, v62
	v_add_u32_e32 v68, 64, v68
	v_add_u32_e32 v196, 0xe000, v172
	v_add_u32_e32 v195, 0xe000, v173
	s_waitcnt vmcnt(3)
	ds_write_b128 v168, v[6:9]
	s_waitcnt vmcnt(2)
	ds_write_b128 v169, v[10:13] offset:32768
	s_waitcnt vmcnt(1)
	ds_write_b128 v170, v[14:17] offset:32768
	v_mov_b64_e32 v[2:3], s[8:9]
	v_mov_b64_e32 v[16:17], s[22:23]
	s_waitcnt vmcnt(0)
	ds_write_b128 v171, v[18:21] offset:32768
	s_waitcnt lgkmcnt(0)
	s_barrier
; #define SLOAD(i, k0) do { sr_[i].vs0 = *reinterpret_cast<const bf16x8*>(&Vh[(long)((k0) + sr) * DV + sc]); sr_[i].vs1 = *reinterpret_cast<const bf16x8*>(&Vh[(long)((k0) + 32 + sr) * DV + sc]); \
;     _Pragma("unroll") for (int _c = 0; _c < NKC; ++_c) sr_[i].ks[_c] = *reinterpret_cast<const bf16x8*>(&Kh[(long)((k0) + krow[_c]) * DQK + kcol[_c]]); } while (0)
; #define SWRITE(b, i) do { *(LAS bf16x8*)(V_lds + (b) * SHM_V + vst0) = sr_[i].vs0; *(LAS bf16x8*)(V_lds + (b) * SHM_V + vst1) = sr_[i].vs1; \
;     _Pragma("unroll") for (int _c = 0; _c < NKC; ++_c) *(LAS bf16x8*)(K_lds + (b) * SHM_K + kswz<DQK>(krow[_c], kcol[_c] * 2)) = sr_[i].ks[_c]; } while (0)
; #define SWAIT() do { if constexpr (SDEPTH == 2) { if constexpr (NKC == 1) asm volatile("s_waitcnt vmcnt(3)" ::: "memory"); else if constexpr (NKC == 2) asm volatile("s_waitcnt vmcnt(4)" ::: "memory"); else asm volatile("s_waitcnt vmcnt(5)" ::: "memory"); } \
;     else asm volatile("s_waitcnt vmcnt(0)" ::: "memory"); } while (0)
; DI void partialSM(f32x16& p0, f32x16& p1, float& m_reg, float& mn, float& alpha, const float SCALE) {
;   const float C = SCALE * 1.4426950408889634f;
;   float pmax = p0[0];
; #pragma unroll
;   for (int r = 1; r < 16; ++r) pmax = fmaxf(pmax, p0[r]);
; #pragma unroll
;   for (int r = 0; r < 16; ++r) pmax = fmaxf(pmax, p1[r]);
;   { auto rr = __builtin_amdgcn_permlane32_swap(__float_as_uint(pmax), __float_as_uint(pmax), false, false);
;     pmax = fmaxf(__uint_as_float(rr[0]), __uint_as_float(rr[1])); }
;   if (__builtin_expect(__all(pmax - m_reg <= THR / SCALE), 1)) { mn = m_reg; alpha = 1.f; }
;   else { mn = fmaxf(m_reg, pmax); alpha = __builtin_amdgcn_exp2f((m_reg - mn) * C); m_reg = mn; }
; template <int DQK, int SDEPTH, bool OUT_BF16, int QREG = DQK / 16, bool OUT_F16 = false> ...
;     ...
;   SLOAD(SE, 0); asm volatile("s_waitcnt vmcnt(0)" ::: "memory"); SWRITE(0, SE); __syncthreads();
;   QKT(pA0, pA1, K_lds); partialSM(pA0, pA1, m_reg, mnA, alA, SCALE);
;   SLOAD(SO, KVBLK); if constexpr (SDEPTH == 2) { if (2 < NT) SLOAD(SE, 2 * KVBLK); }
;   SWAIT(); SWRITE(1, SO); __syncthreads();
	ds_read_b128 v[18:21], v172 offset:32768
	ds_read_b128 v[22:25], v172 offset:45056
	s_waitcnt lgkmcnt(1)
	v_mfma_f32_32x32x16_bf16 v[34:49], v[18:21], v[110:113], 0
	ds_read_b128 v[50:53], v173 offset:32768
	ds_read_b128 v[88:91], v173 offset:45056
	v_mov_b64_e32 v[4:5], s[10:11]
	v_mov_b64_e32 v[6:7], s[12:13]
	v_mov_b64_e32 v[8:9], s[14:15]
	v_mov_b64_e32 v[10:11], s[16:17]
	v_mov_b64_e32 v[12:13], s[18:19]
	v_mov_b64_e32 v[14:15], s[20:21]
	s_waitcnt lgkmcnt(2)
	v_mfma_f32_32x32x16_bf16 v[18:33], v[22:25], v[110:113], 0
	s_waitcnt lgkmcnt(1)
	v_mfma_f32_32x32x16_bf16 v[34:49], v[50:53], v[106:109], v[34:49]
	v_or_b32_e32 v50, 64, v0
	v_xad_u32 v174, v50, v56, v57
	v_add_u32_e32 v193, 0xe000, v174
	s_waitcnt lgkmcnt(0)
	v_mfma_f32_32x32x16_bf16 v[18:33], v[88:91], v[106:109], v[18:33]
	ds_read_b128 v[50:53], v174 offset:32768
	ds_read_b128 v[88:91], v174 offset:45056
	s_waitcnt lgkmcnt(1)
	v_mfma_f32_32x32x16_bf16 v[34:49], v[50:53], v[102:105], v[34:49]
	v_or_b32_e32 v50, 0x60, v0
	v_xad_u32 v175, v50, v56, v57
	v_add_u32_e32 v192, 0xe000, v175
	s_waitcnt lgkmcnt(0)
	v_mfma_f32_32x32x16_bf16 v[18:33], v[88:91], v[102:105], v[18:33]
	ds_read_b128 v[50:53], v175 offset:32768
	ds_read_b128 v[88:91], v175 offset:45056
	s_waitcnt lgkmcnt(1)
	v_mfma_f32_32x32x16_bf16 v[34:49], v[50:53], v[98:101], v[34:49]
	v_or_b32_e32 v50, 0x80, v0
	v_xad_u32 v176, v50, v56, v57
	v_add_u32_e32 v191, 0xe000, v176
	s_waitcnt lgkmcnt(0)
	v_mfma_f32_32x32x16_bf16 v[18:33], v[88:91], v[98:101], v[18:33]
	ds_read_b128 v[50:53], v176 offset:32768
	ds_read_b128 v[88:91], v176 offset:45056
	ds_read_b128 v[92:95], v162
	s_waitcnt lgkmcnt(0)
	v_mfma_f32_32x32x16_bf16 v[34:49], v[50:53], v[92:95], v[34:49]
	v_or_b32_e32 v50, 0xa0, v0
	v_xad_u32 v177, v50, v56, v57
	v_add_u32_e32 v190, 0xe000, v177
	v_mfma_f32_32x32x16_bf16 v[18:33], v[88:91], v[92:95], v[18:33]
	ds_read_b128 v[50:53], v177 offset:32768
	ds_read_b128 v[88:91], v177 offset:45056
	ds_read_b128 v[92:95], v162 offset:1024
	s_waitcnt lgkmcnt(0)
	v_mfma_f32_32x32x16_bf16 v[34:49], v[50:53], v[92:95], v[34:49]
	v_or_b32_e32 v50, 0xc0, v0
	v_xad_u32 v178, v50, v56, v57
	v_add_u32_e32 v189, 0xe000, v178
	v_mfma_f32_32x32x16_bf16 v[18:33], v[88:91], v[92:95], v[18:33]
	ds_read_b128 v[50:53], v178 offset:32768
	ds_read_b128 v[88:91], v178 offset:45056
	ds_read_b128 v[92:95], v162 offset:2048
	s_waitcnt lgkmcnt(0)
	v_mfma_f32_32x32x16_bf16 v[34:49], v[50:53], v[92:95], v[34:49]
	v_or_b32_e32 v50, 0xe0, v0
	v_xad_u32 v179, v50, v56, v57
	v_add_u32_e32 v188, 0xe000, v179
	v_mfma_f32_32x32x16_bf16 v[18:33], v[88:91], v[92:95], v[18:33]
	ds_read_b128 v[50:53], v179 offset:32768
	ds_read_b128 v[88:91], v179 offset:45056
	ds_read_b128 v[92:95], v162 offset:3072
	s_waitcnt lgkmcnt(0)
	v_mfma_f32_32x32x16_bf16 v[34:49], v[50:53], v[92:95], v[34:49]
	v_or_b32_e32 v50, 0x100, v0
	v_xad_u32 v180, v50, v56, v57
	v_add_u32_e32 v187, 0xe000, v180
	v_mfma_f32_32x32x16_bf16 v[18:33], v[88:91], v[92:95], v[18:33]
	ds_read_b128 v[50:53], v180 offset:32768
	ds_read_b128 v[88:91], v180 offset:45056
	ds_read_b128 v[92:95], v162 offset:4096
	s_waitcnt lgkmcnt(0)
	v_mfma_f32_32x32x16_bf16 v[34:49], v[50:53], v[92:95], v[34:49]
	v_or_b32_e32 v50, 0x120, v0
	v_xad_u32 v181, v50, v56, v57
	v_add_u32_e32 v186, 0xe000, v181
	v_mfma_f32_32x32x16_bf16 v[18:33], v[88:91], v[92:95], v[18:33]
	ds_read_b128 v[50:53], v181 offset:32768
	ds_read_b128 v[88:91], v181 offset:45056
	ds_read_b128 v[92:95], v162 offset:5120
	s_waitcnt lgkmcnt(0)
	v_mfma_f32_32x32x16_bf16 v[34:49], v[50:53], v[92:95], v[34:49]
	v_or_b32_e32 v50, 0x140, v0
	v_xad_u32 v182, v50, v56, v57
	v_add_u32_e32 v185, 0xe000, v182
	v_mfma_f32_32x32x16_bf16 v[18:33], v[88:91], v[92:95], v[18:33]
	ds_read_b128 v[50:53], v182 offset:32768
	ds_read_b128 v[88:91], v182 offset:45056
	ds_read_b128 v[92:95], v162 offset:6144
	s_waitcnt lgkmcnt(0)
	v_mfma_f32_32x32x16_bf16 v[34:49], v[50:53], v[92:95], v[34:49]
	v_or_b32_e32 v50, 0x160, v0
	v_xad_u32 v183, v50, v56, v57
	v_add_u32_e32 v184, 0xe000, v183
	v_mfma_f32_32x32x16_bf16 v[18:33], v[88:91], v[92:95], v[18:33]
	ds_read_b128 v[50:53], v183 offset:32768
	ds_read_b128 v[88:91], v183 offset:45056
	ds_read_b128 v[92:95], v162 offset:7168
	s_waitcnt lgkmcnt(0)
	v_mfma_f32_32x32x16_bf16 v[34:49], v[50:53], v[92:95], v[34:49]
	v_mfma_f32_32x32x16_bf16 v[18:33], v[88:91], v[92:95], v[18:33]
	s_nop 10
	v_max_f32_e32 v50, v35, v35
	v_max_f32_e32 v51, v34, v34
	v_max_f32_e32 v50, v51, v50
	v_max3_f32 v50, v50, v36, v37
	v_max3_f32 v50, v50, v38, v39
	v_max3_f32 v50, v50, v40, v41
	v_max3_f32 v50, v50, v42, v43
	v_max3_f32 v50, v50, v44, v45
	v_max3_f32 v50, v50, v46, v47
	v_max3_f32 v50, v50, v48, v49
	v_max3_f32 v50, v50, v18, v19
	v_max3_f32 v50, v50, v20, v21
	v_max3_f32 v50, v50, v22, v23
	v_max3_f32 v50, v50, v24, v25
	v_max3_f32 v50, v50, v26, v27
	v_max3_f32 v50, v50, v28, v29
	v_max3_f32 v50, v50, v30, v31
	v_max3_f32 v50, v50, v32, v33
	v_mov_b32_e32 v51, v50
	s_nop 1
	v_permlane32_swap_b32_e32 v50, v51
	v_max_f32_e32 v51, v51, v51
	v_max_f32_e32 v50, v50, v50
	v_max_f32_e32 v87, v50, v51
	v_add_f32_e32 v50, 0x7149f2ca, v87
	v_cmp_ge_f32_e32 vcc, s96, v50
	v_add_co_u32_e64 v50, s[0:1], s0, v54
	s_cmp_eq_u64 vcc, exec
	s_nop 0
	v_addc_co_u32_e64 v51, s[0:1], 0, v55, s[0:1]
	s_movk_i32 s0, 0x6000
	s_nop 0
	v_add_co_u32_e64 v54, s[0:1], s0, v54
	global_load_dwordx4 v[50:53], v[50:51], off
	s_nop 0
	v_addc_co_u32_e64 v55, s[0:1], 0, v55, s[0:1]
	v_mad_i64_i32 v[58:59], s[0:1], v58, s27, v[66:67]
	global_load_dwordx4 v[54:57], v[54:55], off
	v_lshl_add_u64 v[58:59], v[58:59], 0, v[74:75]
	v_mad_i64_i32 v[62:63], s[0:1], v62, s27, v[66:67]
	global_load_dwordx4 v[58:61], v[58:59], off
	v_lshl_add_u64 v[62:63], v[62:63], 0, v[78:79]
	v_mad_i64_i32 v[66:67], s[0:1], v68, s27, v[66:67]
	global_load_dwordx4 v[62:65], v[62:63], off
	v_lshl_add_u64 v[66:67], v[66:67], 0, v[82:83]
	global_load_dwordx4 v[66:69], v[66:67], off
	s_waitcnt vmcnt(0)
; #define SBAR() __builtin_amdgcn_sched_barrier(0)
; #define SLOAD(i, k0) do { sr_[i].vs0 = *reinterpret_cast<const bf16x8*>(&Vh[(long)((k0) + sr) * DV + sc]); sr_[i].vs1 = *reinterpret_cast<const bf16x8*>(&Vh[(long)((k0) + 32 + sr) * DV + sc]); \
;     _Pragma("unroll") for (int _c = 0; _c < NKC; ++_c) sr_[i].ks[_c] = *reinterpret_cast<const bf16x8*>(&Kh[(long)((k0) + krow[_c]) * DQK + kcol[_c]]); } while (0)
; #define SWRITE(b, i) do { *(LAS bf16x8*)(V_lds + (b) * SHM_V + vst0) = sr_[i].vs0; *(LAS bf16x8*)(V_lds + (b) * SHM_V + vst1) = sr_[i].vs1; \
;     _Pragma("unroll") for (int _c = 0; _c < NKC; ++_c) *(LAS bf16x8*)(K_lds + (b) * SHM_K + kswz<DQK>(krow[_c], kcol[_c] * 2)) = sr_[i].ks[_c]; } while (0)
; #define SWAIT() do { if constexpr (SDEPTH == 2) { if constexpr (NKC == 1) asm volatile("s_waitcnt vmcnt(3)" ::: "memory"); else if constexpr (NKC == 2) asm volatile("s_waitcnt vmcnt(4)" ::: "memory"); else asm volatile("s_waitcnt vmcnt(5)" ::: "memory"); } \
;     else asm volatile("s_waitcnt vmcnt(0)" ::: "memory"); } while (0)
; DI void partialSM(f32x16& p0, f32x16& p1, float& m_reg, float& mn, float& alpha, const float SCALE) {
;     ...
;   if (__builtin_expect(__all(pmax - m_reg <= THR / SCALE), 1)) { mn = m_reg; alpha = 1.f; }
;   else { mn = fmaxf(m_reg, pmax); alpha = __builtin_amdgcn_exp2f((m_reg - mn) * C); m_reg = mn; }
;   const float mnC = -mn * C;
; #pragma unroll
;   for (int r = 0; r < 16; ++r) p0[r] = fmaf(p0[r], C, mnC);
; #pragma unroll
;   for (int r = 0; r < 16; ++r) p1[r] = fmaf(p1[r], C, mnC);
; #pragma unroll
;   for (int r = 0; r < 16; ++r) p0[r] = __builtin_amdgcn_exp2f(p0[r]);
; template <int DQK, int SDEPTH, bool OUT_BF16, int QREG = DQK / 16, bool OUT_F16 = false> ...
;     ...
;   SLOAD(SO, KVBLK); if constexpr (SDEPTH == 2) { if (2 < NT) SLOAD(SE, 2 * KVBLK); }
;   SWAIT(); SWRITE(1, SO); __syncthreads();
;   for (int j = 1; j + 1 < NT; j += 2) {
;     SBAR(); QKT(pB0, pB1, K_lds + SHM_K);
;     finishSM(pA0, pA1, alA, l_reg, pa0, pa1, pa2, pa3); SBAR();
	s_waitcnt vmcnt(4)
	ds_write_b128 v167, v[50:53] offset:16384
	s_waitcnt vmcnt(3)
	ds_write_b128 v168, v[54:57] offset:16384
	s_waitcnt vmcnt(2)
	ds_write_b128 v169, v[58:61] offset:57344
	s_waitcnt vmcnt(1)
	ds_write_b128 v170, v[62:65] offset:57344
	s_waitcnt vmcnt(0)
	ds_write_b128 v171, v[66:69] offset:57344
	s_cselect_b64 vcc, -1, 0
	v_max_f32_e32 v51, 0xf149f2ca, v87
	v_cndmask_b32_e32 v194, v51, v239, vcc
	v_mul_f32_e32 v50, 0xbdd53b94, v194
	v_fmamk_f32 v34, v34, 0x3dd53b94, v50
	v_exp_f32_e32 v134, v34
	v_fmamk_f32 v34, v35, 0x3dd53b94, v50
	v_exp_f32_e32 v135, v34
	v_fmamk_f32 v34, v36, 0x3dd53b94, v50
	v_exp_f32_e32 v136, v34
	v_fmamk_f32 v34, v37, 0x3dd53b94, v50
	v_exp_f32_e32 v138, v34
	v_fmamk_f32 v34, v38, 0x3dd53b94, v50
	v_exp_f32_e32 v155, v34
	v_fmamk_f32 v34, v39, 0x3dd53b94, v50
	v_exp_f32_e32 v156, v34
	v_fmamk_f32 v34, v40, 0x3dd53b94, v50
	v_exp_f32_e32 v137, v34
	v_fmamk_f32 v34, v41, 0x3dd53b94, v50
	v_pk_fma_f32 v[126:127], v[18:19], s[30:31], v[50:51] op_sel_hi:[1,0,0]
	v_sub_f32_e32 v18, 0xf149f2ca, v51
	v_exp_f32_e32 v154, v34
	v_fmamk_f32 v34, v42, 0x3dd53b94, v50
	v_mul_f32_e32 v18, 0x3dd53b94, v18
	v_exp_f32_e32 v131, v34
	v_fmamk_f32 v34, v43, 0x3dd53b94, v50
	v_exp_f32_e32 v18, v18
	v_exp_f32_e32 v133, v34
	v_fmamk_f32 v34, v44, 0x3dd53b94, v50
	v_exp_f32_e32 v139, v34
	v_fmamk_f32 v34, v45, 0x3dd53b94, v50
	v_exp_f32_e32 v152, v34
	v_fmamk_f32 v34, v46, 0x3dd53b94, v50
	s_add_i32 s2, 0, 0x4000
	v_exp_f32_e32 v132, v34
	v_fmamk_f32 v34, v47, 0x3dd53b94, v50
	v_cndmask_b32_e64 v197, v18, 1.0, vcc
	v_add_u32_e32 v165, s2, v86
	v_mad_i64_i32 v[18:19], s[2:3], s38, v240, v[80:81]
	v_exp_f32_e32 v140, v34
	v_fmamk_f32 v34, v48, 0x3dd53b94, v50
	v_lshl_add_u64 v[144:145], v[18:19], 0, v[82:83]
	v_mad_i64_i32 v[18:19], s[2:3], s38, v240, v[76:77]
	v_exp_f32_e32 v141, v34
	v_fmamk_f32 v34, v49, 0x3dd53b94, v50
	v_lshl_add_u64 v[146:147], v[18:19], 0, v[78:79]
	v_mad_i64_i32 v[18:19], s[2:3], s38, v240, v[72:73]
	v_exp_f32_e32 v153, v34
	v_lshl_add_u64 v[148:149], v[18:19], 0, v[74:75]
	v_mov_b32_e32 v18, 0x210000
	v_mad_i64_i32 v[150:151], s[2:3], s38, v18, v[70:71]
	v_and_b32_e32 v18, 15, v84
	v_pk_fma_f32 v[114:115], v[32:33], s[30:31], v[50:51] op_sel_hi:[1,0,0]
	v_pk_fma_f32 v[120:121], v[30:31], s[30:31], v[50:51] op_sel_hi:[1,0,0]
	v_pk_fma_f32 v[128:129], v[28:29], s[30:31], v[50:51] op_sel_hi:[1,0,0]
	v_pk_fma_f32 v[116:117], v[26:27], s[30:31], v[50:51] op_sel_hi:[1,0,0]
	v_pk_fma_f32 v[118:119], v[24:25], s[30:31], v[50:51] op_sel_hi:[1,0,0]
	v_pk_fma_f32 v[122:123], v[22:23], s[30:31], v[50:51] op_sel_hi:[1,0,0]
	v_pk_fma_f32 v[124:125], v[20:21], s[30:31], v[50:51] op_sel_hi:[1,0,0]
	v_lshl_or_b32 v150, v18, 4, v150
	v_mov_b64_e32 v[64:65], v[16:17]
	v_mov_b64_e32 v[48:49], v[16:17]
	v_mov_b64_e32 v[32:33], v[16:17]
	v_cmp_gt_u32_e64 s[0:1], 32, v85
	v_mov_b64_e32 v[62:63], v[14:15]
	v_mov_b64_e32 v[60:61], v[12:13]
	v_mov_b64_e32 v[58:59], v[10:11]
	v_mov_b64_e32 v[56:57], v[8:9]
	v_mov_b64_e32 v[54:55], v[6:7]
	v_mov_b64_e32 v[52:53], v[4:5]
	v_mov_b64_e32 v[50:51], v[2:3]
	v_mov_b64_e32 v[46:47], v[14:15]
	v_mov_b64_e32 v[44:45], v[12:13]
	v_mov_b64_e32 v[42:43], v[10:11]
	v_mov_b64_e32 v[40:41], v[8:9]
	v_mov_b64_e32 v[38:39], v[6:7]
	v_mov_b64_e32 v[36:37], v[4:5]
	v_mov_b64_e32 v[34:35], v[2:3]
	v_mov_b64_e32 v[30:31], v[14:15]
	v_mov_b64_e32 v[28:29], v[12:13]
	v_mov_b64_e32 v[26:27], v[10:11]
	v_mov_b64_e32 v[24:25], v[8:9]
	v_mov_b64_e32 v[22:23], v[6:7]
	v_mov_b64_e32 v[20:21], v[4:5]
	v_mov_b64_e32 v[18:19], v[2:3]
	s_waitcnt lgkmcnt(0)
	s_barrier
	s_add_u32 s80, s4, 0x4487c000
	s_addc_u32 s81, s5, 0
	s_add_u32 s82, s4, 0x4487e000
	s_addc_u32 s83, s5, 0
	s_add_u32 s84, s4, s97
	s_addc_u32 s85, s5, 0
	s_add_u32 s86, s4, 0x44880000
	s_addc_u32 s87, s5, 0
	s_add_u32 s88, s4, 0x44882000
	s_addc_u32 s89, s5, 0
	s_add_u32 s90, s4, s79
	s_addc_u32 s91, s5, 0
.LBB0_748:
	ds_read_b128 v[66:69], v196
	ds_read_b128 v[70:73], v196 offset:12288
	ds_read_b128 v[198:201], v195
	ds_read_b128 v[202:205], v195 offset:12288
	v_add_f32_e32 v130, 0, v134
	v_add_f32_e32 v130, v135, v130
	s_waitcnt lgkmcnt(3)
	v_mfma_f32_32x32x16_bf16 v[82:97], v[66:69], v[110:113], 0
	v_add_f32_e32 v130, v136, v130
	v_add_f32_e32 v130, v138, v130
	v_add_f32_e32 v130, v155, v130
	v_add_f32_e32 v130, v156, v130
	v_add_f32_e32 v130, v137, v130
	v_add_f32_e32 v130, v154, v130
	v_add_f32_e32 v130, v131, v130
	s_waitcnt lgkmcnt(2)
	v_mfma_f32_32x32x16_bf16 v[66:81], v[70:73], v[110:113], 0
	v_add_f32_e32 v130, v133, v130
	v_add_f32_e32 v130, v139, v130
	v_add_f32_e32 v130, v152, v130
	v_exp_f32_e32 v126, v126
	v_add_f32_e32 v130, v132, v130
	v_exp_f32_e32 v127, v127
	v_add_f32_e32 v130, v140, v130
	s_waitcnt lgkmcnt(1)
	v_mfma_f32_32x32x16_bf16 v[82:97], v[198:201], v[106:109], v[82:97]
	v_exp_f32_e32 v124, v124
	v_add_f32_e32 v130, v141, v130
	v_exp_f32_e32 v125, v125
	v_add_f32_e32 v130, v153, v130
	v_exp_f32_e32 v122, v122
	v_add_f32_e32 v130, v126, v130
	v_exp_f32_e32 v123, v123
	s_waitcnt lgkmcnt(0)
	v_mfma_f32_32x32x16_bf16 v[66:81], v[202:205], v[106:109], v[66:81]
	ds_read_b128 v[198:201], v193
	ds_read_b128 v[202:205], v193 offset:12288
	v_add_f32_e32 v130, v127, v130
	v_exp_f32_e32 v118, v118
	v_add_f32_e32 v130, v124, v130
	v_exp_f32_e32 v119, v119
	v_add_f32_e32 v130, v125, v130
	v_exp_f32_e32 v116, v116
	s_waitcnt lgkmcnt(1)
	v_mfma_f32_32x32x16_bf16 v[82:97], v[198:201], v[102:105], v[82:97]
	v_add_f32_e32 v130, v122, v130
	v_exp_f32_e32 v117, v117
	v_add_f32_e32 v130, v123, v130
	v_exp_f32_e32 v128, v128
	v_add_f32_e32 v130, v118, v130
	v_exp_f32_e32 v129, v129
	v_add_f32_e32 v130, v119, v130
	s_waitcnt lgkmcnt(0)
; #define LAS __attribute__((address_space(3)))
; DI void finishSM(f32x16& p0, f32x16& p1, float alpha, float& l_reg, bf16x8& pa0, bf16x8& pa1, bf16x8& pa2, bf16x8& pa3) {
; #pragma unroll
;   for (int r = 0; r < 16; ++r) p1[r] = __builtin_amdgcn_exp2f(p1[r]);
;   float ps = 0;
; #pragma unroll
;   for (int r = 0; r < 16; ++r) ps += p0[r];
; #pragma unroll
;   for (int r = 0; r < 16; ++r) ps += p1[r];
;   { auto rr = __builtin_amdgcn_permlane32_swap(__float_as_uint(ps), __float_as_uint(ps), false, false);
;     ps = __uint_as_float(rr[0]) + __uint_as_float(rr[1]); }
;   l_reg = l_reg * alpha + ps;
;     ...
;   PK4(p0, 0, pa0); PK4(p0, 8, pa1); PK4(p1, 0, pa2); PK4(p1, 8, pa3);
;     ...
; }
; template <int DQK> DI void qkt(f32x16& p0, f32x16& p1, const LAS char* Ks, const bf16x8* qr, int r32, int hi) {
;   p0 = f32x16{}; p1 = f32x16{};
; #pragma unroll
;   for (int d0 = 0; d0 < DQK / 16; ++d0) { const int cb = (d0 * 16 + hi * 8) * 2;
;     const bf16x8 b0 = *(const LAS bf16x8*)(Ks + kswz<DQK>(r32, cb));
;     const bf16x8 b1 = *(const LAS bf16x8*)(Ks + kswz<DQK>(32 + r32, cb));
;     p0 = __builtin_amdgcn_mfma_f32_32x32x16_bf16(b0, qr[d0], p0, 0, 0, 0);
;     p1 = __builtin_amdgcn_mfma_f32_32x32x16_bf16(b1, qr[d0], p1, 0, 0, 0); }
; }
; DI int v_st(int k, int c) { const int kk = (k & ~0xC) | ((k & 4) << 1) | ((k & 8) >> 1); return ((kk >> 3) * 4 + (c >> 5)) * 512 + ((kk & 7) * 32 + (c & 31)) * 2; }
; DI int v_rd_base(int lane) { return ((lane & 3) << 3) | (((lane >> 2) & 3) << 6) | (((lane >> 4) & 1) << 5) | (((lane >> 5) & 1) << 8); }
; template <int OFF> DI s16x4 tr_read(int vb) { s16x4 r; asm volatile("ds_read_b64_tr_b16 %0, %1 offset:%2" : "=&v"(r) : "v"(vb), "i"(OFF) : "memory"); return r; }
; template <int D0> DI void pv_one(f32x16& od, int vb, bf16x8 pa0, bf16x8 pa1, bf16x8 pa2, bf16x8 pa3) {
;   const s16x4 l0 = tr_read<v_rd_off(D0, 0, 0)>(vb), h0 = tr_read<v_rd_off(D0, 0, 1)>(vb), l1 = tr_read<v_rd_off(D0, 1, 0)>(vb), h1 = tr_read<v_rd_off(D0, 1, 1)>(vb);
;   const s16x4 l2 = tr_read<v_rd_off(D0, 2, 0)>(vb), h2 = tr_read<v_rd_off(D0, 2, 1)>(vb), l3 = tr_read<v_rd_off(D0, 3, 0)>(vb), h3 = tr_read<v_rd_off(D0, 3, 1)>(vb);
;   asm volatile("s_waitcnt lgkmcnt(0)" ::: "memory"); SBAR();
;     ...
;   od = __builtin_amdgcn_mfma_f32_32x32x16_bf16(pa0, PK(l0, h0), od, 0, 0, 0);
;   od = __builtin_amdgcn_mfma_f32_32x32x16_bf16(pa1, PK(l1, h1), od, 0, 0, 0);
	v_mfma_f32_32x32x16_bf16 v[66:81], v[202:205], v[102:105], v[66:81]
	ds_read_b128 v[198:201], v192
	ds_read_b128 v[202:205], v192 offset:12288
	v_exp_f32_e32 v120, v120
	v_add_f32_e32 v130, v116, v130
	v_exp_f32_e32 v121, v121
	v_add_f32_e32 v130, v117, v130
	v_exp_f32_e32 v114, v114
	v_add_f32_e32 v130, v128, v130
	s_waitcnt lgkmcnt(1)
	v_mfma_f32_32x32x16_bf16 v[82:97], v[198:201], v[98:101], v[82:97]
	v_exp_f32_e32 v115, v115
	v_add_f32_e32 v130, v129, v130
	v_add_f32_e32 v130, v120, v130
	v_add_f32_e32 v130, v121, v130
	v_add_f32_e32 v130, v114, v130
	v_cvt_pk_bf16_f32 v134, v134, v135
	v_cvt_pk_bf16_f32 v135, v136, v138
	s_waitcnt lgkmcnt(0)
	v_mfma_f32_32x32x16_bf16 v[66:81], v[202:205], v[98:101], v[66:81]
	ds_read_b128 v[198:201], v191
	ds_read_b128 v[202:205], v191 offset:12288
	ds_read_b128 v[206:209], v162
	v_cvt_pk_bf16_f32 v136, v155, v156
	v_cvt_pk_bf16_f32 v137, v137, v154
	s_nop 0
	v_permlane32_swap_b32_e32 v134, v136
	v_cvt_pk_bf16_f32 v138, v131, v133
	v_cvt_pk_bf16_f32 v139, v139, v152
	s_waitcnt lgkmcnt(0)
	v_mfma_f32_32x32x16_bf16 v[82:97], v[198:201], v[206:209], v[82:97]
	v_cvt_pk_bf16_f32 v140, v132, v140
	v_cvt_pk_bf16_f32 v141, v141, v153
	v_cvt_pk_bf16_f32 v214, v126, v127
	v_cvt_pk_bf16_f32 v215, v124, v125
	v_cvt_pk_bf16_f32 v216, v122, v123
	v_cvt_pk_bf16_f32 v217, v118, v119
	v_cvt_pk_bf16_f32 v218, v116, v117
	v_mfma_f32_32x32x16_bf16 v[66:81], v[202:205], v[206:209], v[66:81]
	ds_read_b128 v[198:201], v190
	ds_read_b128 v[202:205], v190 offset:12288
	ds_read_b128 v[206:209], v162 offset:1024
	v_cvt_pk_bf16_f32 v219, v128, v129
	v_cvt_pk_bf16_f32 v220, v120, v121
	v_cvt_pk_bf16_f32 v221, v114, v115
	v_permlane32_swap_b32_e32 v135, v137
	v_permlane32_swap_b32_e32 v138, v140
	s_waitcnt lgkmcnt(0)
	v_mfma_f32_32x32x16_bf16 v[82:97], v[198:201], v[206:209], v[82:97]
	v_permlane32_swap_b32_e32 v139, v141
	v_permlane32_swap_b32_e32 v214, v216
	v_permlane32_swap_b32_e32 v215, v217
	v_permlane32_swap_b32_e32 v218, v220
	v_mfma_f32_32x32x16_bf16 v[66:81], v[202:205], v[206:209], v[66:81]
	ds_read_b128 v[198:201], v189
	ds_read_b128 v[202:205], v189 offset:12288
	ds_read_b128 v[206:209], v162 offset:2048
	v_permlane32_swap_b32_e32 v219, v221
	s_waitcnt lgkmcnt(0)
	v_mfma_f32_32x32x16_bf16 v[82:97], v[198:201], v[206:209], v[82:97]
	v_mfma_f32_32x32x16_bf16 v[66:81], v[202:205], v[206:209], v[66:81]
	ds_read_b128 v[198:201], v188
	ds_read_b128 v[202:205], v188 offset:12288
	ds_read_b128 v[206:209], v162 offset:3072
	s_waitcnt lgkmcnt(0)
	v_mfma_f32_32x32x16_bf16 v[82:97], v[198:201], v[206:209], v[82:97]
	v_mfma_f32_32x32x16_bf16 v[66:81], v[202:205], v[206:209], v[66:81]
	ds_read_b128 v[198:201], v187
	ds_read_b128 v[202:205], v187 offset:12288
	ds_read_b128 v[206:209], v162 offset:4096
	s_waitcnt lgkmcnt(0)
	v_mfma_f32_32x32x16_bf16 v[82:97], v[198:201], v[206:209], v[82:97]
	v_mfma_f32_32x32x16_bf16 v[66:81], v[202:205], v[206:209], v[66:81]
	ds_read_b128 v[198:201], v186
	ds_read_b128 v[202:205], v186 offset:12288
	ds_read_b128 v[206:209], v162 offset:5120
	s_waitcnt lgkmcnt(0)
	v_mfma_f32_32x32x16_bf16 v[82:97], v[198:201], v[206:209], v[82:97]
	v_mfma_f32_32x32x16_bf16 v[66:81], v[202:205], v[206:209], v[66:81]
	ds_read_b128 v[198:201], v185
	ds_read_b128 v[202:205], v185 offset:12288
	ds_read_b128 v[206:209], v162 offset:6144
	s_waitcnt lgkmcnt(0)
	v_mfma_f32_32x32x16_bf16 v[82:97], v[198:201], v[206:209], v[82:97]
	v_mfma_f32_32x32x16_bf16 v[66:81], v[202:205], v[206:209], v[66:81]
	ds_read_b128 v[198:201], v184
	ds_read_b128 v[202:205], v184 offset:12288
	ds_read_b128 v[206:209], v162 offset:7168
	s_waitcnt lgkmcnt(0)
	v_mfma_f32_32x32x16_bf16 v[82:97], v[198:201], v[206:209], v[82:97]
	v_add_f32_e32 v198, v115, v130
	v_mov_b32_e32 v199, v198
	s_nop 1
	v_permlane32_swap_b32_e32 v198, v199
	global_load_dwordx4 v[114:117], v150, s[80:81]
	global_load_dwordx4 v[118:121], v150, s[82:83]
	global_load_dwordx4 v[122:125], v148, s[84:85]
	global_load_dwordx4 v[126:129], v146, s[84:85]
	global_load_dwordx4 v[130:133], v144, s[84:85]
	v_mfma_f32_32x32x16_bf16 v[66:81], v[202:205], v[206:209], v[66:81]
	ds_read_b64_tr_b16 v[200:201], v163 offset:0
	ds_read_b64_tr_b16 v[202:203], v163 offset:0x800
	ds_read_b64_tr_b16 v[204:205], v163 offset:0x1000
	ds_read_b64_tr_b16 v[206:207], v163 offset:0x1800
	ds_read_b64_tr_b16 v[208:209], v163 offset:0x2000
	ds_read_b64_tr_b16 v[210:211], v163 offset:0x2800
	ds_read_b64_tr_b16 v[222:223], v163 offset:0x3000
	ds_read_b64_tr_b16 v[224:225], v163 offset:0x3800
	s_waitcnt lgkmcnt(0)
	s_nop 0
	v_mfma_f32_32x32x16_bf16 v[2:17], v[134:137], v[200:203], v[2:17]
	ds_read_b64_tr_b16 v[200:201], v163 offset:0x200
	ds_read_b64_tr_b16 v[202:203], v163 offset:0xa00
	v_mfma_f32_32x32x16_bf16 v[2:17], v[138:141], v[204:207], v[2:17]
	ds_read_b64_tr_b16 v[204:205], v163 offset:0x1200
	ds_read_b64_tr_b16 v[206:207], v163 offset:0x1a00
	v_mfma_f32_32x32x16_bf16 v[2:17], v[214:217], v[208:211], v[2:17]
	ds_read_b64_tr_b16 v[208:209], v163 offset:0x2200
	ds_read_b64_tr_b16 v[210:211], v163 offset:0x2a00
	v_mfma_f32_32x32x16_bf16 v[2:17], v[218:221], v[222:225], v[2:17]
	ds_read_b64_tr_b16 v[222:223], v163 offset:0x3200
	ds_read_b64_tr_b16 v[224:225], v163 offset:0x3a00
	s_waitcnt lgkmcnt(0)
	v_mfma_f32_32x32x16_bf16 v[50:65], v[134:137], v[200:203], v[50:65]
	ds_read_b64_tr_b16 v[200:201], v163 offset:0x400
	ds_read_b64_tr_b16 v[202:203], v163 offset:0xc00
	v_mfma_f32_32x32x16_bf16 v[50:65], v[138:141], v[204:207], v[50:65]
	ds_read_b64_tr_b16 v[204:205], v163 offset:0x1400
	ds_read_b64_tr_b16 v[206:207], v163 offset:0x1c00
	v_mfma_f32_32x32x16_bf16 v[50:65], v[214:217], v[208:211], v[50:65]
	ds_read_b64_tr_b16 v[208:209], v163 offset:0x2400
	ds_read_b64_tr_b16 v[210:211], v163 offset:0x2c00
	v_mfma_f32_32x32x16_bf16 v[50:65], v[218:221], v[222:225], v[50:65]
	ds_read_b64_tr_b16 v[222:223], v163 offset:0x3400
	ds_read_b64_tr_b16 v[224:225], v163 offset:0x3c00
	s_waitcnt lgkmcnt(0)
; #define SWRITE(b, i) do { *(LAS bf16x8*)(V_lds + (b) * SHM_V + vst0) = sr_[i].vs0; *(LAS bf16x8*)(V_lds + (b) * SHM_V + vst1) = sr_[i].vs1; \
;     _Pragma("unroll") for (int _c = 0; _c < NKC; ++_c) *(LAS bf16x8*)(K_lds + (b) * SHM_K + kswz<DQK>(krow[_c], kcol[_c] * 2)) = sr_[i].ks[_c]; } while (0)
; #define SWAIT() do { if constexpr (SDEPTH == 2) { if constexpr (NKC == 1) asm volatile("s_waitcnt vmcnt(3)" ::: "memory"); else if constexpr (NKC == 2) asm volatile("s_waitcnt vmcnt(4)" ::: "memory"); else asm volatile("s_waitcnt vmcnt(5)" ::: "memory"); } \
;     else asm volatile("s_waitcnt vmcnt(0)" ::: "memory"); } while (0)
; #define RESC(a) do { if (__any((a) < 1.f)) { if (hi == 0) al_l[r32] = (a); asm volatile("s_waitcnt lgkmcnt(0)" ::: "memory"); \
;     _Pragma("unroll") for (int d = 0; d < 4; ++d) _Pragma("unroll") for (int r = 0; r < 16; ++r) o[d][r] *= al_l[crow(r, hi)]; } } while (0)
; DI void partialSM(f32x16& p0, f32x16& p1, float& m_reg, float& mn, float& alpha, const float SCALE) {
;   const float C = SCALE * 1.4426950408889634f;
;   float pmax = p0[0];
; #pragma unroll
;   for (int r = 1; r < 16; ++r) pmax = fmaxf(pmax, p0[r]);
; #pragma unroll
;   for (int r = 0; r < 16; ++r) pmax = fmaxf(pmax, p1[r]);
;   { auto rr = __builtin_amdgcn_permlane32_swap(__float_as_uint(pmax), __float_as_uint(pmax), false, false);
;     pmax = fmaxf(__uint_as_float(rr[0]), __uint_as_float(rr[1])); }
;   if (__builtin_expect(__all(pmax - m_reg <= THR / SCALE), 1)) { mn = m_reg; alpha = 1.f; }
;   else { mn = fmaxf(m_reg, pmax); alpha = __builtin_amdgcn_exp2f((m_reg - mn) * C); m_reg = mn; }
; template <int DQK, int SDEPTH, bool OUT_BF16, int QREG = DQK / 16, bool OUT_F16 = false> ...
;     ...
;     __syncthreads(); SWAIT(); SWRITE(0, SE);
;     RESC(alB); __syncthreads();
	v_mfma_f32_32x32x16_bf16 v[34:49], v[134:137], v[200:203], v[34:49]
	ds_read_b64_tr_b16 v[200:201], v163 offset:0x600
	ds_read_b64_tr_b16 v[202:203], v163 offset:0xe00
	v_mfma_f32_32x32x16_bf16 v[34:49], v[138:141], v[204:207], v[34:49]
	ds_read_b64_tr_b16 v[204:205], v163 offset:0x1600
	ds_read_b64_tr_b16 v[206:207], v163 offset:0x1e00
	v_mfma_f32_32x32x16_bf16 v[34:49], v[214:217], v[208:211], v[34:49]
	ds_read_b64_tr_b16 v[208:209], v163 offset:0x2600
	ds_read_b64_tr_b16 v[210:211], v163 offset:0x2e00
	v_mfma_f32_32x32x16_bf16 v[34:49], v[218:221], v[222:225], v[34:49]
	ds_read_b64_tr_b16 v[222:223], v163 offset:0x3600
	ds_read_b64_tr_b16 v[224:225], v163 offset:0x3e00
	s_waitcnt lgkmcnt(0)
	v_mfma_f32_32x32x16_bf16 v[18:33], v[134:137], v[200:203], v[18:33]
	v_max_f32_e32 v134, v83, v83
	v_max_f32_e32 v135, v82, v82
	v_max_f32_e32 v134, v135, v134
	v_max3_f32 v134, v134, v84, v85
	v_max3_f32 v134, v134, v86, v87
	v_max3_f32 v134, v134, v88, v89
	v_max3_f32 v134, v134, v90, v91
	v_max3_f32 v134, v134, v92, v93
	v_max3_f32 v134, v134, v94, v95
	v_mfma_f32_32x32x16_bf16 v[18:33], v[138:141], v[204:207], v[18:33]
	v_max3_f32 v134, v134, v96, v97
	v_max3_f32 v134, v134, v66, v67
	v_max3_f32 v134, v134, v68, v69
	v_max3_f32 v134, v134, v70, v71
	v_max3_f32 v134, v134, v72, v73
	v_max3_f32 v134, v134, v74, v75
	v_max3_f32 v134, v134, v76, v77
	v_max3_f32 v134, v134, v78, v79
	v_mfma_f32_32x32x16_bf16 v[18:33], v[214:217], v[208:211], v[18:33]
	v_max3_f32 v134, v134, v80, v81
	v_mov_b32_e32 v135, v134
	s_nop 1
	v_permlane32_swap_b32_e32 v134, v135
	v_max_f32_e32 v135, v135, v135
	v_max_f32_e32 v134, v134, v134
	v_max_f32_e32 v134, v134, v135
	v_sub_f32_e32 v135, v134, v194
	v_cmp_ge_f32_e32 vcc, s96, v135
	v_max_f32_e32 v135, v194, v194
	v_max_f32_e32 v134, v135, v134
	v_mfma_f32_32x32x16_bf16 v[18:33], v[218:221], v[222:225], v[18:33]
	v_sub_f32_e32 v135, v194, v134
	v_mul_f32_e32 v135, 0x3dd53b94, v135
	s_barrier
	s_waitcnt vmcnt(0)
	s_waitcnt vmcnt(4)
	ds_write_b128 v167, v[114:117]
	s_waitcnt vmcnt(3)
	ds_write_b128 v168, v[118:121]
	s_waitcnt vmcnt(2)
	ds_write_b128 v169, v[122:125] offset:32768
	s_waitcnt vmcnt(1)
	ds_write_b128 v170, v[126:129] offset:32768
	s_waitcnt vmcnt(0)
	ds_write_b128 v171, v[130:133] offset:32768
	v_exp_f32_e32 v114, v135
	s_cmp_eq_u64 vcc, exec
	s_cselect_b64 s[2:3], -1, 0
	v_cndmask_b32_e64 v200, v114, 1.0, s[2:3]
	v_cmp_gt_f32_e32 vcc, 1.0, v200
	s_cbranch_vccz .LBB0_752
	s_and_saveexec_b64 s[10:11], s[0:1]
	ds_write_b32 v164, v200 offset:128
	s_or_b64 exec, exec, s[10:11]
	s_waitcnt lgkmcnt(0)
	v_add_u32_e32 v126, v143, v0
	ds_read_b128 v[114:117], v126 offset:224
	ds_read_b128 v[118:121], v126 offset:192
	ds_read_b128 v[122:125], v126 offset:160
	ds_read_b128 v[126:129], v126 offset:128
	s_waitcnt lgkmcnt(3)
	v_pk_mul_f32 v[14:15], v[14:15], v[114:115]
	s_waitcnt lgkmcnt(2)
	v_pk_mul_f32 v[10:11], v[10:11], v[118:119]
	s_waitcnt lgkmcnt(1)
	v_pk_mul_f32 v[6:7], v[6:7], v[122:123]
	v_pk_mul_f32 v[16:17], v[16:17], v[116:117]
	v_pk_mul_f32 v[12:13], v[12:13], v[120:121]
	v_pk_mul_f32 v[8:9], v[8:9], v[124:125]
	s_waitcnt lgkmcnt(0)
	v_pk_mul_f32 v[4:5], v[4:5], v[128:129]
	v_pk_mul_f32 v[2:3], v[2:3], v[126:127]
	v_pk_mul_f32 v[62:63], v[62:63], v[114:115]
	v_pk_mul_f32 v[58:59], v[58:59], v[118:119]
	v_pk_mul_f32 v[54:55], v[54:55], v[122:123]
	v_pk_mul_f32 v[64:65], v[64:65], v[116:117]
	v_pk_mul_f32 v[60:61], v[60:61], v[120:121]
	v_pk_mul_f32 v[56:57], v[56:57], v[124:125]
	v_pk_mul_f32 v[52:53], v[52:53], v[128:129]
	v_pk_mul_f32 v[50:51], v[50:51], v[126:127]
	v_pk_mul_f32 v[46:47], v[46:47], v[114:115]
	v_pk_mul_f32 v[42:43], v[42:43], v[118:119]
	v_pk_mul_f32 v[38:39], v[38:39], v[122:123]
	v_pk_mul_f32 v[48:49], v[48:49], v[116:117]
	v_pk_mul_f32 v[44:45], v[44:45], v[120:121]
	v_pk_mul_f32 v[40:41], v[40:41], v[124:125]
	v_pk_mul_f32 v[36:37], v[36:37], v[128:129]
	v_pk_mul_f32 v[34:35], v[34:35], v[126:127]
	v_pk_mul_f32 v[30:31], v[30:31], v[114:115]
	v_pk_mul_f32 v[26:27], v[26:27], v[118:119]
	v_pk_mul_f32 v[22:23], v[22:23], v[122:123]
	v_pk_mul_f32 v[32:33], v[32:33], v[116:117]
	v_pk_mul_f32 v[28:29], v[28:29], v[120:121]
	v_pk_mul_f32 v[24:25], v[24:25], v[124:125]
	v_pk_mul_f32 v[20:21], v[20:21], v[128:129]
	v_pk_mul_f32 v[18:19], v[18:19], v[126:127]
; #define SBAR() __builtin_amdgcn_sched_barrier(0)
; #define SLOAD(i, k0) do { sr_[i].vs0 = *reinterpret_cast<const bf16x8*>(&Vh[(long)((k0) + sr) * DV + sc]); sr_[i].vs1 = *reinterpret_cast<const bf16x8*>(&Vh[(long)((k0) + 32 + sr) * DV + sc]); \
;     _Pragma("unroll") for (int _c = 0; _c < NKC; ++_c) sr_[i].ks[_c] = *reinterpret_cast<const bf16x8*>(&Kh[(long)((k0) + krow[_c]) * DQK + kcol[_c]]); } while (0)
; DI void partialSM(f32x16& p0, f32x16& p1, float& m_reg, float& mn, float& alpha, const float SCALE) {
;   const float C = SCALE * 1.4426950408889634f;
;   float pmax = p0[0];
; #pragma unroll
;   for (int r = 1; r < 16; ++r) pmax = fmaxf(pmax, p0[r]);
; #pragma unroll
;   for (int r = 0; r < 16; ++r) pmax = fmaxf(pmax, p1[r]);
;   { auto rr = __builtin_amdgcn_permlane32_swap(__float_as_uint(pmax), __float_as_uint(pmax), false, false);
;     pmax = fmaxf(__uint_as_float(rr[0]), __uint_as_float(rr[1])); }
;   if (__builtin_expect(__all(pmax - m_reg <= THR / SCALE), 1)) { mn = m_reg; alpha = 1.f; }
;   else { mn = fmaxf(m_reg, pmax); alpha = __builtin_amdgcn_exp2f((m_reg - mn) * C); m_reg = mn; }
;   const float mnC = -mn * C;
; #pragma unroll
;   for (int r = 0; r < 16; ++r) p0[r] = fmaf(p0[r], C, mnC);
; #pragma unroll
;   for (int r = 0; r < 16; ++r) p1[r] = fmaf(p1[r], C, mnC);
; #pragma unroll
;   for (int r = 0; r < 16; ++r) p0[r] = __builtin_amdgcn_exp2f(p0[r]);
; }
; template <int DQK, int SDEPTH, bool OUT_BF16, int QREG = DQK / 16, bool OUT_F16 = false> ...
;     ...
;     SBAR(); QKT(pA0, pA1, K_lds);
;     finishSM(pB0, pB1, alB, l_reg, pa0, pa1, pa2, pa3); SBAR();
;     if (SDEPTH == 1 || j + 3 < NT) SLOAD(SE, (j + 1 + SDEPTH) * KVBLK); SBAR();
;     pv_d0(o, vb0 + SHM_V, pa0, pa1, pa2, pa3); partialSM(pA0, pA1, m_reg, mnA, alA, SCALE);
.LBB0_752:
	v_cndmask_b32_e64 v194, v134, v194, s[2:3]
	v_mul_f32_e32 v130, 0xbdd53b94, v194
	v_fmamk_f32 v82, v82, 0x3dd53b94, v130
	v_fmamk_f32 v83, v83, 0x3dd53b94, v130
	v_fmamk_f32 v84, v84, 0x3dd53b94, v130
	v_fmamk_f32 v85, v85, 0x3dd53b94, v130
	v_fmamk_f32 v86, v86, 0x3dd53b94, v130
	v_fmamk_f32 v87, v87, 0x3dd53b94, v130
	v_fmamk_f32 v88, v88, 0x3dd53b94, v130
	v_fmamk_f32 v89, v89, 0x3dd53b94, v130
	v_fmamk_f32 v90, v90, 0x3dd53b94, v130
	v_fmamk_f32 v91, v91, 0x3dd53b94, v130
	v_fmamk_f32 v92, v92, 0x3dd53b94, v130
	v_fmamk_f32 v93, v93, 0x3dd53b94, v130
	v_fmamk_f32 v94, v94, 0x3dd53b94, v130
	v_fmamk_f32 v95, v95, 0x3dd53b94, v130
	v_fmamk_f32 v96, v96, 0x3dd53b94, v130
	v_fmamk_f32 v97, v97, 0x3dd53b94, v130
	v_fmamk_f32 v135, v66, 0x3dd53b94, v130
	v_fmamk_f32 v134, v68, 0x3dd53b94, v130
	v_fmamk_f32 v133, v70, 0x3dd53b94, v130
	v_fmamk_f32 v132, v72, 0x3dd53b94, v130
	v_fmamk_f32 v131, v74, 0x3dd53b94, v130
	v_fmamk_f32 v138, v76, 0x3dd53b94, v130
	v_fmamk_f32 v137, v78, 0x3dd53b94, v130
	v_fmamk_f32 v136, v80, 0x3dd53b94, v130
	v_fmamk_f32 v139, v67, 0x3dd53b94, v130
	v_fmamk_f32 v140, v69, 0x3dd53b94, v130
	v_fmamk_f32 v141, v71, 0x3dd53b94, v130
	v_fmamk_f32 v201, v73, 0x3dd53b94, v130
	v_fmamk_f32 v210, v75, 0x3dd53b94, v130
	v_fmamk_f32 v211, v77, 0x3dd53b94, v130
	v_fmamk_f32 v218, v79, 0x3dd53b94, v130
	v_fmac_f32_e32 v130, 0x3dd53b94, v81
	v_exp_f32_e32 v123, v82
	v_exp_f32_e32 v125, v83
	v_exp_f32_e32 v126, v84
	v_exp_f32_e32 v127, v85
	v_exp_f32_e32 v128, v86
	v_exp_f32_e32 v129, v87
	v_exp_f32_e32 v122, v88
	v_exp_f32_e32 v124, v89
	v_exp_f32_e32 v117, v90
	v_exp_f32_e32 v119, v91
	v_exp_f32_e32 v120, v92
	v_exp_f32_e32 v121, v93
	v_exp_f32_e32 v114, v94
	v_exp_f32_e32 v115, v95
	v_exp_f32_e32 v116, v96
	v_exp_f32_e32 v118, v97
	s_waitcnt lgkmcnt(0)
	s_barrier
	ds_read_b128 v[66:69], v172 offset:32768
	ds_read_b128 v[70:73], v172 offset:45056
	ds_read_b128 v[202:205], v173 offset:32768
	ds_read_b128 v[206:209], v173 offset:45056
	v_exp_f32_e32 v219, v140
	v_exp_f32_e32 v133, v133
	v_exp_f32_e32 v220, v141
	s_waitcnt lgkmcnt(3)
	v_mfma_f32_32x32x16_bf16 v[82:97], v[66:69], v[110:113], 0
	v_exp_f32_e32 v132, v132
	v_exp_f32_e32 v221, v201
	v_exp_f32_e32 v131, v131
	s_waitcnt lgkmcnt(2)
	v_mfma_f32_32x32x16_bf16 v[66:81], v[70:73], v[110:113], 0
	v_exp_f32_e32 v210, v210
	v_exp_f32_e32 v223, v138
	v_exp_f32_e32 v211, v211
	s_waitcnt lgkmcnt(1)
	v_mfma_f32_32x32x16_bf16 v[82:97], v[202:205], v[106:109], v[82:97]
	v_exp_f32_e32 v224, v137
	v_exp_f32_e32 v225, v218
	v_exp_f32_e32 v226, v136
	s_waitcnt lgkmcnt(0)
	v_mfma_f32_32x32x16_bf16 v[66:81], v[206:209], v[106:109], v[66:81]
	v_exp_f32_e32 v130, v130
	v_cvt_pk_bf16_f32 v136, v128, v129
	v_cvt_pk_bf16_f32 v137, v122, v124
	ds_read_b128 v[202:205], v174 offset:32768
	ds_read_b128 v[206:209], v174 offset:45056
	s_waitcnt lgkmcnt(1)
	v_mfma_f32_32x32x16_bf16 v[82:97], v[202:205], v[102:105], v[82:97]
	v_cvt_pk_bf16_f32 v138, v117, v119
	v_cvt_pk_bf16_f32 v140, v114, v115
	v_cvt_pk_bf16_f32 v141, v116, v118
	s_waitcnt lgkmcnt(0)
	v_mfma_f32_32x32x16_bf16 v[66:81], v[206:209], v[102:105], v[66:81]
	v_cvt_pk_bf16_f32 v222, v131, v210
	v_permlane32_swap_b32_e32 v138, v140
	v_exp_f32_e32 v246, v134
	ds_read_b128 v[202:205], v175 offset:32768
	ds_read_b128 v[206:209], v175 offset:45056
	s_waitcnt lgkmcnt(1)
	v_mfma_f32_32x32x16_bf16 v[82:97], v[202:205], v[98:101], v[82:97]
	v_add_f32_e32 v134, 0, v123
	v_add_f32_e32 v134, v125, v134
	v_add_f32_e32 v134, v126, v134
	s_waitcnt lgkmcnt(0)
	v_mfma_f32_32x32x16_bf16 v[66:81], v[206:209], v[98:101], v[66:81]
	v_add_f32_e32 v134, v127, v134
	v_add_f32_e32 v134, v128, v134
	v_add_f32_e32 v134, v129, v134
	ds_read_b128 v[202:205], v176 offset:32768
	ds_read_b128 v[206:209], v176 offset:45056
	ds_read_b128 v[214:217], v162
	s_waitcnt lgkmcnt(0)
	v_mfma_f32_32x32x16_bf16 v[82:97], v[202:205], v[214:217], v[82:97]
	v_add_f32_e32 v134, v122, v134
	v_add_f32_e32 v134, v124, v134
	v_add_f32_e32 v134, v117, v134
	v_mfma_f32_32x32x16_bf16 v[66:81], v[206:209], v[214:217], v[66:81]
	v_add_f32_e32 v134, v119, v134
	v_add_f32_e32 v134, v120, v134
	v_add_f32_e32 v134, v121, v134
	ds_read_b128 v[202:205], v177 offset:32768
	ds_read_b128 v[206:209], v177 offset:45056
	ds_read_b128 v[214:217], v162 offset:1024
	s_waitcnt lgkmcnt(0)
	v_mfma_f32_32x32x16_bf16 v[82:97], v[202:205], v[214:217], v[82:97]
	v_exp_f32_e32 v244, v135
	v_add_f32_e32 v134, v114, v134
	v_exp_f32_e32 v245, v139
	v_mfma_f32_32x32x16_bf16 v[66:81], v[206:209], v[214:217], v[66:81]
	v_add_f32_e32 v134, v115, v134
	v_add_f32_e32 v134, v116, v134
	v_add_f32_e32 v134, v118, v134
	v_add_f32_e32 v134, v244, v134
	ds_read_b128 v[202:205], v178 offset:32768
	ds_read_b128 v[206:209], v178 offset:45056
	ds_read_b128 v[214:217], v162 offset:2048
	s_waitcnt lgkmcnt(0)
	v_mfma_f32_32x32x16_bf16 v[82:97], v[202:205], v[214:217], v[82:97]
	v_add_f32_e32 v134, v245, v134
	v_add_f32_e32 v134, v246, v134
	v_add_f32_e32 v134, v219, v134
	v_mfma_f32_32x32x16_bf16 v[66:81], v[206:209], v[214:217], v[66:81]
	v_add_f32_e32 v134, v133, v134
	v_add_f32_e32 v134, v220, v134
	v_add_f32_e32 v134, v132, v134
	ds_read_b128 v[202:205], v179 offset:32768
	ds_read_b128 v[206:209], v179 offset:45056
	ds_read_b128 v[214:217], v162 offset:3072
	s_waitcnt lgkmcnt(0)
	v_mfma_f32_32x32x16_bf16 v[82:97], v[202:205], v[214:217], v[82:97]
	v_add_f32_e32 v134, v221, v134
	v_add_f32_e32 v134, v131, v134
	v_add_f32_e32 v134, v210, v134
	v_mfma_f32_32x32x16_bf16 v[66:81], v[206:209], v[214:217], v[66:81]
	v_add_f32_e32 v134, v223, v134
	v_add_f32_e32 v134, v211, v134
	v_add_f32_e32 v134, v224, v134
	ds_read_b128 v[202:205], v180 offset:32768
	ds_read_b128 v[206:209], v180 offset:45056
	ds_read_b128 v[214:217], v162 offset:4096
	s_waitcnt lgkmcnt(0)
; #define LAS __attribute__((address_space(3)))
; DI void finishSM(f32x16& p0, f32x16& p1, float alpha, float& l_reg, bf16x8& pa0, bf16x8& pa1, bf16x8& pa2, bf16x8& pa3) {
; #pragma unroll
;   for (int r = 0; r < 16; ++r) p1[r] = __builtin_amdgcn_exp2f(p1[r]);
;   float ps = 0;
; #pragma unroll
;   for (int r = 0; r < 16; ++r) ps += p0[r];
; #pragma unroll
;   for (int r = 0; r < 16; ++r) ps += p1[r];
;   { auto rr = __builtin_amdgcn_permlane32_swap(__float_as_uint(ps), __float_as_uint(ps), false, false);
;     ps = __uint_as_float(rr[0]) + __uint_as_float(rr[1]); }
;   l_reg = l_reg * alpha + ps;
;     ...
;   PK4(p0, 0, pa0); PK4(p0, 8, pa1); PK4(p1, 0, pa2); PK4(p1, 8, pa3);
;     ...
; }
; template <int DQK> DI void qkt(f32x16& p0, f32x16& p1, const LAS char* Ks, const bf16x8* qr, int r32, int hi) {
;   p0 = f32x16{}; p1 = f32x16{};
; #pragma unroll
;   for (int d0 = 0; d0 < DQK / 16; ++d0) { const int cb = (d0 * 16 + hi * 8) * 2;
;     const bf16x8 b0 = *(const LAS bf16x8*)(Ks + kswz<DQK>(r32, cb));
;     const bf16x8 b1 = *(const LAS bf16x8*)(Ks + kswz<DQK>(32 + r32, cb));
;     p0 = __builtin_amdgcn_mfma_f32_32x32x16_bf16(b0, qr[d0], p0, 0, 0, 0);
;     p1 = __builtin_amdgcn_mfma_f32_32x32x16_bf16(b1, qr[d0], p1, 0, 0, 0); }
; }
; DI int v_st(int k, int c) { const int kk = (k & ~0xC) | ((k & 4) << 1) | ((k & 8) >> 1); return ((kk >> 3) * 4 + (c >> 5)) * 512 + ((kk & 7) * 32 + (c & 31)) * 2; }
; DI int v_rd_base(int lane) { return ((lane & 3) << 3) | (((lane >> 2) & 3) << 6) | (((lane >> 4) & 1) << 5) | (((lane >> 5) & 1) << 8); }
; template <int OFF> DI s16x4 tr_read(int vb) { s16x4 r; asm volatile("ds_read_b64_tr_b16 %0, %1 offset:%2" : "=&v"(r) : "v"(vb), "i"(OFF) : "memory"); return r; }
; template <int D0> DI void pv_one(f32x16& od, int vb, bf16x8 pa0, bf16x8 pa1, bf16x8 pa2, bf16x8 pa3) {
;   const s16x4 l0 = tr_read<v_rd_off(D0, 0, 0)>(vb), h0 = tr_read<v_rd_off(D0, 0, 1)>(vb), l1 = tr_read<v_rd_off(D0, 1, 0)>(vb), h1 = tr_read<v_rd_off(D0, 1, 1)>(vb);
;   const s16x4 l2 = tr_read<v_rd_off(D0, 2, 0)>(vb), h2 = tr_read<v_rd_off(D0, 2, 1)>(vb), l3 = tr_read<v_rd_off(D0, 3, 0)>(vb), h3 = tr_read<v_rd_off(D0, 3, 1)>(vb);
;   asm volatile("s_waitcnt lgkmcnt(0)" ::: "memory"); SBAR();
;     ...
;   od = __builtin_amdgcn_mfma_f32_32x32x16_bf16(pa0, PK(l0, h0), od, 0, 0, 0);
;   od = __builtin_amdgcn_mfma_f32_32x32x16_bf16(pa1, PK(l1, h1), od, 0, 0, 0);
	v_mfma_f32_32x32x16_bf16 v[82:97], v[202:205], v[214:217], v[82:97]
	v_add_f32_e32 v134, v225, v134
	v_add_f32_e32 v134, v226, v134
	v_add_f32_e32 v201, v130, v134
	v_mfma_f32_32x32x16_bf16 v[66:81], v[206:209], v[214:217], v[66:81]
	v_cvt_pk_bf16_f32 v134, v123, v125
	s_nop 0
	v_cvt_pk_bf16_f32 v135, v126, v127
	ds_read_b128 v[202:205], v181 offset:32768
	ds_read_b128 v[206:209], v181 offset:45056
	ds_read_b128 v[214:217], v162 offset:5120
	s_waitcnt lgkmcnt(0)
	v_mfma_f32_32x32x16_bf16 v[82:97], v[202:205], v[214:217], v[82:97]
	v_permlane32_swap_b32_e32 v134, v136
	v_cvt_pk_bf16_f32 v139, v120, v121
	v_cvt_pk_bf16_f32 v218, v244, v245
	v_mfma_f32_32x32x16_bf16 v[66:81], v[206:209], v[214:217], v[66:81]
	v_cvt_pk_bf16_f32 v219, v246, v219
	v_cvt_pk_bf16_f32 v220, v133, v220
	v_cvt_pk_bf16_f32 v221, v132, v221
	ds_read_b128 v[202:205], v182 offset:32768
	ds_read_b128 v[206:209], v182 offset:45056
	ds_read_b128 v[214:217], v162 offset:6144
	s_waitcnt lgkmcnt(0)
	v_mfma_f32_32x32x16_bf16 v[82:97], v[202:205], v[214:217], v[82:97]
	v_cvt_pk_bf16_f32 v223, v223, v211
	v_cvt_pk_bf16_f32 v224, v224, v225
	v_cvt_pk_bf16_f32 v225, v226, v130
	v_mfma_f32_32x32x16_bf16 v[66:81], v[206:209], v[214:217], v[66:81]
	v_permlane32_swap_b32_e32 v135, v137
	v_permlane32_swap_b32_e32 v139, v141
	v_permlane32_swap_b32_e32 v218, v220
	ds_read_b128 v[202:205], v183 offset:32768
	ds_read_b128 v[206:209], v183 offset:45056
	ds_read_b128 v[214:217], v162 offset:7168
	s_waitcnt lgkmcnt(0)
	v_mfma_f32_32x32x16_bf16 v[82:97], v[202:205], v[214:217], v[82:97]
	v_permlane32_swap_b32_e32 v219, v221
	v_permlane32_swap_b32_e32 v222, v224
	v_permlane32_swap_b32_e32 v223, v225
	v_mov_b32_e32 v202, v201
	s_nop 1
	v_permlane32_swap_b32_e32 v201, v202
	v_mfma_f32_32x32x16_bf16 v[66:81], v[206:209], v[214:217], v[66:81]
	global_load_dwordx4 v[114:117], v150, s[86:87]
	global_load_dwordx4 v[118:121], v150, s[88:89]
	global_load_dwordx4 v[122:125], v148, s[90:91]
	global_load_dwordx4 v[126:129], v146, s[90:91]
	global_load_dwordx4 v[130:133], v144, s[90:91]
	ds_read_b64_tr_b16 v[152:153], v165 offset:0
	ds_read_b64_tr_b16 v[154:155], v165 offset:0x800
	ds_read_b64_tr_b16 v[156:157], v165 offset:0x1000
	ds_read_b64_tr_b16 v[158:159], v165 offset:0x1800
	ds_read_b64_tr_b16 v[204:205], v165 offset:0x2000
	ds_read_b64_tr_b16 v[206:207], v165 offset:0x2800
	ds_read_b64_tr_b16 v[208:209], v165 offset:0x3000
	ds_read_b64_tr_b16 v[210:211], v165 offset:0x3800
	s_waitcnt lgkmcnt(0)
	s_nop 0
	v_mfma_f32_32x32x16_bf16 v[2:17], v[134:137], v[152:155], v[2:17]
	ds_read_b64_tr_b16 v[152:153], v165 offset:0x200
	ds_read_b64_tr_b16 v[154:155], v165 offset:0xa00
	v_mfma_f32_32x32x16_bf16 v[2:17], v[138:141], v[156:159], v[2:17]
	ds_read_b64_tr_b16 v[156:157], v165 offset:0x1200
	ds_read_b64_tr_b16 v[158:159], v165 offset:0x1a00
	v_mfma_f32_32x32x16_bf16 v[2:17], v[218:221], v[204:207], v[2:17]
	ds_read_b64_tr_b16 v[204:205], v165 offset:0x2200
	ds_read_b64_tr_b16 v[206:207], v165 offset:0x2a00
	v_mfma_f32_32x32x16_bf16 v[2:17], v[222:225], v[208:211], v[2:17]
	ds_read_b64_tr_b16 v[208:209], v165 offset:0x3200
	ds_read_b64_tr_b16 v[210:211], v165 offset:0x3a00
	s_waitcnt lgkmcnt(0)
	v_mfma_f32_32x32x16_bf16 v[50:65], v[134:137], v[152:155], v[50:65]
	ds_read_b64_tr_b16 v[152:153], v165 offset:0x400
	ds_read_b64_tr_b16 v[154:155], v165 offset:0xc00
	v_mfma_f32_32x32x16_bf16 v[50:65], v[138:141], v[156:159], v[50:65]
	ds_read_b64_tr_b16 v[156:157], v165 offset:0x1400
	ds_read_b64_tr_b16 v[158:159], v165 offset:0x1c00
	v_mfma_f32_32x32x16_bf16 v[50:65], v[218:221], v[204:207], v[50:65]
	ds_read_b64_tr_b16 v[204:205], v165 offset:0x2400
	ds_read_b64_tr_b16 v[206:207], v165 offset:0x2c00
	v_mfma_f32_32x32x16_bf16 v[50:65], v[222:225], v[208:211], v[50:65]
	ds_read_b64_tr_b16 v[208:209], v165 offset:0x3400
	ds_read_b64_tr_b16 v[210:211], v165 offset:0x3c00
	s_waitcnt lgkmcnt(0)
	v_mfma_f32_32x32x16_bf16 v[34:49], v[134:137], v[152:155], v[34:49]
	ds_read_b64_tr_b16 v[152:153], v165 offset:0x600
	ds_read_b64_tr_b16 v[154:155], v165 offset:0xe00
	v_mfma_f32_32x32x16_bf16 v[34:49], v[138:141], v[156:159], v[34:49]
	ds_read_b64_tr_b16 v[156:157], v165 offset:0x1600
	ds_read_b64_tr_b16 v[158:159], v165 offset:0x1e00
	v_mfma_f32_32x32x16_bf16 v[34:49], v[218:221], v[204:207], v[34:49]
	ds_read_b64_tr_b16 v[204:205], v165 offset:0x2600
	ds_read_b64_tr_b16 v[206:207], v165 offset:0x2e00
	v_mfma_f32_32x32x16_bf16 v[34:49], v[222:225], v[208:211], v[34:49]
	ds_read_b64_tr_b16 v[208:209], v165 offset:0x3600
	ds_read_b64_tr_b16 v[210:211], v165 offset:0x3e00
	s_waitcnt lgkmcnt(0)
	v_mfma_f32_32x32x16_bf16 v[18:33], v[134:137], v[152:155], v[18:33]
	v_max_f32_e32 v134, v83, v83
	v_max_f32_e32 v135, v82, v82
	v_max_f32_e32 v134, v135, v134
	v_max3_f32 v134, v134, v84, v85
	v_max3_f32 v134, v134, v86, v87
	v_max3_f32 v134, v134, v88, v89
	v_max3_f32 v134, v134, v90, v91
	v_max3_f32 v134, v134, v92, v93
	v_max3_f32 v134, v134, v94, v95
	v_mfma_f32_32x32x16_bf16 v[18:33], v[138:141], v[156:159], v[18:33]
	v_max3_f32 v134, v134, v96, v97
	v_max3_f32 v134, v134, v66, v67
	v_max3_f32 v134, v134, v68, v69
	v_max3_f32 v134, v134, v70, v71
	v_max3_f32 v134, v134, v72, v73
	v_max3_f32 v134, v134, v74, v75
	v_max3_f32 v134, v134, v76, v77
	v_max3_f32 v134, v134, v78, v79
	v_mfma_f32_32x32x16_bf16 v[18:33], v[218:221], v[204:207], v[18:33]
	v_max3_f32 v134, v134, v80, v81
	v_mov_b32_e32 v135, v134
	s_nop 1
	v_permlane32_swap_b32_e32 v134, v135
	v_max_f32_e32 v135, v135, v135
	v_max_f32_e32 v134, v134, v134
	v_max_f32_e32 v134, v134, v135
	v_sub_f32_e32 v135, v134, v194
	v_cmp_ge_f32_e32 vcc, s96, v135
	v_max_f32_e32 v135, v194, v194
	v_max_f32_e32 v134, v135, v134
	v_mfma_f32_32x32x16_bf16 v[18:33], v[222:225], v[208:211], v[18:33]
	v_sub_f32_e32 v135, v194, v134
	v_mul_f32_e32 v135, 0x3dd53b94, v135
	s_barrier
; #define SWRITE(b, i) do { *(LAS bf16x8*)(V_lds + (b) * SHM_V + vst0) = sr_[i].vs0; *(LAS bf16x8*)(V_lds + (b) * SHM_V + vst1) = sr_[i].vs1; \
;     _Pragma("unroll") for (int _c = 0; _c < NKC; ++_c) *(LAS bf16x8*)(K_lds + (b) * SHM_K + kswz<DQK>(krow[_c], kcol[_c] * 2)) = sr_[i].ks[_c]; } while (0)
; #define SWAIT() do { if constexpr (SDEPTH == 2) { if constexpr (NKC == 1) asm volatile("s_waitcnt vmcnt(3)" ::: "memory"); else if constexpr (NKC == 2) asm volatile("s_waitcnt vmcnt(4)" ::: "memory"); else asm volatile("s_waitcnt vmcnt(5)" ::: "memory"); } \
;     else asm volatile("s_waitcnt vmcnt(0)" ::: "memory"); } while (0)
; #define RESC(a) do { if (__any((a) < 1.f)) { if (hi == 0) al_l[r32] = (a); asm volatile("s_waitcnt lgkmcnt(0)" ::: "memory"); \
;     _Pragma("unroll") for (int d = 0; d < 4; ++d) _Pragma("unroll") for (int r = 0; r < 16; ++r) o[d][r] *= al_l[crow(r, hi)]; } } while (0)
; template <int DQK, int SDEPTH, bool OUT_BF16, int QREG = DQK / 16, bool OUT_F16 = false> ...
;     ...
;     __syncthreads(); SWAIT(); SWRITE(1, SO);
;     RESC(alA); __syncthreads();
	s_waitcnt vmcnt(0)
	s_waitcnt vmcnt(4)
	ds_write_b128 v167, v[114:117] offset:16384
	s_waitcnt vmcnt(3)
	ds_write_b128 v168, v[118:121] offset:16384
	s_waitcnt vmcnt(2)
	ds_write_b128 v169, v[122:125] offset:57344
	s_waitcnt vmcnt(1)
	ds_write_b128 v170, v[126:129] offset:57344
	s_waitcnt vmcnt(0)
	ds_write_b128 v171, v[130:133] offset:57344
	v_exp_f32_e32 v114, v135
	s_cmp_eq_u64 vcc, exec
	s_cselect_b64 s[2:3], -1, 0
	v_cndmask_b32_e64 v130, v114, 1.0, s[2:3]
	v_cmp_gt_f32_e32 vcc, 1.0, v130
	s_cbranch_vccz .LBB0_756
	s_and_saveexec_b64 s[10:11], s[0:1]
	ds_write_b32 v164, v130 offset:128
	s_or_b64 exec, exec, s[10:11]
	s_waitcnt lgkmcnt(0)
	v_add_u32_e32 v126, v143, v0
	ds_read_b128 v[114:117], v126 offset:224
	ds_read_b128 v[118:121], v126 offset:192
	ds_read_b128 v[122:125], v126 offset:160
	ds_read_b128 v[126:129], v126 offset:128
	s_waitcnt lgkmcnt(3)
	v_pk_mul_f32 v[14:15], v[14:15], v[114:115]
	s_waitcnt lgkmcnt(2)
	v_pk_mul_f32 v[10:11], v[10:11], v[118:119]
	s_waitcnt lgkmcnt(1)
	v_pk_mul_f32 v[6:7], v[6:7], v[122:123]
	v_pk_mul_f32 v[16:17], v[16:17], v[116:117]
	v_pk_mul_f32 v[12:13], v[12:13], v[120:121]
	v_pk_mul_f32 v[8:9], v[8:9], v[124:125]
	s_waitcnt lgkmcnt(0)
	v_pk_mul_f32 v[4:5], v[4:5], v[128:129]
	v_pk_mul_f32 v[2:3], v[2:3], v[126:127]
	v_pk_mul_f32 v[62:63], v[62:63], v[114:115]
	v_pk_mul_f32 v[58:59], v[58:59], v[118:119]
	v_pk_mul_f32 v[54:55], v[54:55], v[122:123]
	v_pk_mul_f32 v[64:65], v[64:65], v[116:117]
	v_pk_mul_f32 v[60:61], v[60:61], v[120:121]
	v_pk_mul_f32 v[56:57], v[56:57], v[124:125]
	v_pk_mul_f32 v[52:53], v[52:53], v[128:129]
	v_pk_mul_f32 v[50:51], v[50:51], v[126:127]
	v_pk_mul_f32 v[46:47], v[46:47], v[114:115]
	v_pk_mul_f32 v[42:43], v[42:43], v[118:119]
	v_pk_mul_f32 v[38:39], v[38:39], v[122:123]
	v_pk_mul_f32 v[48:49], v[48:49], v[116:117]
	v_pk_mul_f32 v[44:45], v[44:45], v[120:121]
	v_pk_mul_f32 v[40:41], v[40:41], v[124:125]
	v_pk_mul_f32 v[36:37], v[36:37], v[128:129]
	v_pk_mul_f32 v[34:35], v[34:35], v[126:127]
	v_pk_mul_f32 v[30:31], v[30:31], v[114:115]
	v_pk_mul_f32 v[26:27], v[26:27], v[118:119]
	v_pk_mul_f32 v[22:23], v[22:23], v[122:123]
	v_pk_mul_f32 v[32:33], v[32:33], v[116:117]
	v_pk_mul_f32 v[28:29], v[28:29], v[120:121]
	v_pk_mul_f32 v[24:25], v[24:25], v[124:125]
	v_pk_mul_f32 v[20:21], v[20:21], v[128:129]
	v_pk_mul_f32 v[18:19], v[18:19], v[126:127]

; #define LAS __attribute__((address_space(3)))
; DI int v_st(int k, int c) { const int kk = (k & ~0xC) | ((k & 4) << 1) | ((k & 8) >> 1); return ((kk >> 3) * 4 + (c >> 5)) * 512 + ((kk & 7) * 32 + (c & 31)) * 2; }
; template <int DQK, int SDEPTH, bool OUT_BF16, int QREG = DQK / 16, bool OUT_F16 = false> ...
;     ...
;   const int sr = tid >> 4, sc = (tid & 15) * 8, vst0 = v_st(sr, sc), vst1 = v_st(32 + sr, sc);
;   int krow[NKC], kcol[NKC];
; #pragma unroll
;   for (int i = 0; i < NKC; ++i) { const int ci = tid + i * 512; krow[i] = ci / CPR; kcol[i] = (ci % CPR) * 8; }
;   const int vb0 = (int)(uintptr_t)V_lds + v_rd_base(lane);
;   struct { bf16x8 vs0, vs1, ks[NKC]; } sr_[SDEPTH];
;     ...
;   f32x16 pA0, pA1, pB0, pB1; float mnA, mnB, alA, alB; bf16x8 pa0, pa1, pa2, pa3; const int NT = seq / KVBLK;
;   constexpr int SE = 0, SO = SDEPTH - 1;
;   SLOAD(SE, 0); asm volatile("s_waitcnt vmcnt(0)" ::: "memory"); SWRITE(0, SE); __syncthreads();
; DI void diff_unit(const Frame& F, int t) {
;     const bf16_t* Qd = (const bf16_t*)(F.big + WB_QD); const bf16_t* Kd = (const bf16_t*)(F.big + WB_KD); const bf16_t* Vd = (const bf16_t*)(F.big + WB_VD);
;     int hd, qb, half = -1; bool ctx = false;
;     if (t < DIFF_NWHOLE) { hd = t / DIFF_QB_WHOLE; qb = t % DIFF_QB_WHOLE; }
;     else if (t < DIFF_NWHOLE + 16) { ctx = true; hd = t - DIFF_NWHOLE; qb = 0; }
;     else { const int idx = t - DIFF_NWHOLE - 16; half = idx & 1; const int uu = idx >> 1; hd = uu / (32 - DIFF_QB_WHOLE); qb = DIFF_QB_WHOLE + uu % (32 - DIFF_QB_WHOLE); }
;     const int bh = hd >> 1, sub = hd & 1, b = bh >> 2, h = bh & 3;
;     const int tok0 = ctx ? 0 : CTX + qb * 256; const int row0 = ctx ? MLAT + b * CTX : b * SEQ + qb * 256;
;     const int key0 = half == 1 ? LTOT / 2 : 0, nkeys = ctx ? CTX : (half >= 0 ? LTOT / 2 : LTOT);
;     _Float16* Ob = half == 1 ? (_Float16*)(F.ws + WS_OD2) : (_Float16*)(F.big + WB_OD);
;     f32x2* st = half >= 0 ? (f32x2*)(F.big + WB_DST) + ((size_t)((half * 2 + sub) * 4 + h) * MT + row0) : (f32x2*)nullptr;
;     att::attn_body<64, 2, false, 4, true>(Qd + ((size_t)hd * LTOT + tok0) * 64, Kd + ((size_t)hd * LTOT + key0) * 64, Vd + ((size_t)bh * LTOT + key0) * 128, Ob + ((size_t)sub * MT + row0) * 512 + h * 128, 512, nkeys, (LAS char*)F.lds, F.tid, nullptr, -1, st);
.LBB0_781:
	s_add_i32 s2, s0, 0x100
	s_ashr_i32 s3, s2, 31
	s_and_b64 s[0:1], s[42:43], exec
	s_cselect_b32 s3, 0, s3
	s_cselect_b32 s2, 0, s2
	s_cmp_eq_u32 s8, 1
	s_cselect_b64 s[40:41], -1, 0
	s_and_b64 s[0:1], s[40:41], exec
	s_mul_i32 s10, s24, 0x2100
	s_cselect_b32 s28, 0x1080, 0
	s_mul_hi_i32 s8, s24, 0x2100
	s_add_u32 s0, s2, s10
	s_addc_u32 s1, s3, s8
	s_lshl_b64 s[0:1], s[0:1], 7
	s_add_u32 s0, s4, s0
	s_addc_u32 s1, s5, s1
	s_add_u32 s2, s10, s28
	s_addc_u32 s3, s8, 0
	s_lshl_b64 s[2:3], s[2:3], 7
	s_add_u32 s2, s4, s2
	s_addc_u32 s3, s5, s3
	s_mul_i32 s10, s25, 0x2100
	s_mul_hi_i32 s8, s25, 0x2100
	s_add_u32 s10, s10, s28
	s_addc_u32 s11, s8, 0
	s_lshl_b64 s[10:11], s[10:11], 8
	v_ashrrev_i32_e32 v4, 31, v2
	s_add_u32 s8, s4, s10
	v_lshrrev_b32_e32 v4, 29, v4
	s_addc_u32 s11, s5, s11
	v_ashrrev_i32_e32 v16, 4, v2
	v_add_u32_e32 v4, v2, v4
	s_add_u32 s10, s8, 0x37404000
	v_lshlrev_b32_e32 v3, 3, v58
	v_ashrrev_i32_e32 v20, 3, v4
	v_and_b32_e32 v4, -8, v4
	v_ashrrev_i32_e32 v17, 31, v16
	s_addc_u32 s11, s11, 0
	v_and_b32_e32 v0, 0x78, v3
	v_add_u32_e32 v18, 32, v16
	v_sub_u32_e32 v26, v2, v4
	v_lshlrev_b64 v[50:51], 8, v[16:17]
	v_lshlrev_b32_e32 v12, 3, v26
	v_lshl_add_u64 v[4:5], s[10:11], 0, v[50:51]
	v_lshlrev_b32_e32 v6, 1, v0
	v_mov_b32_e32 v7, v1
	v_ashrrev_i32_e32 v19, 31, v18
	v_ashrrev_i32_e32 v21, 31, v20
	v_lshl_add_u64 v[56:57], v[4:5], 0, v[6:7]
	v_lshlrev_b64 v[4:5], 8, v[18:19]
	v_ashrrev_i32_e32 v13, 31, v12
	v_lshlrev_b64 v[52:53], 7, v[20:21]
	v_lshl_add_u64 v[4:5], s[10:11], 0, v[4:5]
	v_lshl_add_u64 v[14:15], s[2:3], 0, v[52:53]
	v_lshlrev_b64 v[54:55], 1, v[12:13]
	v_lshl_add_u64 v[8:9], v[4:5], 0, v[6:7]
	v_lshl_add_u64 v[76:77], v[14:15], 0, v[54:55]
	s_mov_b32 s2, 0x36384000
	global_load_dwordx4 v[4:7], v[56:57], off
	s_nop 0
	global_load_dwordx4 v[8:11], v[8:9], off
	v_add_co_u32_e32 v12, vcc, s2, v76
	v_ashrrev_i32_e32 v17, 1, v2
	s_movk_i32 s2, 0xffe0
	v_addc_co_u32_e32 v13, vcc, 0, v77, vcc
	v_bfi_b32 v154, s2, v17, v58
	global_load_dwordx4 v[12:15], v[12:13], off
	v_ashrrev_i32_e32 v155, 31, v154
	v_bfe_u32 v166, v58, 5, 1
	v_lshlrev_b64 v[22:23], 7, v[154:155]
	v_lshl_add_u64 v[22:23], s[0:1], 0, v[22:23]
	v_lshlrev_b32_e32 v0, 4, v166
	v_lshl_add_u64 v[22:23], v[22:23], 0, v[0:1]
	s_mov_b32 s0, 0x35304000
	v_add_co_u32_e32 v24, vcc, s0, v22
	s_mov_b64 s[0:1], 0x35304000
	s_nop 0
	v_addc_co_u32_e32 v25, vcc, 0, v23, vcc
	global_load_dwordx4 v[110:113], v[24:25], off
	v_lshl_add_u64 v[22:23], v[22:23], 0, s[0:1]
	global_load_dwordx4 v[106:109], v[22:23], off offset:32
	global_load_dwordx4 v[102:105], v[22:23], off offset:64
	global_load_dwordx4 v[98:101], v[22:23], off offset:96
	v_and_b32_e32 v19, 0xfffff0, v16
	v_lshlrev_b32_e32 v21, 1, v16
	v_and_or_b32 v19, v21, 8, v19
	v_lshrrev_b32_e32 v24, 1, v16
	v_bfe_u32 v3, v3, 5, 2
	v_and_b32_e32 v16, 3, v16
	v_and_b32_e32 v21, 0xfffff0, v18
	v_lshlrev_b32_e32 v18, 1, v18
	v_lshrrev_b32_e32 v19, 1, v19
	v_lshlrev_b32_e32 v59, 4, v58
	v_and_or_b32 v16, v24, 4, v16
	v_and_or_b32 v18, v18, 8, v21
	v_or_b32_e32 v19, v19, v3
	v_and_b32_e32 v25, 48, v59
	v_lshlrev_b32_e32 v16, 6, v16
	v_lshrrev_b32_e32 v18, 1, v18
	v_lshlrev_b32_e32 v19, 9, v19
	v_or_b32_e32 v3, v18, v3
	v_or3_b32 v18, v19, v16, v25
	v_lshlrev_b32_e32 v3, 9, v3
	v_add_u32_e32 v172, 0, v18
	v_or3_b32 v3, v3, v16, v25
	s_waitcnt vmcnt(0)
	v_add_u32_e32 v173, 0, v3
	v_lshlrev_b32_e32 v3, 7, v20
	v_and_b32_e32 v167, 31, v58
	s_movk_i32 s0, 0x70
	v_and_b32_e32 v2, 0x3fffffc0, v2
	v_lshl_add_u32 v157, v2, 2, 0
	v_and_b32_e32 v78, 63, v58
	s_mul_hi_i32 s3, s25, 0x210000
	s_mul_i32 s25, s25, 0x210000
	s_mov_b32 s8, s9
	v_and_b32_e32 v156, 0xffffffe0, v17
	s_mov_b32 s10, s9
	s_mov_b32 s11, s9
	s_mov_b32 s12, s9
	s_mov_b32 s13, s9
	s_mov_b32 s14, s9
	s_mov_b32 s15, s9
	s_mov_b32 s16, s9
	s_mov_b32 s17, s9
	s_mov_b32 s18, s9
	s_mov_b32 s19, s9
	s_mov_b32 s20, s9
	s_mov_b32 s21, s9
	s_mov_b32 s22, s9
	s_mov_b32 s23, s9
	s_mov_b32 s46, 1
	v_lshl_add_u32 v168, v167, 2, v157
	v_mov_b32_e32 v170, 0
	s_waitcnt vmcnt(6)
	ds_write_b128 v172, v[4:7]
	v_bitop3_b32 v4, v20, v26, 7 bitop3:0x6c
	v_lshl_add_u32 v4, v4, 4, 0
	v_add_u32_e32 v174, v4, v3
	s_waitcnt vmcnt(5)
	ds_write_b128 v173, v[8:11]
	v_bitop3_b32 v3, v0, v59, s0 bitop3:0x78
	s_movk_i32 s0, 0x4000
	v_add_co_u32_e32 v2, vcc, s0, v56
	s_waitcnt vmcnt(4)
	ds_write_b128 v174, v[12:15] offset:32768
	v_lshl_add_u32 v12, v167, 7, 0
	v_add_u32_e32 v175, v12, v3
	s_waitcnt lgkmcnt(0)
	s_barrier
; #define SLOAD(i, k0) do { sr_[i].vs0 = *reinterpret_cast<const bf16x8*>(&Vh[(long)((k0) + sr) * DV + sc]); sr_[i].vs1 = *reinterpret_cast<const bf16x8*>(&Vh[(long)((k0) + 32 + sr) * DV + sc]); \
;     _Pragma("unroll") for (int _c = 0; _c < NKC; ++_c) sr_[i].ks[_c] = *reinterpret_cast<const bf16x8*>(&Kh[(long)((k0) + krow[_c]) * DQK + kcol[_c]]); } while (0)
; #define SWRITE(b, i) do { *(LAS bf16x8*)(V_lds + (b) * SHM_V + vst0) = sr_[i].vs0; *(LAS bf16x8*)(V_lds + (b) * SHM_V + vst1) = sr_[i].vs1; \
;     _Pragma("unroll") for (int _c = 0; _c < NKC; ++_c) *(LAS bf16x8*)(K_lds + (b) * SHM_K + kswz<DQK>(krow[_c], kcol[_c] * 2)) = sr_[i].ks[_c]; } while (0)
; #define SWAIT() do { if constexpr (SDEPTH == 2) { if constexpr (NKC == 1) asm volatile("s_waitcnt vmcnt(3)" ::: "memory"); else if constexpr (NKC == 2) asm volatile("s_waitcnt vmcnt(4)" ::: "memory"); else asm volatile("s_waitcnt vmcnt(5)" ::: "memory"); } \
;     else asm volatile("s_waitcnt vmcnt(0)" ::: "memory"); } while (0)
; DI void partialSM(f32x16& p0, f32x16& p1, float& m_reg, float& mn, float& alpha, const float SCALE) {
;   const float C = SCALE * 1.4426950408889634f;
;   float pmax = p0[0];
; #pragma unroll
;   for (int r = 1; r < 16; ++r) pmax = fmaxf(pmax, p0[r]);
; #pragma unroll
;   for (int r = 0; r < 16; ++r) pmax = fmaxf(pmax, p1[r]);
;   { auto rr = __builtin_amdgcn_permlane32_swap(__float_as_uint(pmax), __float_as_uint(pmax), false, false);
;     pmax = fmaxf(__uint_as_float(rr[0]), __uint_as_float(rr[1])); }
;   if (__builtin_expect(__all(pmax - m_reg <= THR / SCALE), 1)) { mn = m_reg; alpha = 1.f; }
;   else { mn = fmaxf(m_reg, pmax); alpha = __builtin_amdgcn_exp2f((m_reg - mn) * C); m_reg = mn; }
;   const float mnC = -mn * C;
; #pragma unroll
;   for (int r = 0; r < 16; ++r) p0[r] = fmaf(p0[r], C, mnC);
; #pragma unroll
;   for (int r = 0; r < 16; ++r) p1[r] = fmaf(p1[r], C, mnC);
; #pragma unroll
;   for (int r = 0; r < 16; ++r) p0[r] = __builtin_amdgcn_exp2f(p0[r]);
; }
; template <int DQK, int SDEPTH, bool OUT_BF16, int QREG = DQK / 16, bool OUT_F16 = false> ...
;     ...
;   SLOAD(SE, 0); asm volatile("s_waitcnt vmcnt(0)" ::: "memory"); SWRITE(0, SE); __syncthreads();
;   QKT(pA0, pA1, K_lds); partialSM(pA0, pA1, m_reg, mnA, alA, SCALE);
;   SLOAD(SO, KVBLK); if constexpr (SDEPTH == 2) { if (2 < NT) SLOAD(SE, 2 * KVBLK); }
;   SWAIT(); SWRITE(1, SO); __syncthreads();
	ds_read_b128 v[4:7], v175 offset:32768
	ds_read_b128 v[8:11], v175 offset:36864
	v_and_b32_e32 v13, 0x70, v59
	v_bitop3_b32 v3, v0, v13, 32 bitop3:0x36
	v_add_u32_e32 v176, v12, v3
	s_waitcnt vmcnt(3) lgkmcnt(1)
	v_mfma_f32_32x32x16_bf16 v[18:33], v[4:7], v[110:113], 0
	ds_read_b128 v[4:7], v176 offset:32768
	v_addc_co_u32_e32 v3, vcc, 0, v57, vcc
	s_movk_i32 s0, 0x6000
	v_lshlrev_b32_e32 v14, 3, v78
	s_waitcnt lgkmcnt(1)
	v_mfma_f32_32x32x16_bf16 v[34:49], v[8:11], v[110:113], 0
	ds_read_b128 v[8:11], v176 offset:36864
	s_waitcnt vmcnt(2) lgkmcnt(1)
	v_mfma_f32_32x32x16_bf16 v[18:33], v[4:7], v[106:109], v[18:33]
	v_add_co_u32_e32 v4, vcc, s0, v56
	s_mov_b32 s0, 0x36386000
	s_nop 0
	v_addc_co_u32_e32 v5, vcc, 0, v57, vcc
	v_bitop3_b32 v6, v0, v13, 64 bitop3:0x36
	global_load_dwordx4 v[60:63], v[2:3], off
	global_load_dwordx4 v[64:67], v[4:5], off
	v_add_co_u32_e32 v2, vcc, s0, v76
	v_add_u32_e32 v178, v12, v6
	s_nop 0
	v_addc_co_u32_e32 v3, vcc, 0, v77, vcc
	global_load_dwordx4 v[68:71], v[2:3], off
	ds_read_b128 v[2:5], v178 offset:32768
	v_and_b32_e32 v6, 0xc0, v59
	v_lshlrev_b32_e32 v7, 1, v58
	s_waitcnt lgkmcnt(1)
	v_mfma_f32_32x32x16_bf16 v[34:49], v[8:11], v[106:109], v[34:49]
	v_and_or_b32 v6, v14, 24, v6
	v_and_b32_e32 v7, 32, v7
	v_and_b32_e32 v8, 0x100, v14
	s_movk_i32 s0, 0x60
	v_or3_b32 v59, v6, v7, v8
	ds_read_b128 v[6:9], v178 offset:36864
	v_add_u32_e32 v171, 0, v59
	s_waitcnt vmcnt(4) lgkmcnt(1)
	v_mfma_f32_32x32x16_bf16 v[18:33], v[2:5], v[102:105], v[18:33]
	v_bitop3_b32 v2, v0, v13, s0 bitop3:0x36
	v_add_u32_e32 v177, v12, v2
	ds_read_b128 v[2:5], v177 offset:32768
	ds_read_b128 v[72:75], v177 offset:36864
	s_mov_b32 s0, 0x8000
	s_waitcnt lgkmcnt(2)
	v_mfma_f32_32x32x16_bf16 v[34:49], v[6:9], v[102:105], v[34:49]
	s_waitcnt vmcnt(3) lgkmcnt(1)
	v_mfma_f32_32x32x16_bf16 v[18:33], v[2:5], v[98:101], v[18:33]
	v_mov_b64_e32 v[2:3], s[8:9]
	v_mov_b64_e32 v[4:5], s[10:11]
	v_mov_b64_e32 v[6:7], s[12:13]
	v_mov_b64_e32 v[8:9], s[14:15]
	v_mov_b64_e32 v[10:11], s[16:17]
	v_mov_b64_e32 v[12:13], s[18:19]
	v_mov_b64_e32 v[14:15], s[20:21]
	s_waitcnt lgkmcnt(0)
	v_mfma_f32_32x32x16_bf16 v[34:49], v[72:75], v[98:101], v[34:49]
	s_nop 2
	v_max_f32_e32 v72, v19, v19
	v_max_f32_e32 v73, v18, v18
	v_max_f32_e32 v72, v73, v72
	v_max3_f32 v72, v72, v20, v21
	v_max3_f32 v72, v72, v22, v23
	v_max3_f32 v72, v72, v24, v25
	v_max3_f32 v72, v72, v26, v27
	v_max3_f32 v72, v72, v28, v29
	v_max3_f32 v72, v72, v30, v31
	v_max3_f32 v72, v72, v32, v33
	v_max3_f32 v72, v72, v34, v35
	v_max3_f32 v72, v72, v36, v37
	v_max3_f32 v72, v72, v38, v39
	v_max3_f32 v72, v72, v40, v41
	v_max3_f32 v72, v72, v42, v43
	v_max3_f32 v72, v72, v44, v45
	v_max3_f32 v72, v72, v46, v47
	v_max3_f32 v72, v72, v48, v49
	v_mov_b32_e32 v73, v72
	s_nop 1
	v_permlane32_swap_b32_e32 v72, v73
	v_max_f32_e32 v73, v73, v73
	v_max_f32_e32 v72, v72, v72
	v_max_f32_e32 v74, v72, v73
	v_add_f32_e32 v72, 0x7149f2ca, v74
	v_cmp_ge_f32_e32 vcc, s26, v72
	v_add_co_u32_e64 v72, s[0:1], s0, v56
	s_cmp_eq_u64 vcc, exec
	s_nop 0
	v_addc_co_u32_e64 v73, s[0:1], 0, v57, s[0:1]
	s_mov_b32 s0, 0xa000
	s_nop 0
	v_add_co_u32_e64 v56, s[0:1], s0, v56
	global_load_dwordx4 v[114:117], v[72:73], off
	s_nop 0
	v_addc_co_u32_e64 v57, s[0:1], 0, v57, s[0:1]
	s_mov_b32 s0, 0x36388000
	s_nop 0
	v_add_co_u32_e64 v72, s[0:1], s0, v76
	s_cselect_b64 vcc, -1, 0
	s_nop 0
	v_addc_co_u32_e64 v73, s[0:1], 0, v77, s[0:1]
	global_load_dwordx4 v[118:121], v[56:57], off
	global_load_dwordx4 v[122:125], v[72:73], off
	v_max_f32_e32 v56, 0xf149f2ca, v74
	v_cndmask_b32_e32 v142, v56, v239, vcc
	v_sub_f32_e32 v57, 0xf149f2ca, v56
	v_mul_f32_e32 v56, 0xbe38aa3b, v142
	v_fmamk_f32 v18, v18, 0x3e38aa3b, v56
	v_exp_f32_e32 v146, v18
	v_fmamk_f32 v18, v19, 0x3e38aa3b, v56
	v_exp_f32_e32 v148, v18
	v_fmamk_f32 v18, v20, 0x3e38aa3b, v56
	v_exp_f32_e32 v150, v18
	v_fmamk_f32 v18, v21, 0x3e38aa3b, v56
	v_exp_f32_e32 v152, v18
	v_fmamk_f32 v18, v22, 0x3e38aa3b, v56
	v_exp_f32_e32 v162, v18
	v_fmamk_f32 v18, v23, 0x3e38aa3b, v56
	v_exp_f32_e32 v164, v18
	v_fmamk_f32 v18, v24, 0x3e38aa3b, v56
	v_exp_f32_e32 v165, v18
	v_fmamk_f32 v18, v25, 0x3e38aa3b, v56
	v_exp_f32_e32 v186, v18
	v_fmamk_f32 v18, v26, 0x3e38aa3b, v56
	v_mul_f32_e32 v57, 0x3e38aa3b, v57
	v_exp_f32_e32 v144, v18
	v_fmamk_f32 v18, v27, 0x3e38aa3b, v56
	s_add_i32 s2, 0, 0x4000
	v_exp_f32_e32 v57, v57
	v_exp_f32_e32 v145, v18
	v_fmamk_f32 v18, v28, 0x3e38aa3b, v56
	v_add_u32_e32 v169, s2, v59
	s_lshl_b32 s2, s28, 8
	v_exp_f32_e32 v147, v18
	v_fmamk_f32 v18, v29, 0x3e38aa3b, v56
	s_add_u32 s2, s25, s2
	v_exp_f32_e32 v149, v18
	v_fmamk_f32 v18, v30, 0x3e38aa3b, v56
	s_addc_u32 s3, s3, 0
	v_mov_b64_e32 v[16:17], s[22:23]
	v_exp_f32_e32 v151, v18
	v_fmamk_f32 v18, v31, 0x3e38aa3b, v56
	v_lshl_add_u64 v[158:159], s[2:3], 0, v[50:51]
	s_mul_i32 s2, s24, 0x108000
	s_lshl_b32 s8, s28, 7
	v_pk_fma_f32 v[126:127], v[48:49], s[34:35], v[56:57] op_sel_hi:[1,0,0]
	v_pk_fma_f32 v[132:133], v[46:47], s[34:35], v[56:57] op_sel_hi:[1,0,0]
	v_pk_fma_f32 v[136:137], v[44:45], s[34:35], v[56:57] op_sel_hi:[1,0,0]
	v_pk_fma_f32 v[128:129], v[42:43], s[34:35], v[56:57] op_sel_hi:[1,0,0]
	v_pk_fma_f32 v[130:131], v[40:41], s[34:35], v[56:57] op_sel_hi:[1,0,0]
	v_pk_fma_f32 v[134:135], v[38:39], s[34:35], v[56:57] op_sel_hi:[1,0,0]
	v_pk_fma_f32 v[138:139], v[36:37], s[34:35], v[56:57] op_sel_hi:[1,0,0]
	v_pk_fma_f32 v[140:141], v[34:35], s[34:35], v[56:57] op_sel_hi:[1,0,0]
	v_exp_f32_e32 v153, v18
	v_fmamk_f32 v18, v32, 0x3e38aa3b, v56
	v_fmac_f32_e32 v56, 0x3e38aa3b, v33
	s_mul_hi_i32 s3, s24, 0x108000
	s_add_u32 s2, s2, s8
	v_exp_f32_e32 v163, v18
	v_exp_f32_e32 v183, v56
	v_and_b32_e32 v18, 15, v58
	s_addc_u32 s3, s3, 0
	s_waitcnt vmcnt(3)
	v_lshl_or_b32 v158, v18, 4, v158
	v_lshl_add_u64 v[18:19], s[2:3], 0, v[52:53]
	s_waitcnt vmcnt(5)
	ds_write_b128 v172, v[60:63] offset:16384
	s_waitcnt vmcnt(4)
	ds_write_b128 v173, v[64:67] offset:16384
	s_waitcnt vmcnt(3)
	ds_write_b128 v174, v[68:71] offset:40960
	v_cndmask_b32_e64 v179, v57, 1.0, vcc
	v_lshl_add_u64 v[160:161], v[18:19], 0, v[54:55]
	v_mov_b64_e32 v[64:65], v[16:17]
	v_mov_b64_e32 v[48:49], v[16:17]
	v_mov_b64_e32 v[32:33], v[16:17]
	v_cmp_gt_u32_e64 s[0:1], 32, v78
	v_mov_b64_e32 v[62:63], v[14:15]
	v_mov_b64_e32 v[60:61], v[12:13]
	v_mov_b64_e32 v[58:59], v[10:11]
	v_mov_b64_e32 v[56:57], v[8:9]
	v_mov_b64_e32 v[54:55], v[6:7]
	v_mov_b64_e32 v[52:53], v[4:5]
	v_mov_b64_e32 v[50:51], v[2:3]
	v_mov_b64_e32 v[46:47], v[14:15]
	v_mov_b64_e32 v[44:45], v[12:13]
	v_mov_b64_e32 v[42:43], v[10:11]
	v_mov_b64_e32 v[40:41], v[8:9]
	v_mov_b64_e32 v[38:39], v[6:7]
	v_mov_b64_e32 v[36:37], v[4:5]
	v_mov_b64_e32 v[34:35], v[2:3]
	v_mov_b64_e32 v[30:31], v[14:15]
	v_mov_b64_e32 v[28:29], v[12:13]
	v_mov_b64_e32 v[26:27], v[10:11]
	v_mov_b64_e32 v[24:25], v[8:9]
	v_mov_b64_e32 v[22:23], v[6:7]
	v_mov_b64_e32 v[20:21], v[4:5]
	v_mov_b64_e32 v[18:19], v[2:3]
	s_waitcnt lgkmcnt(0)
	s_barrier
; #define SBAR() __builtin_amdgcn_sched_barrier(0)
; #define SLOAD(i, k0) do { sr_[i].vs0 = *reinterpret_cast<const bf16x8*>(&Vh[(long)((k0) + sr) * DV + sc]); sr_[i].vs1 = *reinterpret_cast<const bf16x8*>(&Vh[(long)((k0) + 32 + sr) * DV + sc]); \
;     _Pragma("unroll") for (int _c = 0; _c < NKC; ++_c) sr_[i].ks[_c] = *reinterpret_cast<const bf16x8*>(&Kh[(long)((k0) + krow[_c]) * DQK + kcol[_c]]); } while (0)
; DI void finishSM(f32x16& p0, f32x16& p1, float alpha, float& l_reg, bf16x8& pa0, bf16x8& pa1, bf16x8& pa2, bf16x8& pa3) {
; #pragma unroll
;   for (int r = 0; r < 16; ++r) p1[r] = __builtin_amdgcn_exp2f(p1[r]);
;   float ps = 0;
; #pragma unroll
;   for (int r = 0; r < 16; ++r) ps += p0[r];
; #pragma unroll
;   for (int r = 0; r < 16; ++r) ps += p1[r];
;   { auto rr = __builtin_amdgcn_permlane32_swap(__float_as_uint(ps), __float_as_uint(ps), false, false);
;     ps = __uint_as_float(rr[0]) + __uint_as_float(rr[1]); }
;   l_reg = l_reg * alpha + ps;
;     ...
;   PK4(p0, 0, pa0); PK4(p0, 8, pa1); PK4(p1, 0, pa2); PK4(p1, 8, pa3);
;     ...
; }
; template <int DQK, int SDEPTH, bool OUT_BF16, int QREG = DQK / 16, bool OUT_F16 = false> ...
;     ...
;   for (int j = 1; j + 1 < NT; j += 2) {
;     SBAR(); QKT(pB0, pB1, K_lds + SHM_K);
;     finishSM(pA0, pA1, alA, l_reg, pa0, pa1, pa2, pa3); SBAR();
;     SLOAD(SO, (j + SDEPTH) * KVBLK); SBAR();
;     pv_d0(o, vb0, pa0, pa1, pa2, pa3); partialSM(pB0, pB1, m_reg, mnB, alB, SCALE);
	v_mov_b32_e32 v208, v146
	v_mov_b32_e32 v209, v148
	v_mov_b32_e32 v210, v150
	v_mov_b32_e32 v211, v152
	v_mov_b32_e32 v214, v162
	v_mov_b32_e32 v215, v164
	v_mov_b32_e32 v216, v165
	v_mov_b32_e32 v217, v186
	v_mov_b32_e32 v218, v144
	v_mov_b32_e32 v219, v145
	v_mov_b32_e32 v220, v147
	v_mov_b32_e32 v221, v149
	v_mov_b32_e32 v222, v151
	v_mov_b32_e32 v223, v153
	v_mov_b32_e32 v224, v163
	v_mov_b32_e32 v225, v183
	v_exp_f32_e32 v226, v140
	v_exp_f32_e32 v227, v141
	v_exp_f32_e32 v228, v138
	v_exp_f32_e32 v229, v139
	v_exp_f32_e32 v230, v134
	v_exp_f32_e32 v231, v135
	v_exp_f32_e32 v244, v130
	v_exp_f32_e32 v245, v131
	v_exp_f32_e32 v246, v128
	v_exp_f32_e32 v247, v129
	v_exp_f32_e32 v248, v136
	v_exp_f32_e32 v249, v137
	v_exp_f32_e32 v250, v132
	v_exp_f32_e32 v251, v133
	v_exp_f32_e32 v252, v126
	v_exp_f32_e32 v202, v127
	s_add_u32 s80, s4, 0x37410000
	s_addc_u32 s81, s5, 0
	s_add_u32 s82, s4, 0x37412000
	s_addc_u32 s83, s5, 0
	s_add_u32 s84, s4, 0x3638a000
	s_addc_u32 s85, s5, 0
	s_add_u32 s86, s4, 0x37414000
	s_addc_u32 s87, s5, 0
	s_add_u32 s88, s4, 0x37416000
	s_addc_u32 s89, s5, 0
	s_add_u32 s90, s4, 0x3638c000
	s_addc_u32 s91, s5, 0
.LBB0_782:
	ds_read_b128 v[66:69], v175 offset:40960
	ds_read_b128 v[70:73], v175 offset:45056
	ds_read_b128 v[188:191], v176 offset:40960
	ds_read_b128 v[192:195], v176 offset:45056
	v_add_f32_e32 v180, 0, v208
	v_add_f32_e32 v180, v209, v180
	v_cvt_pk_bf16_f32 v138, v208, v209
	v_add_f32_e32 v180, v210, v180
	v_add_f32_e32 v180, v211, v180
	s_waitcnt lgkmcnt(3)
	v_mfma_f32_32x32x16_bf16 v[82:97], v[66:69], v[110:113], 0
	v_cvt_pk_bf16_f32 v139, v210, v211
	v_add_f32_e32 v180, v214, v180
	v_add_f32_e32 v180, v215, v180
	v_cvt_pk_bf16_f32 v140, v214, v215
	v_add_f32_e32 v180, v216, v180
	v_add_f32_e32 v180, v217, v180
	v_cvt_pk_bf16_f32 v141, v216, v217
	s_waitcnt lgkmcnt(2)
	v_mfma_f32_32x32x16_bf16 v[66:81], v[70:73], v[110:113], 0
	v_add_f32_e32 v180, v218, v180
	v_add_f32_e32 v180, v219, v180
	v_cvt_pk_bf16_f32 v144, v218, v219
	v_add_f32_e32 v180, v220, v180
	v_add_f32_e32 v180, v221, v180
	v_cvt_pk_bf16_f32 v145, v220, v221
	s_waitcnt lgkmcnt(1)
	v_mfma_f32_32x32x16_bf16 v[82:97], v[188:191], v[106:109], v[82:97]
	v_add_f32_e32 v180, v222, v180
	v_add_f32_e32 v180, v223, v180
	v_cvt_pk_bf16_f32 v146, v222, v223
	v_add_f32_e32 v180, v224, v180
	v_add_f32_e32 v180, v225, v180
	v_cvt_pk_bf16_f32 v147, v224, v225
	s_waitcnt lgkmcnt(0)
	v_mfma_f32_32x32x16_bf16 v[66:81], v[192:195], v[106:109], v[66:81]
	ds_read_b128 v[188:191], v178 offset:40960
	ds_read_b128 v[192:195], v178 offset:45056
	v_add_f32_e32 v180, v226, v180
	v_add_f32_e32 v180, v227, v180
	v_cvt_pk_bf16_f32 v148, v226, v227
	v_add_f32_e32 v180, v228, v180
	v_add_f32_e32 v180, v229, v180
	v_cvt_pk_bf16_f32 v149, v228, v229
	s_waitcnt lgkmcnt(1)
	v_mfma_f32_32x32x16_bf16 v[82:97], v[188:191], v[102:105], v[82:97]
	v_add_f32_e32 v180, v230, v180
	v_add_f32_e32 v180, v231, v180
	v_cvt_pk_bf16_f32 v150, v230, v231
	v_add_f32_e32 v180, v244, v180
	v_add_f32_e32 v180, v245, v180
	v_cvt_pk_bf16_f32 v151, v244, v245
	s_waitcnt lgkmcnt(0)
	v_mfma_f32_32x32x16_bf16 v[66:81], v[192:195], v[102:105], v[66:81]
	ds_read_b128 v[188:191], v177 offset:40960
	ds_read_b128 v[192:195], v177 offset:45056
	v_add_f32_e32 v180, v246, v180
	v_add_f32_e32 v180, v247, v180
	v_cvt_pk_bf16_f32 v182, v246, v247
	v_add_f32_e32 v180, v248, v180
	v_add_f32_e32 v180, v249, v180
	v_cvt_pk_bf16_f32 v183, v248, v249
	s_waitcnt lgkmcnt(1)
	v_mfma_f32_32x32x16_bf16 v[82:97], v[188:191], v[98:101], v[82:97]
	v_add_f32_e32 v180, v250, v180
	v_add_f32_e32 v180, v251, v180
	v_cvt_pk_bf16_f32 v184, v250, v251
	v_add_f32_e32 v180, v252, v180
	v_add_f32_e32 v180, v202, v180
	v_cvt_pk_bf16_f32 v185, v252, v202
	v_mov_b32_e32 v181, v180
	s_waitcnt lgkmcnt(0)
	v_mfma_f32_32x32x16_bf16 v[66:81], v[192:195], v[98:101], v[66:81]
	v_permlane32_swap_b32_e32 v138, v140
	v_permlane32_swap_b32_e32 v139, v141
	v_permlane32_swap_b32_e32 v144, v146
	v_permlane32_swap_b32_e32 v145, v147
	v_permlane32_swap_b32_e32 v148, v150
	v_permlane32_swap_b32_e32 v149, v151
	v_permlane32_swap_b32_e32 v180, v181
	v_permlane32_swap_b32_e32 v182, v184
	v_permlane32_swap_b32_e32 v183, v185
	global_load_dwordx4 v[126:129], v158, s[80:81]
	global_load_dwordx4 v[130:133], v158, s[82:83]
	global_load_dwordx4 v[134:137], v160, s[84:85]
	ds_read_b64_tr_b16 v[186:187], v171 offset:0x0
	ds_read_b64_tr_b16 v[188:189], v171 offset:0x800
	ds_read_b64_tr_b16 v[190:191], v171 offset:0x1000
	ds_read_b64_tr_b16 v[192:193], v171 offset:0x1800
	ds_read_b64_tr_b16 v[194:195], v171 offset:0x2000
	ds_read_b64_tr_b16 v[196:197], v171 offset:0x2800
	ds_read_b64_tr_b16 v[198:199], v171 offset:0x3000
	ds_read_b64_tr_b16 v[200:201], v171 offset:0x3800
	s_waitcnt lgkmcnt(0)
	s_nop 0
	v_mfma_f32_32x32x16_bf16 v[2:17], v[138:141], v[186:189], v[2:17]
	ds_read_b64_tr_b16 v[186:187], v171 offset:0x200
	ds_read_b64_tr_b16 v[188:189], v171 offset:0xa00
	v_max3_f32 v203, v82, v83, v84
	v_max3_f32 v204, v85, v86, v87
	v_max3_f32 v203, v203, v88, v89
	v_max3_f32 v204, v204, v90, v91
	v_max3_f32 v203, v203, v92, v93
	v_max3_f32 v204, v204, v94, v95
	v_mfma_f32_32x32x16_bf16 v[2:17], v[144:147], v[190:193], v[2:17]
	ds_read_b64_tr_b16 v[190:191], v171 offset:0x1200
	ds_read_b64_tr_b16 v[192:193], v171 offset:0x1a00
	v_max3_f32 v203, v203, v96, v97
	v_max3_f32 v204, v204, v66, v67
	v_max3_f32 v203, v203, v68, v69
	v_max3_f32 v204, v204, v70, v71
	v_max3_f32 v203, v203, v72, v73
	v_max3_f32 v204, v204, v74, v75
	v_mfma_f32_32x32x16_bf16 v[2:17], v[148:151], v[194:197], v[2:17]
	ds_read_b64_tr_b16 v[194:195], v171 offset:0x2200
	ds_read_b64_tr_b16 v[196:197], v171 offset:0x2a00
	v_max3_f32 v203, v203, v76, v77
	v_max3_f32 v204, v204, v78, v79
	v_max3_f32 v203, v203, v80, v81
	v_max_f32_e32 v203, v203, v204
	v_mov_b32_e32 v204, v203
	v_mfma_f32_32x32x16_bf16 v[2:17], v[182:185], v[198:201], v[2:17]
	ds_read_b64_tr_b16 v[198:199], v171 offset:0x3200
	ds_read_b64_tr_b16 v[200:201], v171 offset:0x3a00
	v_permlane32_swap_b32_e32 v203, v204
	v_max_f32_e32 v203, v203, v204
	v_sub_f32_e32 v204, v203, v142
	v_cmp_ge_f32_e32 vcc, s26, v204
	v_max_f32_e32 v203, v142, v203
	v_sub_f32_e32 v204, v142, v203
	s_waitcnt lgkmcnt(0)
; #define SBAR() __builtin_amdgcn_sched_barrier(0)
; template <int OFF> DI s16x4 tr_read(int vb) { s16x4 r; asm volatile("ds_read_b64_tr_b16 %0, %1 offset:%2" : "=&v"(r) : "v"(vb), "i"(OFF) : "memory"); return r; }
; #define SWRITE(b, i) do { *(LAS bf16x8*)(V_lds + (b) * SHM_V + vst0) = sr_[i].vs0; *(LAS bf16x8*)(V_lds + (b) * SHM_V + vst1) = sr_[i].vs1; \
;     _Pragma("unroll") for (int _c = 0; _c < NKC; ++_c) *(LAS bf16x8*)(K_lds + (b) * SHM_K + kswz<DQK>(krow[_c], kcol[_c] * 2)) = sr_[i].ks[_c]; } while (0)
; #define SWAIT() do { if constexpr (SDEPTH == 2) { if constexpr (NKC == 1) asm volatile("s_waitcnt vmcnt(3)" ::: "memory"); else if constexpr (NKC == 2) asm volatile("s_waitcnt vmcnt(4)" ::: "memory"); else asm volatile("s_waitcnt vmcnt(5)" ::: "memory"); } \
;     else asm volatile("s_waitcnt vmcnt(0)" ::: "memory"); } while (0)
; template <int D0> DI void pv_one(f32x16& od, int vb, bf16x8 pa0, bf16x8 pa1, bf16x8 pa2, bf16x8 pa3) {
;   const s16x4 l0 = tr_read<v_rd_off(D0, 0, 0)>(vb), h0 = tr_read<v_rd_off(D0, 0, 1)>(vb), l1 = tr_read<v_rd_off(D0, 1, 0)>(vb), h1 = tr_read<v_rd_off(D0, 1, 1)>(vb);
;   const s16x4 l2 = tr_read<v_rd_off(D0, 2, 0)>(vb), h2 = tr_read<v_rd_off(D0, 2, 1)>(vb), l3 = tr_read<v_rd_off(D0, 3, 0)>(vb), h3 = tr_read<v_rd_off(D0, 3, 1)>(vb);
;   asm volatile("s_waitcnt lgkmcnt(0)" ::: "memory"); SBAR();
;     ...
;   od = __builtin_amdgcn_mfma_f32_32x32x16_bf16(pa0, PK(l0, h0), od, 0, 0, 0);
;   od = __builtin_amdgcn_mfma_f32_32x32x16_bf16(pa1, PK(l1, h1), od, 0, 0, 0);
;   od = __builtin_amdgcn_mfma_f32_32x32x16_bf16(pa2, PK(l2, h2), od, 0, 0, 0);
;   od = __builtin_amdgcn_mfma_f32_32x32x16_bf16(pa3, PK(l3, h3), od, 0, 0, 0);
;     ...
; }
; DI void pv_d0(f32x16* o, int vb, bf16x8 pa0, bf16x8 pa1, bf16x8 pa2, bf16x8 pa3) {
;   pv_one<0>(o[0], vb, pa0, pa1, pa2, pa3); pv_one<1>(o[1], vb, pa0, pa1, pa2, pa3); pv_one<2>(o[2], vb, pa0, pa1, pa2, pa3); pv_one<3>(o[3], vb, pa0, pa1, pa2, pa3);
; }
; template <int DQK, int SDEPTH, bool OUT_BF16, int QREG = DQK / 16, bool OUT_F16 = false> ...
;     ...
;     pv_d0(o, vb0, pa0, pa1, pa2, pa3); partialSM(pB0, pB1, m_reg, mnB, alB, SCALE);
;     __syncthreads(); SWAIT(); SWRITE(0, SE);
;     RESC(alB); __syncthreads();
	v_mfma_f32_32x32x16_bf16 v[50:65], v[138:141], v[186:189], v[50:65]
	ds_read_b64_tr_b16 v[186:187], v171 offset:0x400
	ds_read_b64_tr_b16 v[188:189], v171 offset:0xc00
	v_mul_f32_e32 v204, 0x3e38aa3b, v204
	v_exp_f32_e32 v204, v204
	s_cmp_eq_u64 vcc, exec
	s_cselect_b64 s[2:3], -1, 0
	v_mfma_f32_32x32x16_bf16 v[50:65], v[144:147], v[190:193], v[50:65]
	ds_read_b64_tr_b16 v[190:191], v171 offset:0x1400
	ds_read_b64_tr_b16 v[192:193], v171 offset:0x1c00
	v_cndmask_b32_e64 v202, v203, v142, s[2:3]
	v_mul_f32_e32 v202, 0xbe38aa3b, v202
	v_fmamk_f32 v208, v82, 0x3e38aa3b, v202
	v_fmamk_f32 v209, v83, 0x3e38aa3b, v202
	v_fmamk_f32 v210, v84, 0x3e38aa3b, v202
	v_mfma_f32_32x32x16_bf16 v[50:65], v[148:151], v[194:197], v[50:65]
	ds_read_b64_tr_b16 v[194:195], v171 offset:0x2400
	ds_read_b64_tr_b16 v[196:197], v171 offset:0x2c00
	v_fmamk_f32 v211, v85, 0x3e38aa3b, v202
	v_fmamk_f32 v214, v86, 0x3e38aa3b, v202
	v_fmamk_f32 v215, v87, 0x3e38aa3b, v202
	v_exp_f32_e32 v208, v208
	v_exp_f32_e32 v209, v209
	v_exp_f32_e32 v210, v210
	v_mfma_f32_32x32x16_bf16 v[50:65], v[182:185], v[198:201], v[50:65]
	ds_read_b64_tr_b16 v[198:199], v171 offset:0x3400
	ds_read_b64_tr_b16 v[200:201], v171 offset:0x3c00
	v_fmamk_f32 v216, v88, 0x3e38aa3b, v202
	v_fmamk_f32 v217, v89, 0x3e38aa3b, v202
	v_fmamk_f32 v218, v90, 0x3e38aa3b, v202
	v_exp_f32_e32 v211, v211
	v_exp_f32_e32 v214, v214
	v_exp_f32_e32 v215, v215
	s_waitcnt lgkmcnt(0)
	v_mfma_f32_32x32x16_bf16 v[34:49], v[138:141], v[186:189], v[34:49]
	ds_read_b64_tr_b16 v[186:187], v171 offset:0x600
	ds_read_b64_tr_b16 v[188:189], v171 offset:0xe00
	v_fmamk_f32 v219, v91, 0x3e38aa3b, v202
	v_fmamk_f32 v220, v92, 0x3e38aa3b, v202
	v_fmamk_f32 v221, v93, 0x3e38aa3b, v202
	v_exp_f32_e32 v216, v216
	v_exp_f32_e32 v217, v217
	v_exp_f32_e32 v218, v218
	v_mfma_f32_32x32x16_bf16 v[34:49], v[144:147], v[190:193], v[34:49]
	ds_read_b64_tr_b16 v[190:191], v171 offset:0x1600
	ds_read_b64_tr_b16 v[192:193], v171 offset:0x1e00
	v_fmamk_f32 v222, v94, 0x3e38aa3b, v202
	v_fmamk_f32 v223, v95, 0x3e38aa3b, v202
	v_fmamk_f32 v224, v96, 0x3e38aa3b, v202
	v_exp_f32_e32 v219, v219
	v_exp_f32_e32 v220, v220
	v_exp_f32_e32 v221, v221
	v_mfma_f32_32x32x16_bf16 v[34:49], v[148:151], v[194:197], v[34:49]
	ds_read_b64_tr_b16 v[194:195], v171 offset:0x2600
	ds_read_b64_tr_b16 v[196:197], v171 offset:0x2e00
	v_fmamk_f32 v225, v97, 0x3e38aa3b, v202
	v_fmamk_f32 v226, v66, 0x3e38aa3b, v202
	v_fmamk_f32 v227, v67, 0x3e38aa3b, v202
	v_exp_f32_e32 v222, v222
	v_exp_f32_e32 v223, v223
	v_exp_f32_e32 v224, v224
	v_mfma_f32_32x32x16_bf16 v[34:49], v[182:185], v[198:201], v[34:49]
	ds_read_b64_tr_b16 v[198:199], v171 offset:0x3600
	ds_read_b64_tr_b16 v[200:201], v171 offset:0x3e00
	v_fmamk_f32 v228, v68, 0x3e38aa3b, v202
	v_fmamk_f32 v229, v69, 0x3e38aa3b, v202
	v_fmamk_f32 v230, v70, 0x3e38aa3b, v202
	v_exp_f32_e32 v225, v225
	v_exp_f32_e32 v226, v226
	v_exp_f32_e32 v227, v227
	s_waitcnt lgkmcnt(0)
	v_mfma_f32_32x32x16_bf16 v[18:33], v[138:141], v[186:189], v[18:33]
	v_fmamk_f32 v231, v71, 0x3e38aa3b, v202
	v_fmamk_f32 v244, v72, 0x3e38aa3b, v202
	v_fmamk_f32 v245, v73, 0x3e38aa3b, v202
	v_exp_f32_e32 v228, v228
	v_exp_f32_e32 v229, v229
	v_exp_f32_e32 v230, v230
	v_mfma_f32_32x32x16_bf16 v[18:33], v[144:147], v[190:193], v[18:33]
	v_fmamk_f32 v246, v74, 0x3e38aa3b, v202
	v_fmamk_f32 v247, v75, 0x3e38aa3b, v202
	v_fmamk_f32 v248, v76, 0x3e38aa3b, v202
	v_exp_f32_e32 v231, v231
	v_exp_f32_e32 v244, v244
	v_exp_f32_e32 v245, v245
	v_mfma_f32_32x32x16_bf16 v[18:33], v[148:151], v[194:197], v[18:33]
	v_fmamk_f32 v249, v77, 0x3e38aa3b, v202
	v_fmamk_f32 v250, v78, 0x3e38aa3b, v202
	v_fmamk_f32 v251, v79, 0x3e38aa3b, v202
	v_exp_f32_e32 v246, v246
	v_exp_f32_e32 v247, v247
	v_exp_f32_e32 v248, v248
	v_mfma_f32_32x32x16_bf16 v[18:33], v[182:185], v[198:201], v[18:33]
	v_fmamk_f32 v252, v80, 0x3e38aa3b, v202
	v_fmac_f32_e32 v202, 0x3e38aa3b, v81
	v_exp_f32_e32 v249, v249
	v_exp_f32_e32 v250, v250
	v_exp_f32_e32 v251, v251
	v_exp_f32_e32 v252, v252
	v_exp_f32_e32 v202, v202
	v_cndmask_b32_e64 v183, v203, v142, s[2:3]
	s_barrier
	s_waitcnt vmcnt(3)
	v_cndmask_b32_e64 v182, v204, 1.0, s[2:3]
	v_cmp_gt_f32_e32 vcc, 1.0, v182
	s_waitcnt vmcnt(5)
	ds_write_b128 v172, v[114:117]
	s_waitcnt vmcnt(4)
	ds_write_b128 v173, v[118:121]
	s_waitcnt vmcnt(3)
	ds_write_b128 v174, v[122:125] offset:32768
	s_cbranch_vccz .LBB0_786
	s_and_saveexec_b64 s[10:11], s[0:1]
	ds_write_b32 v168, v182 offset:49280
	s_or_b64 exec, exec, s[10:11]
	s_waitcnt lgkmcnt(0)
	v_add_u32_e32 v139, v157, v0
	ds_read_b128 v[144:147], v139 offset:49376
	ds_read_b128 v[148:151], v139 offset:49344
	ds_read_b128 v[184:187], v139 offset:49312
	ds_read_b128 v[188:191], v139 offset:49280
	s_waitcnt lgkmcnt(3)
	v_pk_mul_f32 v[14:15], v[14:15], v[144:145]
	s_waitcnt lgkmcnt(2)
	v_pk_mul_f32 v[10:11], v[10:11], v[148:149]
	s_waitcnt lgkmcnt(1)
	v_pk_mul_f32 v[6:7], v[6:7], v[184:185]
	v_pk_mul_f32 v[16:17], v[16:17], v[146:147]
	v_pk_mul_f32 v[12:13], v[12:13], v[150:151]
	v_pk_mul_f32 v[8:9], v[8:9], v[186:187]
	s_waitcnt lgkmcnt(0)
	v_pk_mul_f32 v[4:5], v[4:5], v[190:191]
	v_pk_mul_f32 v[2:3], v[2:3], v[188:189]
	v_pk_mul_f32 v[62:63], v[62:63], v[144:145]
	v_pk_mul_f32 v[58:59], v[58:59], v[148:149]
	v_pk_mul_f32 v[54:55], v[54:55], v[184:185]
	v_pk_mul_f32 v[64:65], v[64:65], v[146:147]
	v_pk_mul_f32 v[60:61], v[60:61], v[150:151]
	v_pk_mul_f32 v[56:57], v[56:57], v[186:187]
	v_pk_mul_f32 v[52:53], v[52:53], v[190:191]
	v_pk_mul_f32 v[50:51], v[50:51], v[188:189]
	v_pk_mul_f32 v[46:47], v[46:47], v[144:145]
	v_pk_mul_f32 v[42:43], v[42:43], v[148:149]
	v_pk_mul_f32 v[38:39], v[38:39], v[184:185]
	v_pk_mul_f32 v[48:49], v[48:49], v[146:147]
	v_pk_mul_f32 v[44:45], v[44:45], v[150:151]
	v_pk_mul_f32 v[40:41], v[40:41], v[186:187]
	v_pk_mul_f32 v[36:37], v[36:37], v[190:191]
	v_pk_mul_f32 v[34:35], v[34:35], v[188:189]
	v_pk_mul_f32 v[30:31], v[30:31], v[144:145]
	v_pk_mul_f32 v[26:27], v[26:27], v[148:149]
	v_pk_mul_f32 v[22:23], v[22:23], v[184:185]
	v_pk_mul_f32 v[32:33], v[32:33], v[146:147]
	v_pk_mul_f32 v[28:29], v[28:29], v[150:151]
	v_pk_mul_f32 v[24:25], v[24:25], v[186:187]
	v_pk_mul_f32 v[20:21], v[20:21], v[190:191]
	v_pk_mul_f32 v[18:19], v[18:19], v[188:189]
; #define SBAR() __builtin_amdgcn_sched_barrier(0)
; #define SLOAD(i, k0) do { sr_[i].vs0 = *reinterpret_cast<const bf16x8*>(&Vh[(long)((k0) + sr) * DV + sc]); sr_[i].vs1 = *reinterpret_cast<const bf16x8*>(&Vh[(long)((k0) + 32 + sr) * DV + sc]); \
;     _Pragma("unroll") for (int _c = 0; _c < NKC; ++_c) sr_[i].ks[_c] = *reinterpret_cast<const bf16x8*>(&Kh[(long)((k0) + krow[_c]) * DQK + kcol[_c]]); } while (0)
; DI void finishSM(f32x16& p0, f32x16& p1, float alpha, float& l_reg, bf16x8& pa0, bf16x8& pa1, bf16x8& pa2, bf16x8& pa3) {
; #pragma unroll
;   for (int r = 0; r < 16; ++r) p1[r] = __builtin_amdgcn_exp2f(p1[r]);
;   float ps = 0;
; #pragma unroll
;   for (int r = 0; r < 16; ++r) ps += p0[r];
; #pragma unroll
;   for (int r = 0; r < 16; ++r) ps += p1[r];
;   { auto rr = __builtin_amdgcn_permlane32_swap(__float_as_uint(ps), __float_as_uint(ps), false, false);
;     ps = __uint_as_float(rr[0]) + __uint_as_float(rr[1]); }
;   l_reg = l_reg * alpha + ps;
;     ...
;   PK4(p0, 0, pa0); PK4(p0, 8, pa1); PK4(p1, 0, pa2); PK4(p1, 8, pa3);
;     ...
; }
; template <int DQK, int SDEPTH, bool OUT_BF16, int QREG = DQK / 16, bool OUT_F16 = false> ...
;     ...
;     SBAR(); QKT(pA0, pA1, K_lds);
;     finishSM(pB0, pB1, alB, l_reg, pa0, pa1, pa2, pa3); SBAR();
;     if (SDEPTH == 1 || j + 3 < NT) SLOAD(SE, (j + 1 + SDEPTH) * KVBLK); SBAR();
.LBB0_786:
	s_waitcnt lgkmcnt(0)
	s_barrier
	ds_read_b128 v[66:69], v175 offset:32768
	ds_read_b128 v[70:73], v175 offset:36864
	ds_read_b128 v[188:191], v176 offset:32768
	ds_read_b128 v[192:195], v176 offset:36864
	v_add_f32_e32 v184, 0, v208
	v_add_f32_e32 v184, v209, v184
	v_cvt_pk_bf16_f32 v138, v208, v209
	v_add_f32_e32 v184, v210, v184
	v_add_f32_e32 v184, v211, v184
	s_waitcnt lgkmcnt(3)
	v_mfma_f32_32x32x16_bf16 v[82:97], v[66:69], v[110:113], 0
	v_cvt_pk_bf16_f32 v139, v210, v211
	v_add_f32_e32 v184, v214, v184
	v_add_f32_e32 v184, v215, v184
	v_cvt_pk_bf16_f32 v140, v214, v215
	v_add_f32_e32 v184, v216, v184
	v_add_f32_e32 v184, v217, v184
	v_cvt_pk_bf16_f32 v141, v216, v217
	s_waitcnt lgkmcnt(2)
	v_mfma_f32_32x32x16_bf16 v[66:81], v[70:73], v[110:113], 0
	v_add_f32_e32 v184, v218, v184
	v_add_f32_e32 v184, v219, v184
	v_cvt_pk_bf16_f32 v142, v218, v219
	v_add_f32_e32 v184, v220, v184
	v_add_f32_e32 v184, v221, v184
	v_cvt_pk_bf16_f32 v143, v220, v221
	s_waitcnt lgkmcnt(1)
	v_mfma_f32_32x32x16_bf16 v[82:97], v[188:191], v[106:109], v[82:97]
	v_add_f32_e32 v184, v222, v184
	v_add_f32_e32 v184, v223, v184
	v_cvt_pk_bf16_f32 v144, v222, v223
	v_add_f32_e32 v184, v224, v184
	v_add_f32_e32 v184, v225, v184
	v_cvt_pk_bf16_f32 v145, v224, v225
	s_waitcnt lgkmcnt(0)
	v_mfma_f32_32x32x16_bf16 v[66:81], v[192:195], v[106:109], v[66:81]
	ds_read_b128 v[188:191], v178 offset:32768
	ds_read_b128 v[192:195], v178 offset:36864
	v_add_f32_e32 v184, v226, v184
	v_add_f32_e32 v184, v227, v184
	v_cvt_pk_bf16_f32 v146, v226, v227
	v_add_f32_e32 v184, v228, v184
	v_add_f32_e32 v184, v229, v184
	v_cvt_pk_bf16_f32 v147, v228, v229
	s_waitcnt lgkmcnt(1)
	v_mfma_f32_32x32x16_bf16 v[82:97], v[188:191], v[102:105], v[82:97]
	v_add_f32_e32 v184, v230, v184
	v_add_f32_e32 v184, v231, v184
	v_cvt_pk_bf16_f32 v148, v230, v231
	v_add_f32_e32 v184, v244, v184
	v_add_f32_e32 v184, v245, v184
	v_cvt_pk_bf16_f32 v149, v244, v245
	s_waitcnt lgkmcnt(0)
	v_mfma_f32_32x32x16_bf16 v[66:81], v[192:195], v[102:105], v[66:81]
	ds_read_b128 v[188:191], v177 offset:32768
	ds_read_b128 v[192:195], v177 offset:36864
	v_add_f32_e32 v184, v246, v184
	v_add_f32_e32 v184, v247, v184
	v_cvt_pk_bf16_f32 v150, v246, v247
	v_add_f32_e32 v184, v248, v184
	v_add_f32_e32 v184, v249, v184
	v_cvt_pk_bf16_f32 v151, v248, v249
	s_waitcnt lgkmcnt(1)
	v_mfma_f32_32x32x16_bf16 v[82:97], v[188:191], v[98:101], v[82:97]
	v_add_f32_e32 v184, v250, v184
	v_add_f32_e32 v184, v251, v184
	v_cvt_pk_bf16_f32 v152, v250, v251
	v_add_f32_e32 v184, v252, v184
	v_add_f32_e32 v184, v202, v184
	v_cvt_pk_bf16_f32 v153, v252, v202
	v_mov_b32_e32 v185, v184
	s_waitcnt lgkmcnt(0)
	v_mfma_f32_32x32x16_bf16 v[66:81], v[192:195], v[98:101], v[66:81]
	v_permlane32_swap_b32_e32 v138, v140
	v_permlane32_swap_b32_e32 v139, v141
	v_permlane32_swap_b32_e32 v142, v144
	v_permlane32_swap_b32_e32 v143, v145
	v_permlane32_swap_b32_e32 v146, v148
	v_permlane32_swap_b32_e32 v147, v149
	v_permlane32_swap_b32_e32 v184, v185
	v_permlane32_swap_b32_e32 v150, v152
	v_permlane32_swap_b32_e32 v151, v153
	s_cmp_le_u32 s7, s46
	s_cselect_b64 s[2:3], -1, 0
	s_or_b64 s[10:11], s[42:43], s[2:3]
	s_and_b64 vcc, exec, s[10:11]
	s_cbranch_vccnz .LBB0_788
	global_load_dwordx4 v[114:117], v158, s[86:87]
	global_load_dwordx4 v[118:121], v158, s[88:89]
	global_load_dwordx4 v[122:125], v160, s[90:91]

; #define PG8_STAGE(bufoff, gbase, voff) do { _Pragma("unroll") for (int _i = 0; _i < 2; ++_i) \
;         __builtin_amdgcn_global_load_lds((const unsigned*)((const char*)(gbase) + (voff)[_i]), (LAS unsigned*)(lds + (bufoff) + ldsw + _i * 8192), 16, 0, 0); } while (0)
; #define PG8_LDA(dst, b, h) do { _Pragma("unroll") for (int m = 0; m < 4; ++m) _Pragma("unroll") for (int k = 0; k < 2; ++k) dst[m][k] = *(const LAS bf16x8*)(lds + PG8_SA(b, h) + aoff + m * 2048 + k * 1024); } while (0)
; #define PG8_LDB(dst, b, h) do { _Pragma("unroll") for (int n = 0; n < 2; ++n) _Pragma("unroll") for (int k = 0; k < 2; ++k) dst[n][k] = *(const LAS bf16x8*)(lds + PG8_SB(b, h) + boff + n * 2048 + k * 1024); } while (0)
; #define PG8_MMA(ai, bj, At, Bt) do { __builtin_amdgcn_s_setprio(1); _Pragma("unroll") for (int m = 0; m < 4; ++m) _Pragma("unroll") for (int n = 0; n < 2; ++n) _Pragma("unroll") for (int k = 0; k < 2; ++k) \
;         acc[ai][bj][m][n] = __builtin_amdgcn_mfma_f32_16x16x32_bf16(Bt[n][k], At[m][k], acc[ai][bj][m][n], 0, 0, 0); __builtin_amdgcn_s_setprio(0); } while (0)
; #define PG8_WAIT_V(n) asm volatile("s_waitcnt vmcnt(" #n ")" ::: "memory")
; #define PG8_WAIT_L(n) asm volatile("s_waitcnt lgkmcnt(" #n ")" ::: "memory")
; #define PG8_BAR __builtin_amdgcn_s_barrier()
; #define PG8_SCHED __builtin_amdgcn_sched_barrier(0)
; template <class Epi, class Sched>
; __device__ __forceinline__ void gemm_phase(LAS unsigned char* lds, const Gemm g, const Sched& S, const Epi& E, const int tid) {
;     ...
;             PG8_LDB(B0, 0, 0); PG8_SCHED; PG8_LDA(At, 0, 0); PG8_STAGE(PG8_SA(1, 1), a1 + hstep, voffA);
;             PG8_WAIT_L(8); PG8_BAR; PG8_WAIT_L(0); PG8_MMA(0, 0, At, B0); PG8_BAR; PG8_SCHED;
;             PG8_LDB(B1, 0, 1); PG8_STAGE(PG8_SB(0, 0), b2, voffB);
;             PG8_BAR; PG8_WAIT_L(0); PG8_MMA(0, 1, At, B1); PG8_BAR;
;             PG8_LDA(At, 0, 1); PG8_STAGE(PG8_SA(0, 0), a2, voffA);
;             PG8_BAR; PG8_WAIT_L(0); PG8_MMA(1, 0, At, B0); PG8_BAR; PG8_SCHED;
;             PG8_STAGE(PG8_SB(0, 1), b2 + hstep, voffB);
;             PG8_WAIT_V(6); PG8_BAR; PG8_MMA(1, 1, At, B1); PG8_BAR;
.LBB0_1208:
	s_add_u32 s20, s18, 0xe61bc080
	s_addc_u32 s21, s19, -1
	s_cmp_lg_u32 s45, 28
	s_cselect_b32 s20, s20, 0
	s_cselect_b32 s21, s21, 0
	s_add_u32 s22, s4, s20
	s_addc_u32 s23, s5, s21
	s_add_i32 s46, 0, 0x10000
	v_add_u32_e32 v154, s46, v140
	ds_read_b128 v[142:145], v154
	ds_read_b128 v[146:149], v154 offset:1024
	ds_read_b128 v[150:153], v154 offset:2048
	ds_read_b128 v[154:157], v154 offset:3072
	s_add_u32 s20, s0, s20
	s_addc_u32 s21, s1, s21
	v_lshl_add_u64 v[190:191], v[136:137], 0, s[18:19]
	s_add_i32 m0, s25, 0xc000
	ds_read_b128 v[158:161], v141
	ds_read_b128 v[162:165], v141 offset:1024
	ds_read_b128 v[166:169], v141 offset:2048
	ds_read_b128 v[170:173], v141 offset:3072
	ds_read_b128 v[174:177], v141 offset:4096
	ds_read_b128 v[178:181], v141 offset:5120
	ds_read_b128 v[182:185], v141 offset:6144
	ds_read_b128 v[186:189], v141 offset:7168
	global_load_lds_dwordx4 v[190:191], off
	s_add_i32 m0, s25, 0xe000
	v_lshl_add_u64 v[190:191], v[138:139], 0, s[18:19]
	global_load_lds_dwordx4 v[190:191], off
	s_waitcnt lgkmcnt(8)
	s_barrier
	s_waitcnt lgkmcnt(0)
	v_mfma_f32_16x16x32_bf16 v[126:129], v[142:145], v[158:161], v[126:129]
	v_mfma_f32_16x16x32_bf16 v[122:125], v[150:153], v[158:161], v[122:125]
	v_mfma_f32_16x16x32_bf16 v[118:121], v[142:145], v[166:169], v[118:121]
	v_mfma_f32_16x16x32_bf16 v[110:113], v[150:153], v[166:169], v[110:113]
	v_mfma_f32_16x16x32_bf16 v[98:101], v[142:145], v[174:177], v[98:101]
	v_mfma_f32_16x16x32_bf16 v[90:93], v[150:153], v[174:177], v[90:93]
	v_mfma_f32_16x16x32_bf16 v[82:85], v[142:145], v[182:185], v[82:85]
	v_mfma_f32_16x16x32_bf16 v[74:77], v[150:153], v[182:185], v[74:77]
	v_mfma_f32_16x16x32_bf16 v[126:129], v[146:149], v[162:165], v[126:129]
	v_mfma_f32_16x16x32_bf16 v[122:125], v[154:157], v[162:165], v[122:125]
	v_mfma_f32_16x16x32_bf16 v[118:121], v[146:149], v[170:173], v[118:121]
	v_mfma_f32_16x16x32_bf16 v[110:113], v[154:157], v[170:173], v[110:113]
	v_mfma_f32_16x16x32_bf16 v[98:101], v[146:149], v[178:181], v[98:101]
	v_mfma_f32_16x16x32_bf16 v[90:93], v[154:157], v[178:181], v[90:93]
	v_mfma_f32_16x16x32_bf16 v[82:85], v[146:149], v[186:189], v[82:85]
	v_mfma_f32_16x16x32_bf16 v[74:77], v[154:157], v[186:189], v[74:77]
	s_barrier
	s_add_i32 s48, 0, 0x14000
	s_add_i32 s46, s46, s24
	v_add_u32_e32 v202, s48, v140
	s_mov_b32 m0, s46
	ds_read_b128 v[190:193], v202
	ds_read_b128 v[194:197], v202 offset:1024
	ds_read_b128 v[198:201], v202 offset:2048
	ds_read_b128 v[202:205], v202 offset:3072
	global_load_lds_dwordx4 v0, s[20:21]
	s_add_i32 m0, s46, 0x2000
	s_nop 0
	global_load_lds_dwordx4 v134, s[20:21]
	s_barrier
	s_waitcnt lgkmcnt(0)
	v_mfma_f32_16x16x32_bf16 v[114:117], v[190:193], v[158:161], v[114:117]
	v_mfma_f32_16x16x32_bf16 v[106:109], v[198:201], v[158:161], v[106:109]
	v_mfma_f32_16x16x32_bf16 v[102:105], v[190:193], v[166:169], v[102:105]
	v_mfma_f32_16x16x32_bf16 v[94:97], v[198:201], v[166:169], v[94:97]
	v_mfma_f32_16x16x32_bf16 v[86:89], v[190:193], v[174:177], v[86:89]
	v_mfma_f32_16x16x32_bf16 v[78:81], v[198:201], v[174:177], v[78:81]
	v_mfma_f32_16x16x32_bf16 v[70:73], v[190:193], v[182:185], v[70:73]
	v_mfma_f32_16x16x32_bf16 v[66:69], v[198:201], v[182:185], v[66:69]
	v_mfma_f32_16x16x32_bf16 v[114:117], v[194:197], v[162:165], v[114:117]
	v_mfma_f32_16x16x32_bf16 v[106:109], v[202:205], v[162:165], v[106:109]
	v_mfma_f32_16x16x32_bf16 v[102:105], v[194:197], v[170:173], v[102:105]
	v_mfma_f32_16x16x32_bf16 v[94:97], v[202:205], v[170:173], v[94:97]
	v_mfma_f32_16x16x32_bf16 v[86:89], v[194:197], v[178:181], v[86:89]
	v_mfma_f32_16x16x32_bf16 v[78:81], v[202:205], v[178:181], v[78:81]
	v_mfma_f32_16x16x32_bf16 v[70:73], v[194:197], v[186:189], v[70:73]
	v_mfma_f32_16x16x32_bf16 v[66:69], v[202:205], v[186:189], v[66:69]
	s_mov_b32 m0, s25
	v_lshl_add_u64 v[210:211], s[22:23], 0, v[130:131]
	s_barrier
	ds_read_b128 v[158:161], v141 offset:16384
	ds_read_b128 v[162:165], v141 offset:17408
	ds_read_b128 v[166:169], v141 offset:18432
	ds_read_b128 v[170:173], v141 offset:19456
	ds_read_b128 v[174:177], v141 offset:20480
	ds_read_b128 v[178:181], v141 offset:21504
	ds_read_b128 v[182:185], v141 offset:22528
	ds_read_b128 v[186:189], v141 offset:23552
	global_load_lds_dwordx4 v[210:211], off
	s_mov_b32 m0, s28
	v_lshl_add_u64 v[214:215], s[22:23], 0, v[132:133]
	global_load_lds_dwordx4 v[214:215], off
	s_barrier
	s_waitcnt lgkmcnt(0)
	v_mfma_f32_16x16x32_bf16 v[62:65], v[142:145], v[158:161], v[62:65]
	v_mfma_f32_16x16x32_bf16 v[58:61], v[150:153], v[158:161], v[58:61]
	v_mfma_f32_16x16x32_bf16 v[50:53], v[142:145], v[166:169], v[50:53]
	v_mfma_f32_16x16x32_bf16 v[42:45], v[150:153], v[166:169], v[42:45]
	v_mfma_f32_16x16x32_bf16 v[34:37], v[142:145], v[174:177], v[34:37]
	v_mfma_f32_16x16x32_bf16 v[26:29], v[150:153], v[174:177], v[26:29]
	v_mfma_f32_16x16x32_bf16 v[18:21], v[142:145], v[182:185], v[18:21]
	v_mfma_f32_16x16x32_bf16 v[10:13], v[150:153], v[182:185], v[10:13]
	v_mfma_f32_16x16x32_bf16 v[62:65], v[146:149], v[162:165], v[62:65]
	v_mfma_f32_16x16x32_bf16 v[58:61], v[154:157], v[162:165], v[58:61]
	v_mfma_f32_16x16x32_bf16 v[50:53], v[146:149], v[170:173], v[50:53]
	v_mfma_f32_16x16x32_bf16 v[42:45], v[154:157], v[170:173], v[42:45]
	v_mfma_f32_16x16x32_bf16 v[34:37], v[146:149], v[178:181], v[34:37]
	v_mfma_f32_16x16x32_bf16 v[26:29], v[154:157], v[178:181], v[26:29]
	v_mfma_f32_16x16x32_bf16 v[18:21], v[146:149], v[186:189], v[18:21]
	v_mfma_f32_16x16x32_bf16 v[10:13], v[154:157], v[186:189], v[10:13]
	s_barrier
	s_add_u32 s46, s20, 0x80000
	s_addc_u32 s47, s21, 0
	s_add_i32 s48, s48, s24
	s_mov_b32 m0, s48
	s_nop 0
	global_load_lds_dwordx4 v0, s[46:47]
	s_add_i32 m0, s48, 0x2000
	s_nop 0
	global_load_lds_dwordx4 v134, s[46:47]
	s_waitcnt vmcnt(6)
	s_barrier
; #define PG8_STAGE(bufoff, gbase, voff) do { _Pragma("unroll") for (int _i = 0; _i < 2; ++_i) \
;         __builtin_amdgcn_global_load_lds((const unsigned*)((const char*)(gbase) + (voff)[_i]), (LAS unsigned*)(lds + (bufoff) + ldsw + _i * 8192), 16, 0, 0); } while (0)
; #define PG8_LDA(dst, b, h) do { _Pragma("unroll") for (int m = 0; m < 4; ++m) _Pragma("unroll") for (int k = 0; k < 2; ++k) dst[m][k] = *(const LAS bf16x8*)(lds + PG8_SA(b, h) + aoff + m * 2048 + k * 1024); } while (0)
; #define PG8_LDB(dst, b, h) do { _Pragma("unroll") for (int n = 0; n < 2; ++n) _Pragma("unroll") for (int k = 0; k < 2; ++k) dst[n][k] = *(const LAS bf16x8*)(lds + PG8_SB(b, h) + boff + n * 2048 + k * 1024); } while (0)
; #define PG8_MMA(ai, bj, At, Bt) do { __builtin_amdgcn_s_setprio(1); _Pragma("unroll") for (int m = 0; m < 4; ++m) _Pragma("unroll") for (int n = 0; n < 2; ++n) _Pragma("unroll") for (int k = 0; k < 2; ++k) \
;         acc[ai][bj][m][n] = __builtin_amdgcn_mfma_f32_16x16x32_bf16(Bt[n][k], At[m][k], acc[ai][bj][m][n], 0, 0, 0); __builtin_amdgcn_s_setprio(0); } while (0)
; #define PG8_WAIT_V(n) asm volatile("s_waitcnt vmcnt(" #n ")" ::: "memory")
; #define PG8_WAIT_L(n) asm volatile("s_waitcnt lgkmcnt(" #n ")" ::: "memory")
; #define PG8_BAR __builtin_amdgcn_s_barrier()
; #define PG8_SCHED __builtin_amdgcn_sched_barrier(0)
; template <class Epi, class Sched>
; __device__ __forceinline__ void gemm_phase(LAS unsigned char* lds, const Gemm g, const Sched& S, const Epi& E, const int tid) {
;     ...
;             PG8_WAIT_V(6); PG8_BAR; PG8_MMA(1, 1, At, B1); PG8_BAR;
;             PG8_LDB(B0, 1, 0); PG8_SCHED; PG8_LDA(At, 1, 0); PG8_STAGE(PG8_SA(0, 1), a2 + hstep, voffA);
;             PG8_WAIT_L(8); PG8_BAR; PG8_WAIT_L(0); PG8_MMA(0, 0, At, B0); PG8_BAR; PG8_SCHED;
;             PG8_LDB(B1, 1, 1); PG8_STAGE(PG8_SB(1, 0), b3, voffB);
;             PG8_BAR; PG8_WAIT_L(0); PG8_MMA(0, 1, At, B1); PG8_BAR;
;             PG8_LDA(At, 1, 1); PG8_STAGE(PG8_SA(1, 0), a3, voffA);
;             PG8_BAR; PG8_WAIT_L(0); PG8_MMA(1, 0, At, B0); PG8_BAR; PG8_SCHED;
;             PG8_STAGE(PG8_SB(1, 1), b3 + hstep, voffB);
;             PG8_WAIT_V(6); PG8_BAR; PG8_MMA(1, 1, At, B1); PG8_BAR;
	v_mfma_f32_16x16x32_bf16 v[54:57], v[190:193], v[158:161], v[54:57]
	v_mfma_f32_16x16x32_bf16 v[46:49], v[198:201], v[158:161], v[46:49]
	v_mfma_f32_16x16x32_bf16 v[38:41], v[190:193], v[166:169], v[38:41]
	v_mfma_f32_16x16x32_bf16 v[30:33], v[198:201], v[166:169], v[30:33]
	v_mfma_f32_16x16x32_bf16 v[22:25], v[190:193], v[174:177], v[22:25]
	v_mfma_f32_16x16x32_bf16 v[14:17], v[198:201], v[174:177], v[14:17]
	v_mfma_f32_16x16x32_bf16 v[6:9], v[190:193], v[182:185], v[6:9]
	v_mfma_f32_16x16x32_bf16 v[2:5], v[198:201], v[182:185], v[2:5]
	v_mfma_f32_16x16x32_bf16 v[54:57], v[194:197], v[162:165], v[54:57]
	v_mfma_f32_16x16x32_bf16 v[46:49], v[202:205], v[162:165], v[46:49]
	v_mfma_f32_16x16x32_bf16 v[38:41], v[194:197], v[170:173], v[38:41]
	v_mfma_f32_16x16x32_bf16 v[30:33], v[202:205], v[170:173], v[30:33]
	v_mfma_f32_16x16x32_bf16 v[22:25], v[194:197], v[178:181], v[22:25]
	v_mfma_f32_16x16x32_bf16 v[14:17], v[202:205], v[178:181], v[14:17]
	v_mfma_f32_16x16x32_bf16 v[6:9], v[194:197], v[186:189], v[6:9]
	v_mfma_f32_16x16x32_bf16 v[2:5], v[202:205], v[186:189], v[2:5]
	s_add_i32 s46, 0, 0x18000
	v_add_u32_e32 v154, s46, v140
	s_barrier
	ds_read_b128 v[142:145], v154
	ds_read_b128 v[146:149], v154 offset:1024
	ds_read_b128 v[150:153], v154 offset:2048
	ds_read_b128 v[154:157], v154 offset:3072
	s_add_u32 s22, s22, 0x80000
	s_addc_u32 s23, s23, 0
	s_mov_b32 m0, s29
	ds_read_b128 v[158:161], v141 offset:32768
	ds_read_b128 v[162:165], v141 offset:33792
	ds_read_b128 v[166:169], v141 offset:34816
	ds_read_b128 v[170:173], v141 offset:35840
	ds_read_b128 v[174:177], v141 offset:36864
	ds_read_b128 v[178:181], v141 offset:37888
	ds_read_b128 v[182:185], v141 offset:38912
	global_load_lds_dwordx4 v130, s[22:23]
	s_mov_b32 m0, s42
	ds_read_b128 v[186:189], v141 offset:39936
	global_load_lds_dwordx4 v132, s[22:23]
	s_waitcnt lgkmcnt(8)
	s_barrier
	s_waitcnt lgkmcnt(0)
	v_mfma_f32_16x16x32_bf16 v[126:129], v[142:145], v[158:161], v[126:129]
	v_mfma_f32_16x16x32_bf16 v[122:125], v[150:153], v[158:161], v[122:125]
	v_mfma_f32_16x16x32_bf16 v[118:121], v[142:145], v[166:169], v[118:121]
	v_mfma_f32_16x16x32_bf16 v[110:113], v[150:153], v[166:169], v[110:113]
	v_mfma_f32_16x16x32_bf16 v[98:101], v[142:145], v[174:177], v[98:101]
	v_mfma_f32_16x16x32_bf16 v[90:93], v[150:153], v[174:177], v[90:93]
	v_mfma_f32_16x16x32_bf16 v[82:85], v[142:145], v[182:185], v[82:85]
	v_mfma_f32_16x16x32_bf16 v[74:77], v[150:153], v[182:185], v[74:77]
	v_mfma_f32_16x16x32_bf16 v[126:129], v[146:149], v[162:165], v[126:129]
	v_mfma_f32_16x16x32_bf16 v[122:125], v[154:157], v[162:165], v[122:125]
	v_mfma_f32_16x16x32_bf16 v[118:121], v[146:149], v[170:173], v[118:121]
	v_mfma_f32_16x16x32_bf16 v[110:113], v[154:157], v[170:173], v[110:113]
	v_mfma_f32_16x16x32_bf16 v[98:101], v[146:149], v[178:181], v[98:101]
	v_mfma_f32_16x16x32_bf16 v[90:93], v[154:157], v[178:181], v[90:93]
	v_mfma_f32_16x16x32_bf16 v[82:85], v[146:149], v[186:189], v[82:85]
	v_mfma_f32_16x16x32_bf16 v[74:77], v[154:157], v[186:189], v[74:77]
	s_barrier
	s_add_i32 s22, 0, 0x1c000
	s_add_i32 s23, s46, s24
	v_add_u32_e32 v202, s22, v140
	s_add_u32 s98, s20, s36
	s_addc_u32 s99, s21, s37
	s_mov_b32 m0, s23
	ds_read_b128 v[190:193], v202
	ds_read_b128 v[194:197], v202 offset:1024
	ds_read_b128 v[198:201], v202 offset:2048
	ds_read_b128 v[202:205], v202 offset:3072
	global_load_lds_dwordx4 v0, s[98:99]
	s_add_i32 m0, s23, 0x2000
	s_add_u32 s98, s20, s36
	s_addc_u32 s99, s21, s37
	global_load_lds_dwordx4 v134, s[98:99]
	s_barrier
; #define PG8_STAGE(bufoff, gbase, voff) do { _Pragma("unroll") for (int _i = 0; _i < 2; ++_i) \
;         __builtin_amdgcn_global_load_lds((const unsigned*)((const char*)(gbase) + (voff)[_i]), (LAS unsigned*)(lds + (bufoff) + ldsw + _i * 8192), 16, 0, 0); } while (0)
; #define PG8_LDA(dst, b, h) do { _Pragma("unroll") for (int m = 0; m < 4; ++m) _Pragma("unroll") for (int k = 0; k < 2; ++k) dst[m][k] = *(const LAS bf16x8*)(lds + PG8_SA(b, h) + aoff + m * 2048 + k * 1024); } while (0)
; #define PG8_MMA(ai, bj, At, Bt) do { __builtin_amdgcn_s_setprio(1); _Pragma("unroll") for (int m = 0; m < 4; ++m) _Pragma("unroll") for (int n = 0; n < 2; ++n) _Pragma("unroll") for (int k = 0; k < 2; ++k) \
;         acc[ai][bj][m][n] = __builtin_amdgcn_mfma_f32_16x16x32_bf16(Bt[n][k], At[m][k], acc[ai][bj][m][n], 0, 0, 0); __builtin_amdgcn_s_setprio(0); } while (0)
; #define PG8_WAIT_V(n) asm volatile("s_waitcnt vmcnt(" #n ")" ::: "memory")
; #define PG8_WAIT_L(n) asm volatile("s_waitcnt lgkmcnt(" #n ")" ::: "memory")
; #define PG8_BAR __builtin_amdgcn_s_barrier()
; #define PG8_SCHED __builtin_amdgcn_sched_barrier(0)
; template <class Epi, class Sched>
; __device__ __forceinline__ void gemm_phase(LAS unsigned char* lds, const Gemm g, const Sched& S, const Epi& E, const int tid) {
;     ...
;             PG8_BAR; PG8_WAIT_L(0); PG8_MMA(0, 1, At, B1); PG8_BAR;
;             PG8_LDA(At, 1, 1); PG8_STAGE(PG8_SA(1, 0), a3, voffA);
;             PG8_BAR; PG8_WAIT_L(0); PG8_MMA(1, 0, At, B0); PG8_BAR; PG8_SCHED;
;             PG8_STAGE(PG8_SB(1, 1), b3 + hstep, voffB);
;             PG8_WAIT_V(6); PG8_BAR; PG8_MMA(1, 1, At, B1); PG8_BAR;
;         }
;         if constexpr (!Epi::AFTER_DRAIN) { if constexpr (Epi::PRELOAD) E(acc, cur, wr, wc, fr, fq, lds); else E(acc, cur, wr, wc, fr, fq); S.done(cur); }
;         if (!has_next) break;
; #pragma unroll
;         for (int a = 0; a < 2; ++a)
; #pragma unroll
;             for (int b = 0; b < 2; ++b)
; #pragma unroll
;                 for (int m = 0; m < 4; ++m)
; #pragma unroll
;                     for (int n = 0; n < 2; ++n) acc[a][b][m][n] = (f32x4){0.f, 0.f, 0.f, 0.f};
;         cur = nxt; cA = nA; cB = nB; ++ui;
;     }
;     PG8_WAIT_V(0);
;     if (wr == 0) PG8_BAR;
	s_waitcnt lgkmcnt(0)
	v_mfma_f32_16x16x32_bf16 v[114:117], v[190:193], v[158:161], v[114:117]
	v_mfma_f32_16x16x32_bf16 v[106:109], v[198:201], v[158:161], v[106:109]
	v_mfma_f32_16x16x32_bf16 v[102:105], v[190:193], v[166:169], v[102:105]
	v_mfma_f32_16x16x32_bf16 v[94:97], v[198:201], v[166:169], v[94:97]
	v_mfma_f32_16x16x32_bf16 v[86:89], v[190:193], v[174:177], v[86:89]
	v_mfma_f32_16x16x32_bf16 v[78:81], v[198:201], v[174:177], v[78:81]
	v_mfma_f32_16x16x32_bf16 v[70:73], v[190:193], v[182:185], v[70:73]
	v_mfma_f32_16x16x32_bf16 v[66:69], v[198:201], v[182:185], v[66:69]
	v_mfma_f32_16x16x32_bf16 v[114:117], v[194:197], v[162:165], v[114:117]
	v_mfma_f32_16x16x32_bf16 v[106:109], v[202:205], v[162:165], v[106:109]
	v_mfma_f32_16x16x32_bf16 v[102:105], v[194:197], v[170:173], v[102:105]
	v_mfma_f32_16x16x32_bf16 v[94:97], v[202:205], v[170:173], v[94:97]
	v_mfma_f32_16x16x32_bf16 v[86:89], v[194:197], v[178:181], v[86:89]
	v_mfma_f32_16x16x32_bf16 v[78:81], v[202:205], v[178:181], v[78:81]
	v_mfma_f32_16x16x32_bf16 v[70:73], v[194:197], v[186:189], v[70:73]
	v_mfma_f32_16x16x32_bf16 v[66:69], v[202:205], v[186:189], v[66:69]
	s_mov_b32 m0, s43
	v_lshl_add_u64 v[206:207], v[210:211], 0, s[36:37]
	s_barrier
	ds_read_b128 v[158:161], v141 offset:49152
	ds_read_b128 v[162:165], v141 offset:50176
	ds_read_b128 v[166:169], v141 offset:51200
	ds_read_b128 v[170:173], v141 offset:52224
	ds_read_b128 v[174:177], v141 offset:53248
	ds_read_b128 v[178:181], v141 offset:54272
	ds_read_b128 v[182:185], v141 offset:55296
	ds_read_b128 v[186:189], v141 offset:56320
	global_load_lds_dwordx4 v[206:207], off
	s_mov_b32 m0, s44
	v_lshl_add_u64 v[206:207], v[214:215], 0, s[36:37]
	global_load_lds_dwordx4 v[206:207], off
	s_barrier
	s_waitcnt lgkmcnt(0)
	v_mfma_f32_16x16x32_bf16 v[62:65], v[142:145], v[158:161], v[62:65]
	v_mfma_f32_16x16x32_bf16 v[58:61], v[150:153], v[158:161], v[58:61]
	v_mfma_f32_16x16x32_bf16 v[50:53], v[142:145], v[166:169], v[50:53]
	v_mfma_f32_16x16x32_bf16 v[42:45], v[150:153], v[166:169], v[42:45]
	v_mfma_f32_16x16x32_bf16 v[34:37], v[142:145], v[174:177], v[34:37]
	v_mfma_f32_16x16x32_bf16 v[26:29], v[150:153], v[174:177], v[26:29]
	v_mfma_f32_16x16x32_bf16 v[18:21], v[142:145], v[182:185], v[18:21]
	v_mfma_f32_16x16x32_bf16 v[10:13], v[150:153], v[182:185], v[10:13]
	v_mfma_f32_16x16x32_bf16 v[62:65], v[146:149], v[162:165], v[62:65]
	v_mfma_f32_16x16x32_bf16 v[58:61], v[154:157], v[162:165], v[58:61]
	v_mfma_f32_16x16x32_bf16 v[50:53], v[146:149], v[170:173], v[50:53]
	v_mfma_f32_16x16x32_bf16 v[42:45], v[154:157], v[170:173], v[42:45]
	v_mfma_f32_16x16x32_bf16 v[34:37], v[146:149], v[178:181], v[34:37]
	v_mfma_f32_16x16x32_bf16 v[26:29], v[154:157], v[178:181], v[26:29]
	v_mfma_f32_16x16x32_bf16 v[18:21], v[146:149], v[186:189], v[18:21]
	v_mfma_f32_16x16x32_bf16 v[10:13], v[154:157], v[186:189], v[10:13]
	s_barrier
	s_add_u32 s20, s20, 0x80080
	s_addc_u32 s21, s21, 0
	s_add_i32 s22, s22, s24
	s_mov_b32 m0, s22
	s_nop 0
	global_load_lds_dwordx4 v0, s[20:21]
	s_add_i32 m0, s22, 0x2000
	s_nop 0
	global_load_lds_dwordx4 v134, s[20:21]
	s_waitcnt vmcnt(6)
	s_barrier
	v_mfma_f32_16x16x32_bf16 v[54:57], v[190:193], v[158:161], v[54:57]
	v_mfma_f32_16x16x32_bf16 v[46:49], v[198:201], v[158:161], v[46:49]
	v_mfma_f32_16x16x32_bf16 v[38:41], v[190:193], v[166:169], v[38:41]
	v_mfma_f32_16x16x32_bf16 v[30:33], v[198:201], v[166:169], v[30:33]
	v_mfma_f32_16x16x32_bf16 v[22:25], v[190:193], v[174:177], v[22:25]
	v_mfma_f32_16x16x32_bf16 v[14:17], v[198:201], v[174:177], v[14:17]
	v_mfma_f32_16x16x32_bf16 v[6:9], v[190:193], v[182:185], v[6:9]
	v_mfma_f32_16x16x32_bf16 v[2:5], v[198:201], v[182:185], v[2:5]
	v_mfma_f32_16x16x32_bf16 v[54:57], v[194:197], v[162:165], v[54:57]
	v_mfma_f32_16x16x32_bf16 v[46:49], v[202:205], v[162:165], v[46:49]
	v_mfma_f32_16x16x32_bf16 v[38:41], v[194:197], v[170:173], v[38:41]
	v_mfma_f32_16x16x32_bf16 v[30:33], v[202:205], v[170:173], v[30:33]
	v_mfma_f32_16x16x32_bf16 v[22:25], v[194:197], v[178:181], v[22:25]
	v_mfma_f32_16x16x32_bf16 v[14:17], v[202:205], v[178:181], v[14:17]
	v_mfma_f32_16x16x32_bf16 v[6:9], v[194:197], v[186:189], v[6:9]
	v_mfma_f32_16x16x32_bf16 v[2:5], v[202:205], v[186:189], v[2:5]
	s_add_i32 s45, s45, 2
	s_add_u32 s18, s18, 0x100
	s_addc_u32 s19, s19, 0
	s_cmp_lt_u32 s45, 30
	s_barrier
	s_cbranch_scc1 .LBB0_1208
	s_waitcnt vmcnt(0)
	s_cmpk_gt_u32 s38, 0xff
	s_cbranch_scc1 .LBB0_1211
	s_barrier

; #define PG8_STAGE(bufoff, gbase, voff) do { _Pragma("unroll") for (int _i = 0; _i < 2; ++_i) \
;         __builtin_amdgcn_global_load_lds((const unsigned*)((const char*)(gbase) + (voff)[_i]), (LAS unsigned*)(lds + (bufoff) + ldsw + _i * 8192), 16, 0, 0); } while (0)
; #define PG8_LDA(dst, b, h) do { _Pragma("unroll") for (int m = 0; m < 4; ++m) _Pragma("unroll") for (int k = 0; k < 2; ++k) dst[m][k] = *(const LAS bf16x8*)(lds + PG8_SA(b, h) + aoff + m * 2048 + k * 1024); } while (0)
; #define PG8_LDB(dst, b, h) do { _Pragma("unroll") for (int n = 0; n < 2; ++n) _Pragma("unroll") for (int k = 0; k < 2; ++k) dst[n][k] = *(const LAS bf16x8*)(lds + PG8_SB(b, h) + boff + n * 2048 + k * 1024); } while (0)
; #define PG8_WAIT_L(n) asm volatile("s_waitcnt lgkmcnt(" #n ")" ::: "memory")
; #define PG8_BAR __builtin_amdgcn_s_barrier()
; template <class Epi, class Sched>
; __device__ __forceinline__ void gemm_phase(LAS unsigned char* lds, const Gemm g, const Sched& S, const Epi& E, const int tid) {
;     ...
;         const bool has_next = S.next(ui + 1, nxt);
;         const char* nA = has_next ? (const char*)g.A + (size_t)nxt.pm * tstep + (size_t)nxt.ks * nxt.nt * kstep : cA; const char* nB = has_next ? (const char*)g.Bt + (size_t)nxt.pn * tstep + (size_t)nxt.ks * nxt.nt * kstep : cB;
;         const int nt = cur.nt;
;         for (int t = 0; t < nt; t += 2) {
;             const bool last = (t == nt - 2);
;             const char* a1 = cA + (size_t)(t + 1) * kstep;
;             const char* a2 = last ? nA : cA + (size_t)(t + 2) * kstep; const char* b2 = last ? nB : cB + (size_t)(t + 2) * kstep;
;             const char* a3 = a2 + kstep; const char* b3 = b2 + kstep;
;             if (last && has_next) S.a_ready(nxt);
;             if constexpr (Epi::PRELOAD) { if (last) E.preload(cur, lds, wid, lane); }
;             PG8_LDB(B0, 0, 0); PG8_SCHED; PG8_LDA(At, 0, 0); PG8_STAGE(PG8_SA(1, 1), a1 + hstep, voffA);
;             PG8_WAIT_L(8); PG8_BAR; PG8_WAIT_L(0); PG8_MMA(0, 0, At, B0); PG8_BAR; PG8_SCHED;
;             PG8_LDB(B1, 0, 1); PG8_STAGE(PG8_SB(0, 0), b2, voffB);
;             PG8_BAR; PG8_WAIT_L(0); PG8_MMA(0, 1, At, B1); PG8_BAR;
;             PG8_LDA(At, 0, 1); PG8_STAGE(PG8_SA(0, 0), a2, voffA);
;             PG8_BAR; PG8_WAIT_L(0); PG8_MMA(1, 0, At, B0); PG8_BAR; PG8_SCHED;
;             PG8_STAGE(PG8_SB(0, 1), b2 + hstep, voffB);
.LBB0_1261:
	s_add_u32 s17, s12, s7
	s_addc_u32 s19, s13, 0
	s_add_u32 s40, s17, 0x100
	s_addc_u32 s41, s19, 0
	s_and_b64 s[38:39], s[22:23], exec
	s_cselect_b32 s43, s15, s41
	s_cselect_b32 s42, s14, s40
	s_add_u32 s7, s10, s7
	s_addc_u32 s38, s11, 0
	s_add_u32 s7, s7, 0x100
	s_addc_u32 s38, s38, 0
	s_add_i32 s68, 0, 0x10000
	s_and_b64 s[22:23], s[22:23], exec
	s_cselect_b32 s45, s3, s38
	s_cselect_b32 s44, s2, s7
	s_add_u32 s46, s17, 0x80080
	s_addc_u32 s47, s19, 0
	s_add_i32 s72, s68, s53
	s_add_i32 m0, s5, 0xc000
	s_add_i32 s73, s5, 0xe000
	s_add_i32 s71, 0, 0x14000
	s_add_i32 s70, s72, 0x2000
	s_add_u32 s40, s44, 0x80000
	v_add_u32_e32 v148, s68, v133
	s_addc_u32 s41, s45, 0
	s_add_i32 s67, s71, s53
	ds_read_b128 v[136:139], v148
	ds_read_b128 v[140:143], v148 offset:1024
	ds_read_b128 v[144:147], v148 offset:2048
	ds_read_b128 v[148:151], v148 offset:3072
	s_add_i32 s66, s67, 0x2000
	s_add_i32 s65, 0, 0x18000
	s_add_u32 s38, s42, 0x80000
	s_addc_u32 s39, s43, 0
	s_add_i32 s19, s65, s53
	s_add_i32 s17, 0, 0x1c000
	s_add_i32 s7, s19, 0x2000
	s_add_u32 s22, s44, 0x80080
	s_addc_u32 s23, s45, 0
	s_add_i32 s69, s17, s53
	s_add_i32 s68, s69, 0x2000
	ds_read_b128 v[152:155], v135
	ds_read_b128 v[156:159], v135 offset:1024
	ds_read_b128 v[160:163], v135 offset:2048
	ds_read_b128 v[164:167], v135 offset:3072
	ds_read_b128 v[168:171], v135 offset:4096
	ds_read_b128 v[172:175], v135 offset:5120
	ds_read_b128 v[176:179], v135 offset:6144
	global_load_lds_dwordx4 v0, s[46:47]
	s_mov_b32 m0, s73
	ds_read_b128 v[180:183], v135 offset:7168
	global_load_lds_dwordx4 v130, s[46:47]
	s_waitcnt lgkmcnt(8)
	s_barrier
	s_waitcnt lgkmcnt(0)
	v_mfma_f32_16x16x32_bf16 v[126:129], v[136:139], v[152:155], v[126:129]
	v_mfma_f32_16x16x32_bf16 v[122:125], v[144:147], v[152:155], v[122:125]
	v_mfma_f32_16x16x32_bf16 v[118:121], v[136:139], v[160:163], v[118:121]
	v_mfma_f32_16x16x32_bf16 v[114:117], v[144:147], v[160:163], v[114:117]
	v_mfma_f32_16x16x32_bf16 v[106:109], v[136:139], v[168:171], v[106:109]
	v_mfma_f32_16x16x32_bf16 v[98:101], v[144:147], v[168:171], v[98:101]
	v_mfma_f32_16x16x32_bf16 v[90:93], v[136:139], v[176:179], v[90:93]
	v_mfma_f32_16x16x32_bf16 v[82:85], v[144:147], v[176:179], v[82:85]
	v_mfma_f32_16x16x32_bf16 v[126:129], v[140:143], v[156:159], v[126:129]
	v_mfma_f32_16x16x32_bf16 v[122:125], v[148:151], v[156:159], v[122:125]
	v_mfma_f32_16x16x32_bf16 v[118:121], v[140:143], v[164:167], v[118:121]
	v_mfma_f32_16x16x32_bf16 v[114:117], v[148:151], v[164:167], v[114:117]
	v_mfma_f32_16x16x32_bf16 v[106:109], v[140:143], v[172:175], v[106:109]
	v_mfma_f32_16x16x32_bf16 v[98:101], v[148:151], v[172:175], v[98:101]
	v_mfma_f32_16x16x32_bf16 v[90:93], v[140:143], v[180:183], v[90:93]
	v_mfma_f32_16x16x32_bf16 v[82:85], v[148:151], v[180:183], v[82:85]
	s_barrier
	s_mov_b32 m0, s72
	v_add_u32_e32 v196, s71, v133
	ds_read_b128 v[184:187], v196
	ds_read_b128 v[188:191], v196 offset:1024
	ds_read_b128 v[192:195], v196 offset:2048
	ds_read_b128 v[196:199], v196 offset:3072
	global_load_lds_dwordx4 v0, s[44:45]
	s_mov_b32 m0, s70
	s_nop 0
	global_load_lds_dwordx4 v130, s[44:45]
	s_barrier
	s_waitcnt lgkmcnt(0)
	v_mfma_f32_16x16x32_bf16 v[110:113], v[184:187], v[152:155], v[110:113]
	v_mfma_f32_16x16x32_bf16 v[102:105], v[192:195], v[152:155], v[102:105]
	v_mfma_f32_16x16x32_bf16 v[94:97], v[184:187], v[160:163], v[94:97]
	v_mfma_f32_16x16x32_bf16 v[86:89], v[192:195], v[160:163], v[86:89]
	v_mfma_f32_16x16x32_bf16 v[78:81], v[184:187], v[168:171], v[78:81]
	v_mfma_f32_16x16x32_bf16 v[74:77], v[192:195], v[168:171], v[74:77]
	v_mfma_f32_16x16x32_bf16 v[70:73], v[184:187], v[176:179], v[70:73]
	v_mfma_f32_16x16x32_bf16 v[66:69], v[192:195], v[176:179], v[66:69]
	v_mfma_f32_16x16x32_bf16 v[110:113], v[188:191], v[156:159], v[110:113]
	v_mfma_f32_16x16x32_bf16 v[102:105], v[196:199], v[156:159], v[102:105]
	v_mfma_f32_16x16x32_bf16 v[94:97], v[188:191], v[164:167], v[94:97]
	v_mfma_f32_16x16x32_bf16 v[86:89], v[196:199], v[164:167], v[86:89]
	v_mfma_f32_16x16x32_bf16 v[78:81], v[188:191], v[172:175], v[78:81]
	v_mfma_f32_16x16x32_bf16 v[74:77], v[196:199], v[172:175], v[74:77]
	v_mfma_f32_16x16x32_bf16 v[70:73], v[188:191], v[180:183], v[70:73]
	v_mfma_f32_16x16x32_bf16 v[66:69], v[196:199], v[180:183], v[66:69]
	s_mov_b32 m0, s5
	s_barrier
	ds_read_b128 v[152:155], v135 offset:16384
	ds_read_b128 v[156:159], v135 offset:17408
	ds_read_b128 v[160:163], v135 offset:18432
	ds_read_b128 v[164:167], v135 offset:19456
	ds_read_b128 v[168:171], v135 offset:20480
	ds_read_b128 v[172:175], v135 offset:21504
	ds_read_b128 v[176:179], v135 offset:22528
	ds_read_b128 v[180:183], v135 offset:23552
	global_load_lds_dwordx4 v0, s[42:43]
	s_mov_b32 m0, s28
	s_nop 0
	global_load_lds_dwordx4 v130, s[42:43]
	s_barrier
	s_waitcnt lgkmcnt(0)
	v_mfma_f32_16x16x32_bf16 v[62:65], v[136:139], v[152:155], v[62:65]
	v_mfma_f32_16x16x32_bf16 v[58:61], v[144:147], v[152:155], v[58:61]
	v_mfma_f32_16x16x32_bf16 v[54:57], v[136:139], v[160:163], v[54:57]
	v_mfma_f32_16x16x32_bf16 v[50:53], v[144:147], v[160:163], v[50:53]
	v_mfma_f32_16x16x32_bf16 v[38:41], v[136:139], v[168:171], v[38:41]
	v_mfma_f32_16x16x32_bf16 v[34:37], v[144:147], v[168:171], v[34:37]
	v_mfma_f32_16x16x32_bf16 v[22:25], v[136:139], v[176:179], v[22:25]
	v_mfma_f32_16x16x32_bf16 v[18:21], v[144:147], v[176:179], v[18:21]
	v_mfma_f32_16x16x32_bf16 v[62:65], v[140:143], v[156:159], v[62:65]
	v_mfma_f32_16x16x32_bf16 v[58:61], v[148:151], v[156:159], v[58:61]
	v_mfma_f32_16x16x32_bf16 v[54:57], v[140:143], v[164:167], v[54:57]
	v_mfma_f32_16x16x32_bf16 v[50:53], v[148:151], v[164:167], v[50:53]
	v_mfma_f32_16x16x32_bf16 v[38:41], v[140:143], v[172:175], v[38:41]
	v_mfma_f32_16x16x32_bf16 v[34:37], v[148:151], v[172:175], v[34:37]
	v_mfma_f32_16x16x32_bf16 v[22:25], v[140:143], v[180:183], v[22:25]
	v_mfma_f32_16x16x32_bf16 v[18:21], v[148:151], v[180:183], v[18:21]
	s_barrier
; #define PG8_STAGE(bufoff, gbase, voff) do { _Pragma("unroll") for (int _i = 0; _i < 2; ++_i) \
;         __builtin_amdgcn_global_load_lds((const unsigned*)((const char*)(gbase) + (voff)[_i]), (LAS unsigned*)(lds + (bufoff) + ldsw + _i * 8192), 16, 0, 0); } while (0)
; #define PG8_LDA(dst, b, h) do { _Pragma("unroll") for (int m = 0; m < 4; ++m) _Pragma("unroll") for (int k = 0; k < 2; ++k) dst[m][k] = *(const LAS bf16x8*)(lds + PG8_SA(b, h) + aoff + m * 2048 + k * 1024); } while (0)
; #define PG8_LDB(dst, b, h) do { _Pragma("unroll") for (int n = 0; n < 2; ++n) _Pragma("unroll") for (int k = 0; k < 2; ++k) dst[n][k] = *(const LAS bf16x8*)(lds + PG8_SB(b, h) + boff + n * 2048 + k * 1024); } while (0)
; #define PG8_MMA(ai, bj, At, Bt) do { __builtin_amdgcn_s_setprio(1); _Pragma("unroll") for (int m = 0; m < 4; ++m) _Pragma("unroll") for (int n = 0; n < 2; ++n) _Pragma("unroll") for (int k = 0; k < 2; ++k) \
;         acc[ai][bj][m][n] = __builtin_amdgcn_mfma_f32_16x16x32_bf16(Bt[n][k], At[m][k], acc[ai][bj][m][n], 0, 0, 0); __builtin_amdgcn_s_setprio(0); } while (0)
; #define PG8_WAIT_V(n) asm volatile("s_waitcnt vmcnt(" #n ")" ::: "memory")
; #define PG8_WAIT_L(n) asm volatile("s_waitcnt lgkmcnt(" #n ")" ::: "memory")
; #define PG8_BAR __builtin_amdgcn_s_barrier()
; #define PG8_SCHED __builtin_amdgcn_sched_barrier(0)
; template <class Epi, class Sched>
; __device__ __forceinline__ void gemm_phase(LAS unsigned char* lds, const Gemm g, const Sched& S, const Epi& E, const int tid) {
;     ...
;             PG8_STAGE(PG8_SB(0, 1), b2 + hstep, voffB);
;             PG8_WAIT_V(6); PG8_BAR; PG8_MMA(1, 1, At, B1); PG8_BAR;
;             PG8_LDB(B0, 1, 0); PG8_SCHED; PG8_LDA(At, 1, 0); PG8_STAGE(PG8_SA(0, 1), a2 + hstep, voffA);
;             PG8_WAIT_L(8); PG8_BAR; PG8_WAIT_L(0); PG8_MMA(0, 0, At, B0); PG8_BAR; PG8_SCHED;
;             PG8_LDB(B1, 1, 1); PG8_STAGE(PG8_SB(1, 0), b3, voffB);
;             PG8_BAR; PG8_WAIT_L(0); PG8_MMA(0, 1, At, B1); PG8_BAR;
;             PG8_LDA(At, 1, 1); PG8_STAGE(PG8_SA(1, 0), a3, voffA);
;             PG8_BAR; PG8_WAIT_L(0); PG8_MMA(1, 0, At, B0); PG8_BAR; PG8_SCHED;
;             PG8_STAGE(PG8_SB(1, 1), b3 + hstep, voffB);
	s_mov_b32 m0, s67
	s_nop 0
	global_load_lds_dwordx4 v0, s[40:41]
	s_mov_b32 m0, s66
	s_nop 0
	global_load_lds_dwordx4 v130, s[40:41]
	s_waitcnt vmcnt(6)
	s_barrier
	v_mfma_f32_16x16x32_bf16 v[46:49], v[184:187], v[152:155], v[46:49]
	v_mfma_f32_16x16x32_bf16 v[42:45], v[192:195], v[152:155], v[42:45]
	v_mfma_f32_16x16x32_bf16 v[30:33], v[184:187], v[160:163], v[30:33]
	v_mfma_f32_16x16x32_bf16 v[26:29], v[192:195], v[160:163], v[26:29]
	v_mfma_f32_16x16x32_bf16 v[14:17], v[184:187], v[168:171], v[14:17]
	v_mfma_f32_16x16x32_bf16 v[10:13], v[192:195], v[168:171], v[10:13]
	v_mfma_f32_16x16x32_bf16 v[6:9], v[184:187], v[176:179], v[6:9]
	v_mfma_f32_16x16x32_bf16 v[2:5], v[192:195], v[176:179], v[2:5]
	v_mfma_f32_16x16x32_bf16 v[46:49], v[188:191], v[156:159], v[46:49]
	v_mfma_f32_16x16x32_bf16 v[42:45], v[196:199], v[156:159], v[42:45]
	v_mfma_f32_16x16x32_bf16 v[30:33], v[188:191], v[164:167], v[30:33]
	v_mfma_f32_16x16x32_bf16 v[26:29], v[196:199], v[164:167], v[26:29]
	v_mfma_f32_16x16x32_bf16 v[14:17], v[188:191], v[172:175], v[14:17]
	v_mfma_f32_16x16x32_bf16 v[10:13], v[196:199], v[172:175], v[10:13]
	v_mfma_f32_16x16x32_bf16 v[6:9], v[188:191], v[180:183], v[6:9]
	v_mfma_f32_16x16x32_bf16 v[2:5], v[196:199], v[180:183], v[2:5]
	v_add_u32_e32 v148, s65, v133
	s_barrier
	ds_read_b128 v[136:139], v148
	ds_read_b128 v[140:143], v148 offset:1024
	ds_read_b128 v[144:147], v148 offset:2048
	ds_read_b128 v[148:151], v148 offset:3072
	s_mov_b32 m0, s54
	ds_read_b128 v[152:155], v135 offset:32768
	ds_read_b128 v[156:159], v135 offset:33792
	ds_read_b128 v[160:163], v135 offset:34816
	ds_read_b128 v[164:167], v135 offset:35840
	ds_read_b128 v[168:171], v135 offset:36864
	ds_read_b128 v[172:175], v135 offset:37888
	ds_read_b128 v[176:179], v135 offset:38912
	global_load_lds_dwordx4 v0, s[38:39]
	s_mov_b32 m0, s55
	ds_read_b128 v[180:183], v135 offset:39936
	global_load_lds_dwordx4 v130, s[38:39]
	s_waitcnt lgkmcnt(8)
	s_barrier
	s_waitcnt lgkmcnt(0)
	v_mfma_f32_16x16x32_bf16 v[126:129], v[136:139], v[152:155], v[126:129]
	v_mfma_f32_16x16x32_bf16 v[122:125], v[144:147], v[152:155], v[122:125]
	v_mfma_f32_16x16x32_bf16 v[118:121], v[136:139], v[160:163], v[118:121]
	v_mfma_f32_16x16x32_bf16 v[114:117], v[144:147], v[160:163], v[114:117]
	v_mfma_f32_16x16x32_bf16 v[106:109], v[136:139], v[168:171], v[106:109]
	v_mfma_f32_16x16x32_bf16 v[98:101], v[144:147], v[168:171], v[98:101]
	v_mfma_f32_16x16x32_bf16 v[90:93], v[136:139], v[176:179], v[90:93]
	v_mfma_f32_16x16x32_bf16 v[82:85], v[144:147], v[176:179], v[82:85]
	v_mfma_f32_16x16x32_bf16 v[126:129], v[140:143], v[156:159], v[126:129]
	v_mfma_f32_16x16x32_bf16 v[122:125], v[148:151], v[156:159], v[122:125]
	v_mfma_f32_16x16x32_bf16 v[118:121], v[140:143], v[164:167], v[118:121]
	v_mfma_f32_16x16x32_bf16 v[114:117], v[148:151], v[164:167], v[114:117]
	v_mfma_f32_16x16x32_bf16 v[106:109], v[140:143], v[172:175], v[106:109]
	v_mfma_f32_16x16x32_bf16 v[98:101], v[148:151], v[172:175], v[98:101]
	v_mfma_f32_16x16x32_bf16 v[90:93], v[140:143], v[180:183], v[90:93]
	v_mfma_f32_16x16x32_bf16 v[82:85], v[148:151], v[180:183], v[82:85]
	s_barrier
	s_mov_b32 m0, s19
	v_add_u32_e32 v196, s17, v133
	s_add_u32 s98, s44, s36
	s_addc_u32 s99, s45, s37
	ds_read_b128 v[184:187], v196
	ds_read_b128 v[188:191], v196 offset:1024
	ds_read_b128 v[192:195], v196 offset:2048
	ds_read_b128 v[196:199], v196 offset:3072
	global_load_lds_dwordx4 v0, s[98:99]
	s_mov_b32 m0, s7
	s_add_u32 s98, s44, s36
	s_addc_u32 s99, s45, s37
	global_load_lds_dwordx4 v130, s[98:99]
	s_barrier
	s_waitcnt lgkmcnt(0)
	v_mfma_f32_16x16x32_bf16 v[110:113], v[184:187], v[152:155], v[110:113]
	v_mfma_f32_16x16x32_bf16 v[102:105], v[192:195], v[152:155], v[102:105]
	v_mfma_f32_16x16x32_bf16 v[94:97], v[184:187], v[160:163], v[94:97]
	v_mfma_f32_16x16x32_bf16 v[86:89], v[192:195], v[160:163], v[86:89]
	v_mfma_f32_16x16x32_bf16 v[78:81], v[184:187], v[168:171], v[78:81]
	v_mfma_f32_16x16x32_bf16 v[74:77], v[192:195], v[168:171], v[74:77]
	v_mfma_f32_16x16x32_bf16 v[70:73], v[184:187], v[176:179], v[70:73]
	v_mfma_f32_16x16x32_bf16 v[66:69], v[192:195], v[176:179], v[66:69]
	v_mfma_f32_16x16x32_bf16 v[110:113], v[188:191], v[156:159], v[110:113]
	v_mfma_f32_16x16x32_bf16 v[102:105], v[196:199], v[156:159], v[102:105]
	v_mfma_f32_16x16x32_bf16 v[94:97], v[188:191], v[164:167], v[94:97]
	v_mfma_f32_16x16x32_bf16 v[86:89], v[196:199], v[164:167], v[86:89]
	v_mfma_f32_16x16x32_bf16 v[78:81], v[188:191], v[172:175], v[78:81]
	v_mfma_f32_16x16x32_bf16 v[74:77], v[196:199], v[172:175], v[74:77]
	v_mfma_f32_16x16x32_bf16 v[70:73], v[188:191], v[180:183], v[70:73]
	v_mfma_f32_16x16x32_bf16 v[66:69], v[196:199], v[180:183], v[66:69]
	s_mov_b32 m0, s59
	s_add_u32 s98, s42, s36
	s_addc_u32 s99, s43, s37
	s_barrier
	ds_read_b128 v[152:155], v135 offset:49152
	ds_read_b128 v[156:159], v135 offset:50176
	ds_read_b128 v[160:163], v135 offset:51200
	ds_read_b128 v[164:167], v135 offset:52224
	ds_read_b128 v[168:171], v135 offset:53248
	ds_read_b128 v[172:175], v135 offset:54272
	ds_read_b128 v[176:179], v135 offset:55296
	ds_read_b128 v[180:183], v135 offset:56320
	global_load_lds_dwordx4 v0, s[98:99]
	s_mov_b32 m0, s60
	s_add_u32 s98, s42, s36
	s_addc_u32 s99, s43, s37
	global_load_lds_dwordx4 v130, s[98:99]
	s_barrier
; #define PG8_STAGE(bufoff, gbase, voff) do { _Pragma("unroll") for (int _i = 0; _i < 2; ++_i) \
;         __builtin_amdgcn_global_load_lds((const unsigned*)((const char*)(gbase) + (voff)[_i]), (LAS unsigned*)(lds + (bufoff) + ldsw + _i * 8192), 16, 0, 0); } while (0)
; #define PG8_MMA(ai, bj, At, Bt) do { __builtin_amdgcn_s_setprio(1); _Pragma("unroll") for (int m = 0; m < 4; ++m) _Pragma("unroll") for (int n = 0; n < 2; ++n) _Pragma("unroll") for (int k = 0; k < 2; ++k) \
;         acc[ai][bj][m][n] = __builtin_amdgcn_mfma_f32_16x16x32_bf16(Bt[n][k], At[m][k], acc[ai][bj][m][n], 0, 0, 0); __builtin_amdgcn_s_setprio(0); } while (0)
; #define PG8_WAIT_V(n) asm volatile("s_waitcnt vmcnt(" #n ")" ::: "memory")
; #define PG8_WAIT_L(n) asm volatile("s_waitcnt lgkmcnt(" #n ")" ::: "memory")
; #define PG8_BAR __builtin_amdgcn_s_barrier()
; #define PG8_SCHED __builtin_amdgcn_sched_barrier(0)
;     __device__ __forceinline__ void operator()(const f32x4 (&acc)[2][2][4][2], const Unit& u, int wr, int wc, int fr, int fq) const {
;         const int row0 = u.pm * BM + wr * 64 + fr, col0 = u.pn * BM + wc * 32 + 4 * fq;
;         float* base = (u.nt < ntfull) ? part + ((size_t)u.ks * MCTX - MLAT) * ldc : C;
; #pragma unroll
;         for (int ai = 0; ai < 2; ++ai)
; #pragma unroll
;             for (int m = 0; m < 4; ++m) { float* rowp = base + (size_t)(row0 + ai * HALF + m * 16) * ldc + col0;
; #pragma unroll
;                 for (int bj = 0; bj < 2; ++bj)
; #pragma unroll
;                     for (int n = 0; n < 2; ++n) *(f32x4*)(rowp + bj * HALF + n * 16) = acc[ai][bj][m][n]; }
;     }
; template <class Epi, class Sched>
; __device__ __forceinline__ void gemm_phase(LAS unsigned char* lds, const Gemm g, const Sched& S, const Epi& E, const int tid) {
;     ...
;             PG8_BAR; PG8_WAIT_L(0); PG8_MMA(1, 0, At, B0); PG8_BAR; PG8_SCHED;
;             PG8_STAGE(PG8_SB(1, 1), b3 + hstep, voffB);
;             PG8_WAIT_V(6); PG8_BAR; PG8_MMA(1, 1, At, B1); PG8_BAR;
;         }
;         if constexpr (!Epi::AFTER_DRAIN) { if constexpr (Epi::PRELOAD) E(acc, cur, wr, wc, fr, fq, lds); else E(acc, cur, wr, wc, fr, fq); S.done(cur); }
	s_waitcnt lgkmcnt(0)
	v_mfma_f32_16x16x32_bf16 v[62:65], v[136:139], v[152:155], v[62:65]
	v_mfma_f32_16x16x32_bf16 v[58:61], v[144:147], v[152:155], v[58:61]
	v_mfma_f32_16x16x32_bf16 v[54:57], v[136:139], v[160:163], v[54:57]
	v_mfma_f32_16x16x32_bf16 v[50:53], v[144:147], v[160:163], v[50:53]
	v_mfma_f32_16x16x32_bf16 v[38:41], v[136:139], v[168:171], v[38:41]
	v_mfma_f32_16x16x32_bf16 v[34:37], v[144:147], v[168:171], v[34:37]
	v_mfma_f32_16x16x32_bf16 v[22:25], v[136:139], v[176:179], v[22:25]
	v_mfma_f32_16x16x32_bf16 v[18:21], v[144:147], v[176:179], v[18:21]
	v_mfma_f32_16x16x32_bf16 v[62:65], v[140:143], v[156:159], v[62:65]
	v_mfma_f32_16x16x32_bf16 v[58:61], v[148:151], v[156:159], v[58:61]
	v_mfma_f32_16x16x32_bf16 v[54:57], v[140:143], v[164:167], v[54:57]
	v_mfma_f32_16x16x32_bf16 v[50:53], v[148:151], v[164:167], v[50:53]
	v_mfma_f32_16x16x32_bf16 v[38:41], v[140:143], v[172:175], v[38:41]
	v_mfma_f32_16x16x32_bf16 v[34:37], v[148:151], v[172:175], v[34:37]
	v_mfma_f32_16x16x32_bf16 v[22:25], v[140:143], v[180:183], v[22:25]
	v_mfma_f32_16x16x32_bf16 v[18:21], v[148:151], v[180:183], v[18:21]
	s_barrier
	s_mov_b32 m0, s69
	s_nop 0
	global_load_lds_dwordx4 v0, s[22:23]
	s_mov_b32 m0, s68
	s_nop 0
	global_load_lds_dwordx4 v130, s[22:23]
	s_waitcnt vmcnt(6)
	s_barrier
	v_mfma_f32_16x16x32_bf16 v[46:49], v[184:187], v[152:155], v[46:49]
	v_mfma_f32_16x16x32_bf16 v[42:45], v[192:195], v[152:155], v[42:45]
	v_mfma_f32_16x16x32_bf16 v[30:33], v[184:187], v[160:163], v[30:33]
	v_mfma_f32_16x16x32_bf16 v[26:29], v[192:195], v[160:163], v[26:29]
	v_mfma_f32_16x16x32_bf16 v[14:17], v[184:187], v[168:171], v[14:17]
	v_mfma_f32_16x16x32_bf16 v[10:13], v[192:195], v[168:171], v[10:13]
	v_mfma_f32_16x16x32_bf16 v[6:9], v[184:187], v[176:179], v[6:9]
	v_mfma_f32_16x16x32_bf16 v[2:5], v[192:195], v[176:179], v[2:5]
	v_mfma_f32_16x16x32_bf16 v[46:49], v[188:191], v[156:159], v[46:49]
	v_mfma_f32_16x16x32_bf16 v[42:45], v[196:199], v[156:159], v[42:45]
	v_mfma_f32_16x16x32_bf16 v[30:33], v[188:191], v[164:167], v[30:33]
	v_mfma_f32_16x16x32_bf16 v[26:29], v[196:199], v[164:167], v[26:29]
	v_mfma_f32_16x16x32_bf16 v[14:17], v[188:191], v[172:175], v[14:17]
	v_mfma_f32_16x16x32_bf16 v[10:13], v[196:199], v[172:175], v[10:13]
	v_mfma_f32_16x16x32_bf16 v[6:9], v[188:191], v[180:183], v[6:9]
	v_mfma_f32_16x16x32_bf16 v[2:5], v[196:199], v[180:183], v[2:5]
	s_movk_i32 s7, 0x100
	s_andn2_b64 vcc, exec, s[20:21]
	s_mov_b64 s[22:23], -1
	s_mov_b64 s[20:21], 0
	s_barrier
	s_cbranch_vccz .LBB0_1261
	s_ashr_i32 s7, s6, 31
	s_lshl_b64 s[6:7], s[6:7], 22
	s_add_u32 s6, s61, s6
	v_lshl_or_b32 v136, s4, 8, v134
	v_lshl_add_u32 v138, s29, 8, v132
	s_addc_u32 s7, s62, s7
	v_ashrrev_i32_e32 v137, 31, v136
	v_ashrrev_i32_e32 v139, 31, v138
	v_lshl_add_u64 v[136:137], v[136:137], 2, s[6:7]
	v_lshlrev_b64 v[140:141], 13, v[138:139]
	v_lshl_add_u64 v[140:141], v[136:137], 0, v[140:141]
	global_store_dwordx4 v[140:141], v[126:129], off
	global_store_dwordx4 v[140:141], v[122:125], off offset:64
	global_store_dwordx4 v[140:141], v[110:113], off offset:512
	global_store_dwordx4 v[140:141], v[102:105], off offset:576
	s_mov_b32 s4, 0x100000
	s_mov_b64 s[6:7], 0x100000
	v_or_b32_e32 v102, 16, v138
	v_ashrrev_i32_e32 v103, 31, v102
	v_lshlrev_b64 v[102:103], 13, v[102:103]
	v_lshl_add_u64 v[102:103], v[136:137], 0, v[102:103]
	global_store_dwordx4 v[102:103], v[118:121], off
	global_store_dwordx4 v[102:103], v[114:117], off offset:64
	global_store_dwordx4 v[102:103], v[94:97], off offset:512
	global_store_dwordx4 v[102:103], v[86:89], off offset:576
	s_mov_b32 s29, s64
	s_mov_b64 s[10:11], s[2:3]
	v_or_b32_e32 v86, 32, v138
	v_ashrrev_i32_e32 v87, 31, v86
	v_lshlrev_b64 v[86:87], 13, v[86:87]
	v_lshl_add_u64 v[86:87], v[136:137], 0, v[86:87]
	global_store_dwordx4 v[86:87], v[106:109], off
	global_store_dwordx4 v[86:87], v[98:101], off offset:64
	global_store_dwordx4 v[86:87], v[78:81], off offset:512
	global_store_dwordx4 v[86:87], v[74:77], off offset:576
	s_mov_b64 s[12:13], s[14:15]
	s_nop 0
	v_or_b32_e32 v74, 48, v138
	v_ashrrev_i32_e32 v75, 31, v74
	v_lshlrev_b64 v[74:75], 13, v[74:75]
	v_lshl_add_u64 v[74:75], v[136:137], 0, v[74:75]
	global_store_dwordx4 v[74:75], v[90:93], off
	global_store_dwordx4 v[74:75], v[82:85], off offset:64
	global_store_dwordx4 v[74:75], v[70:73], off offset:512
	global_store_dwordx4 v[74:75], v[66:69], off offset:576
	s_nop 1
	v_add_co_u32_e32 v68, vcc, s4, v140
	s_mov_b32 s4, 0x120000
	s_nop 0
	v_addc_co_u32_e32 v69, vcc, 0, v141, vcc
	v_lshl_add_u64 v[66:67], v[140:141], 0, s[6:7]
	global_store_dwordx4 v[68:69], v[62:65], off
	global_store_dwordx4 v[66:67], v[58:61], off offset:64
	global_store_dwordx4 v[66:67], v[46:49], off offset:512
	global_store_dwordx4 v[66:67], v[42:45], off offset:576
	s_mov_b64 s[6:7], 0x120000
	s_nop 0
	v_add_co_u32_e32 v44, vcc, s4, v140
	s_mov_b32 s4, 0x140000
	s_nop 0
	v_addc_co_u32_e32 v45, vcc, 0, v141, vcc
	v_lshl_add_u64 v[42:43], v[140:141], 0, s[6:7]
	global_store_dwordx4 v[44:45], v[54:57], off
	global_store_dwordx4 v[42:43], v[50:53], off offset:64
	global_store_dwordx4 v[42:43], v[30:33], off offset:512
	global_store_dwordx4 v[42:43], v[26:29], off offset:576
	s_mov_b64 s[6:7], 0x140000
	s_nop 0
	v_add_co_u32_e32 v28, vcc, s4, v140
	v_lshl_add_u64 v[26:27], v[140:141], 0, s[6:7]
	s_nop 0
	v_addc_co_u32_e32 v29, vcc, 0, v141, vcc
	global_store_dwordx4 v[28:29], v[38:41], off
	global_store_dwordx4 v[26:27], v[34:37], off offset:64
	global_store_dwordx4 v[26:27], v[14:17], off offset:512
	global_store_dwordx4 v[26:27], v[10:13], off offset:576
	s_mov_b64 s[6:7], 0x160000
	s_mov_b32 s4, s18
	v_add_co_u32_e32 v12, vcc, 0x160000, v140
	v_lshl_add_u64 v[10:11], v[140:141], 0, s[6:7]
	s_nop 0
	v_addc_co_u32_e32 v13, vcc, 0, v141, vcc
	s_and_b64 vcc, exec, s[0:1]
	s_mov_b32 s6, s16
	global_store_dwordx4 v[12:13], v[22:25], off
	global_store_dwordx4 v[10:11], v[18:21], off offset:64
	global_store_dwordx4 v[10:11], v[6:9], off offset:512
	global_store_dwordx4 v[10:11], v[2:5], off offset:576
	s_cbranch_vccz .LBB0_1256
	s_waitcnt vmcnt(0)
	s_cmpk_gt_u32 s49, 0xff
	s_cbranch_scc1 .LBB0_1265
	s_barrier

; #define PG8_STAGE(bufoff, gbase, voff) do { _Pragma("unroll") for (int _i = 0; _i < 2; ++_i) \
;         __builtin_amdgcn_global_load_lds((const unsigned*)((const char*)(gbase) + (voff)[_i]), (LAS unsigned*)(lds + (bufoff) + ldsw + _i * 8192), 16, 0, 0); } while (0)
; #define PG8_LDA(dst, b, h) do { _Pragma("unroll") for (int m = 0; m < 4; ++m) _Pragma("unroll") for (int k = 0; k < 2; ++k) dst[m][k] = *(const LAS bf16x8*)(lds + PG8_SA(b, h) + aoff + m * 2048 + k * 1024); } while (0)
; #define PG8_LDB(dst, b, h) do { _Pragma("unroll") for (int n = 0; n < 2; ++n) _Pragma("unroll") for (int k = 0; k < 2; ++k) dst[n][k] = *(const LAS bf16x8*)(lds + PG8_SB(b, h) + boff + n * 2048 + k * 1024); } while (0)
; #define PG8_MMA(ai, bj, At, Bt) do { __builtin_amdgcn_s_setprio(1); _Pragma("unroll") for (int m = 0; m < 4; ++m) _Pragma("unroll") for (int n = 0; n < 2; ++n) _Pragma("unroll") for (int k = 0; k < 2; ++k) \
;         acc[ai][bj][m][n] = __builtin_amdgcn_mfma_f32_16x16x32_bf16(Bt[n][k], At[m][k], acc[ai][bj][m][n], 0, 0, 0); __builtin_amdgcn_s_setprio(0); } while (0)
; #define PG8_WAIT_L(n) asm volatile("s_waitcnt lgkmcnt(" #n ")" ::: "memory")
; #define PG8_BAR __builtin_amdgcn_s_barrier()
; #define PG8_SCHED __builtin_amdgcn_sched_barrier(0)
; template <class Epi, class Sched>
; __device__ __forceinline__ void gemm_phase(LAS unsigned char* lds, const Gemm g, const Sched& S, const Epi& E, const int tid) {
;     ...
;             const char* a1 = cA + (size_t)(t + 1) * kstep;
;             const char* a2 = last ? nA : cA + (size_t)(t + 2) * kstep; const char* b2 = last ? nB : cB + (size_t)(t + 2) * kstep;
;             const char* a3 = a2 + kstep; const char* b3 = b2 + kstep;
;             if (last && has_next) S.a_ready(nxt);
;             if constexpr (Epi::PRELOAD) { if (last) E.preload(cur, lds, wid, lane); }
;             PG8_LDB(B0, 0, 0); PG8_SCHED; PG8_LDA(At, 0, 0); PG8_STAGE(PG8_SA(1, 1), a1 + hstep, voffA);
;             PG8_WAIT_L(8); PG8_BAR; PG8_WAIT_L(0); PG8_MMA(0, 0, At, B0); PG8_BAR; PG8_SCHED;
;             PG8_LDB(B1, 0, 1); PG8_STAGE(PG8_SB(0, 0), b2, voffB);
;             PG8_BAR; PG8_WAIT_L(0); PG8_MMA(0, 1, At, B1); PG8_BAR;
;             PG8_LDA(At, 0, 1); PG8_STAGE(PG8_SA(0, 0), a2, voffA);
;             PG8_BAR; PG8_WAIT_L(0); PG8_MMA(1, 0, At, B0); PG8_BAR; PG8_SCHED;
;             PG8_STAGE(PG8_SB(0, 1), b2 + hstep, voffB);
.LBB0_1393:
	s_add_u32 s50, s48, 0x100
	s_addc_u32 s51, s49, 0
	s_and_b64 s[24:25], s[52:53], exec
	s_cselect_b32 s55, s45, s51
	s_cselect_b32 s54, s44, s50
	s_cselect_b32 s53, s3, s23
	s_cselect_b32 s52, s2, s5
	s_add_i32 s24, 0, 0x10000
	v_add_u32_e32 v144, s24, v209
	ds_read_b128 v[132:135], v144
	ds_read_b128 v[136:139], v144 offset:1024
	ds_read_b128 v[140:143], v144 offset:2048
	ds_read_b128 v[144:147], v144 offset:3072
	v_lshl_add_u64 v[176:177], s[48:49], 0, v[186:187]
	s_add_i32 m0, s7, 0xc000
	ds_read_b128 v[148:151], v216
	ds_read_b128 v[152:155], v216 offset:1024
	ds_read_b128 v[156:159], v216 offset:2048
	ds_read_b128 v[160:163], v216 offset:3072
	ds_read_b128 v[164:167], v216 offset:4096
	ds_read_b128 v[168:171], v216 offset:5120
	ds_read_b128 v[172:175], v216 offset:6144
	ds_read_b128 v[190:193], v216 offset:7168
	global_load_lds_dwordx4 v[176:177], off
	s_add_i32 m0, s7, 0xe000
	v_lshl_add_u64 v[176:177], s[48:49], 0, v[188:189]
	global_load_lds_dwordx4 v[176:177], off
	s_waitcnt lgkmcnt(8)
	s_barrier
	s_waitcnt lgkmcnt(0)
	v_mfma_f32_16x16x32_bf16 v[126:129], v[132:135], v[148:151], v[126:129]
	v_mfma_f32_16x16x32_bf16 v[122:125], v[140:143], v[148:151], v[122:125]
	v_mfma_f32_16x16x32_bf16 v[118:121], v[132:135], v[156:159], v[118:121]
	v_mfma_f32_16x16x32_bf16 v[114:117], v[140:143], v[156:159], v[114:117]
	v_mfma_f32_16x16x32_bf16 v[102:105], v[132:135], v[164:167], v[102:105]
	v_mfma_f32_16x16x32_bf16 v[98:101], v[140:143], v[164:167], v[98:101]
	v_mfma_f32_16x16x32_bf16 v[86:89], v[132:135], v[172:175], v[86:89]
	v_mfma_f32_16x16x32_bf16 v[82:85], v[140:143], v[172:175], v[82:85]
	v_mfma_f32_16x16x32_bf16 v[126:129], v[136:139], v[152:155], v[126:129]
	v_mfma_f32_16x16x32_bf16 v[122:125], v[144:147], v[152:155], v[122:125]
	v_mfma_f32_16x16x32_bf16 v[118:121], v[136:139], v[160:163], v[118:121]
	v_mfma_f32_16x16x32_bf16 v[114:117], v[144:147], v[160:163], v[114:117]
	v_mfma_f32_16x16x32_bf16 v[102:105], v[136:139], v[168:171], v[102:105]
	v_mfma_f32_16x16x32_bf16 v[98:101], v[144:147], v[168:171], v[98:101]
	v_mfma_f32_16x16x32_bf16 v[86:89], v[136:139], v[190:193], v[86:89]
	v_mfma_f32_16x16x32_bf16 v[82:85], v[144:147], v[190:193], v[82:85]
	s_barrier
	s_add_i32 s28, 0, 0x14000
	v_add_u32_e32 v176, s28, v209
	s_add_i32 s24, s24, s66
	ds_read_b128 v[194:197], v176
	ds_read_b128 v[198:201], v176 offset:1024
	ds_read_b128 v[202:205], v176 offset:2048
	ds_read_b128 v[218:221], v176 offset:3072
	s_mov_b32 m0, s24
	v_lshl_add_u64 v[206:207], s[52:53], 0, v[182:183]
	global_load_lds_dwordx4 v0, s[52:53]
	s_add_i32 m0, s24, 0x2000
	s_nop 0
	global_load_lds_dwordx4 v[206:207], off
	s_barrier
	s_waitcnt lgkmcnt(0)
	v_mfma_f32_16x16x32_bf16 v[110:113], v[194:197], v[148:151], v[110:113]
	v_mfma_f32_16x16x32_bf16 v[106:109], v[202:205], v[148:151], v[106:109]
	v_mfma_f32_16x16x32_bf16 v[94:97], v[194:197], v[156:159], v[94:97]
	v_mfma_f32_16x16x32_bf16 v[90:93], v[202:205], v[156:159], v[90:93]
	v_mfma_f32_16x16x32_bf16 v[78:81], v[194:197], v[164:167], v[78:81]
	v_mfma_f32_16x16x32_bf16 v[74:77], v[202:205], v[164:167], v[74:77]
	v_mfma_f32_16x16x32_bf16 v[70:73], v[194:197], v[172:175], v[70:73]
	v_mfma_f32_16x16x32_bf16 v[66:69], v[202:205], v[172:175], v[66:69]
	v_mfma_f32_16x16x32_bf16 v[110:113], v[198:201], v[152:155], v[110:113]
	v_mfma_f32_16x16x32_bf16 v[106:109], v[218:221], v[152:155], v[106:109]
	v_mfma_f32_16x16x32_bf16 v[94:97], v[198:201], v[160:163], v[94:97]
	v_mfma_f32_16x16x32_bf16 v[90:93], v[218:221], v[160:163], v[90:93]
	v_mfma_f32_16x16x32_bf16 v[78:81], v[198:201], v[168:171], v[78:81]
	v_mfma_f32_16x16x32_bf16 v[74:77], v[218:221], v[168:171], v[74:77]
	v_mfma_f32_16x16x32_bf16 v[70:73], v[198:201], v[190:193], v[70:73]
	v_mfma_f32_16x16x32_bf16 v[66:69], v[218:221], v[190:193], v[66:69]
	s_mov_b32 m0, s7
	s_barrier
	ds_read_b128 v[148:151], v216 offset:16384
	ds_read_b128 v[152:155], v216 offset:17408
	ds_read_b128 v[156:159], v216 offset:18432
	ds_read_b128 v[160:163], v216 offset:19456
	ds_read_b128 v[164:167], v216 offset:20480
	ds_read_b128 v[168:171], v216 offset:21504
	ds_read_b128 v[172:175], v216 offset:22528
	ds_read_b128 v[190:193], v216 offset:23552
	global_load_lds_dwordx4 v178, s[54:55]
	s_mov_b32 m0, s11
	s_nop 0
	global_load_lds_dwordx4 v180, s[54:55]
	s_barrier
	s_waitcnt lgkmcnt(0)
	v_mfma_f32_16x16x32_bf16 v[62:65], v[132:135], v[148:151], v[62:65]
	v_mfma_f32_16x16x32_bf16 v[58:61], v[140:143], v[148:151], v[58:61]
	v_mfma_f32_16x16x32_bf16 v[54:57], v[132:135], v[156:159], v[54:57]
	v_mfma_f32_16x16x32_bf16 v[50:53], v[140:143], v[156:159], v[50:53]
	v_mfma_f32_16x16x32_bf16 v[38:41], v[132:135], v[164:167], v[38:41]
	v_mfma_f32_16x16x32_bf16 v[34:37], v[140:143], v[164:167], v[34:37]
	v_mfma_f32_16x16x32_bf16 v[22:25], v[132:135], v[172:175], v[22:25]
	v_mfma_f32_16x16x32_bf16 v[18:21], v[140:143], v[172:175], v[18:21]
	v_mfma_f32_16x16x32_bf16 v[62:65], v[136:139], v[152:155], v[62:65]
	v_mfma_f32_16x16x32_bf16 v[58:61], v[144:147], v[152:155], v[58:61]
	v_mfma_f32_16x16x32_bf16 v[54:57], v[136:139], v[160:163], v[54:57]
	v_mfma_f32_16x16x32_bf16 v[50:53], v[144:147], v[160:163], v[50:53]
	v_mfma_f32_16x16x32_bf16 v[38:41], v[136:139], v[168:171], v[38:41]
	v_mfma_f32_16x16x32_bf16 v[34:37], v[144:147], v[168:171], v[34:37]
	v_mfma_f32_16x16x32_bf16 v[22:25], v[136:139], v[190:193], v[22:25]
	v_mfma_f32_16x16x32_bf16 v[18:21], v[144:147], v[190:193], v[18:21]
	s_barrier
	s_add_u32 s24, s52, 0x80000
	s_addc_u32 s25, s53, 0
	s_add_i32 s28, s28, s66
	s_mov_b32 m0, s28
	s_nop 0
	global_load_lds_dwordx4 v0, s[24:25]
	s_add_i32 m0, s28, 0x2000
	s_nop 0
	global_load_lds_dwordx4 v182, s[24:25]
	s_waitcnt vmcnt(6)
	s_barrier
; #define PG8_STAGE(bufoff, gbase, voff) do { _Pragma("unroll") for (int _i = 0; _i < 2; ++_i) \
;         __builtin_amdgcn_global_load_lds((const unsigned*)((const char*)(gbase) + (voff)[_i]), (LAS unsigned*)(lds + (bufoff) + ldsw + _i * 8192), 16, 0, 0); } while (0)
; #define PG8_LDA(dst, b, h) do { _Pragma("unroll") for (int m = 0; m < 4; ++m) _Pragma("unroll") for (int k = 0; k < 2; ++k) dst[m][k] = *(const LAS bf16x8*)(lds + PG8_SA(b, h) + aoff + m * 2048 + k * 1024); } while (0)
; #define PG8_LDB(dst, b, h) do { _Pragma("unroll") for (int n = 0; n < 2; ++n) _Pragma("unroll") for (int k = 0; k < 2; ++k) dst[n][k] = *(const LAS bf16x8*)(lds + PG8_SB(b, h) + boff + n * 2048 + k * 1024); } while (0)
; #define PG8_MMA(ai, bj, At, Bt) do { __builtin_amdgcn_s_setprio(1); _Pragma("unroll") for (int m = 0; m < 4; ++m) _Pragma("unroll") for (int n = 0; n < 2; ++n) _Pragma("unroll") for (int k = 0; k < 2; ++k) \
;         acc[ai][bj][m][n] = __builtin_amdgcn_mfma_f32_16x16x32_bf16(Bt[n][k], At[m][k], acc[ai][bj][m][n], 0, 0, 0); __builtin_amdgcn_s_setprio(0); } while (0)
; #define PG8_WAIT_V(n) asm volatile("s_waitcnt vmcnt(" #n ")" ::: "memory")
; #define PG8_WAIT_L(n) asm volatile("s_waitcnt lgkmcnt(" #n ")" ::: "memory")
; #define PG8_BAR __builtin_amdgcn_s_barrier()
; #define PG8_SCHED __builtin_amdgcn_sched_barrier(0)
; template <class Epi, class Sched>
; __device__ __forceinline__ void gemm_phase(LAS unsigned char* lds, const Gemm g, const Sched& S, const Epi& E, const int tid) {
;     ...
;             PG8_WAIT_V(6); PG8_BAR; PG8_MMA(1, 1, At, B1); PG8_BAR;
;             PG8_LDB(B0, 1, 0); PG8_SCHED; PG8_LDA(At, 1, 0); PG8_STAGE(PG8_SA(0, 1), a2 + hstep, voffA);
;             PG8_WAIT_L(8); PG8_BAR; PG8_WAIT_L(0); PG8_MMA(0, 0, At, B0); PG8_BAR; PG8_SCHED;
;             PG8_LDB(B1, 1, 1); PG8_STAGE(PG8_SB(1, 0), b3, voffB);
;             PG8_BAR; PG8_WAIT_L(0); PG8_MMA(0, 1, At, B1); PG8_BAR;
;             PG8_LDA(At, 1, 1); PG8_STAGE(PG8_SA(1, 0), a3, voffA);
	v_mfma_f32_16x16x32_bf16 v[46:49], v[194:197], v[148:151], v[46:49]
	v_mfma_f32_16x16x32_bf16 v[42:45], v[202:205], v[148:151], v[42:45]
	v_mfma_f32_16x16x32_bf16 v[30:33], v[194:197], v[156:159], v[30:33]
	v_mfma_f32_16x16x32_bf16 v[26:29], v[202:205], v[156:159], v[26:29]
	v_mfma_f32_16x16x32_bf16 v[14:17], v[194:197], v[164:167], v[14:17]
	v_mfma_f32_16x16x32_bf16 v[10:13], v[202:205], v[164:167], v[10:13]
	v_mfma_f32_16x16x32_bf16 v[6:9], v[194:197], v[172:175], v[6:9]
	v_mfma_f32_16x16x32_bf16 v[2:5], v[202:205], v[172:175], v[2:5]
	v_mfma_f32_16x16x32_bf16 v[46:49], v[198:201], v[152:155], v[46:49]
	v_mfma_f32_16x16x32_bf16 v[42:45], v[218:221], v[152:155], v[42:45]
	v_mfma_f32_16x16x32_bf16 v[30:33], v[198:201], v[160:163], v[30:33]
	v_mfma_f32_16x16x32_bf16 v[26:29], v[218:221], v[160:163], v[26:29]
	v_mfma_f32_16x16x32_bf16 v[14:17], v[198:201], v[168:171], v[14:17]
	v_mfma_f32_16x16x32_bf16 v[10:13], v[218:221], v[168:171], v[10:13]
	v_mfma_f32_16x16x32_bf16 v[6:9], v[198:201], v[190:193], v[6:9]
	v_mfma_f32_16x16x32_bf16 v[2:5], v[218:221], v[190:193], v[2:5]
	s_add_i32 s28, 0, 0x18000
	v_add_u32_e32 v144, s28, v209
	s_barrier
	ds_read_b128 v[132:135], v144
	ds_read_b128 v[136:139], v144 offset:1024
	ds_read_b128 v[140:143], v144 offset:2048
	ds_read_b128 v[144:147], v144 offset:3072
	s_add_u32 s24, s54, 0x80000
	s_addc_u32 s25, s55, 0
	s_mov_b32 m0, s67
	ds_read_b128 v[148:151], v216 offset:32768
	ds_read_b128 v[152:155], v216 offset:33792
	ds_read_b128 v[156:159], v216 offset:34816
	ds_read_b128 v[160:163], v216 offset:35840
	ds_read_b128 v[164:167], v216 offset:36864
	ds_read_b128 v[168:171], v216 offset:37888
	ds_read_b128 v[172:175], v216 offset:38912
	global_load_lds_dwordx4 v178, s[24:25]
	s_mov_b32 m0, s68
	ds_read_b128 v[190:193], v216 offset:39936
	global_load_lds_dwordx4 v180, s[24:25]
	s_waitcnt lgkmcnt(8)
	s_barrier
	s_waitcnt lgkmcnt(0)
	v_mfma_f32_16x16x32_bf16 v[126:129], v[132:135], v[148:151], v[126:129]
	v_mfma_f32_16x16x32_bf16 v[122:125], v[140:143], v[148:151], v[122:125]
	v_mfma_f32_16x16x32_bf16 v[118:121], v[132:135], v[156:159], v[118:121]
	v_mfma_f32_16x16x32_bf16 v[114:117], v[140:143], v[156:159], v[114:117]
	v_mfma_f32_16x16x32_bf16 v[102:105], v[132:135], v[164:167], v[102:105]
	v_mfma_f32_16x16x32_bf16 v[98:101], v[140:143], v[164:167], v[98:101]
	v_mfma_f32_16x16x32_bf16 v[86:89], v[132:135], v[172:175], v[86:89]
	v_mfma_f32_16x16x32_bf16 v[82:85], v[140:143], v[172:175], v[82:85]
	v_mfma_f32_16x16x32_bf16 v[126:129], v[136:139], v[152:155], v[126:129]
	v_mfma_f32_16x16x32_bf16 v[122:125], v[144:147], v[152:155], v[122:125]
	v_mfma_f32_16x16x32_bf16 v[118:121], v[136:139], v[160:163], v[118:121]
	v_mfma_f32_16x16x32_bf16 v[114:117], v[144:147], v[160:163], v[114:117]
	v_mfma_f32_16x16x32_bf16 v[102:105], v[136:139], v[168:171], v[102:105]
	v_mfma_f32_16x16x32_bf16 v[98:101], v[144:147], v[168:171], v[98:101]
	v_mfma_f32_16x16x32_bf16 v[86:89], v[136:139], v[190:193], v[86:89]
	v_mfma_f32_16x16x32_bf16 v[82:85], v[144:147], v[190:193], v[82:85]
	s_barrier
	s_add_i32 s29, 0, 0x1c000
	s_add_i32 s24, s28, s66
	v_add_u32_e32 v217, s29, v209
	s_add_u32 s98, s52, s36
	s_addc_u32 s99, s53, s37
	s_mov_b32 m0, s24
	ds_read_b128 v[194:197], v217
	ds_read_b128 v[198:201], v217 offset:1024
	ds_read_b128 v[202:205], v217 offset:2048
	ds_read_b128 v[218:221], v217 offset:3072
	global_load_lds_dwordx4 v0, s[98:99]
	s_add_i32 m0, s24, 0x2000
	s_add_u32 s98, s52, s36
	s_addc_u32 s99, s53, s37
	global_load_lds_dwordx4 v182, s[98:99]
	s_barrier
; #define PG8_STAGE(bufoff, gbase, voff) do { _Pragma("unroll") for (int _i = 0; _i < 2; ++_i) \
;         __builtin_amdgcn_global_load_lds((const unsigned*)((const char*)(gbase) + (voff)[_i]), (LAS unsigned*)(lds + (bufoff) + ldsw + _i * 8192), 16, 0, 0); } while (0)
; #define PG8_LDA(dst, b, h) do { _Pragma("unroll") for (int m = 0; m < 4; ++m) _Pragma("unroll") for (int k = 0; k < 2; ++k) dst[m][k] = *(const LAS bf16x8*)(lds + PG8_SA(b, h) + aoff + m * 2048 + k * 1024); } while (0)
; #define PG8_MMA(ai, bj, At, Bt) do { __builtin_amdgcn_s_setprio(1); _Pragma("unroll") for (int m = 0; m < 4; ++m) _Pragma("unroll") for (int n = 0; n < 2; ++n) _Pragma("unroll") for (int k = 0; k < 2; ++k) \
;         acc[ai][bj][m][n] = __builtin_amdgcn_mfma_f32_16x16x32_bf16(Bt[n][k], At[m][k], acc[ai][bj][m][n], 0, 0, 0); __builtin_amdgcn_s_setprio(0); } while (0)
; #define PG8_WAIT_V(n) asm volatile("s_waitcnt vmcnt(" #n ")" ::: "memory")
; #define PG8_WAIT_L(n) asm volatile("s_waitcnt lgkmcnt(" #n ")" ::: "memory")
; #define PG8_BAR __builtin_amdgcn_s_barrier()
; #define PG8_SCHED __builtin_amdgcn_sched_barrier(0)
; template <class Epi, class Sched>
; __device__ __forceinline__ void gemm_phase(LAS unsigned char* lds, const Gemm g, const Sched& S, const Epi& E, const int tid) {
;     ...
;             PG8_BAR; PG8_WAIT_L(0); PG8_MMA(0, 1, At, B1); PG8_BAR;
;             PG8_LDA(At, 1, 1); PG8_STAGE(PG8_SA(1, 0), a3, voffA);
;             PG8_BAR; PG8_WAIT_L(0); PG8_MMA(1, 0, At, B0); PG8_BAR; PG8_SCHED;
;             PG8_STAGE(PG8_SB(1, 1), b3 + hstep, voffB);
;             PG8_WAIT_V(6); PG8_BAR; PG8_MMA(1, 1, At, B1); PG8_BAR;
;         }
	s_waitcnt lgkmcnt(0)
	v_mfma_f32_16x16x32_bf16 v[110:113], v[194:197], v[148:151], v[110:113]
	v_mfma_f32_16x16x32_bf16 v[106:109], v[202:205], v[148:151], v[106:109]
	v_mfma_f32_16x16x32_bf16 v[94:97], v[194:197], v[156:159], v[94:97]
	v_mfma_f32_16x16x32_bf16 v[90:93], v[202:205], v[156:159], v[90:93]
	v_mfma_f32_16x16x32_bf16 v[78:81], v[194:197], v[164:167], v[78:81]
	v_mfma_f32_16x16x32_bf16 v[74:77], v[202:205], v[164:167], v[74:77]
	v_mfma_f32_16x16x32_bf16 v[70:73], v[194:197], v[172:175], v[70:73]
	v_mfma_f32_16x16x32_bf16 v[66:69], v[202:205], v[172:175], v[66:69]
	v_mfma_f32_16x16x32_bf16 v[110:113], v[198:201], v[152:155], v[110:113]
	v_mfma_f32_16x16x32_bf16 v[106:109], v[218:221], v[152:155], v[106:109]
	v_mfma_f32_16x16x32_bf16 v[94:97], v[198:201], v[160:163], v[94:97]
	v_mfma_f32_16x16x32_bf16 v[90:93], v[218:221], v[160:163], v[90:93]
	v_mfma_f32_16x16x32_bf16 v[78:81], v[198:201], v[168:171], v[78:81]
	v_mfma_f32_16x16x32_bf16 v[74:77], v[218:221], v[168:171], v[74:77]
	v_mfma_f32_16x16x32_bf16 v[70:73], v[198:201], v[190:193], v[70:73]
	v_mfma_f32_16x16x32_bf16 v[66:69], v[218:221], v[190:193], v[66:69]
	s_mov_b32 m0, s72
	s_add_u32 s98, s54, s36
	s_addc_u32 s99, s55, s37
	s_barrier
	ds_read_b128 v[148:151], v216 offset:49152
	ds_read_b128 v[152:155], v216 offset:50176
	ds_read_b128 v[156:159], v216 offset:51200
	ds_read_b128 v[160:163], v216 offset:52224
	ds_read_b128 v[164:167], v216 offset:53248
	ds_read_b128 v[168:171], v216 offset:54272
	ds_read_b128 v[172:175], v216 offset:55296
	ds_read_b128 v[190:193], v216 offset:56320
	global_load_lds_dwordx4 v178, s[98:99]
	s_mov_b32 m0, s73
	s_add_u32 s98, s54, s36
	s_addc_u32 s99, s55, s37
	global_load_lds_dwordx4 v180, s[98:99]
	s_barrier
	s_waitcnt lgkmcnt(0)
	v_mfma_f32_16x16x32_bf16 v[62:65], v[132:135], v[148:151], v[62:65]
	v_mfma_f32_16x16x32_bf16 v[58:61], v[140:143], v[148:151], v[58:61]
	v_mfma_f32_16x16x32_bf16 v[54:57], v[132:135], v[156:159], v[54:57]
	v_mfma_f32_16x16x32_bf16 v[50:53], v[140:143], v[156:159], v[50:53]
	v_mfma_f32_16x16x32_bf16 v[38:41], v[132:135], v[164:167], v[38:41]
	v_mfma_f32_16x16x32_bf16 v[34:37], v[140:143], v[164:167], v[34:37]
	v_mfma_f32_16x16x32_bf16 v[22:25], v[132:135], v[172:175], v[22:25]
	v_mfma_f32_16x16x32_bf16 v[18:21], v[140:143], v[172:175], v[18:21]
	v_mfma_f32_16x16x32_bf16 v[62:65], v[136:139], v[152:155], v[62:65]
	v_mfma_f32_16x16x32_bf16 v[58:61], v[144:147], v[152:155], v[58:61]
	v_mfma_f32_16x16x32_bf16 v[54:57], v[136:139], v[160:163], v[54:57]
	v_mfma_f32_16x16x32_bf16 v[50:53], v[144:147], v[160:163], v[50:53]
	v_mfma_f32_16x16x32_bf16 v[38:41], v[136:139], v[168:171], v[38:41]
	v_mfma_f32_16x16x32_bf16 v[34:37], v[144:147], v[168:171], v[34:37]
	v_mfma_f32_16x16x32_bf16 v[22:25], v[136:139], v[190:193], v[22:25]
	v_mfma_f32_16x16x32_bf16 v[18:21], v[144:147], v[190:193], v[18:21]
	s_barrier
	s_add_u32 s24, s52, 0x80080
	s_addc_u32 s25, s53, 0
	s_add_i32 s28, s29, s66
	s_mov_b32 m0, s28
	s_nop 0
	global_load_lds_dwordx4 v0, s[24:25]
	s_add_i32 m0, s28, 0x2000
	s_nop 0
	global_load_lds_dwordx4 v182, s[24:25]
	s_waitcnt vmcnt(6)
	s_barrier
	v_mfma_f32_16x16x32_bf16 v[46:49], v[194:197], v[148:151], v[46:49]
	v_mfma_f32_16x16x32_bf16 v[42:45], v[202:205], v[148:151], v[42:45]
	v_mfma_f32_16x16x32_bf16 v[30:33], v[194:197], v[156:159], v[30:33]
	v_mfma_f32_16x16x32_bf16 v[26:29], v[202:205], v[156:159], v[26:29]
	v_mfma_f32_16x16x32_bf16 v[14:17], v[194:197], v[164:167], v[14:17]
	v_mfma_f32_16x16x32_bf16 v[10:13], v[202:205], v[164:167], v[10:13]
	v_mfma_f32_16x16x32_bf16 v[6:9], v[194:197], v[172:175], v[6:9]
	v_mfma_f32_16x16x32_bf16 v[2:5], v[202:205], v[172:175], v[2:5]
	v_mfma_f32_16x16x32_bf16 v[46:49], v[198:201], v[152:155], v[46:49]
	v_mfma_f32_16x16x32_bf16 v[42:45], v[218:221], v[152:155], v[42:45]
	v_mfma_f32_16x16x32_bf16 v[30:33], v[198:201], v[160:163], v[30:33]
	v_mfma_f32_16x16x32_bf16 v[26:29], v[218:221], v[160:163], v[26:29]
	v_mfma_f32_16x16x32_bf16 v[14:17], v[198:201], v[168:171], v[14:17]
	v_mfma_f32_16x16x32_bf16 v[10:13], v[218:221], v[168:171], v[10:13]
	v_mfma_f32_16x16x32_bf16 v[6:9], v[198:201], v[190:193], v[6:9]
	v_mfma_f32_16x16x32_bf16 v[2:5], v[218:221], v[190:193], v[2:5]
	s_add_i32 s24, s21, 2
	s_add_u32 s5, s5, 0x100
	s_addc_u32 s23, s23, 0
	s_cmp_ge_i32 s21, s78
	s_mov_b64 s[48:49], s[50:51]
	s_mov_b32 s21, s24
	s_barrier
	s_cbranch_scc1 .LBB0_1396

; #define PG8_STAGE(bufoff, gbase, voff) do { _Pragma("unroll") for (int _i = 0; _i < 2; ++_i) \
;         __builtin_amdgcn_global_load_lds((const unsigned*)((const char*)(gbase) + (voff)[_i]), (LAS unsigned*)(lds + (bufoff) + ldsw + _i * 8192), 16, 0, 0); } while (0)
; #define PG8_LDA(dst, b, h) do { _Pragma("unroll") for (int m = 0; m < 4; ++m) _Pragma("unroll") for (int k = 0; k < 2; ++k) dst[m][k] = *(const LAS bf16x8*)(lds + PG8_SA(b, h) + aoff + m * 2048 + k * 1024); } while (0)
; #define PG8_LDB(dst, b, h) do { _Pragma("unroll") for (int n = 0; n < 2; ++n) _Pragma("unroll") for (int k = 0; k < 2; ++k) dst[n][k] = *(const LAS bf16x8*)(lds + PG8_SB(b, h) + boff + n * 2048 + k * 1024); } while (0)
; #define PG8_MMA(ai, bj, At, Bt) do { __builtin_amdgcn_s_setprio(1); _Pragma("unroll") for (int m = 0; m < 4; ++m) _Pragma("unroll") for (int n = 0; n < 2; ++n) _Pragma("unroll") for (int k = 0; k < 2; ++k) \
;         acc[ai][bj][m][n] = __builtin_amdgcn_mfma_f32_16x16x32_bf16(Bt[n][k], At[m][k], acc[ai][bj][m][n], 0, 0, 0); __builtin_amdgcn_s_setprio(0); } while (0)
; #define PG8_WAIT_L(n) asm volatile("s_waitcnt lgkmcnt(" #n ")" ::: "memory")
; #define PG8_BAR __builtin_amdgcn_s_barrier()
; template <class Epi, class Sched>
; __device__ __forceinline__ void gemm_phase(LAS unsigned char* lds, const Gemm g, const Sched& S, const Epi& E, const int tid) {
;     ...
;             const bool last = (t == nt - 2);
;             const char* a1 = cA + (size_t)(t + 1) * kstep;
;             const char* a2 = last ? nA : cA + (size_t)(t + 2) * kstep; const char* b2 = last ? nB : cB + (size_t)(t + 2) * kstep;
;             const char* a3 = a2 + kstep; const char* b3 = b2 + kstep;
;             if (last && has_next) S.a_ready(nxt);
;             if constexpr (Epi::PRELOAD) { if (last) E.preload(cur, lds, wid, lane); }
;             PG8_LDB(B0, 0, 0); PG8_SCHED; PG8_LDA(At, 0, 0); PG8_STAGE(PG8_SA(1, 1), a1 + hstep, voffA);
;             PG8_WAIT_L(8); PG8_BAR; PG8_WAIT_L(0); PG8_MMA(0, 0, At, B0); PG8_BAR; PG8_SCHED;
;             PG8_LDB(B1, 0, 1); PG8_STAGE(PG8_SB(0, 0), b2, voffB);
;             PG8_BAR; PG8_WAIT_L(0); PG8_MMA(0, 1, At, B1); PG8_BAR;
;             PG8_LDA(At, 0, 1); PG8_STAGE(PG8_SA(0, 0), a2, voffA);
;             PG8_BAR; PG8_WAIT_L(0); PG8_MMA(1, 0, At, B0); PG8_BAR; PG8_SCHED;
;             PG8_STAGE(PG8_SB(0, 1), b2 + hstep, voffB);
.LBB0_1573:
	s_add_u32 s40, s38, 0xe1edc080
	s_addc_u32 s41, s39, -1
	s_cmpk_lg_i32 s65, 0x54
	s_cselect_b32 s40, s40, 0
	s_cselect_b32 s41, s41, 0
	s_add_u32 s42, s4, s40
	s_addc_u32 s43, s5, s41
	s_add_i32 s66, 0, 0x10000
	v_add_u32_e32 v154, s66, v140
	ds_read_b128 v[142:145], v154
	ds_read_b128 v[146:149], v154 offset:1024
	ds_read_b128 v[150:153], v154 offset:2048
	ds_read_b128 v[154:157], v154 offset:3072
	s_add_u32 s40, s0, s40
	s_addc_u32 s41, s1, s41
	v_lshl_add_u64 v[190:191], v[136:137], 0, s[38:39]
	s_add_i32 m0, s25, 0xc000
	ds_read_b128 v[158:161], v141
	ds_read_b128 v[162:165], v141 offset:1024
	ds_read_b128 v[166:169], v141 offset:2048
	ds_read_b128 v[170:173], v141 offset:3072
	ds_read_b128 v[174:177], v141 offset:4096
	ds_read_b128 v[178:181], v141 offset:5120
	ds_read_b128 v[182:185], v141 offset:6144
	ds_read_b128 v[186:189], v141 offset:7168
	global_load_lds_dwordx4 v[190:191], off
	s_add_i32 m0, s25, 0xe000
	v_lshl_add_u64 v[190:191], v[138:139], 0, s[38:39]
	global_load_lds_dwordx4 v[190:191], off
	s_waitcnt lgkmcnt(8)
	s_barrier
	s_waitcnt lgkmcnt(0)
	v_mfma_f32_16x16x32_bf16 v[126:129], v[142:145], v[158:161], v[126:129]
	v_mfma_f32_16x16x32_bf16 v[122:125], v[150:153], v[158:161], v[122:125]
	v_mfma_f32_16x16x32_bf16 v[118:121], v[142:145], v[166:169], v[118:121]
	v_mfma_f32_16x16x32_bf16 v[110:113], v[150:153], v[166:169], v[110:113]
	v_mfma_f32_16x16x32_bf16 v[98:101], v[142:145], v[174:177], v[98:101]
	v_mfma_f32_16x16x32_bf16 v[90:93], v[150:153], v[174:177], v[90:93]
	v_mfma_f32_16x16x32_bf16 v[82:85], v[142:145], v[182:185], v[82:85]
	v_mfma_f32_16x16x32_bf16 v[74:77], v[150:153], v[182:185], v[74:77]
	v_mfma_f32_16x16x32_bf16 v[126:129], v[146:149], v[162:165], v[126:129]
	v_mfma_f32_16x16x32_bf16 v[122:125], v[154:157], v[162:165], v[122:125]
	v_mfma_f32_16x16x32_bf16 v[118:121], v[146:149], v[170:173], v[118:121]
	v_mfma_f32_16x16x32_bf16 v[110:113], v[154:157], v[170:173], v[110:113]
	v_mfma_f32_16x16x32_bf16 v[98:101], v[146:149], v[178:181], v[98:101]
	v_mfma_f32_16x16x32_bf16 v[90:93], v[154:157], v[178:181], v[90:93]
	v_mfma_f32_16x16x32_bf16 v[82:85], v[146:149], v[186:189], v[82:85]
	v_mfma_f32_16x16x32_bf16 v[74:77], v[154:157], v[186:189], v[74:77]
	s_barrier
	s_add_i32 s68, 0, 0x14000
	s_add_i32 s66, s66, s24
	v_add_u32_e32 v202, s68, v140
	s_mov_b32 m0, s66
	ds_read_b128 v[190:193], v202
	ds_read_b128 v[194:197], v202 offset:1024
	ds_read_b128 v[198:201], v202 offset:2048
	ds_read_b128 v[202:205], v202 offset:3072
	global_load_lds_dwordx4 v0, s[40:41]
	s_add_i32 m0, s66, 0x2000
	s_nop 0
	global_load_lds_dwordx4 v134, s[40:41]
	s_barrier
	s_waitcnt lgkmcnt(0)
	v_mfma_f32_16x16x32_bf16 v[114:117], v[190:193], v[158:161], v[114:117]
	v_mfma_f32_16x16x32_bf16 v[106:109], v[198:201], v[158:161], v[106:109]
	v_mfma_f32_16x16x32_bf16 v[102:105], v[190:193], v[166:169], v[102:105]
	v_mfma_f32_16x16x32_bf16 v[94:97], v[198:201], v[166:169], v[94:97]
	v_mfma_f32_16x16x32_bf16 v[86:89], v[190:193], v[174:177], v[86:89]
	v_mfma_f32_16x16x32_bf16 v[78:81], v[198:201], v[174:177], v[78:81]
	v_mfma_f32_16x16x32_bf16 v[70:73], v[190:193], v[182:185], v[70:73]
	v_mfma_f32_16x16x32_bf16 v[66:69], v[198:201], v[182:185], v[66:69]
	v_mfma_f32_16x16x32_bf16 v[114:117], v[194:197], v[162:165], v[114:117]
	v_mfma_f32_16x16x32_bf16 v[106:109], v[202:205], v[162:165], v[106:109]
	v_mfma_f32_16x16x32_bf16 v[102:105], v[194:197], v[170:173], v[102:105]
	v_mfma_f32_16x16x32_bf16 v[94:97], v[202:205], v[170:173], v[94:97]
	v_mfma_f32_16x16x32_bf16 v[86:89], v[194:197], v[178:181], v[86:89]
	v_mfma_f32_16x16x32_bf16 v[78:81], v[202:205], v[178:181], v[78:81]
	v_mfma_f32_16x16x32_bf16 v[70:73], v[194:197], v[186:189], v[70:73]
	v_mfma_f32_16x16x32_bf16 v[66:69], v[202:205], v[186:189], v[66:69]
	s_mov_b32 m0, s25
	v_lshl_add_u64 v[210:211], s[42:43], 0, v[130:131]
	s_barrier
	ds_read_b128 v[158:161], v141 offset:16384
	ds_read_b128 v[162:165], v141 offset:17408
	ds_read_b128 v[166:169], v141 offset:18432
	ds_read_b128 v[170:173], v141 offset:19456
	ds_read_b128 v[174:177], v141 offset:20480
	ds_read_b128 v[178:181], v141 offset:21504
	ds_read_b128 v[182:185], v141 offset:22528
	ds_read_b128 v[186:189], v141 offset:23552
	global_load_lds_dwordx4 v[210:211], off
	s_mov_b32 m0, s28
	v_lshl_add_u64 v[214:215], s[42:43], 0, v[132:133]
	global_load_lds_dwordx4 v[214:215], off
	s_barrier
	s_waitcnt lgkmcnt(0)
	v_mfma_f32_16x16x32_bf16 v[62:65], v[142:145], v[158:161], v[62:65]
	v_mfma_f32_16x16x32_bf16 v[58:61], v[150:153], v[158:161], v[58:61]
	v_mfma_f32_16x16x32_bf16 v[50:53], v[142:145], v[166:169], v[50:53]
	v_mfma_f32_16x16x32_bf16 v[42:45], v[150:153], v[166:169], v[42:45]
	v_mfma_f32_16x16x32_bf16 v[34:37], v[142:145], v[174:177], v[34:37]
	v_mfma_f32_16x16x32_bf16 v[26:29], v[150:153], v[174:177], v[26:29]
	v_mfma_f32_16x16x32_bf16 v[18:21], v[142:145], v[182:185], v[18:21]
	v_mfma_f32_16x16x32_bf16 v[10:13], v[150:153], v[182:185], v[10:13]
	v_mfma_f32_16x16x32_bf16 v[62:65], v[146:149], v[162:165], v[62:65]
	v_mfma_f32_16x16x32_bf16 v[58:61], v[154:157], v[162:165], v[58:61]
	v_mfma_f32_16x16x32_bf16 v[50:53], v[146:149], v[170:173], v[50:53]
	v_mfma_f32_16x16x32_bf16 v[42:45], v[154:157], v[170:173], v[42:45]
	v_mfma_f32_16x16x32_bf16 v[34:37], v[146:149], v[178:181], v[34:37]
	v_mfma_f32_16x16x32_bf16 v[26:29], v[154:157], v[178:181], v[26:29]
	v_mfma_f32_16x16x32_bf16 v[18:21], v[146:149], v[186:189], v[18:21]
	v_mfma_f32_16x16x32_bf16 v[10:13], v[154:157], v[186:189], v[10:13]
	s_barrier
; #define PG8_STAGE(bufoff, gbase, voff) do { _Pragma("unroll") for (int _i = 0; _i < 2; ++_i) \
;         __builtin_amdgcn_global_load_lds((const unsigned*)((const char*)(gbase) + (voff)[_i]), (LAS unsigned*)(lds + (bufoff) + ldsw + _i * 8192), 16, 0, 0); } while (0)
; #define PG8_LDA(dst, b, h) do { _Pragma("unroll") for (int m = 0; m < 4; ++m) _Pragma("unroll") for (int k = 0; k < 2; ++k) dst[m][k] = *(const LAS bf16x8*)(lds + PG8_SA(b, h) + aoff + m * 2048 + k * 1024); } while (0)
; #define PG8_LDB(dst, b, h) do { _Pragma("unroll") for (int n = 0; n < 2; ++n) _Pragma("unroll") for (int k = 0; k < 2; ++k) dst[n][k] = *(const LAS bf16x8*)(lds + PG8_SB(b, h) + boff + n * 2048 + k * 1024); } while (0)
; #define PG8_MMA(ai, bj, At, Bt) do { __builtin_amdgcn_s_setprio(1); _Pragma("unroll") for (int m = 0; m < 4; ++m) _Pragma("unroll") for (int n = 0; n < 2; ++n) _Pragma("unroll") for (int k = 0; k < 2; ++k) \
;         acc[ai][bj][m][n] = __builtin_amdgcn_mfma_f32_16x16x32_bf16(Bt[n][k], At[m][k], acc[ai][bj][m][n], 0, 0, 0); __builtin_amdgcn_s_setprio(0); } while (0)
; #define PG8_WAIT_V(n) asm volatile("s_waitcnt vmcnt(" #n ")" ::: "memory")
; #define PG8_WAIT_L(n) asm volatile("s_waitcnt lgkmcnt(" #n ")" ::: "memory")
; #define PG8_BAR __builtin_amdgcn_s_barrier()
; #define PG8_SCHED __builtin_amdgcn_sched_barrier(0)
; template <class Epi, class Sched>
; __device__ __forceinline__ void gemm_phase(LAS unsigned char* lds, const Gemm g, const Sched& S, const Epi& E, const int tid) {
;     ...
;             PG8_STAGE(PG8_SB(0, 1), b2 + hstep, voffB);
;             PG8_WAIT_V(6); PG8_BAR; PG8_MMA(1, 1, At, B1); PG8_BAR;
;             PG8_LDB(B0, 1, 0); PG8_SCHED; PG8_LDA(At, 1, 0); PG8_STAGE(PG8_SA(0, 1), a2 + hstep, voffA);
;             PG8_WAIT_L(8); PG8_BAR; PG8_WAIT_L(0); PG8_MMA(0, 0, At, B0); PG8_BAR; PG8_SCHED;
;             PG8_LDB(B1, 1, 1); PG8_STAGE(PG8_SB(1, 0), b3, voffB);
;             PG8_BAR; PG8_WAIT_L(0); PG8_MMA(0, 1, At, B1); PG8_BAR;
;             PG8_LDA(At, 1, 1); PG8_STAGE(PG8_SA(1, 0), a3, voffA);
	s_add_u32 s66, s40, 0x160000
	s_addc_u32 s67, s41, 0
	s_add_i32 s68, s68, s24
	s_mov_b32 m0, s68
	s_nop 0
	global_load_lds_dwordx4 v0, s[66:67]
	s_add_i32 m0, s68, 0x2000
	s_nop 0
	global_load_lds_dwordx4 v134, s[66:67]
	s_waitcnt vmcnt(6)
	s_barrier
	v_mfma_f32_16x16x32_bf16 v[54:57], v[190:193], v[158:161], v[54:57]
	v_mfma_f32_16x16x32_bf16 v[46:49], v[198:201], v[158:161], v[46:49]
	v_mfma_f32_16x16x32_bf16 v[38:41], v[190:193], v[166:169], v[38:41]
	v_mfma_f32_16x16x32_bf16 v[30:33], v[198:201], v[166:169], v[30:33]
	v_mfma_f32_16x16x32_bf16 v[22:25], v[190:193], v[174:177], v[22:25]
	v_mfma_f32_16x16x32_bf16 v[14:17], v[198:201], v[174:177], v[14:17]
	v_mfma_f32_16x16x32_bf16 v[6:9], v[190:193], v[182:185], v[6:9]
	v_mfma_f32_16x16x32_bf16 v[2:5], v[198:201], v[182:185], v[2:5]
	v_mfma_f32_16x16x32_bf16 v[54:57], v[194:197], v[162:165], v[54:57]
	v_mfma_f32_16x16x32_bf16 v[46:49], v[202:205], v[162:165], v[46:49]
	v_mfma_f32_16x16x32_bf16 v[38:41], v[194:197], v[170:173], v[38:41]
	v_mfma_f32_16x16x32_bf16 v[30:33], v[202:205], v[170:173], v[30:33]
	v_mfma_f32_16x16x32_bf16 v[22:25], v[194:197], v[178:181], v[22:25]
	v_mfma_f32_16x16x32_bf16 v[14:17], v[202:205], v[178:181], v[14:17]
	v_mfma_f32_16x16x32_bf16 v[6:9], v[194:197], v[186:189], v[6:9]
	v_mfma_f32_16x16x32_bf16 v[2:5], v[202:205], v[186:189], v[2:5]
	s_add_i32 s66, 0, 0x18000
	v_add_u32_e32 v154, s66, v140
	s_barrier
	ds_read_b128 v[142:145], v154
	ds_read_b128 v[146:149], v154 offset:1024
	ds_read_b128 v[150:153], v154 offset:2048
	ds_read_b128 v[154:157], v154 offset:3072
	s_add_u32 s42, s42, 0x160000
	s_addc_u32 s43, s43, 0
	s_mov_b32 m0, s29
	ds_read_b128 v[158:161], v141 offset:32768
	ds_read_b128 v[162:165], v141 offset:33792
	ds_read_b128 v[166:169], v141 offset:34816
	ds_read_b128 v[170:173], v141 offset:35840
	ds_read_b128 v[174:177], v141 offset:36864
	ds_read_b128 v[178:181], v141 offset:37888
	ds_read_b128 v[182:185], v141 offset:38912
	global_load_lds_dwordx4 v130, s[42:43]
	s_mov_b32 m0, s62
	ds_read_b128 v[186:189], v141 offset:39936
	global_load_lds_dwordx4 v132, s[42:43]
	s_waitcnt lgkmcnt(8)
	s_barrier
	s_waitcnt lgkmcnt(0)
	v_mfma_f32_16x16x32_bf16 v[126:129], v[142:145], v[158:161], v[126:129]
	v_mfma_f32_16x16x32_bf16 v[122:125], v[150:153], v[158:161], v[122:125]
	v_mfma_f32_16x16x32_bf16 v[118:121], v[142:145], v[166:169], v[118:121]
	v_mfma_f32_16x16x32_bf16 v[110:113], v[150:153], v[166:169], v[110:113]
	v_mfma_f32_16x16x32_bf16 v[98:101], v[142:145], v[174:177], v[98:101]
	v_mfma_f32_16x16x32_bf16 v[90:93], v[150:153], v[174:177], v[90:93]
	v_mfma_f32_16x16x32_bf16 v[82:85], v[142:145], v[182:185], v[82:85]
	v_mfma_f32_16x16x32_bf16 v[74:77], v[150:153], v[182:185], v[74:77]
	v_mfma_f32_16x16x32_bf16 v[126:129], v[146:149], v[162:165], v[126:129]
	v_mfma_f32_16x16x32_bf16 v[122:125], v[154:157], v[162:165], v[122:125]
	v_mfma_f32_16x16x32_bf16 v[118:121], v[146:149], v[170:173], v[118:121]
	v_mfma_f32_16x16x32_bf16 v[110:113], v[154:157], v[170:173], v[110:113]
	v_mfma_f32_16x16x32_bf16 v[98:101], v[146:149], v[178:181], v[98:101]
	v_mfma_f32_16x16x32_bf16 v[90:93], v[154:157], v[178:181], v[90:93]
	v_mfma_f32_16x16x32_bf16 v[82:85], v[146:149], v[186:189], v[82:85]
	v_mfma_f32_16x16x32_bf16 v[74:77], v[154:157], v[186:189], v[74:77]
	s_barrier
	s_add_i32 s42, 0, 0x1c000
	s_add_i32 s43, s66, s24
	v_add_u32_e32 v202, s42, v140
	s_add_u32 s98, s40, s36
	s_addc_u32 s99, s41, s37
	s_mov_b32 m0, s43
	ds_read_b128 v[190:193], v202
	ds_read_b128 v[194:197], v202 offset:1024
	ds_read_b128 v[198:201], v202 offset:2048
	ds_read_b128 v[202:205], v202 offset:3072
	global_load_lds_dwordx4 v0, s[98:99]
	s_add_i32 m0, s43, 0x2000
	s_add_u32 s98, s40, s36
	s_addc_u32 s99, s41, s37
	global_load_lds_dwordx4 v134, s[98:99]
	s_barrier
; #define PG8_STAGE(bufoff, gbase, voff) do { _Pragma("unroll") for (int _i = 0; _i < 2; ++_i) \
;         __builtin_amdgcn_global_load_lds((const unsigned*)((const char*)(gbase) + (voff)[_i]), (LAS unsigned*)(lds + (bufoff) + ldsw + _i * 8192), 16, 0, 0); } while (0)
; #define PG8_LDA(dst, b, h) do { _Pragma("unroll") for (int m = 0; m < 4; ++m) _Pragma("unroll") for (int k = 0; k < 2; ++k) dst[m][k] = *(const LAS bf16x8*)(lds + PG8_SA(b, h) + aoff + m * 2048 + k * 1024); } while (0)
; #define PG8_MMA(ai, bj, At, Bt) do { __builtin_amdgcn_s_setprio(1); _Pragma("unroll") for (int m = 0; m < 4; ++m) _Pragma("unroll") for (int n = 0; n < 2; ++n) _Pragma("unroll") for (int k = 0; k < 2; ++k) \
;         acc[ai][bj][m][n] = __builtin_amdgcn_mfma_f32_16x16x32_bf16(Bt[n][k], At[m][k], acc[ai][bj][m][n], 0, 0, 0); __builtin_amdgcn_s_setprio(0); } while (0)
; #define PG8_WAIT_V(n) asm volatile("s_waitcnt vmcnt(" #n ")" ::: "memory")
; #define PG8_WAIT_L(n) asm volatile("s_waitcnt lgkmcnt(" #n ")" ::: "memory")
; #define PG8_BAR __builtin_amdgcn_s_barrier()
; #define PG8_SCHED __builtin_amdgcn_sched_barrier(0)
; template <class Epi, class Sched>
; __device__ __forceinline__ void gemm_phase(LAS unsigned char* lds, const Gemm g, const Sched& S, const Epi& E, const int tid) {
;     ...
;             PG8_LDA(At, 1, 1); PG8_STAGE(PG8_SA(1, 0), a3, voffA);
;             PG8_BAR; PG8_WAIT_L(0); PG8_MMA(1, 0, At, B0); PG8_BAR; PG8_SCHED;
;             PG8_STAGE(PG8_SB(1, 1), b3 + hstep, voffB);
;             PG8_WAIT_V(6); PG8_BAR; PG8_MMA(1, 1, At, B1); PG8_BAR;
;         }
;         if constexpr (!Epi::AFTER_DRAIN) { if constexpr (Epi::PRELOAD) E(acc, cur, wr, wc, fr, fq, lds); else E(acc, cur, wr, wc, fr, fq); S.done(cur); }
;         if (!has_next) break;
; #pragma unroll
;         for (int a = 0; a < 2; ++a)
; #pragma unroll
;             for (int b = 0; b < 2; ++b)
; #pragma unroll
;                 for (int m = 0; m < 4; ++m)
; #pragma unroll
;                     for (int n = 0; n < 2; ++n) acc[a][b][m][n] = (f32x4){0.f, 0.f, 0.f, 0.f};
;         cur = nxt; cA = nA; cB = nB; ++ui;
;     }
;     PG8_WAIT_V(0);
;     if (wr == 0) PG8_BAR;
	s_waitcnt lgkmcnt(0)
	v_mfma_f32_16x16x32_bf16 v[114:117], v[190:193], v[158:161], v[114:117]
	v_mfma_f32_16x16x32_bf16 v[106:109], v[198:201], v[158:161], v[106:109]
	v_mfma_f32_16x16x32_bf16 v[102:105], v[190:193], v[166:169], v[102:105]
	v_mfma_f32_16x16x32_bf16 v[94:97], v[198:201], v[166:169], v[94:97]
	v_mfma_f32_16x16x32_bf16 v[86:89], v[190:193], v[174:177], v[86:89]
	v_mfma_f32_16x16x32_bf16 v[78:81], v[198:201], v[174:177], v[78:81]
	v_mfma_f32_16x16x32_bf16 v[70:73], v[190:193], v[182:185], v[70:73]
	v_mfma_f32_16x16x32_bf16 v[66:69], v[198:201], v[182:185], v[66:69]
	v_mfma_f32_16x16x32_bf16 v[114:117], v[194:197], v[162:165], v[114:117]
	v_mfma_f32_16x16x32_bf16 v[106:109], v[202:205], v[162:165], v[106:109]
	v_mfma_f32_16x16x32_bf16 v[102:105], v[194:197], v[170:173], v[102:105]
	v_mfma_f32_16x16x32_bf16 v[94:97], v[202:205], v[170:173], v[94:97]
	v_mfma_f32_16x16x32_bf16 v[86:89], v[194:197], v[178:181], v[86:89]
	v_mfma_f32_16x16x32_bf16 v[78:81], v[202:205], v[178:181], v[78:81]
	v_mfma_f32_16x16x32_bf16 v[70:73], v[194:197], v[186:189], v[70:73]
	v_mfma_f32_16x16x32_bf16 v[66:69], v[202:205], v[186:189], v[66:69]
	s_mov_b32 m0, s63
	v_lshl_add_u64 v[206:207], v[210:211], 0, s[36:37]
	s_barrier
	ds_read_b128 v[158:161], v141 offset:49152
	ds_read_b128 v[162:165], v141 offset:50176
	ds_read_b128 v[166:169], v141 offset:51200
	ds_read_b128 v[170:173], v141 offset:52224
	ds_read_b128 v[174:177], v141 offset:53248
	ds_read_b128 v[178:181], v141 offset:54272
	ds_read_b128 v[182:185], v141 offset:55296
	ds_read_b128 v[186:189], v141 offset:56320
	global_load_lds_dwordx4 v[206:207], off
	s_mov_b32 m0, s64
	v_lshl_add_u64 v[206:207], v[214:215], 0, s[36:37]
	global_load_lds_dwordx4 v[206:207], off
	s_barrier
	s_waitcnt lgkmcnt(0)
	v_mfma_f32_16x16x32_bf16 v[62:65], v[142:145], v[158:161], v[62:65]
	v_mfma_f32_16x16x32_bf16 v[58:61], v[150:153], v[158:161], v[58:61]
	v_mfma_f32_16x16x32_bf16 v[50:53], v[142:145], v[166:169], v[50:53]
	v_mfma_f32_16x16x32_bf16 v[42:45], v[150:153], v[166:169], v[42:45]
	v_mfma_f32_16x16x32_bf16 v[34:37], v[142:145], v[174:177], v[34:37]
	v_mfma_f32_16x16x32_bf16 v[26:29], v[150:153], v[174:177], v[26:29]
	v_mfma_f32_16x16x32_bf16 v[18:21], v[142:145], v[182:185], v[18:21]
	v_mfma_f32_16x16x32_bf16 v[10:13], v[150:153], v[182:185], v[10:13]
	v_mfma_f32_16x16x32_bf16 v[62:65], v[146:149], v[162:165], v[62:65]
	v_mfma_f32_16x16x32_bf16 v[58:61], v[154:157], v[162:165], v[58:61]
	v_mfma_f32_16x16x32_bf16 v[50:53], v[146:149], v[170:173], v[50:53]
	v_mfma_f32_16x16x32_bf16 v[42:45], v[154:157], v[170:173], v[42:45]
	v_mfma_f32_16x16x32_bf16 v[34:37], v[146:149], v[178:181], v[34:37]
	v_mfma_f32_16x16x32_bf16 v[26:29], v[154:157], v[178:181], v[26:29]
	v_mfma_f32_16x16x32_bf16 v[18:21], v[146:149], v[186:189], v[18:21]
	v_mfma_f32_16x16x32_bf16 v[10:13], v[154:157], v[186:189], v[10:13]
	s_barrier
	s_add_u32 s40, s40, 0x160080
	s_addc_u32 s41, s41, 0
	s_add_i32 s42, s42, s24
	s_mov_b32 m0, s42
	s_nop 0
	global_load_lds_dwordx4 v0, s[40:41]
	s_add_i32 m0, s42, 0x2000
	s_nop 0
	global_load_lds_dwordx4 v134, s[40:41]
	s_waitcnt vmcnt(6)
	s_barrier
	v_mfma_f32_16x16x32_bf16 v[54:57], v[190:193], v[158:161], v[54:57]
	v_mfma_f32_16x16x32_bf16 v[46:49], v[198:201], v[158:161], v[46:49]
	v_mfma_f32_16x16x32_bf16 v[38:41], v[190:193], v[166:169], v[38:41]
	v_mfma_f32_16x16x32_bf16 v[30:33], v[198:201], v[166:169], v[30:33]
	v_mfma_f32_16x16x32_bf16 v[22:25], v[190:193], v[174:177], v[22:25]
	v_mfma_f32_16x16x32_bf16 v[14:17], v[198:201], v[174:177], v[14:17]
	v_mfma_f32_16x16x32_bf16 v[6:9], v[190:193], v[182:185], v[6:9]
	v_mfma_f32_16x16x32_bf16 v[2:5], v[198:201], v[182:185], v[2:5]
	v_mfma_f32_16x16x32_bf16 v[54:57], v[194:197], v[162:165], v[54:57]
	v_mfma_f32_16x16x32_bf16 v[46:49], v[202:205], v[162:165], v[46:49]
	v_mfma_f32_16x16x32_bf16 v[38:41], v[194:197], v[170:173], v[38:41]
	v_mfma_f32_16x16x32_bf16 v[30:33], v[202:205], v[170:173], v[30:33]
	v_mfma_f32_16x16x32_bf16 v[22:25], v[194:197], v[178:181], v[22:25]
	v_mfma_f32_16x16x32_bf16 v[14:17], v[202:205], v[178:181], v[14:17]
	v_mfma_f32_16x16x32_bf16 v[6:9], v[194:197], v[186:189], v[6:9]
	v_mfma_f32_16x16x32_bf16 v[2:5], v[202:205], v[186:189], v[2:5]
	s_add_i32 s65, s65, 2
	s_add_u32 s38, s38, 0x100
	s_addc_u32 s39, s39, 0
	s_cmpk_lt_u32 s65, 0x56
	s_barrier
	s_cbranch_scc1 .LBB0_1573
	s_waitcnt vmcnt(0)
	s_cmpk_gt_u32 s44, 0xff
	s_cbranch_scc1 .LBB0_1576
	s_barrier

; #define PG8_STAGE(bufoff, gbase, voff) do { _Pragma("unroll") for (int _i = 0; _i < 2; ++_i) \
;         __builtin_amdgcn_global_load_lds((const unsigned*)((const char*)(gbase) + (voff)[_i]), (LAS unsigned*)(lds + (bufoff) + ldsw + _i * 8192), 16, 0, 0); } while (0)
; #define PG8_LDA(dst, b, h) do { _Pragma("unroll") for (int m = 0; m < 4; ++m) _Pragma("unroll") for (int k = 0; k < 2; ++k) dst[m][k] = *(const LAS bf16x8*)(lds + PG8_SA(b, h) + aoff + m * 2048 + k * 1024); } while (0)
; #define PG8_LDB(dst, b, h) do { _Pragma("unroll") for (int n = 0; n < 2; ++n) _Pragma("unroll") for (int k = 0; k < 2; ++k) dst[n][k] = *(const LAS bf16x8*)(lds + PG8_SB(b, h) + boff + n * 2048 + k * 1024); } while (0)
; #define PG8_MMA(ai, bj, At, Bt) do { __builtin_amdgcn_s_setprio(1); _Pragma("unroll") for (int m = 0; m < 4; ++m) _Pragma("unroll") for (int n = 0; n < 2; ++n) _Pragma("unroll") for (int k = 0; k < 2; ++k) \
;         acc[ai][bj][m][n] = __builtin_amdgcn_mfma_f32_16x16x32_bf16(Bt[n][k], At[m][k], acc[ai][bj][m][n], 0, 0, 0); __builtin_amdgcn_s_setprio(0); } while (0)
; #define PG8_WAIT_L(n) asm volatile("s_waitcnt lgkmcnt(" #n ")" ::: "memory")
; #define PG8_BAR __builtin_amdgcn_s_barrier()
; template <class Epi, class Sched>
; __device__ __forceinline__ void gemm_phase(LAS unsigned char* lds, const Gemm g, const Sched& S, const Epi& E, const int tid) {
;     ...
;             const bool last = (t == nt - 2);
;             const char* a1 = cA + (size_t)(t + 1) * kstep;
;             const char* a2 = last ? nA : cA + (size_t)(t + 2) * kstep; const char* b2 = last ? nB : cB + (size_t)(t + 2) * kstep;
;             const char* a3 = a2 + kstep; const char* b3 = b2 + kstep;
;             if (last && has_next) S.a_ready(nxt);
;             if constexpr (Epi::PRELOAD) { if (last) E.preload(cur, lds, wid, lane); }
;             PG8_LDB(B0, 0, 0); PG8_SCHED; PG8_LDA(At, 0, 0); PG8_STAGE(PG8_SA(1, 1), a1 + hstep, voffA);
;             PG8_WAIT_L(8); PG8_BAR; PG8_WAIT_L(0); PG8_MMA(0, 0, At, B0); PG8_BAR; PG8_SCHED;
;             PG8_LDB(B1, 0, 1); PG8_STAGE(PG8_SB(0, 0), b2, voffB);
;             PG8_BAR; PG8_WAIT_L(0); PG8_MMA(0, 1, At, B1); PG8_BAR;
;             PG8_LDA(At, 0, 1); PG8_STAGE(PG8_SA(0, 0), a2, voffA);
;             PG8_BAR; PG8_WAIT_L(0); PG8_MMA(1, 0, At, B0); PG8_BAR; PG8_SCHED;
;             PG8_STAGE(PG8_SB(0, 1), b2 + hstep, voffB);
.LBB0_1627:
	s_add_u32 s38, s22, 0xe1edc080
	s_addc_u32 s39, s23, -1
	s_cmpk_lg_i32 s51, 0x54
	s_cselect_b32 s38, s38, 0
	s_cselect_b32 s39, s39, 0
	s_add_u32 s40, s4, s38
	s_addc_u32 s41, s5, s39
	s_add_i32 s59, 0, 0x10000
	v_add_u32_e32 v154, s59, v140
	ds_read_b128 v[142:145], v154
	ds_read_b128 v[146:149], v154 offset:1024
	ds_read_b128 v[150:153], v154 offset:2048
	ds_read_b128 v[154:157], v154 offset:3072
	s_add_u32 s38, s0, s38
	s_addc_u32 s39, s1, s39
	v_lshl_add_u64 v[178:179], v[136:137], 0, s[22:23]
	s_add_i32 m0, s25, 0xc000
	ds_read_b128 v[158:161], v141
	ds_read_b128 v[162:165], v141 offset:1024
	ds_read_b128 v[166:169], v141 offset:2048
	ds_read_b128 v[170:173], v141 offset:3072
	ds_read_b128 v[174:177], v141 offset:4096
	ds_read_b128 v[182:185], v141 offset:5120
	ds_read_b128 v[186:189], v141 offset:6144
	ds_read_b128 v[190:193], v141 offset:7168
	global_load_lds_dwordx4 v[178:179], off
	s_add_i32 m0, s25, 0xe000
	v_lshl_add_u64 v[178:179], v[138:139], 0, s[22:23]
	global_load_lds_dwordx4 v[178:179], off
	s_waitcnt lgkmcnt(8)
	s_barrier
	s_waitcnt lgkmcnt(0)
	v_mfma_f32_16x16x32_bf16 v[6:9], v[142:145], v[158:161], v[6:9]
	v_mfma_f32_16x16x32_bf16 v[14:17], v[150:153], v[158:161], v[14:17]
	v_mfma_f32_16x16x32_bf16 v[18:21], v[142:145], v[166:169], v[18:21]
	v_mfma_f32_16x16x32_bf16 v[22:25], v[150:153], v[166:169], v[22:25]
	v_mfma_f32_16x16x32_bf16 v[34:37], v[142:145], v[174:177], v[34:37]
	v_mfma_f32_16x16x32_bf16 v[38:41], v[150:153], v[174:177], v[38:41]
	v_mfma_f32_16x16x32_bf16 v[50:53], v[142:145], v[186:189], v[50:53]
	v_mfma_f32_16x16x32_bf16 v[54:57], v[150:153], v[186:189], v[54:57]
	v_mfma_f32_16x16x32_bf16 v[6:9], v[146:149], v[162:165], v[6:9]
	v_mfma_f32_16x16x32_bf16 v[14:17], v[154:157], v[162:165], v[14:17]
	v_mfma_f32_16x16x32_bf16 v[18:21], v[146:149], v[170:173], v[18:21]
	v_mfma_f32_16x16x32_bf16 v[22:25], v[154:157], v[170:173], v[22:25]
	v_mfma_f32_16x16x32_bf16 v[34:37], v[146:149], v[182:185], v[34:37]
	v_mfma_f32_16x16x32_bf16 v[38:41], v[154:157], v[182:185], v[38:41]
	v_mfma_f32_16x16x32_bf16 v[50:53], v[146:149], v[190:193], v[50:53]
	v_mfma_f32_16x16x32_bf16 v[54:57], v[154:157], v[190:193], v[54:57]
	s_barrier
	s_add_i32 s62, 0, 0x14000
	v_add_u32_e32 v178, s62, v140
	s_add_i32 s59, s59, s24
	ds_read_b128 v[194:197], v178
	ds_read_b128 v[198:201], v178 offset:1024
	ds_read_b128 v[202:205], v178 offset:2048
	ds_read_b128 v[206:209], v178 offset:3072
	s_mov_b32 m0, s59
	global_load_lds_dwordx4 v0, s[38:39]
	s_add_i32 m0, s59, 0x2000
	s_nop 0
	global_load_lds_dwordx4 v134, s[38:39]
	s_barrier
	s_waitcnt lgkmcnt(0)
	v_mfma_f32_16x16x32_bf16 v[2:5], v[194:197], v[158:161], v[2:5]
	v_mfma_f32_16x16x32_bf16 v[10:13], v[202:205], v[158:161], v[10:13]
	v_mfma_f32_16x16x32_bf16 v[26:29], v[194:197], v[166:169], v[26:29]
	v_mfma_f32_16x16x32_bf16 v[30:33], v[202:205], v[166:169], v[30:33]
	v_mfma_f32_16x16x32_bf16 v[42:45], v[194:197], v[174:177], v[42:45]
	v_mfma_f32_16x16x32_bf16 v[46:49], v[202:205], v[174:177], v[46:49]
	v_mfma_f32_16x16x32_bf16 v[58:61], v[194:197], v[186:189], v[58:61]
	v_mfma_f32_16x16x32_bf16 v[62:65], v[202:205], v[186:189], v[62:65]
	v_mfma_f32_16x16x32_bf16 v[2:5], v[198:201], v[162:165], v[2:5]
	v_mfma_f32_16x16x32_bf16 v[10:13], v[206:209], v[162:165], v[10:13]
	v_mfma_f32_16x16x32_bf16 v[26:29], v[198:201], v[170:173], v[26:29]
	v_mfma_f32_16x16x32_bf16 v[30:33], v[206:209], v[170:173], v[30:33]
	v_mfma_f32_16x16x32_bf16 v[42:45], v[198:201], v[182:185], v[42:45]
	v_mfma_f32_16x16x32_bf16 v[46:49], v[206:209], v[182:185], v[46:49]
	v_mfma_f32_16x16x32_bf16 v[58:61], v[198:201], v[190:193], v[58:61]
	v_mfma_f32_16x16x32_bf16 v[62:65], v[206:209], v[190:193], v[62:65]
	s_mov_b32 m0, s25
	v_lshl_add_u64 v[214:215], s[40:41], 0, v[130:131]
	s_barrier
	ds_read_b128 v[158:161], v141 offset:16384
	ds_read_b128 v[162:165], v141 offset:17408
	ds_read_b128 v[166:169], v141 offset:18432
	ds_read_b128 v[170:173], v141 offset:19456
	ds_read_b128 v[174:177], v141 offset:20480
	ds_read_b128 v[182:185], v141 offset:21504
	ds_read_b128 v[186:189], v141 offset:22528
	ds_read_b128 v[190:193], v141 offset:23552
	global_load_lds_dwordx4 v[214:215], off
	s_mov_b32 m0, s29
	v_lshl_add_u64 v[216:217], s[40:41], 0, v[132:133]
	global_load_lds_dwordx4 v[216:217], off
	s_barrier
	s_waitcnt lgkmcnt(0)
	v_mfma_f32_16x16x32_bf16 v[66:69], v[142:145], v[158:161], v[66:69]
	v_mfma_f32_16x16x32_bf16 v[70:73], v[150:153], v[158:161], v[70:73]
	v_mfma_f32_16x16x32_bf16 v[82:85], v[142:145], v[166:169], v[82:85]
	v_mfma_f32_16x16x32_bf16 v[86:89], v[150:153], v[166:169], v[86:89]
	v_mfma_f32_16x16x32_bf16 v[102:105], v[142:145], v[174:177], v[102:105]
	v_mfma_f32_16x16x32_bf16 v[106:109], v[150:153], v[174:177], v[106:109]
	v_mfma_f32_16x16x32_bf16 v[122:125], v[142:145], v[186:189], v[122:125]
	v_mfma_f32_16x16x32_bf16 v[126:129], v[150:153], v[186:189], v[126:129]
	v_mfma_f32_16x16x32_bf16 v[66:69], v[146:149], v[162:165], v[66:69]
	v_mfma_f32_16x16x32_bf16 v[70:73], v[154:157], v[162:165], v[70:73]
	v_mfma_f32_16x16x32_bf16 v[82:85], v[146:149], v[170:173], v[82:85]
	v_mfma_f32_16x16x32_bf16 v[86:89], v[154:157], v[170:173], v[86:89]
	v_mfma_f32_16x16x32_bf16 v[102:105], v[146:149], v[182:185], v[102:105]
	v_mfma_f32_16x16x32_bf16 v[106:109], v[154:157], v[182:185], v[106:109]
	v_mfma_f32_16x16x32_bf16 v[122:125], v[146:149], v[190:193], v[122:125]
	v_mfma_f32_16x16x32_bf16 v[126:129], v[154:157], v[190:193], v[126:129]
	s_barrier
	s_add_u32 s60, s38, 0x160000
	s_addc_u32 s61, s39, 0
	s_add_i32 s59, s62, s24
	s_mov_b32 m0, s59
	s_nop 0
	global_load_lds_dwordx4 v0, s[60:61]
	s_add_i32 m0, s59, 0x2000
	s_nop 0
	global_load_lds_dwordx4 v134, s[60:61]
	s_waitcnt vmcnt(6)
	s_barrier
; #define PG8_STAGE(bufoff, gbase, voff) do { _Pragma("unroll") for (int _i = 0; _i < 2; ++_i) \
;         __builtin_amdgcn_global_load_lds((const unsigned*)((const char*)(gbase) + (voff)[_i]), (LAS unsigned*)(lds + (bufoff) + ldsw + _i * 8192), 16, 0, 0); } while (0)
; #define PG8_LDA(dst, b, h) do { _Pragma("unroll") for (int m = 0; m < 4; ++m) _Pragma("unroll") for (int k = 0; k < 2; ++k) dst[m][k] = *(const LAS bf16x8*)(lds + PG8_SA(b, h) + aoff + m * 2048 + k * 1024); } while (0)
; #define PG8_LDB(dst, b, h) do { _Pragma("unroll") for (int n = 0; n < 2; ++n) _Pragma("unroll") for (int k = 0; k < 2; ++k) dst[n][k] = *(const LAS bf16x8*)(lds + PG8_SB(b, h) + boff + n * 2048 + k * 1024); } while (0)
; #define PG8_MMA(ai, bj, At, Bt) do { __builtin_amdgcn_s_setprio(1); _Pragma("unroll") for (int m = 0; m < 4; ++m) _Pragma("unroll") for (int n = 0; n < 2; ++n) _Pragma("unroll") for (int k = 0; k < 2; ++k) \
;         acc[ai][bj][m][n] = __builtin_amdgcn_mfma_f32_16x16x32_bf16(Bt[n][k], At[m][k], acc[ai][bj][m][n], 0, 0, 0); __builtin_amdgcn_s_setprio(0); } while (0)
; #define PG8_WAIT_V(n) asm volatile("s_waitcnt vmcnt(" #n ")" ::: "memory")
; #define PG8_WAIT_L(n) asm volatile("s_waitcnt lgkmcnt(" #n ")" ::: "memory")
; #define PG8_BAR __builtin_amdgcn_s_barrier()
; #define PG8_SCHED __builtin_amdgcn_sched_barrier(0)
; template <class Epi, class Sched>
; __device__ __forceinline__ void gemm_phase(LAS unsigned char* lds, const Gemm g, const Sched& S, const Epi& E, const int tid) {
;     ...
;             PG8_WAIT_V(6); PG8_BAR; PG8_MMA(1, 1, At, B1); PG8_BAR;
;             PG8_LDB(B0, 1, 0); PG8_SCHED; PG8_LDA(At, 1, 0); PG8_STAGE(PG8_SA(0, 1), a2 + hstep, voffA);
;             PG8_WAIT_L(8); PG8_BAR; PG8_WAIT_L(0); PG8_MMA(0, 0, At, B0); PG8_BAR; PG8_SCHED;
;             PG8_LDB(B1, 1, 1); PG8_STAGE(PG8_SB(1, 0), b3, voffB);
;             PG8_BAR; PG8_WAIT_L(0); PG8_MMA(0, 1, At, B1); PG8_BAR;
;             PG8_LDA(At, 1, 1); PG8_STAGE(PG8_SA(1, 0), a3, voffA);
	v_mfma_f32_16x16x32_bf16 v[74:77], v[194:197], v[158:161], v[74:77]
	v_mfma_f32_16x16x32_bf16 v[78:81], v[202:205], v[158:161], v[78:81]
	v_mfma_f32_16x16x32_bf16 v[90:93], v[194:197], v[166:169], v[90:93]
	v_mfma_f32_16x16x32_bf16 v[94:97], v[202:205], v[166:169], v[94:97]
	v_mfma_f32_16x16x32_bf16 v[114:117], v[194:197], v[174:177], v[114:117]
	v_mfma_f32_16x16x32_bf16 v[118:121], v[202:205], v[174:177], v[118:121]
	v_mfma_f32_16x16x32_bf16 v[110:113], v[194:197], v[186:189], v[110:113]
	v_mfma_f32_16x16x32_bf16 v[98:101], v[202:205], v[186:189], v[98:101]
	v_mfma_f32_16x16x32_bf16 v[74:77], v[198:201], v[162:165], v[74:77]
	v_mfma_f32_16x16x32_bf16 v[78:81], v[206:209], v[162:165], v[78:81]
	v_mfma_f32_16x16x32_bf16 v[90:93], v[198:201], v[170:173], v[90:93]
	v_mfma_f32_16x16x32_bf16 v[94:97], v[206:209], v[170:173], v[94:97]
	v_mfma_f32_16x16x32_bf16 v[114:117], v[198:201], v[182:185], v[114:117]
	v_mfma_f32_16x16x32_bf16 v[118:121], v[206:209], v[182:185], v[118:121]
	v_mfma_f32_16x16x32_bf16 v[110:113], v[198:201], v[190:193], v[110:113]
	v_mfma_f32_16x16x32_bf16 v[98:101], v[206:209], v[190:193], v[98:101]
	s_add_i32 s59, 0, 0x18000
	v_add_u32_e32 v154, s59, v140
	s_barrier
	ds_read_b128 v[142:145], v154
	ds_read_b128 v[146:149], v154 offset:1024
	ds_read_b128 v[150:153], v154 offset:2048
	ds_read_b128 v[154:157], v154 offset:3072
	s_add_u32 s40, s40, 0x160000
	s_addc_u32 s41, s41, 0
	s_mov_b32 m0, s53
	ds_read_b128 v[158:161], v141 offset:32768
	ds_read_b128 v[162:165], v141 offset:33792
	ds_read_b128 v[166:169], v141 offset:34816
	ds_read_b128 v[170:173], v141 offset:35840
	ds_read_b128 v[174:177], v141 offset:36864
	ds_read_b128 v[182:185], v141 offset:37888
	ds_read_b128 v[186:189], v141 offset:38912
	global_load_lds_dwordx4 v130, s[40:41]
	s_mov_b32 m0, s54
	ds_read_b128 v[190:193], v141 offset:39936
	global_load_lds_dwordx4 v132, s[40:41]
	s_waitcnt lgkmcnt(8)
	s_barrier
	s_waitcnt lgkmcnt(0)
	v_mfma_f32_16x16x32_bf16 v[6:9], v[142:145], v[158:161], v[6:9]
	v_mfma_f32_16x16x32_bf16 v[14:17], v[150:153], v[158:161], v[14:17]
	v_mfma_f32_16x16x32_bf16 v[18:21], v[142:145], v[166:169], v[18:21]
	v_mfma_f32_16x16x32_bf16 v[22:25], v[150:153], v[166:169], v[22:25]
	v_mfma_f32_16x16x32_bf16 v[34:37], v[142:145], v[174:177], v[34:37]
	v_mfma_f32_16x16x32_bf16 v[38:41], v[150:153], v[174:177], v[38:41]
	v_mfma_f32_16x16x32_bf16 v[50:53], v[142:145], v[186:189], v[50:53]
	v_mfma_f32_16x16x32_bf16 v[54:57], v[150:153], v[186:189], v[54:57]
	v_mfma_f32_16x16x32_bf16 v[6:9], v[146:149], v[162:165], v[6:9]
	v_mfma_f32_16x16x32_bf16 v[14:17], v[154:157], v[162:165], v[14:17]
	v_mfma_f32_16x16x32_bf16 v[18:21], v[146:149], v[170:173], v[18:21]
	v_mfma_f32_16x16x32_bf16 v[22:25], v[154:157], v[170:173], v[22:25]
	v_mfma_f32_16x16x32_bf16 v[34:37], v[146:149], v[182:185], v[34:37]
	v_mfma_f32_16x16x32_bf16 v[38:41], v[154:157], v[182:185], v[38:41]
	v_mfma_f32_16x16x32_bf16 v[50:53], v[146:149], v[190:193], v[50:53]
	v_mfma_f32_16x16x32_bf16 v[54:57], v[154:157], v[190:193], v[54:57]
	s_barrier
	s_add_i32 s40, 0, 0x1c000
	s_add_i32 s41, s59, s24
	v_add_u32_e32 v206, s40, v140
	s_add_u32 s98, s38, s36
	s_addc_u32 s99, s39, s37
	s_mov_b32 m0, s41
	ds_read_b128 v[194:197], v206
	ds_read_b128 v[198:201], v206 offset:1024
	ds_read_b128 v[202:205], v206 offset:2048
	ds_read_b128 v[206:209], v206 offset:3072
	global_load_lds_dwordx4 v0, s[98:99]
	s_add_i32 m0, s41, 0x2000
	s_add_u32 s98, s38, s36
	s_addc_u32 s99, s39, s37
	global_load_lds_dwordx4 v134, s[98:99]
	s_barrier
; #define PG8_STAGE(bufoff, gbase, voff) do { _Pragma("unroll") for (int _i = 0; _i < 2; ++_i) \
;         __builtin_amdgcn_global_load_lds((const unsigned*)((const char*)(gbase) + (voff)[_i]), (LAS unsigned*)(lds + (bufoff) + ldsw + _i * 8192), 16, 0, 0); } while (0)
; #define PG8_LDA(dst, b, h) do { _Pragma("unroll") for (int m = 0; m < 4; ++m) _Pragma("unroll") for (int k = 0; k < 2; ++k) dst[m][k] = *(const LAS bf16x8*)(lds + PG8_SA(b, h) + aoff + m * 2048 + k * 1024); } while (0)
; #define PG8_MMA(ai, bj, At, Bt) do { __builtin_amdgcn_s_setprio(1); _Pragma("unroll") for (int m = 0; m < 4; ++m) _Pragma("unroll") for (int n = 0; n < 2; ++n) _Pragma("unroll") for (int k = 0; k < 2; ++k) \
;         acc[ai][bj][m][n] = __builtin_amdgcn_mfma_f32_16x16x32_bf16(Bt[n][k], At[m][k], acc[ai][bj][m][n], 0, 0, 0); __builtin_amdgcn_s_setprio(0); } while (0)
; #define PG8_WAIT_V(n) asm volatile("s_waitcnt vmcnt(" #n ")" ::: "memory")
; #define PG8_WAIT_L(n) asm volatile("s_waitcnt lgkmcnt(" #n ")" ::: "memory")
; #define PG8_BAR __builtin_amdgcn_s_barrier()
; #define PG8_SCHED __builtin_amdgcn_sched_barrier(0)
; template <class Epi, class Sched>
; __device__ __forceinline__ void gemm_phase(LAS unsigned char* lds, const Gemm g, const Sched& S, const Epi& E, const int tid) {
;     ...
;             PG8_LDA(At, 1, 1); PG8_STAGE(PG8_SA(1, 0), a3, voffA);
;             PG8_BAR; PG8_WAIT_L(0); PG8_MMA(1, 0, At, B0); PG8_BAR; PG8_SCHED;
;             PG8_STAGE(PG8_SB(1, 1), b3 + hstep, voffB);
;             PG8_WAIT_V(6); PG8_BAR; PG8_MMA(1, 1, At, B1); PG8_BAR;
;         }
;         if constexpr (!Epi::AFTER_DRAIN) { if constexpr (Epi::PRELOAD) E(acc, cur, wr, wc, fr, fq, lds); else E(acc, cur, wr, wc, fr, fq); S.done(cur); }
;         if (!has_next) break;
; #pragma unroll
;         for (int a = 0; a < 2; ++a)
; #pragma unroll
;             for (int b = 0; b < 2; ++b)
; #pragma unroll
;                 for (int m = 0; m < 4; ++m)
; #pragma unroll
;                     for (int n = 0; n < 2; ++n) acc[a][b][m][n] = (f32x4){0.f, 0.f, 0.f, 0.f};
;         cur = nxt; cA = nA; cB = nB; ++ui;
;     }
;     PG8_WAIT_V(0);
;     if (wr == 0) PG8_BAR;
	s_waitcnt lgkmcnt(0)
	v_mfma_f32_16x16x32_bf16 v[2:5], v[194:197], v[158:161], v[2:5]
	v_mfma_f32_16x16x32_bf16 v[10:13], v[202:205], v[158:161], v[10:13]
	v_mfma_f32_16x16x32_bf16 v[26:29], v[194:197], v[166:169], v[26:29]
	v_mfma_f32_16x16x32_bf16 v[30:33], v[202:205], v[166:169], v[30:33]
	v_mfma_f32_16x16x32_bf16 v[42:45], v[194:197], v[174:177], v[42:45]
	v_mfma_f32_16x16x32_bf16 v[46:49], v[202:205], v[174:177], v[46:49]
	v_mfma_f32_16x16x32_bf16 v[58:61], v[194:197], v[186:189], v[58:61]
	v_mfma_f32_16x16x32_bf16 v[62:65], v[202:205], v[186:189], v[62:65]
	v_mfma_f32_16x16x32_bf16 v[2:5], v[198:201], v[162:165], v[2:5]
	v_mfma_f32_16x16x32_bf16 v[10:13], v[206:209], v[162:165], v[10:13]
	v_mfma_f32_16x16x32_bf16 v[26:29], v[198:201], v[170:173], v[26:29]
	v_mfma_f32_16x16x32_bf16 v[30:33], v[206:209], v[170:173], v[30:33]
	v_mfma_f32_16x16x32_bf16 v[42:45], v[198:201], v[182:185], v[42:45]
	v_mfma_f32_16x16x32_bf16 v[46:49], v[206:209], v[182:185], v[46:49]
	v_mfma_f32_16x16x32_bf16 v[58:61], v[198:201], v[190:193], v[58:61]
	v_mfma_f32_16x16x32_bf16 v[62:65], v[206:209], v[190:193], v[62:65]
	s_mov_b32 m0, s55
	v_lshl_add_u64 v[178:179], v[214:215], 0, s[36:37]
	s_barrier
	ds_read_b128 v[158:161], v141 offset:49152
	ds_read_b128 v[162:165], v141 offset:50176
	ds_read_b128 v[166:169], v141 offset:51200
	ds_read_b128 v[170:173], v141 offset:52224
	ds_read_b128 v[174:177], v141 offset:53248
	ds_read_b128 v[182:185], v141 offset:54272
	ds_read_b128 v[186:189], v141 offset:55296
	ds_read_b128 v[190:193], v141 offset:56320
	global_load_lds_dwordx4 v[178:179], off
	s_mov_b32 m0, s58
	v_lshl_add_u64 v[178:179], v[216:217], 0, s[36:37]
	global_load_lds_dwordx4 v[178:179], off
	s_barrier
	s_waitcnt lgkmcnt(0)
	v_mfma_f32_16x16x32_bf16 v[66:69], v[142:145], v[158:161], v[66:69]
	v_mfma_f32_16x16x32_bf16 v[70:73], v[150:153], v[158:161], v[70:73]
	v_mfma_f32_16x16x32_bf16 v[82:85], v[142:145], v[166:169], v[82:85]
	v_mfma_f32_16x16x32_bf16 v[86:89], v[150:153], v[166:169], v[86:89]
	v_mfma_f32_16x16x32_bf16 v[102:105], v[142:145], v[174:177], v[102:105]
	v_mfma_f32_16x16x32_bf16 v[106:109], v[150:153], v[174:177], v[106:109]
	v_mfma_f32_16x16x32_bf16 v[122:125], v[142:145], v[186:189], v[122:125]
	v_mfma_f32_16x16x32_bf16 v[126:129], v[150:153], v[186:189], v[126:129]
	v_mfma_f32_16x16x32_bf16 v[66:69], v[146:149], v[162:165], v[66:69]
	v_mfma_f32_16x16x32_bf16 v[70:73], v[154:157], v[162:165], v[70:73]
	v_mfma_f32_16x16x32_bf16 v[82:85], v[146:149], v[170:173], v[82:85]
	v_mfma_f32_16x16x32_bf16 v[86:89], v[154:157], v[170:173], v[86:89]
	v_mfma_f32_16x16x32_bf16 v[102:105], v[146:149], v[182:185], v[102:105]
	v_mfma_f32_16x16x32_bf16 v[106:109], v[154:157], v[182:185], v[106:109]
	v_mfma_f32_16x16x32_bf16 v[122:125], v[146:149], v[190:193], v[122:125]
	v_mfma_f32_16x16x32_bf16 v[126:129], v[154:157], v[190:193], v[126:129]
	s_barrier
	s_add_u32 s38, s38, 0x160080
	s_addc_u32 s39, s39, 0
	s_add_i32 s40, s40, s24
	s_mov_b32 m0, s40
	s_nop 0
	global_load_lds_dwordx4 v0, s[38:39]
	s_add_i32 m0, s40, 0x2000
	s_nop 0
	global_load_lds_dwordx4 v134, s[38:39]
	s_waitcnt vmcnt(6)
	s_barrier
	v_mfma_f32_16x16x32_bf16 v[74:77], v[194:197], v[158:161], v[74:77]
	v_mfma_f32_16x16x32_bf16 v[78:81], v[202:205], v[158:161], v[78:81]
	v_mfma_f32_16x16x32_bf16 v[90:93], v[194:197], v[166:169], v[90:93]
	v_mfma_f32_16x16x32_bf16 v[94:97], v[202:205], v[166:169], v[94:97]
	v_mfma_f32_16x16x32_bf16 v[114:117], v[194:197], v[174:177], v[114:117]
	v_mfma_f32_16x16x32_bf16 v[118:121], v[202:205], v[174:177], v[118:121]
	v_mfma_f32_16x16x32_bf16 v[110:113], v[194:197], v[186:189], v[110:113]
	v_mfma_f32_16x16x32_bf16 v[98:101], v[202:205], v[186:189], v[98:101]
	v_mfma_f32_16x16x32_bf16 v[74:77], v[198:201], v[162:165], v[74:77]
	v_mfma_f32_16x16x32_bf16 v[78:81], v[206:209], v[162:165], v[78:81]
	v_mfma_f32_16x16x32_bf16 v[90:93], v[198:201], v[170:173], v[90:93]
	v_mfma_f32_16x16x32_bf16 v[94:97], v[206:209], v[170:173], v[94:97]
	v_mfma_f32_16x16x32_bf16 v[114:117], v[198:201], v[182:185], v[114:117]
	v_mfma_f32_16x16x32_bf16 v[118:121], v[206:209], v[182:185], v[118:121]
	v_mfma_f32_16x16x32_bf16 v[110:113], v[198:201], v[190:193], v[110:113]
	v_mfma_f32_16x16x32_bf16 v[98:101], v[206:209], v[190:193], v[98:101]
	s_add_i32 s51, s51, 2
	s_add_u32 s22, s22, 0x100
	s_addc_u32 s23, s23, 0
	s_cmpk_lt_u32 s51, 0x56
	s_barrier
	s_cbranch_scc1 .LBB0_1627
	s_waitcnt vmcnt(0)
	s_cmpk_gt_u32 s42, 0xff
	s_cbranch_scc1 .LBB0_1630
	s_barrier

; #define PG8_STAGE(bufoff, gbase, voff) do { _Pragma("unroll") for (int _i = 0; _i < 2; ++_i) \
;         __builtin_amdgcn_global_load_lds((const unsigned*)((const char*)(gbase) + (voff)[_i]), (LAS unsigned*)(lds + (bufoff) + ldsw + _i * 8192), 16, 0, 0); } while (0)
; #define PG8_LDA(dst, b, h) do { _Pragma("unroll") for (int m = 0; m < 4; ++m) _Pragma("unroll") for (int k = 0; k < 2; ++k) dst[m][k] = *(const LAS bf16x8*)(lds + PG8_SA(b, h) + aoff + m * 2048 + k * 1024); } while (0)
; #define PG8_LDB(dst, b, h) do { _Pragma("unroll") for (int n = 0; n < 2; ++n) _Pragma("unroll") for (int k = 0; k < 2; ++k) dst[n][k] = *(const LAS bf16x8*)(lds + PG8_SB(b, h) + boff + n * 2048 + k * 1024); } while (0)
; #define PG8_MMA(ai, bj, At, Bt) do { __builtin_amdgcn_s_setprio(1); _Pragma("unroll") for (int m = 0; m < 4; ++m) _Pragma("unroll") for (int n = 0; n < 2; ++n) _Pragma("unroll") for (int k = 0; k < 2; ++k) \
;         acc[ai][bj][m][n] = __builtin_amdgcn_mfma_f32_16x16x32_bf16(Bt[n][k], At[m][k], acc[ai][bj][m][n], 0, 0, 0); __builtin_amdgcn_s_setprio(0); } while (0)
; #define PG8_WAIT_L(n) asm volatile("s_waitcnt lgkmcnt(" #n ")" ::: "memory")
; #define PG8_BAR __builtin_amdgcn_s_barrier()
; template <class Epi, class Sched>
; __device__ __forceinline__ void gemm_phase(LAS unsigned char* lds, const Gemm g, const Sched& S, const Epi& E, const int tid) {
;     ...
;             const bool last = (t == nt - 2);
;             const char* a1 = cA + (size_t)(t + 1) * kstep;
;             const char* a2 = last ? nA : cA + (size_t)(t + 2) * kstep; const char* b2 = last ? nB : cB + (size_t)(t + 2) * kstep;
;             const char* a3 = a2 + kstep; const char* b3 = b2 + kstep;
;             if (last && has_next) S.a_ready(nxt);
;             if constexpr (Epi::PRELOAD) { if (last) E.preload(cur, lds, wid, lane); }
;             PG8_LDB(B0, 0, 0); PG8_SCHED; PG8_LDA(At, 0, 0); PG8_STAGE(PG8_SA(1, 1), a1 + hstep, voffA);
;             PG8_WAIT_L(8); PG8_BAR; PG8_WAIT_L(0); PG8_MMA(0, 0, At, B0); PG8_BAR; PG8_SCHED;
;             PG8_LDB(B1, 0, 1); PG8_STAGE(PG8_SB(0, 0), b2, voffB);
;             PG8_BAR; PG8_WAIT_L(0); PG8_MMA(0, 1, At, B1); PG8_BAR;
;             PG8_LDA(At, 0, 1); PG8_STAGE(PG8_SA(0, 0), a2, voffA);
;             PG8_BAR; PG8_WAIT_L(0); PG8_MMA(1, 0, At, B0); PG8_BAR; PG8_SCHED;
;             PG8_STAGE(PG8_SB(0, 1), b2 + hstep, voffB);
.LBB0_1680:
	s_add_u32 s14, s12, 0x100
	s_addc_u32 s15, s13, 0
	s_add_i32 s53, 0, 0x10000
	v_add_u32_e32 v152, s53, v137
	ds_read_b128 v[140:143], v152
	ds_read_b128 v[144:147], v152 offset:1024
	ds_read_b128 v[148:151], v152 offset:2048
	ds_read_b128 v[152:155], v152 offset:3072
	s_cmp_eq_u32 s52, 4
	s_cselect_b32 s19, s7, s15
	s_cselect_b32 s18, s6, s14
	s_cselect_b32 s17, s3, s11
	s_cselect_b32 s16, s2, s5
	v_lshl_add_u64 v[188:189], s[12:13], 0, v[132:133]
	s_add_i32 m0, s28, 0xc000
	ds_read_b128 v[156:159], v139
	ds_read_b128 v[160:163], v139 offset:1024
	ds_read_b128 v[164:167], v139 offset:2048
	ds_read_b128 v[168:171], v139 offset:3072
	ds_read_b128 v[172:175], v139 offset:4096
	ds_read_b128 v[176:179], v139 offset:5120
	ds_read_b128 v[180:183], v139 offset:6144
	ds_read_b128 v[184:187], v139 offset:7168
	global_load_lds_dwordx4 v[188:189], off
	s_add_i32 m0, s28, 0xe000
	v_lshl_add_u64 v[188:189], s[12:13], 0, v[134:135]
	global_load_lds_dwordx4 v[188:189], off
	s_waitcnt lgkmcnt(8)
	s_barrier
	s_waitcnt lgkmcnt(0)
	v_mfma_f32_16x16x32_bf16 v[126:129], v[140:143], v[156:159], v[126:129]
	v_mfma_f32_16x16x32_bf16 v[122:125], v[148:151], v[156:159], v[122:125]
	v_mfma_f32_16x16x32_bf16 v[118:121], v[140:143], v[164:167], v[118:121]
	v_mfma_f32_16x16x32_bf16 v[114:117], v[148:151], v[164:167], v[114:117]
	v_mfma_f32_16x16x32_bf16 v[106:109], v[140:143], v[172:175], v[106:109]
	v_mfma_f32_16x16x32_bf16 v[98:101], v[148:151], v[172:175], v[98:101]
	v_mfma_f32_16x16x32_bf16 v[90:93], v[140:143], v[180:183], v[90:93]
	v_mfma_f32_16x16x32_bf16 v[82:85], v[148:151], v[180:183], v[82:85]
	v_mfma_f32_16x16x32_bf16 v[126:129], v[144:147], v[160:163], v[126:129]
	v_mfma_f32_16x16x32_bf16 v[122:125], v[152:155], v[160:163], v[122:125]
	v_mfma_f32_16x16x32_bf16 v[118:121], v[144:147], v[168:171], v[118:121]
	v_mfma_f32_16x16x32_bf16 v[114:117], v[152:155], v[168:171], v[114:117]
	v_mfma_f32_16x16x32_bf16 v[106:109], v[144:147], v[176:179], v[106:109]
	v_mfma_f32_16x16x32_bf16 v[98:101], v[152:155], v[176:179], v[98:101]
	v_mfma_f32_16x16x32_bf16 v[90:93], v[144:147], v[184:187], v[90:93]
	v_mfma_f32_16x16x32_bf16 v[82:85], v[152:155], v[184:187], v[82:85]
	s_barrier
	s_add_i32 s54, 0, 0x14000
	s_add_i32 s12, s53, s39
	v_add_u32_e32 v200, s54, v137
	s_mov_b32 m0, s12
	ds_read_b128 v[188:191], v200
	ds_read_b128 v[192:195], v200 offset:1024
	ds_read_b128 v[196:199], v200 offset:2048
	ds_read_b128 v[200:203], v200 offset:3072
	global_load_lds_dwordx4 v0, s[16:17]
	s_add_i32 m0, s12, 0x2000
	s_nop 0
	global_load_lds_dwordx4 v130, s[16:17]
	s_barrier
	s_waitcnt lgkmcnt(0)
	v_mfma_f32_16x16x32_bf16 v[110:113], v[188:191], v[156:159], v[110:113]
	v_mfma_f32_16x16x32_bf16 v[102:105], v[196:199], v[156:159], v[102:105]
	v_mfma_f32_16x16x32_bf16 v[94:97], v[188:191], v[164:167], v[94:97]
	v_mfma_f32_16x16x32_bf16 v[86:89], v[196:199], v[164:167], v[86:89]
	v_mfma_f32_16x16x32_bf16 v[78:81], v[188:191], v[172:175], v[78:81]
	v_mfma_f32_16x16x32_bf16 v[74:77], v[196:199], v[172:175], v[74:77]
	v_mfma_f32_16x16x32_bf16 v[70:73], v[188:191], v[180:183], v[70:73]
	v_mfma_f32_16x16x32_bf16 v[66:69], v[196:199], v[180:183], v[66:69]
	v_mfma_f32_16x16x32_bf16 v[110:113], v[192:195], v[160:163], v[110:113]
	v_mfma_f32_16x16x32_bf16 v[102:105], v[200:203], v[160:163], v[102:105]
	v_mfma_f32_16x16x32_bf16 v[94:97], v[192:195], v[168:171], v[94:97]
	v_mfma_f32_16x16x32_bf16 v[86:89], v[200:203], v[168:171], v[86:89]
	v_mfma_f32_16x16x32_bf16 v[78:81], v[192:195], v[176:179], v[78:81]
	v_mfma_f32_16x16x32_bf16 v[74:77], v[200:203], v[176:179], v[74:77]
	v_mfma_f32_16x16x32_bf16 v[70:73], v[192:195], v[184:187], v[70:73]
	v_mfma_f32_16x16x32_bf16 v[66:69], v[200:203], v[184:187], v[66:69]
	s_mov_b32 m0, s28
	v_lshl_add_u64 v[208:209], s[18:19], 0, v[0:1]
	s_barrier
	ds_read_b128 v[156:159], v139 offset:16384
	ds_read_b128 v[160:163], v139 offset:17408
	ds_read_b128 v[164:167], v139 offset:18432
	ds_read_b128 v[168:171], v139 offset:19456
	ds_read_b128 v[172:175], v139 offset:20480
	ds_read_b128 v[176:179], v139 offset:21504
	ds_read_b128 v[180:183], v139 offset:22528
	ds_read_b128 v[184:187], v139 offset:23552
	global_load_lds_dwordx4 v[208:209], off
	s_mov_b32 m0, s41
	v_lshl_add_u64 v[210:211], s[18:19], 0, v[130:131]
	global_load_lds_dwordx4 v[210:211], off
	s_barrier
	s_waitcnt lgkmcnt(0)
	v_mfma_f32_16x16x32_bf16 v[62:65], v[140:143], v[156:159], v[62:65]
	v_mfma_f32_16x16x32_bf16 v[58:61], v[148:151], v[156:159], v[58:61]
	v_mfma_f32_16x16x32_bf16 v[54:57], v[140:143], v[164:167], v[54:57]
	v_mfma_f32_16x16x32_bf16 v[50:53], v[148:151], v[164:167], v[50:53]
	v_mfma_f32_16x16x32_bf16 v[38:41], v[140:143], v[172:175], v[38:41]
	v_mfma_f32_16x16x32_bf16 v[34:37], v[148:151], v[172:175], v[34:37]
	v_mfma_f32_16x16x32_bf16 v[22:25], v[140:143], v[180:183], v[22:25]
	v_mfma_f32_16x16x32_bf16 v[18:21], v[148:151], v[180:183], v[18:21]
	v_mfma_f32_16x16x32_bf16 v[62:65], v[144:147], v[160:163], v[62:65]
	v_mfma_f32_16x16x32_bf16 v[58:61], v[152:155], v[160:163], v[58:61]
	v_mfma_f32_16x16x32_bf16 v[54:57], v[144:147], v[168:171], v[54:57]
	v_mfma_f32_16x16x32_bf16 v[50:53], v[152:155], v[168:171], v[50:53]
	v_mfma_f32_16x16x32_bf16 v[38:41], v[144:147], v[176:179], v[38:41]
	v_mfma_f32_16x16x32_bf16 v[34:37], v[152:155], v[176:179], v[34:37]
	v_mfma_f32_16x16x32_bf16 v[22:25], v[144:147], v[184:187], v[22:25]
	v_mfma_f32_16x16x32_bf16 v[18:21], v[152:155], v[184:187], v[18:21]
	s_barrier
	s_add_u32 s12, s16, 0x160000
	s_addc_u32 s13, s17, 0
	s_add_i32 s53, s54, s39
	s_mov_b32 m0, s53
	s_nop 0
	global_load_lds_dwordx4 v0, s[12:13]
	s_add_i32 m0, s53, 0x2000
	s_nop 0
	global_load_lds_dwordx4 v130, s[12:13]
	s_waitcnt vmcnt(6)
	s_barrier
; #define PG8_STAGE(bufoff, gbase, voff) do { _Pragma("unroll") for (int _i = 0; _i < 2; ++_i) \
;         __builtin_amdgcn_global_load_lds((const unsigned*)((const char*)(gbase) + (voff)[_i]), (LAS unsigned*)(lds + (bufoff) + ldsw + _i * 8192), 16, 0, 0); } while (0)
; #define PG8_LDA(dst, b, h) do { _Pragma("unroll") for (int m = 0; m < 4; ++m) _Pragma("unroll") for (int k = 0; k < 2; ++k) dst[m][k] = *(const LAS bf16x8*)(lds + PG8_SA(b, h) + aoff + m * 2048 + k * 1024); } while (0)
; #define PG8_LDB(dst, b, h) do { _Pragma("unroll") for (int n = 0; n < 2; ++n) _Pragma("unroll") for (int k = 0; k < 2; ++k) dst[n][k] = *(const LAS bf16x8*)(lds + PG8_SB(b, h) + boff + n * 2048 + k * 1024); } while (0)
; #define PG8_MMA(ai, bj, At, Bt) do { __builtin_amdgcn_s_setprio(1); _Pragma("unroll") for (int m = 0; m < 4; ++m) _Pragma("unroll") for (int n = 0; n < 2; ++n) _Pragma("unroll") for (int k = 0; k < 2; ++k) \
;         acc[ai][bj][m][n] = __builtin_amdgcn_mfma_f32_16x16x32_bf16(Bt[n][k], At[m][k], acc[ai][bj][m][n], 0, 0, 0); __builtin_amdgcn_s_setprio(0); } while (0)
; #define PG8_WAIT_V(n) asm volatile("s_waitcnt vmcnt(" #n ")" ::: "memory")
; #define PG8_WAIT_L(n) asm volatile("s_waitcnt lgkmcnt(" #n ")" ::: "memory")
; #define PG8_BAR __builtin_amdgcn_s_barrier()
; #define PG8_SCHED __builtin_amdgcn_sched_barrier(0)
; template <class Epi, class Sched>
; __device__ __forceinline__ void gemm_phase(LAS unsigned char* lds, const Gemm g, const Sched& S, const Epi& E, const int tid) {
;     ...
;             PG8_STAGE(PG8_SB(0, 1), b2 + hstep, voffB);
;             PG8_WAIT_V(6); PG8_BAR; PG8_MMA(1, 1, At, B1); PG8_BAR;
;             PG8_LDB(B0, 1, 0); PG8_SCHED; PG8_LDA(At, 1, 0); PG8_STAGE(PG8_SA(0, 1), a2 + hstep, voffA);
;             PG8_WAIT_L(8); PG8_BAR; PG8_WAIT_L(0); PG8_MMA(0, 0, At, B0); PG8_BAR; PG8_SCHED;
;             PG8_LDB(B1, 1, 1); PG8_STAGE(PG8_SB(1, 0), b3, voffB);
;             PG8_BAR; PG8_WAIT_L(0); PG8_MMA(0, 1, At, B1); PG8_BAR;
;             PG8_LDA(At, 1, 1); PG8_STAGE(PG8_SA(1, 0), a3, voffA);
;             PG8_BAR; PG8_WAIT_L(0); PG8_MMA(1, 0, At, B0); PG8_BAR; PG8_SCHED;
	v_mfma_f32_16x16x32_bf16 v[46:49], v[188:191], v[156:159], v[46:49]
	v_mfma_f32_16x16x32_bf16 v[42:45], v[196:199], v[156:159], v[42:45]
	v_mfma_f32_16x16x32_bf16 v[30:33], v[188:191], v[164:167], v[30:33]
	v_mfma_f32_16x16x32_bf16 v[26:29], v[196:199], v[164:167], v[26:29]
	v_mfma_f32_16x16x32_bf16 v[14:17], v[188:191], v[172:175], v[14:17]
	v_mfma_f32_16x16x32_bf16 v[10:13], v[196:199], v[172:175], v[10:13]
	v_mfma_f32_16x16x32_bf16 v[6:9], v[188:191], v[180:183], v[6:9]
	v_mfma_f32_16x16x32_bf16 v[2:5], v[196:199], v[180:183], v[2:5]
	v_mfma_f32_16x16x32_bf16 v[46:49], v[192:195], v[160:163], v[46:49]
	v_mfma_f32_16x16x32_bf16 v[42:45], v[200:203], v[160:163], v[42:45]
	v_mfma_f32_16x16x32_bf16 v[30:33], v[192:195], v[168:171], v[30:33]
	v_mfma_f32_16x16x32_bf16 v[26:29], v[200:203], v[168:171], v[26:29]
	v_mfma_f32_16x16x32_bf16 v[14:17], v[192:195], v[176:179], v[14:17]
	v_mfma_f32_16x16x32_bf16 v[10:13], v[200:203], v[176:179], v[10:13]
	v_mfma_f32_16x16x32_bf16 v[6:9], v[192:195], v[184:187], v[6:9]
	v_mfma_f32_16x16x32_bf16 v[2:5], v[200:203], v[184:187], v[2:5]
	s_add_i32 s53, 0, 0x18000
	v_add_u32_e32 v152, s53, v137
	s_barrier
	ds_read_b128 v[140:143], v152
	ds_read_b128 v[144:147], v152 offset:1024
	ds_read_b128 v[148:151], v152 offset:2048
	ds_read_b128 v[152:155], v152 offset:3072
	s_add_u32 s12, s18, 0x160000
	s_addc_u32 s13, s19, 0
	s_mov_b32 m0, s42
	ds_read_b128 v[156:159], v139 offset:32768
	ds_read_b128 v[160:163], v139 offset:33792
	ds_read_b128 v[164:167], v139 offset:34816
	ds_read_b128 v[168:171], v139 offset:35840
	ds_read_b128 v[172:175], v139 offset:36864
	ds_read_b128 v[176:179], v139 offset:37888
	ds_read_b128 v[180:183], v139 offset:38912
	global_load_lds_dwordx4 v0, s[12:13]
	s_mov_b32 m0, s43
	ds_read_b128 v[184:187], v139 offset:39936
	global_load_lds_dwordx4 v130, s[12:13]
	s_waitcnt lgkmcnt(8)
	s_barrier
	s_waitcnt lgkmcnt(0)
	v_mfma_f32_16x16x32_bf16 v[126:129], v[140:143], v[156:159], v[126:129]
	v_mfma_f32_16x16x32_bf16 v[122:125], v[148:151], v[156:159], v[122:125]
	v_mfma_f32_16x16x32_bf16 v[118:121], v[140:143], v[164:167], v[118:121]
	v_mfma_f32_16x16x32_bf16 v[114:117], v[148:151], v[164:167], v[114:117]
	v_mfma_f32_16x16x32_bf16 v[106:109], v[140:143], v[172:175], v[106:109]
	v_mfma_f32_16x16x32_bf16 v[98:101], v[148:151], v[172:175], v[98:101]
	v_mfma_f32_16x16x32_bf16 v[90:93], v[140:143], v[180:183], v[90:93]
	v_mfma_f32_16x16x32_bf16 v[82:85], v[148:151], v[180:183], v[82:85]
	v_mfma_f32_16x16x32_bf16 v[126:129], v[144:147], v[160:163], v[126:129]
	v_mfma_f32_16x16x32_bf16 v[122:125], v[152:155], v[160:163], v[122:125]
	v_mfma_f32_16x16x32_bf16 v[118:121], v[144:147], v[168:171], v[118:121]
	v_mfma_f32_16x16x32_bf16 v[114:117], v[152:155], v[168:171], v[114:117]
	v_mfma_f32_16x16x32_bf16 v[106:109], v[144:147], v[176:179], v[106:109]
	v_mfma_f32_16x16x32_bf16 v[98:101], v[152:155], v[176:179], v[98:101]
	v_mfma_f32_16x16x32_bf16 v[90:93], v[144:147], v[184:187], v[90:93]
	v_mfma_f32_16x16x32_bf16 v[82:85], v[152:155], v[184:187], v[82:85]
	s_barrier
	s_add_i32 s18, 0, 0x1c000
	s_add_i32 s12, s53, s39
	v_add_u32_e32 v200, s18, v137
	s_add_u32 s98, s16, s36
	s_addc_u32 s99, s17, s37
	s_mov_b32 m0, s12
	ds_read_b128 v[188:191], v200
	ds_read_b128 v[192:195], v200 offset:1024
	ds_read_b128 v[196:199], v200 offset:2048
	ds_read_b128 v[200:203], v200 offset:3072
	global_load_lds_dwordx4 v0, s[98:99]
	s_add_i32 m0, s12, 0x2000
	s_add_u32 s98, s16, s36
	s_addc_u32 s99, s17, s37
	global_load_lds_dwordx4 v130, s[98:99]
	s_barrier
	s_waitcnt lgkmcnt(0)
	v_mfma_f32_16x16x32_bf16 v[110:113], v[188:191], v[156:159], v[110:113]
	v_mfma_f32_16x16x32_bf16 v[102:105], v[196:199], v[156:159], v[102:105]
	v_mfma_f32_16x16x32_bf16 v[94:97], v[188:191], v[164:167], v[94:97]
	v_mfma_f32_16x16x32_bf16 v[86:89], v[196:199], v[164:167], v[86:89]
	v_mfma_f32_16x16x32_bf16 v[78:81], v[188:191], v[172:175], v[78:81]
	v_mfma_f32_16x16x32_bf16 v[74:77], v[196:199], v[172:175], v[74:77]
	v_mfma_f32_16x16x32_bf16 v[70:73], v[188:191], v[180:183], v[70:73]
	v_mfma_f32_16x16x32_bf16 v[66:69], v[196:199], v[180:183], v[66:69]
	v_mfma_f32_16x16x32_bf16 v[110:113], v[192:195], v[160:163], v[110:113]
	v_mfma_f32_16x16x32_bf16 v[102:105], v[200:203], v[160:163], v[102:105]
	v_mfma_f32_16x16x32_bf16 v[94:97], v[192:195], v[168:171], v[94:97]
	v_mfma_f32_16x16x32_bf16 v[86:89], v[200:203], v[168:171], v[86:89]
	v_mfma_f32_16x16x32_bf16 v[78:81], v[192:195], v[176:179], v[78:81]
	v_mfma_f32_16x16x32_bf16 v[74:77], v[200:203], v[176:179], v[74:77]
	v_mfma_f32_16x16x32_bf16 v[70:73], v[192:195], v[184:187], v[70:73]
	v_mfma_f32_16x16x32_bf16 v[66:69], v[200:203], v[184:187], v[66:69]
	s_mov_b32 m0, s45
	v_lshl_add_u64 v[204:205], v[208:209], 0, s[36:37]
	s_barrier
	ds_read_b128 v[156:159], v139 offset:49152
	ds_read_b128 v[160:163], v139 offset:50176
	ds_read_b128 v[164:167], v139 offset:51200
	ds_read_b128 v[168:171], v139 offset:52224
	ds_read_b128 v[172:175], v139 offset:53248
	ds_read_b128 v[176:179], v139 offset:54272
	ds_read_b128 v[180:183], v139 offset:55296
	ds_read_b128 v[184:187], v139 offset:56320
	global_load_lds_dwordx4 v[204:205], off
	s_mov_b32 m0, s46
	v_lshl_add_u64 v[204:205], v[210:211], 0, s[36:37]
	global_load_lds_dwordx4 v[204:205], off
	s_barrier
; #define PG8_STAGE(bufoff, gbase, voff) do { _Pragma("unroll") for (int _i = 0; _i < 2; ++_i) \
;         __builtin_amdgcn_global_load_lds((const unsigned*)((const char*)(gbase) + (voff)[_i]), (LAS unsigned*)(lds + (bufoff) + ldsw + _i * 8192), 16, 0, 0); } while (0)
; #define PG8_MMA(ai, bj, At, Bt) do { __builtin_amdgcn_s_setprio(1); _Pragma("unroll") for (int m = 0; m < 4; ++m) _Pragma("unroll") for (int n = 0; n < 2; ++n) _Pragma("unroll") for (int k = 0; k < 2; ++k) \
;         acc[ai][bj][m][n] = __builtin_amdgcn_mfma_f32_16x16x32_bf16(Bt[n][k], At[m][k], acc[ai][bj][m][n], 0, 0, 0); __builtin_amdgcn_s_setprio(0); } while (0)
; #define PG8_WAIT_V(n) asm volatile("s_waitcnt vmcnt(" #n ")" ::: "memory")
; #define PG8_WAIT_L(n) asm volatile("s_waitcnt lgkmcnt(" #n ")" ::: "memory")
; #define PG8_BAR __builtin_amdgcn_s_barrier()
; #define PG8_SCHED __builtin_amdgcn_sched_barrier(0)
;     __device__ __forceinline__ void operator()(const f32x4 (&acc)[2][2][4][2], const Unit& u, int wr, int wc, int fr, int fq) const {
;         const int row0 = u.pm * BM + wr * 64 + fr, col0 = u.pn * BM + wc * 32 + 4 * fq;
;         float* base = (u.nt < ntfull) ? part + ((size_t)u.ks * MCTX - MLAT) * ldc : C;
; #pragma unroll
;         for (int ai = 0; ai < 2; ++ai)
; #pragma unroll
;             for (int m = 0; m < 4; ++m) { float* rowp = base + (size_t)(row0 + ai * HALF + m * 16) * ldc + col0;
; #pragma unroll
;                 for (int bj = 0; bj < 2; ++bj)
; #pragma unroll
;                     for (int n = 0; n < 2; ++n) *(f32x4*)(rowp + bj * HALF + n * 16) = acc[ai][bj][m][n]; }
;     }
; template <class Epi, class Sched>
; __device__ __forceinline__ void gemm_phase(LAS unsigned char* lds, const Gemm g, const Sched& S, const Epi& E, const int tid) {
;     ...
;             PG8_BAR; PG8_WAIT_L(0); PG8_MMA(1, 0, At, B0); PG8_BAR; PG8_SCHED;
;             PG8_STAGE(PG8_SB(1, 1), b3 + hstep, voffB);
;             PG8_WAIT_V(6); PG8_BAR; PG8_MMA(1, 1, At, B1); PG8_BAR;
;         }
;         if constexpr (!Epi::AFTER_DRAIN) { if constexpr (Epi::PRELOAD) E(acc, cur, wr, wc, fr, fq, lds); else E(acc, cur, wr, wc, fr, fq); S.done(cur); }
	s_waitcnt lgkmcnt(0)
	v_mfma_f32_16x16x32_bf16 v[62:65], v[140:143], v[156:159], v[62:65]
	v_mfma_f32_16x16x32_bf16 v[58:61], v[148:151], v[156:159], v[58:61]
	v_mfma_f32_16x16x32_bf16 v[54:57], v[140:143], v[164:167], v[54:57]
	v_mfma_f32_16x16x32_bf16 v[50:53], v[148:151], v[164:167], v[50:53]
	v_mfma_f32_16x16x32_bf16 v[38:41], v[140:143], v[172:175], v[38:41]
	v_mfma_f32_16x16x32_bf16 v[34:37], v[148:151], v[172:175], v[34:37]
	v_mfma_f32_16x16x32_bf16 v[22:25], v[140:143], v[180:183], v[22:25]
	v_mfma_f32_16x16x32_bf16 v[18:21], v[148:151], v[180:183], v[18:21]
	v_mfma_f32_16x16x32_bf16 v[62:65], v[144:147], v[160:163], v[62:65]
	v_mfma_f32_16x16x32_bf16 v[58:61], v[152:155], v[160:163], v[58:61]
	v_mfma_f32_16x16x32_bf16 v[54:57], v[144:147], v[168:171], v[54:57]
	v_mfma_f32_16x16x32_bf16 v[50:53], v[152:155], v[168:171], v[50:53]
	v_mfma_f32_16x16x32_bf16 v[38:41], v[144:147], v[176:179], v[38:41]
	v_mfma_f32_16x16x32_bf16 v[34:37], v[152:155], v[176:179], v[34:37]
	v_mfma_f32_16x16x32_bf16 v[22:25], v[144:147], v[184:187], v[22:25]
	v_mfma_f32_16x16x32_bf16 v[18:21], v[152:155], v[184:187], v[18:21]
	s_barrier
	s_add_u32 s12, s16, 0x160080
	s_addc_u32 s13, s17, 0
	s_add_i32 s16, s18, s39
	s_mov_b32 m0, s16
	s_nop 0
	global_load_lds_dwordx4 v0, s[12:13]
	s_add_i32 m0, s16, 0x2000
	s_nop 0
	global_load_lds_dwordx4 v130, s[12:13]
	s_waitcnt vmcnt(6)
	s_barrier
	v_mfma_f32_16x16x32_bf16 v[46:49], v[188:191], v[156:159], v[46:49]
	v_mfma_f32_16x16x32_bf16 v[42:45], v[196:199], v[156:159], v[42:45]
	v_mfma_f32_16x16x32_bf16 v[30:33], v[188:191], v[164:167], v[30:33]
	v_mfma_f32_16x16x32_bf16 v[26:29], v[196:199], v[164:167], v[26:29]
	v_mfma_f32_16x16x32_bf16 v[14:17], v[188:191], v[172:175], v[14:17]
	v_mfma_f32_16x16x32_bf16 v[10:13], v[196:199], v[172:175], v[10:13]
	v_mfma_f32_16x16x32_bf16 v[6:9], v[188:191], v[180:183], v[6:9]
	v_mfma_f32_16x16x32_bf16 v[2:5], v[196:199], v[180:183], v[2:5]
	v_mfma_f32_16x16x32_bf16 v[46:49], v[192:195], v[160:163], v[46:49]
	v_mfma_f32_16x16x32_bf16 v[42:45], v[200:203], v[160:163], v[42:45]
	v_mfma_f32_16x16x32_bf16 v[30:33], v[192:195], v[168:171], v[30:33]
	v_mfma_f32_16x16x32_bf16 v[26:29], v[200:203], v[168:171], v[26:29]
	v_mfma_f32_16x16x32_bf16 v[14:17], v[192:195], v[176:179], v[14:17]
	v_mfma_f32_16x16x32_bf16 v[10:13], v[200:203], v[176:179], v[10:13]
	v_mfma_f32_16x16x32_bf16 v[6:9], v[192:195], v[184:187], v[6:9]
	v_mfma_f32_16x16x32_bf16 v[2:5], v[200:203], v[184:187], v[2:5]
	s_add_i32 s52, s52, 2
	s_add_u32 s5, s5, 0x100
	s_addc_u32 s11, s11, 0
	s_cmp_gt_u32 s52, 5
	s_mov_b64 s[12:13], s[14:15]
	s_barrier
	s_cbranch_scc0 .LBB0_1680
	s_ashr_i32 s5, s4, 31
	s_lshl_b64 s[4:5], s[4:5], 22
	s_add_u32 s4, s47, s4
	v_lshl_or_b32 v140, s40, 8, v138
	v_lshl_add_u32 v142, s29, 8, v136
	s_addc_u32 s5, s48, s5
	v_ashrrev_i32_e32 v141, 31, v140
	v_ashrrev_i32_e32 v143, 31, v142
	v_lshl_add_u64 v[140:141], v[140:141], 2, s[4:5]
	v_lshlrev_b64 v[144:145], 13, v[142:143]
	v_lshl_add_u64 v[144:145], v[140:141], 0, v[144:145]
	global_store_dwordx4 v[144:145], v[126:129], off
	global_store_dwordx4 v[144:145], v[122:125], off offset:64
	global_store_dwordx4 v[144:145], v[110:113], off offset:512
	global_store_dwordx4 v[144:145], v[102:105], off offset:576
	s_mov_b64 s[4:5], 0x100000
	s_mov_b32 s29, s50
	v_or_b32_e32 v102, 16, v142
	v_ashrrev_i32_e32 v103, 31, v102
	v_lshlrev_b64 v[102:103], 13, v[102:103]
	v_lshl_add_u64 v[102:103], v[140:141], 0, v[102:103]
	global_store_dwordx4 v[102:103], v[118:121], off
	global_store_dwordx4 v[102:103], v[114:117], off offset:64
	global_store_dwordx4 v[102:103], v[94:97], off offset:512
	global_store_dwordx4 v[102:103], v[86:89], off offset:576
	s_mov_b32 s40, s51
	s_mov_b64 s[14:15], s[2:3]
	v_or_b32_e32 v86, 32, v142
	v_ashrrev_i32_e32 v87, 31, v86
	v_lshlrev_b64 v[86:87], 13, v[86:87]
	v_lshl_add_u64 v[86:87], v[140:141], 0, v[86:87]
	global_store_dwordx4 v[86:87], v[106:109], off
	global_store_dwordx4 v[86:87], v[98:101], off offset:64
	global_store_dwordx4 v[86:87], v[78:81], off offset:512
	global_store_dwordx4 v[86:87], v[74:77], off offset:576
	s_mov_b64 s[12:13], s[6:7]
	s_mov_b64 s[52:53], 0xc000
	v_or_b32_e32 v74, 48, v142
	v_ashrrev_i32_e32 v75, 31, v74
	v_lshlrev_b64 v[74:75], 13, v[74:75]
	v_lshl_add_u64 v[74:75], v[140:141], 0, v[74:75]
	global_store_dwordx4 v[74:75], v[90:93], off
	global_store_dwordx4 v[74:75], v[82:85], off offset:64
	global_store_dwordx4 v[74:75], v[70:73], off offset:512
	global_store_dwordx4 v[74:75], v[66:69], off offset:576
	s_mov_b64 s[54:55], 0x8000
	s_nop 0
	v_lshl_add_u64 v[66:67], v[144:145], 0, s[4:5]
	s_mov_b32 s4, 0x100000
	v_add_co_u32_e32 v68, vcc, s4, v144
	s_mov_b64 s[4:5], 0x120000
	s_nop 0
	v_addc_co_u32_e32 v69, vcc, 0, v145, vcc
	global_store_dwordx4 v[68:69], v[62:65], off
	global_store_dwordx4 v[66:67], v[58:61], off offset:64
	global_store_dwordx4 v[66:67], v[46:49], off offset:512
	global_store_dwordx4 v[66:67], v[42:45], off offset:576
	s_nop 1
	v_lshl_add_u64 v[42:43], v[144:145], 0, s[4:5]
	s_mov_b32 s4, 0x120000
	v_add_co_u32_e32 v44, vcc, s4, v144
	s_mov_b64 s[4:5], 0x140000
	s_nop 0
	v_addc_co_u32_e32 v45, vcc, 0, v145, vcc
	global_store_dwordx4 v[44:45], v[54:57], off
	global_store_dwordx4 v[42:43], v[50:53], off offset:64
	global_store_dwordx4 v[42:43], v[30:33], off offset:512
	global_store_dwordx4 v[42:43], v[26:29], off offset:576
	s_nop 1
	v_lshl_add_u64 v[26:27], v[144:145], 0, s[4:5]
	s_mov_b32 s4, 0x140000
	v_add_co_u32_e32 v28, vcc, s4, v144
	s_mov_b64 s[4:5], 0x160000
	s_nop 0
	v_addc_co_u32_e32 v29, vcc, 0, v145, vcc
	global_store_dwordx4 v[28:29], v[38:41], off
	global_store_dwordx4 v[26:27], v[34:37], off offset:64
	global_store_dwordx4 v[26:27], v[14:17], off offset:512
	global_store_dwordx4 v[26:27], v[10:13], off offset:576
	s_nop 1
	v_add_co_u32_e32 v12, vcc, 0x160000, v144
	v_lshl_add_u64 v[10:11], v[144:145], 0, s[4:5]
	s_nop 0
	v_addc_co_u32_e32 v13, vcc, 0, v145, vcc
	s_and_b64 vcc, exec, s[0:1]
	s_mov_b32 s4, s10
	global_store_dwordx4 v[12:13], v[22:25], off
	global_store_dwordx4 v[10:11], v[18:21], off offset:64
	global_store_dwordx4 v[10:11], v[6:9], off offset:512
	global_store_dwordx4 v[10:11], v[2:5], off offset:576
	s_cbranch_vccz .LBB0_1675
	s_waitcnt vmcnt(0)
	s_cmpk_gt_u32 s21, 0xff
	s_cbranch_scc1 .LBB0_1684
	s_barrier
